# attention: running max folded into QK accumulator init (32 fewer v_sub per tile), tile loads via global saddr form; redundant vmcnt(0) dropped in remaining k-loops
# speedup vs baseline: 1.1163x; 1.0252x over previous
; template <int MI, int NI>
; DI void gemm256(f32x4 (&acc)[MI][NI], const u16* __restrict__ A, int lda, const u16* __restrict__ Bt, int ldb, int K, int m0, int n0, char* smem) {
;     ...
;   for (int kt = 0; kt < nk; ++kt) {
;     if (kt + 1 < nk) asm volatile("s_waitcnt vmcnt(%0) lgkmcnt(0)" :: "n"(LPS) : "memory");
;     else asm volatile("s_waitcnt vmcnt(0) lgkmcnt(0)" ::: "memory");
;     __builtin_amdgcn_s_barrier();
;     __builtin_amdgcn_s_setprio(1);
;     const char* sb = smem + st * STAGE + foff;
;     bf16x8 af[MI], bfr[NI];
; #pragma unroll
;     for (int mi = 0; mi < MI; ++mi) af[mi] = *(const bf16x8*)(sb + (wr * MI + mi) * 1024);
; #pragma unroll
;     for (int ni = 0; ni < NI; ++ni) bfr[ni] = *(const bf16x8*)(sb + ABYTES + (wc * NI + ni) * 1024);
;     __builtin_amdgcn_sched_barrier(0x0);
;     if (kt + 2 < nk) { const int s2 = st >= 1 ? st - 1 : 2; G256_ISSUE(s2, (kt + 2) * 32); }
;     __builtin_amdgcn_s_setprio(0);
; #pragma unroll
;     for (int mi = 0; mi < MI; ++mi)
; #pragma unroll
;       for (int ni = 0; ni < NI; ++ni)
;         acc[mi][ni] = __builtin_amdgcn_mfma_f32_16x16x32_bf16(bfr[ni], af[mi], acc[mi][ni], 0, 0, 0);
;     st = st == 2 ? 0 : st + 1;
;   }
.Lpipe_mlp1:
	v_add_u32_e32 v160, s11, v143
	ds_read_b128 v[164:167], v160 offset:4096
	ds_read_b128 v[168:171], v160 offset:5120
	ds_read_b128 v[172:175], v160 offset:6144
	ds_read_b128 v[176:179], v160 offset:7168
	s_add_i32 s12, s11, 0xffffa000
	s_cmp_eq_u32 s11, 0
	s_cselect_b32 s12, 0xc000, s12
	s_add_i32 s13, s12, s14
	s_add_i32 s12, s12, s4
	s_mov_b32 m0, s13
	s_waitcnt lgkmcnt(7)
	v_mfma_f32_16x16x32_bf16 v[126:129], v[180:183], v[144:147], v[126:129]
	global_load_lds_dwordx4 v[198:199], off
	v_mfma_f32_16x16x32_bf16 v[110:113], v[180:183], v[148:151], v[110:113]
	v_lshl_add_u64 v[198:199], v[198:199], 0, s[98:99]
	s_add_i32 m0, s13, 0x400
	v_mfma_f32_16x16x32_bf16 v[94:97], v[180:183], v[152:155], v[94:97]
	global_load_lds_dwordx4 v[200:201], off
	v_mfma_f32_16x16x32_bf16 v[78:81], v[180:183], v[156:159], v[78:81]
	v_lshl_add_u64 v[200:201], v[200:201], 0, s[98:99]
	s_add_i32 m0, s13, 0x800
	s_waitcnt lgkmcnt(6)
	v_mfma_f32_16x16x32_bf16 v[122:125], v[184:187], v[144:147], v[122:125]
	global_load_lds_dwordx4 v[202:203], off
	v_mfma_f32_16x16x32_bf16 v[106:109], v[184:187], v[148:151], v[106:109]
	v_lshl_add_u64 v[202:203], v[202:203], 0, s[98:99]
	s_add_i32 m0, s13, 0xc00
	v_mfma_f32_16x16x32_bf16 v[90:93], v[184:187], v[152:155], v[90:93]
	global_load_lds_dwordx4 v[204:205], off
	v_mfma_f32_16x16x32_bf16 v[74:77], v[184:187], v[156:159], v[74:77]
	v_lshl_add_u64 v[204:205], v[204:205], 0, s[98:99]
	s_mov_b32 m0, s12
	s_waitcnt lgkmcnt(5)
	v_mfma_f32_16x16x32_bf16 v[118:121], v[188:191], v[144:147], v[118:121]
	global_load_lds_dwordx4 v[206:207], off
	v_mfma_f32_16x16x32_bf16 v[102:105], v[188:191], v[148:151], v[102:105]
	v_lshl_add_u64 v[206:207], v[206:207], 0, s[98:99]
	s_add_i32 m0, s12, 0x400
	v_mfma_f32_16x16x32_bf16 v[86:89], v[188:191], v[152:155], v[86:89]
	global_load_lds_dwordx4 v[208:209], off
	v_mfma_f32_16x16x32_bf16 v[70:73], v[188:191], v[156:159], v[70:73]
	v_lshl_add_u64 v[208:209], v[208:209], 0, s[98:99]
	s_waitcnt lgkmcnt(4)
	v_mfma_f32_16x16x32_bf16 v[114:117], v[192:195], v[144:147], v[114:117]
	v_mfma_f32_16x16x32_bf16 v[98:101], v[192:195], v[148:151], v[98:101]
	v_mfma_f32_16x16x32_bf16 v[82:85], v[192:195], v[152:155], v[82:85]
	v_mfma_f32_16x16x32_bf16 v[66:69], v[192:195], v[156:159], v[66:69]
	s_waitcnt vmcnt(6) lgkmcnt(0)
	s_barrier
	s_add_i32 s13, s11, 0x6000
	s_cmp_eq_u32 s11, 0xc000
	s_cselect_b32 s11, 0, s13
	v_add_u32_e32 v196, s11, v143
	v_add_u32_e32 v197, s11, v0
	v_mfma_f32_16x16x32_bf16 v[62:65], v[180:183], v[164:167], v[62:65]
	ds_read_b128 v[144:147], v196
	v_mfma_f32_16x16x32_bf16 v[46:49], v[180:183], v[168:171], v[46:49]
	ds_read_b128 v[148:151], v196 offset:1024
	v_mfma_f32_16x16x32_bf16 v[30:33], v[180:183], v[172:175], v[30:33]
	ds_read_b128 v[152:155], v196 offset:2048
	v_mfma_f32_16x16x32_bf16 v[14:17], v[180:183], v[176:179], v[14:17]
	ds_read_b128 v[156:159], v196 offset:3072
	ds_read_b128 v[180:183], v197 offset:16384
	v_mfma_f32_16x16x32_bf16 v[58:61], v[184:187], v[164:167], v[58:61]
	v_mfma_f32_16x16x32_bf16 v[42:45], v[184:187], v[168:171], v[42:45]
	v_mfma_f32_16x16x32_bf16 v[26:29], v[184:187], v[172:175], v[26:29]
	v_mfma_f32_16x16x32_bf16 v[10:13], v[184:187], v[176:179], v[10:13]
	ds_read_b128 v[184:187], v197 offset:17408
	v_mfma_f32_16x16x32_bf16 v[54:57], v[188:191], v[164:167], v[54:57]
	v_mfma_f32_16x16x32_bf16 v[38:41], v[188:191], v[168:171], v[38:41]
	v_mfma_f32_16x16x32_bf16 v[22:25], v[188:191], v[172:175], v[22:25]
	v_mfma_f32_16x16x32_bf16 v[6:9], v[188:191], v[176:179], v[6:9]
	ds_read_b128 v[188:191], v197 offset:18432
	v_mfma_f32_16x16x32_bf16 v[50:53], v[192:195], v[164:167], v[50:53]
	v_mfma_f32_16x16x32_bf16 v[34:37], v[192:195], v[168:171], v[34:37]
	v_mfma_f32_16x16x32_bf16 v[18:21], v[192:195], v[172:175], v[18:21]
	v_mfma_f32_16x16x32_bf16 v[2:5], v[192:195], v[176:179], v[2:5]
	ds_read_b128 v[192:195], v197 offset:19456
	s_sub_i32 s5, s5, 1
	s_cmp_lg_u32 s5, 0
	s_cbranch_scc1 .Lpipe_mlp1
	v_add_u32_e32 v160, s11, v143
	ds_read_b128 v[164:167], v160 offset:4096
	ds_read_b128 v[168:171], v160 offset:5120
	ds_read_b128 v[172:175], v160 offset:6144
	ds_read_b128 v[176:179], v160 offset:7168
	s_add_i32 s12, s11, 0xffffa000
	s_cmp_eq_u32 s11, 0
	s_cselect_b32 s12, 0xc000, s12
	s_add_i32 s13, s12, s14
	s_add_i32 s12, s12, s4
	s_mov_b32 m0, s13
	s_waitcnt lgkmcnt(7)
	v_mfma_f32_16x16x32_bf16 v[126:129], v[180:183], v[144:147], v[126:129]
	global_load_lds_dwordx4 v[198:199], off
	v_mfma_f32_16x16x32_bf16 v[110:113], v[180:183], v[148:151], v[110:113]
	v_lshl_add_u64 v[198:199], v[198:199], 0, s[98:99]
	s_add_i32 m0, s13, 0x400
	v_mfma_f32_16x16x32_bf16 v[94:97], v[180:183], v[152:155], v[94:97]
	global_load_lds_dwordx4 v[200:201], off
	v_mfma_f32_16x16x32_bf16 v[78:81], v[180:183], v[156:159], v[78:81]
	v_lshl_add_u64 v[200:201], v[200:201], 0, s[98:99]
	s_add_i32 m0, s13, 0x800
	s_waitcnt lgkmcnt(6)
	v_mfma_f32_16x16x32_bf16 v[122:125], v[184:187], v[144:147], v[122:125]
	global_load_lds_dwordx4 v[202:203], off
	v_mfma_f32_16x16x32_bf16 v[106:109], v[184:187], v[148:151], v[106:109]
	v_lshl_add_u64 v[202:203], v[202:203], 0, s[98:99]
	s_add_i32 m0, s13, 0xc00
	v_mfma_f32_16x16x32_bf16 v[90:93], v[184:187], v[152:155], v[90:93]
	global_load_lds_dwordx4 v[204:205], off
	v_mfma_f32_16x16x32_bf16 v[74:77], v[184:187], v[156:159], v[74:77]
	v_lshl_add_u64 v[204:205], v[204:205], 0, s[98:99]
	s_mov_b32 m0, s12
	s_waitcnt lgkmcnt(5)
; template <int MI, int NI>
; DI void gemm256(f32x4 (&acc)[MI][NI], const u16* __restrict__ A, int lda, const u16* __restrict__ Bt, int ldb, int K, int m0, int n0, char* smem) {
;     ...
;   for (int kt = 0; kt < nk; ++kt) {
;     if (kt + 1 < nk) asm volatile("s_waitcnt vmcnt(%0) lgkmcnt(0)" :: "n"(LPS) : "memory");
;     else asm volatile("s_waitcnt vmcnt(0) lgkmcnt(0)" ::: "memory");
;     __builtin_amdgcn_s_barrier();
;     __builtin_amdgcn_s_setprio(1);
;     const char* sb = smem + st * STAGE + foff;
;     bf16x8 af[MI], bfr[NI];
; #pragma unroll
;     for (int mi = 0; mi < MI; ++mi) af[mi] = *(const bf16x8*)(sb + (wr * MI + mi) * 1024);
; #pragma unroll
;     for (int ni = 0; ni < NI; ++ni) bfr[ni] = *(const bf16x8*)(sb + ABYTES + (wc * NI + ni) * 1024);
;     __builtin_amdgcn_sched_barrier(0x0);
;     if (kt + 2 < nk) { const int s2 = st >= 1 ? st - 1 : 2; G256_ISSUE(s2, (kt + 2) * 32); }
;     __builtin_amdgcn_s_setprio(0);
; #pragma unroll
;     for (int mi = 0; mi < MI; ++mi)
; #pragma unroll
;       for (int ni = 0; ni < NI; ++ni)
;         acc[mi][ni] = __builtin_amdgcn_mfma_f32_16x16x32_bf16(bfr[ni], af[mi], acc[mi][ni], 0, 0, 0);
;     st = st == 2 ? 0 : st + 1;
;   }
;   asm volatile("s_waitcnt lgkmcnt(0)" ::: "memory");
;   __builtin_amdgcn_s_barrier();
	v_mfma_f32_16x16x32_bf16 v[118:121], v[188:191], v[144:147], v[118:121]
	global_load_lds_dwordx4 v[206:207], off
	v_mfma_f32_16x16x32_bf16 v[102:105], v[188:191], v[148:151], v[102:105]
	v_lshl_add_u64 v[206:207], v[206:207], 0, s[98:99]
	s_add_i32 m0, s12, 0x400
	v_mfma_f32_16x16x32_bf16 v[86:89], v[188:191], v[152:155], v[86:89]
	global_load_lds_dwordx4 v[208:209], off
	v_mfma_f32_16x16x32_bf16 v[70:73], v[188:191], v[156:159], v[70:73]
	v_lshl_add_u64 v[208:209], v[208:209], 0, s[98:99]
	s_waitcnt lgkmcnt(4)
	v_mfma_f32_16x16x32_bf16 v[114:117], v[192:195], v[144:147], v[114:117]
	v_mfma_f32_16x16x32_bf16 v[98:101], v[192:195], v[148:151], v[98:101]
	v_mfma_f32_16x16x32_bf16 v[82:85], v[192:195], v[152:155], v[82:85]
	v_mfma_f32_16x16x32_bf16 v[66:69], v[192:195], v[156:159], v[66:69]
	s_waitcnt lgkmcnt(0)
	v_mfma_f32_16x16x32_bf16 v[62:65], v[180:183], v[164:167], v[62:65]
	v_mfma_f32_16x16x32_bf16 v[46:49], v[180:183], v[168:171], v[46:49]
	v_mfma_f32_16x16x32_bf16 v[30:33], v[180:183], v[172:175], v[30:33]
	v_mfma_f32_16x16x32_bf16 v[14:17], v[180:183], v[176:179], v[14:17]
	v_mfma_f32_16x16x32_bf16 v[58:61], v[184:187], v[164:167], v[58:61]
	v_mfma_f32_16x16x32_bf16 v[42:45], v[184:187], v[168:171], v[42:45]
	v_mfma_f32_16x16x32_bf16 v[26:29], v[184:187], v[172:175], v[26:29]
	v_mfma_f32_16x16x32_bf16 v[10:13], v[184:187], v[176:179], v[10:13]
	v_mfma_f32_16x16x32_bf16 v[54:57], v[188:191], v[164:167], v[54:57]
	v_mfma_f32_16x16x32_bf16 v[38:41], v[188:191], v[168:171], v[38:41]
	v_mfma_f32_16x16x32_bf16 v[22:25], v[188:191], v[172:175], v[22:25]
	v_mfma_f32_16x16x32_bf16 v[6:9], v[188:191], v[176:179], v[6:9]
	v_mfma_f32_16x16x32_bf16 v[50:53], v[192:195], v[164:167], v[50:53]
	v_mfma_f32_16x16x32_bf16 v[34:37], v[192:195], v[168:171], v[34:37]
	v_mfma_f32_16x16x32_bf16 v[18:21], v[192:195], v[172:175], v[18:21]
	v_mfma_f32_16x16x32_bf16 v[2:5], v[192:195], v[176:179], v[2:5]
	s_waitcnt vmcnt(6) lgkmcnt(0)
	s_barrier
	s_setprio 1
	v_add_u32_e32 v0, v140, v142
	ds_read_b128 v[130:133], v0
	ds_read_b128 v[142:145], v0 offset:1024
	ds_read_b128 v[146:149], v0 offset:2048
	ds_read_b128 v[150:153], v0 offset:3072
	ds_read_b128 v[154:157], v0 offset:4096
	ds_read_b128 v[158:161], v0 offset:5120
	ds_read_b128 v[164:167], v0 offset:6144
	ds_read_b128 v[168:171], v0 offset:7168
	v_add_u32_e32 v212, v140, v141
	ds_read_b128 v[138:141], v212 offset:16384
	ds_read_b128 v[172:175], v212 offset:17408
	ds_read_b128 v[176:179], v212 offset:18432
	ds_read_b128 v[180:183], v212 offset:19456
	s_setprio 0
	s_waitcnt vmcnt(0) lgkmcnt(0)
	s_waitcnt lgkmcnt(3)
	v_mfma_f32_16x16x32_bf16 v[126:129], v[138:141], v[130:133], v[126:129]
	s_barrier
	s_waitcnt lgkmcnt(2)
	v_mfma_f32_16x16x32_bf16 v[122:125], v[172:175], v[130:133], v[122:125]
	s_waitcnt lgkmcnt(1)
	v_mfma_f32_16x16x32_bf16 v[184:187], v[176:179], v[130:133], v[118:121]
	s_waitcnt lgkmcnt(0)
	v_mfma_f32_16x16x32_bf16 v[114:117], v[180:183], v[130:133], v[114:117]
	v_mfma_f32_16x16x32_bf16 v[130:133], v[138:141], v[142:145], v[110:113]
	v_mfma_f32_16x16x32_bf16 v[106:109], v[172:175], v[142:145], v[106:109]
	v_mfma_f32_16x16x32_bf16 v[188:191], v[176:179], v[142:145], v[102:105]
	v_mfma_f32_16x16x32_bf16 v[98:101], v[180:183], v[142:145], v[98:101]
	v_mfma_f32_16x16x32_bf16 v[94:97], v[138:141], v[146:149], v[94:97]
	v_mfma_f32_16x16x32_bf16 v[90:93], v[172:175], v[146:149], v[90:93]
	v_mfma_f32_16x16x32_bf16 v[142:145], v[176:179], v[146:149], v[86:89]
	v_mfma_f32_16x16x32_bf16 v[82:85], v[180:183], v[146:149], v[82:85]
	v_mfma_f32_16x16x32_bf16 v[146:149], v[138:141], v[150:153], v[78:81]
	v_mfma_f32_16x16x32_bf16 v[74:77], v[172:175], v[150:153], v[74:77]
	v_mfma_f32_16x16x32_bf16 v[192:195], v[176:179], v[150:153], v[70:73]
	v_mfma_f32_16x16x32_bf16 v[66:69], v[180:183], v[150:153], v[66:69]
	v_mfma_f32_16x16x32_bf16 v[62:65], v[138:141], v[154:157], v[62:65]
	v_mfma_f32_16x16x32_bf16 v[58:61], v[172:175], v[154:157], v[58:61]
	v_mfma_f32_16x16x32_bf16 v[150:153], v[176:179], v[154:157], v[54:57]
	v_mfma_f32_16x16x32_bf16 v[50:53], v[180:183], v[154:157], v[50:53]
	v_mfma_f32_16x16x32_bf16 v[154:157], v[138:141], v[158:161], v[46:49]
	v_mfma_f32_16x16x32_bf16 v[42:45], v[172:175], v[158:161], v[42:45]
	v_mfma_f32_16x16x32_bf16 v[196:199], v[176:179], v[158:161], v[38:41]
	v_mfma_f32_16x16x32_bf16 v[34:37], v[180:183], v[158:161], v[34:37]
	v_mfma_f32_16x16x32_bf16 v[30:33], v[138:141], v[164:167], v[30:33]
	v_mfma_f32_16x16x32_bf16 v[26:29], v[172:175], v[164:167], v[26:29]
	v_mfma_f32_16x16x32_bf16 v[158:161], v[176:179], v[164:167], v[22:25]
	v_mfma_f32_16x16x32_bf16 v[18:21], v[180:183], v[164:167], v[18:21]
	v_mfma_f32_16x16x32_bf16 v[138:141], v[138:141], v[168:171], v[14:17]
	v_mfma_f32_16x16x32_bf16 v[10:13], v[172:175], v[168:171], v[10:13]
	v_mfma_f32_16x16x32_bf16 v[164:167], v[176:179], v[168:171], v[6:9]
	v_mfma_f32_16x16x32_bf16 v[2:5], v[180:183], v[168:171], v[2:5]
	s_setprio 1
	s_nop 0
	ds_read_b128 v[6:9], v0 offset:24576
	ds_read_b128 v[14:17], v0 offset:25600
	ds_read_b128 v[22:25], v0 offset:26624
	ds_read_b128 v[38:41], v0 offset:27648
	ds_read_b128 v[168:171], v0 offset:28672
	ds_read_b128 v[172:175], v0 offset:29696
	ds_read_b128 v[176:179], v0 offset:30720
	ds_read_b128 v[180:183], v0 offset:31744
	ds_read_b128 v[200:203], v212 offset:40960
	ds_read_b128 v[204:207], v212 offset:41984
	ds_read_b128 v[208:211], v212 offset:43008
	ds_read_b128 v[212:215], v212 offset:44032
	s_setprio 0
	s_waitcnt lgkmcnt(3)
	v_mfma_f32_16x16x32_bf16 v[216:219], v[200:203], v[6:9], v[126:129]
	v_mov_b32_e32 v0, v136
	s_waitcnt lgkmcnt(0)
	s_barrier
; DI unsigned pack2(float a, float b) { float2_t v = {a, b}; bf16x2_t r = __builtin_convertvector(v, bf16x2_t); return __builtin_bit_cast(unsigned, r); }
; DI uint4 widen16(uint2 a, uint2 b) {
;   const auto r0 = __builtin_amdgcn_permlane16_swap(a.x, b.x, false, false);
;   const auto r1 = __builtin_amdgcn_permlane16_swap(a.y, b.y, false, false);
;   return make_uint4(r0[0], r1[0], r0[1], r1[1]);
; }
; DI void phase_mlp1(const Params& p, int l, int Mout, char* smem) {
;     ...
;     for (int mi = 0; mi < 8; mi += 2) {
;       const int m = m0 + wr * 128 + (mi + (lq & 1)) * 16 + lr;
; #pragma unroll
;       for (int ni = 0; ni < 4; ++ni) {
;         const int n = n0 + wc * 64 + ni * 16 + (lq >> 1) * 8;
;         float va[4], vb[4];
; #pragma unroll
;         for (int j = 0; j < 4; ++j) { const float a = fmaxf(acc[mi][ni][j], 0.f); va[j] = a * a; const float b = fmaxf(acc[mi + 1][ni][j], 0.f); vb[j] = b * b; }
;         *(uint4*)(U + (size_t)m * DFF + n) = widen16(make_uint2(pack2(va[0], va[1]), pack2(va[2], va[3])), make_uint2(pack2(vb[0], vb[1]), pack2(vb[2], vb[3])));
;       }
;       __builtin_amdgcn_sched_barrier(0);
;     }
	s_waitcnt lgkmcnt(2)
	v_mfma_f32_16x16x32_bf16 v[118:121], v[204:207], v[6:9], v[122:125]
	v_mov_b32_e32 v126, v137
	v_mov_b32_e32 v127, v134
	v_lshlrev_b32_e32 v129, 2, v126
	v_lshlrev_b32_e32 v126, 4, v126
	v_mfma_f32_16x16x32_bf16 v[122:125], v[200:203], v[14:17], v[130:133]
	v_mov_b32_e32 v128, v135
	v_lshlrev_b32_e32 v127, 7, v127
	v_add_u32_e32 v0, s10, v0
	v_and_b32_e32 v126, 16, v126
	v_add3_u32 v126, v0, v127, v126
	v_lshlrev_b32_e32 v128, 6, v128
	v_and_b32_e32 v129, -8, v129
	v_ashrrev_i32_e32 v127, 31, v126
	v_add3_u32 v132, v129, s9, v128
	v_and_b32_e32 v220, 1, v126
	v_lshrrev_b32_e32 v128, 1, v126
	v_mov_b32_e32 v129, 0
	v_lshlrev_b64 v[128:129], 14, v[128:129]
	v_lshl_or_b32 v128, v220, 6, v128
	v_max_f32_e32 v0, v216, v216
	v_mfma_f32_16x16x32_bf16 v[94:97], v[200:203], v[22:25], v[94:97]
	v_ashrrev_i32_e32 v133, 31, v132
	v_mfma_f32_16x16x32_bf16 v[86:89], v[204:207], v[22:25], v[90:93]
	s_waitcnt lgkmcnt(1)
	v_mfma_f32_16x16x32_bf16 v[78:81], v[208:211], v[22:25], v[142:145]
	s_waitcnt lgkmcnt(0)
	v_mfma_f32_16x16x32_bf16 v[70:73], v[212:215], v[22:25], v[82:85]
	v_mfma_f32_16x16x32_bf16 v[22:25], v[204:207], v[176:179], v[26:29]
	v_mfma_f32_16x16x32_bf16 v[26:29], v[200:203], v[180:183], v[138:141]
	s_nop 2
	v_lshl_add_u64 v[138:139], s[60:61], 0, v[128:129]
	v_max_f32_e32 v128, 0, v0
	v_max_f32_e32 v0, v122, v122
	v_max_f32_e32 v122, 0, v0
	v_max_f32_e32 v0, v217, v217
	v_max_f32_e32 v129, 0, v0
	v_max_f32_e32 v0, v123, v123
	v_max_f32_e32 v123, 0, v0
	v_max_f32_e32 v0, v218, v218
	v_mfma_f32_16x16x32_bf16 v[102:105], v[212:215], v[6:9], v[114:117]
	v_max_f32_e32 v130, 0, v0
	v_max_f32_e32 v0, v124, v124
	v_max_f32_e32 v124, 0, v0
	v_mfma_f32_16x16x32_bf16 v[114:117], v[204:207], v[14:17], v[106:109]
	v_max_f32_e32 v0, v219, v219
	v_max_f32_e32 v131, 0, v0
	v_max_f32_e32 v0, v125, v125
	v_max_f32_e32 v125, 0, v0
	v_max_f32_e32 v0, v118, v118
	v_max_f32_e32 v118, 0, v0
	s_nop 1
	v_max_f32_e32 v0, v114, v114
	v_pk_mul_f32 v[128:129], v[128:129], v[128:129]
	v_pk_mul_f32 v[122:123], v[122:123], v[122:123]
	v_pk_mul_f32 v[130:131], v[130:131], v[130:131]
	v_pk_mul_f32 v[124:125], v[124:125], v[124:125]
	v_max_f32_e32 v114, 0, v0
	v_max_f32_e32 v0, v119, v119
	v_cvt_pk_bf16_f32 v128, v128, v129
	v_cvt_pk_bf16_f32 v129, v130, v131
	v_cvt_pk_bf16_f32 v130, v122, v123
	v_cvt_pk_bf16_f32 v131, v124, v125
	v_and_b32_e32 v220, 31, v132
	v_lshrrev_b32_e32 v122, 5, v132
	v_lshlrev_b32_e32 v122, 7, v122
	v_lshl_or_b32 v122, v220, 1, v122
	v_mov_b32_e32 v123, 0
	v_max_f32_e32 v119, 0, v0
	v_max_f32_e32 v0, v115, v115
	v_mfma_f32_16x16x32_bf16 v[110:113], v[208:211], v[6:9], v[184:187]
	v_permlane16_swap_b32_e32 v128, v130
	v_permlane16_swap_b32_e32 v129, v131
	v_lshl_add_u64 v[124:125], v[138:139], 0, v[122:123]
	v_max_f32_e32 v115, 0, v0
	v_max_f32_e32 v0, v120, v120
	v_mfma_f32_16x16x32_bf16 v[106:109], v[208:211], v[14:17], v[188:191]
	flat_store_dwordx4 v[124:125], v[128:131]
	v_pk_mul_f32 v[118:119], v[118:119], v[118:119]
	s_nop 0
	v_pk_mul_f32 v[128:129], v[114:115], v[114:115]
	v_max_f32_e32 v114, 0, v0
	v_max_f32_e32 v0, v116, v116
	v_max_f32_e32 v116, 0, v0
	v_max_f32_e32 v0, v121, v121
	v_max_f32_e32 v115, 0, v0
	v_max_f32_e32 v0, v117, v117
	v_max_f32_e32 v117, 0, v0
	v_max_f32_e32 v0, v110, v110
	v_max_f32_e32 v110, 0, v0
	v_max_f32_e32 v0, v106, v106
	v_pk_mul_f32 v[120:121], v[114:115], v[114:115]
	v_pk_mul_f32 v[130:131], v[116:117], v[116:117]
	v_max_f32_e32 v106, 0, v0
	v_max_f32_e32 v0, v111, v111
	v_cvt_pk_bf16_f32 v114, v118, v119
	v_cvt_pk_bf16_f32 v115, v120, v121
	v_cvt_pk_bf16_f32 v116, v128, v129
	v_cvt_pk_bf16_f32 v117, v130, v131
	v_max_f32_e32 v111, 0, v0
	v_max_f32_e32 v0, v107, v107
	v_permlane16_swap_b32_e32 v114, v116
	v_permlane16_swap_b32_e32 v115, v117
	v_max_f32_e32 v107, 0, v0
	v_max_f32_e32 v0, v112, v112
	v_mfma_f32_16x16x32_bf16 v[98:101], v[212:215], v[14:17], v[98:101]
	flat_store_dwordx4 v[124:125], v[114:117] offset:32
	v_pk_mul_f32 v[110:111], v[110:111], v[110:111]
	s_nop 0
	v_pk_mul_f32 v[114:115], v[106:107], v[106:107]
	v_max_f32_e32 v106, 0, v0
	v_max_f32_e32 v0, v108, v108
	v_max_f32_e32 v108, 0, v0
	v_max_f32_e32 v0, v113, v113
	v_max_f32_e32 v107, 0, v0
	v_max_f32_e32 v0, v109, v109
	v_max_f32_e32 v109, 0, v0
	v_max_f32_e32 v0, v102, v102
	v_max_f32_e32 v102, 0, v0
	v_max_f32_e32 v0, v98, v98
	v_pk_mul_f32 v[112:113], v[106:107], v[106:107]
	v_pk_mul_f32 v[116:117], v[108:109], v[108:109]
	v_max_f32_e32 v98, 0, v0
	v_max_f32_e32 v0, v103, v103
	v_cvt_pk_bf16_f32 v106, v110, v111
	v_cvt_pk_bf16_f32 v107, v112, v113
	v_cvt_pk_bf16_f32 v108, v114, v115
	v_cvt_pk_bf16_f32 v109, v116, v117
	v_max_f32_e32 v103, 0, v0
	v_max_f32_e32 v0, v99, v99
	v_permlane16_swap_b32_e32 v106, v108
	v_permlane16_swap_b32_e32 v107, v109
	v_max_f32_e32 v99, 0, v0
	v_max_f32_e32 v0, v104, v104
	flat_store_dwordx4 v[124:125], v[106:109] offset:128
	v_pk_mul_f32 v[102:103], v[102:103], v[102:103]
	v_mfma_f32_16x16x32_bf16 v[90:93], v[200:203], v[38:41], v[146:149]
	v_mul_f32_e64 v106, v98, v98
	v_mul_f32_e64 v107, v99, v99
	v_max_f32_e32 v98, 0, v0
	v_max_f32_e32 v0, v100, v100
	v_max_f32_e32 v100, 0, v0
	v_max_f32_e32 v0, v105, v105
	v_max_f32_e32 v99, 0, v0
	v_max_f32_e32 v0, v101, v101
	v_max_f32_e32 v101, 0, v0
	v_pk_mul_f32 v[104:105], v[98:99], v[98:99]
	v_pk_mul_f32 v[108:109], v[100:101], v[100:101]
	v_cvt_pk_bf16_f32 v98, v102, v103
	v_cvt_pk_bf16_f32 v99, v104, v105
	v_cvt_pk_bf16_f32 v100, v106, v107
	v_cvt_pk_bf16_f32 v101, v108, v109
	s_nop 0
	v_permlane16_swap_b32_e32 v98, v100
	v_permlane16_swap_b32_e32 v99, v101
	v_mfma_f32_16x16x32_bf16 v[82:85], v[204:207], v[38:41], v[74:77]
; DI unsigned pack2(float a, float b) { float2_t v = {a, b}; bf16x2_t r = __builtin_convertvector(v, bf16x2_t); return __builtin_bit_cast(unsigned, r); }
; DI uint4 widen16(uint2 a, uint2 b) {
;   const auto r0 = __builtin_amdgcn_permlane16_swap(a.x, b.x, false, false);
;   const auto r1 = __builtin_amdgcn_permlane16_swap(a.y, b.y, false, false);
;   return make_uint4(r0[0], r1[0], r0[1], r1[1]);
; }
; DI void phase_mlp1(const Params& p, int l, int Mout, char* smem) {
;     ...
;     for (int mi = 0; mi < 8; mi += 2) {
;       const int m = m0 + wr * 128 + (mi + (lq & 1)) * 16 + lr;
; #pragma unroll
;       for (int ni = 0; ni < 4; ++ni) {
;         const int n = n0 + wc * 64 + ni * 16 + (lq >> 1) * 8;
;         float va[4], vb[4];
; #pragma unroll
;         for (int j = 0; j < 4; ++j) { const float a = fmaxf(acc[mi][ni][j], 0.f); va[j] = a * a; const float b = fmaxf(acc[mi + 1][ni][j], 0.f); vb[j] = b * b; }
;         *(uint4*)(U + (size_t)m * DFF + n) = widen16(make_uint2(pack2(va[0], va[1]), pack2(va[2], va[3])), make_uint2(pack2(vb[0], vb[1]), pack2(vb[2], vb[3])));
;       }
;       __builtin_amdgcn_sched_barrier(0);
;     }
	flat_store_dwordx4 v[124:125], v[98:101] offset:160
	v_mfma_f32_16x16x32_bf16 v[74:77], v[208:211], v[38:41], v[192:195]
	v_mfma_f32_16x16x32_bf16 v[66:69], v[212:215], v[38:41], v[66:69]
	v_mfma_f32_16x16x32_bf16 v[62:65], v[200:203], v[168:171], v[62:65]
	v_mfma_f32_16x16x32_bf16 v[54:57], v[204:207], v[168:171], v[58:61]
	v_mfma_f32_16x16x32_bf16 v[46:49], v[208:211], v[168:171], v[150:153]
	v_mfma_f32_16x16x32_bf16 v[38:41], v[212:215], v[168:171], v[50:53]
	v_mfma_f32_16x16x32_bf16 v[58:61], v[200:203], v[172:175], v[154:157]
	v_mfma_f32_16x16x32_bf16 v[50:53], v[204:207], v[172:175], v[42:45]
	v_mfma_f32_16x16x32_bf16 v[42:45], v[208:211], v[172:175], v[196:199]
	v_mfma_f32_16x16x32_bf16 v[34:37], v[212:215], v[172:175], v[34:37]
	v_mfma_f32_16x16x32_bf16 v[30:33], v[200:203], v[176:179], v[30:33]
	v_mfma_f32_16x16x32_bf16 v[14:17], v[208:211], v[176:179], v[158:161]
	v_mfma_f32_16x16x32_bf16 v[6:9], v[212:215], v[176:179], v[18:21]
	v_mfma_f32_16x16x32_bf16 v[18:21], v[204:207], v[180:183], v[10:13]
	v_mfma_f32_16x16x32_bf16 v[10:13], v[208:211], v[180:183], v[164:167]
	v_mfma_f32_16x16x32_bf16 v[2:5], v[212:215], v[180:183], v[2:5]
	v_max_f32_e32 v0, v94, v94
	v_max_f32_e32 v94, 0, v0
	v_max_f32_e32 v0, v90, v90
	v_max_f32_e32 v90, 0, v0
	v_max_f32_e32 v0, v95, v95
	v_max_f32_e32 v95, 0, v0
	v_max_f32_e32 v0, v91, v91
	v_max_f32_e32 v91, 0, v0
	v_max_f32_e32 v0, v96, v96
	v_pk_mul_f32 v[100:101], v[90:91], v[90:91]
	v_max_f32_e32 v90, 0, v0
	v_max_f32_e32 v0, v92, v92
	v_max_f32_e32 v92, 0, v0
	v_max_f32_e32 v0, v97, v97
	v_max_f32_e32 v91, 0, v0
	v_max_f32_e32 v0, v93, v93
	v_add_u32_e32 v98, 32, v126
	v_max_f32_e32 v93, 0, v0
	v_max_f32_e32 v0, v86, v86
	v_ashrrev_i32_e32 v99, 31, v98
	v_max_f32_e32 v86, 0, v0
	v_max_f32_e32 v0, v82, v82
	v_and_b32_e32 v220, 1, v98
	v_lshrrev_b32_e32 v98, 1, v98
	v_mov_b32_e32 v99, 0
	v_lshlrev_b64 v[98:99], 14, v[98:99]
	v_lshl_or_b32 v98, v220, 6, v98
	v_pk_mul_f32 v[94:95], v[94:95], v[94:95]
	v_pk_mul_f32 v[96:97], v[90:91], v[90:91]
	v_pk_mul_f32 v[102:103], v[92:93], v[92:93]
	v_max_f32_e32 v82, 0, v0
	v_max_f32_e32 v0, v87, v87
	v_lshl_add_u64 v[98:99], s[60:61], 0, v[98:99]
	v_cvt_pk_bf16_f32 v90, v94, v95
	v_cvt_pk_bf16_f32 v91, v96, v97
	v_cvt_pk_bf16_f32 v92, v100, v101
	v_cvt_pk_bf16_f32 v93, v102, v103
	v_max_f32_e32 v87, 0, v0
	v_max_f32_e32 v0, v83, v83
	v_permlane16_swap_b32_e32 v90, v92
	v_permlane16_swap_b32_e32 v91, v93
	v_lshl_add_u64 v[94:95], v[98:99], 0, v[122:123]
	v_max_f32_e32 v83, 0, v0
	v_max_f32_e32 v0, v88, v88
	flat_store_dwordx4 v[94:95], v[90:93]
	v_pk_mul_f32 v[86:87], v[86:87], v[86:87]
	s_nop 0
	v_pk_mul_f32 v[90:91], v[82:83], v[82:83]
	v_max_f32_e32 v82, 0, v0
	v_max_f32_e32 v0, v84, v84
	v_max_f32_e32 v84, 0, v0
	v_max_f32_e32 v0, v89, v89
	v_max_f32_e32 v83, 0, v0
	v_max_f32_e32 v0, v85, v85
	v_max_f32_e32 v85, 0, v0
	v_max_f32_e32 v0, v78, v78
	v_max_f32_e32 v78, 0, v0
	v_max_f32_e32 v0, v74, v74
	v_pk_mul_f32 v[88:89], v[82:83], v[82:83]
	v_pk_mul_f32 v[92:93], v[84:85], v[84:85]
	v_max_f32_e32 v74, 0, v0
	v_max_f32_e32 v0, v79, v79
	v_cvt_pk_bf16_f32 v82, v86, v87
	v_cvt_pk_bf16_f32 v83, v88, v89
	v_cvt_pk_bf16_f32 v84, v90, v91
	v_cvt_pk_bf16_f32 v85, v92, v93
	v_max_f32_e32 v79, 0, v0
	v_max_f32_e32 v0, v75, v75
	v_permlane16_swap_b32_e32 v82, v84
	v_permlane16_swap_b32_e32 v83, v85
	v_max_f32_e32 v75, 0, v0
	v_max_f32_e32 v0, v80, v80
	flat_store_dwordx4 v[94:95], v[82:85] offset:32
	v_pk_mul_f32 v[78:79], v[78:79], v[78:79]
	s_nop 0
	v_pk_mul_f32 v[82:83], v[74:75], v[74:75]
	v_max_f32_e32 v74, 0, v0
	v_max_f32_e32 v0, v76, v76
	v_max_f32_e32 v76, 0, v0
	v_max_f32_e32 v0, v81, v81
	v_max_f32_e32 v75, 0, v0
	v_max_f32_e32 v0, v77, v77
	v_max_f32_e32 v77, 0, v0
	v_max_f32_e32 v0, v70, v70
	v_max_f32_e32 v70, 0, v0
	v_max_f32_e32 v0, v66, v66
	v_pk_mul_f32 v[80:81], v[74:75], v[74:75]
	v_pk_mul_f32 v[84:85], v[76:77], v[76:77]
	v_max_f32_e32 v66, 0, v0
	v_max_f32_e32 v0, v71, v71
	v_cvt_pk_bf16_f32 v74, v78, v79
	v_cvt_pk_bf16_f32 v75, v80, v81
	v_cvt_pk_bf16_f32 v76, v82, v83
	v_cvt_pk_bf16_f32 v77, v84, v85
	v_max_f32_e32 v71, 0, v0
	v_max_f32_e32 v0, v67, v67
	v_permlane16_swap_b32_e32 v74, v76
	v_permlane16_swap_b32_e32 v75, v77
	v_max_f32_e32 v67, 0, v0
	v_max_f32_e32 v0, v72, v72
	flat_store_dwordx4 v[94:95], v[74:77] offset:128
	v_pk_mul_f32 v[70:71], v[70:71], v[70:71]
	s_nop 0
	v_pk_mul_f32 v[74:75], v[66:67], v[66:67]
	v_max_f32_e32 v66, 0, v0
	v_max_f32_e32 v0, v68, v68
	v_max_f32_e32 v68, 0, v0
	v_max_f32_e32 v0, v73, v73
	v_max_f32_e32 v67, 0, v0
	v_max_f32_e32 v0, v69, v69
	v_max_f32_e32 v69, 0, v0
	v_pk_mul_f32 v[72:73], v[66:67], v[66:67]
	v_pk_mul_f32 v[76:77], v[68:69], v[68:69]
	v_cvt_pk_bf16_f32 v66, v70, v71
	v_cvt_pk_bf16_f32 v67, v72, v73
	v_cvt_pk_bf16_f32 v68, v74, v75
	v_cvt_pk_bf16_f32 v69, v76, v77
	s_nop 0
	v_permlane16_swap_b32_e32 v66, v68
	v_permlane16_swap_b32_e32 v67, v69
	flat_store_dwordx4 v[94:95], v[66:69] offset:160
	v_max_f32_e32 v0, v62, v62
	v_max_f32_e32 v62, 0, v0
	v_max_f32_e32 v0, v58, v58
	v_max_f32_e32 v58, 0, v0
	v_max_f32_e32 v0, v63, v63
	v_max_f32_e32 v63, 0, v0
	v_max_f32_e32 v0, v59, v59
	v_max_f32_e32 v59, 0, v0
	v_max_f32_e32 v0, v64, v64
	v_pk_mul_f32 v[68:69], v[58:59], v[58:59]
	v_max_f32_e32 v58, 0, v0
	v_max_f32_e32 v0, v60, v60
	v_max_f32_e32 v60, 0, v0
	v_max_f32_e32 v0, v65, v65
	v_max_f32_e32 v59, 0, v0
	v_max_f32_e32 v0, v61, v61
	v_add_u32_e32 v66, 64, v126
	v_max_f32_e32 v61, 0, v0
	v_max_f32_e32 v0, v54, v54
	v_ashrrev_i32_e32 v67, 31, v66
	v_max_f32_e32 v54, 0, v0
	v_max_f32_e32 v0, v50, v50
	v_and_b32_e32 v220, 1, v66
	v_lshrrev_b32_e32 v66, 1, v66
	v_mov_b32_e32 v67, 0
; DI unsigned pack2(float a, float b) { float2_t v = {a, b}; bf16x2_t r = __builtin_convertvector(v, bf16x2_t); return __builtin_bit_cast(unsigned, r); }
; DI void phase_mlp1(const Params& p, int l, int Mout, char* smem) {
;     ...
;   for (int it = 0;; ++it) {
;     int tm, tn;
;     if (!tile_map(it, ntm, 32, blk__, gridDim.x, tm, tn)) break;
;     ...
;     for (int mi = 0; mi < 8; mi += 2) {
;       const int m = m0 + wr * 128 + (mi + (lq & 1)) * 16 + lr;
; #pragma unroll
;       for (int ni = 0; ni < 4; ++ni) {
;         const int n = n0 + wc * 64 + ni * 16 + (lq >> 1) * 8;
;         float va[4], vb[4];
; #pragma unroll
;         for (int j = 0; j < 4; ++j) { const float a = fmaxf(acc[mi][ni][j], 0.f); va[j] = a * a; const float b = fmaxf(acc[mi + 1][ni][j], 0.f); vb[j] = b * b; }
;         *(uint4*)(U + (size_t)m * DFF + n) = widen16(make_uint2(pack2(va[0], va[1]), pack2(va[2], va[3])), make_uint2(pack2(vb[0], vb[1]), pack2(vb[2], vb[3])));
;       }
;       __builtin_amdgcn_sched_barrier(0);
;     }
	v_lshlrev_b64 v[66:67], 14, v[66:67]
	v_lshl_or_b32 v66, v220, 6, v66
	v_pk_mul_f32 v[62:63], v[62:63], v[62:63]
	v_pk_mul_f32 v[64:65], v[58:59], v[58:59]
	v_pk_mul_f32 v[70:71], v[60:61], v[60:61]
	v_max_f32_e32 v50, 0, v0
	v_max_f32_e32 v0, v55, v55
	v_lshl_add_u64 v[66:67], s[60:61], 0, v[66:67]
	v_cvt_pk_bf16_f32 v58, v62, v63
	v_cvt_pk_bf16_f32 v59, v64, v65
	v_cvt_pk_bf16_f32 v60, v68, v69
	v_cvt_pk_bf16_f32 v61, v70, v71
	v_max_f32_e32 v55, 0, v0
	v_max_f32_e32 v0, v51, v51
	v_permlane16_swap_b32_e32 v58, v60
	v_permlane16_swap_b32_e32 v59, v61
	v_lshl_add_u64 v[62:63], v[66:67], 0, v[122:123]
	v_max_f32_e32 v51, 0, v0
	v_max_f32_e32 v0, v56, v56
	flat_store_dwordx4 v[62:63], v[58:61]
	v_pk_mul_f32 v[54:55], v[54:55], v[54:55]
	s_nop 0
	v_pk_mul_f32 v[58:59], v[50:51], v[50:51]
	v_max_f32_e32 v50, 0, v0
	v_max_f32_e32 v0, v52, v52
	v_max_f32_e32 v52, 0, v0
	v_max_f32_e32 v0, v57, v57
	v_max_f32_e32 v51, 0, v0
	v_max_f32_e32 v0, v53, v53
	v_max_f32_e32 v53, 0, v0
	v_max_f32_e32 v0, v46, v46
	v_max_f32_e32 v46, 0, v0
	v_max_f32_e32 v0, v42, v42
	v_pk_mul_f32 v[56:57], v[50:51], v[50:51]
	v_pk_mul_f32 v[60:61], v[52:53], v[52:53]
	v_max_f32_e32 v42, 0, v0
	v_max_f32_e32 v0, v47, v47
	v_cvt_pk_bf16_f32 v50, v54, v55
	v_cvt_pk_bf16_f32 v51, v56, v57
	v_cvt_pk_bf16_f32 v52, v58, v59
	v_cvt_pk_bf16_f32 v53, v60, v61
	v_max_f32_e32 v47, 0, v0
	v_max_f32_e32 v0, v43, v43
	v_permlane16_swap_b32_e32 v50, v52
	v_permlane16_swap_b32_e32 v51, v53
	v_max_f32_e32 v43, 0, v0
	v_max_f32_e32 v0, v48, v48
	flat_store_dwordx4 v[62:63], v[50:53] offset:32
	v_pk_mul_f32 v[46:47], v[46:47], v[46:47]
	s_nop 0
	v_pk_mul_f32 v[50:51], v[42:43], v[42:43]
	v_max_f32_e32 v42, 0, v0
	v_max_f32_e32 v0, v44, v44
	v_max_f32_e32 v44, 0, v0
	v_max_f32_e32 v0, v49, v49
	v_max_f32_e32 v43, 0, v0
	v_max_f32_e32 v0, v45, v45
	v_max_f32_e32 v45, 0, v0
	v_max_f32_e32 v0, v38, v38
	v_max_f32_e32 v38, 0, v0
	v_max_f32_e32 v0, v34, v34
	v_pk_mul_f32 v[48:49], v[42:43], v[42:43]
	v_pk_mul_f32 v[52:53], v[44:45], v[44:45]
	v_max_f32_e32 v34, 0, v0
	v_max_f32_e32 v0, v39, v39
	v_cvt_pk_bf16_f32 v42, v46, v47
	v_cvt_pk_bf16_f32 v43, v48, v49
	v_cvt_pk_bf16_f32 v44, v50, v51
	v_cvt_pk_bf16_f32 v45, v52, v53
	v_max_f32_e32 v39, 0, v0
	v_max_f32_e32 v0, v35, v35
	v_permlane16_swap_b32_e32 v42, v44
	v_permlane16_swap_b32_e32 v43, v45
	v_max_f32_e32 v35, 0, v0
	v_max_f32_e32 v0, v40, v40
	flat_store_dwordx4 v[62:63], v[42:45] offset:128
	v_pk_mul_f32 v[38:39], v[38:39], v[38:39]
	s_nop 0
	v_pk_mul_f32 v[42:43], v[34:35], v[34:35]
	v_max_f32_e32 v34, 0, v0
	v_max_f32_e32 v0, v36, v36
	v_max_f32_e32 v36, 0, v0
	v_max_f32_e32 v0, v41, v41
	v_max_f32_e32 v35, 0, v0
	v_max_f32_e32 v0, v37, v37
	v_max_f32_e32 v37, 0, v0
	v_pk_mul_f32 v[40:41], v[34:35], v[34:35]
	v_pk_mul_f32 v[44:45], v[36:37], v[36:37]
	v_cvt_pk_bf16_f32 v34, v38, v39
	v_cvt_pk_bf16_f32 v35, v40, v41
	v_cvt_pk_bf16_f32 v36, v42, v43
	v_cvt_pk_bf16_f32 v37, v44, v45
	s_nop 0
	v_permlane16_swap_b32_e32 v34, v36
	v_permlane16_swap_b32_e32 v35, v37
	flat_store_dwordx4 v[62:63], v[34:37] offset:160
	v_max_f32_e32 v0, v30, v30
	v_max_f32_e32 v30, 0, v0
	v_max_f32_e32 v0, v26, v26
	v_max_f32_e32 v26, 0, v0
	v_max_f32_e32 v0, v31, v31
	v_max_f32_e32 v31, 0, v0
	v_max_f32_e32 v0, v27, v27
	v_max_f32_e32 v27, 0, v0
	v_max_f32_e32 v0, v32, v32
	v_pk_mul_f32 v[36:37], v[26:27], v[26:27]
	v_max_f32_e32 v26, 0, v0
	v_max_f32_e32 v0, v28, v28
	v_max_f32_e32 v28, 0, v0
	v_max_f32_e32 v0, v33, v33
	v_max_f32_e32 v27, 0, v0
	v_max_f32_e32 v0, v29, v29
	v_add_u32_e32 v34, 0x60, v126
	v_max_f32_e32 v29, 0, v0
	v_max_f32_e32 v0, v22, v22
	v_ashrrev_i32_e32 v35, 31, v34
	v_max_f32_e32 v22, 0, v0
	v_max_f32_e32 v0, v18, v18
	v_and_b32_e32 v220, 1, v34
	v_lshrrev_b32_e32 v34, 1, v34
	v_mov_b32_e32 v35, 0
	v_lshlrev_b64 v[34:35], 14, v[34:35]
	v_lshl_or_b32 v34, v220, 6, v34
	v_pk_mul_f32 v[30:31], v[30:31], v[30:31]
	v_pk_mul_f32 v[32:33], v[26:27], v[26:27]
	v_pk_mul_f32 v[38:39], v[28:29], v[28:29]
	v_max_f32_e32 v18, 0, v0
	v_max_f32_e32 v0, v23, v23
	v_lshl_add_u64 v[34:35], s[60:61], 0, v[34:35]
	v_cvt_pk_bf16_f32 v26, v30, v31
	v_cvt_pk_bf16_f32 v27, v32, v33
	v_cvt_pk_bf16_f32 v28, v36, v37
	v_cvt_pk_bf16_f32 v29, v38, v39
	v_max_f32_e32 v23, 0, v0
	v_max_f32_e32 v0, v19, v19
	v_permlane16_swap_b32_e32 v26, v28
	v_permlane16_swap_b32_e32 v27, v29
	v_lshl_add_u64 v[30:31], v[34:35], 0, v[122:123]
	v_max_f32_e32 v19, 0, v0
	v_max_f32_e32 v0, v24, v24
	flat_store_dwordx4 v[30:31], v[26:29]
	v_pk_mul_f32 v[22:23], v[22:23], v[22:23]
	s_nop 0
	v_pk_mul_f32 v[26:27], v[18:19], v[18:19]
	v_max_f32_e32 v18, 0, v0
	v_max_f32_e32 v0, v20, v20
	v_max_f32_e32 v20, 0, v0
	v_max_f32_e32 v0, v25, v25
	v_max_f32_e32 v19, 0, v0
	v_max_f32_e32 v0, v21, v21
	v_max_f32_e32 v21, 0, v0
	v_max_f32_e32 v0, v14, v14
	v_max_f32_e32 v14, 0, v0
	v_max_f32_e32 v0, v10, v10
	v_pk_mul_f32 v[24:25], v[18:19], v[18:19]
	v_pk_mul_f32 v[28:29], v[20:21], v[20:21]
	v_max_f32_e32 v10, 0, v0
	v_max_f32_e32 v0, v15, v15
	v_cvt_pk_bf16_f32 v18, v22, v23
	v_cvt_pk_bf16_f32 v19, v24, v25
	v_cvt_pk_bf16_f32 v20, v26, v27
	v_cvt_pk_bf16_f32 v21, v28, v29
	v_max_f32_e32 v15, 0, v0
	v_max_f32_e32 v0, v11, v11
	v_permlane16_swap_b32_e32 v18, v20
	v_permlane16_swap_b32_e32 v19, v21
	v_max_f32_e32 v11, 0, v0
	v_max_f32_e32 v0, v16, v16
	flat_store_dwordx4 v[30:31], v[18:21] offset:32
	v_pk_mul_f32 v[14:15], v[14:15], v[14:15]
	s_nop 0
	v_pk_mul_f32 v[18:19], v[10:11], v[10:11]
	v_max_f32_e32 v10, 0, v0
	v_max_f32_e32 v0, v12, v12
	v_max_f32_e32 v12, 0, v0
	v_max_f32_e32 v0, v17, v17
	v_max_f32_e32 v11, 0, v0
	v_max_f32_e32 v0, v13, v13
	v_max_f32_e32 v13, 0, v0
	v_max_f32_e32 v0, v6, v6
	v_max_f32_e32 v6, 0, v0
	v_max_f32_e32 v0, v2, v2
	v_pk_mul_f32 v[16:17], v[10:11], v[10:11]
	v_pk_mul_f32 v[20:21], v[12:13], v[12:13]
	v_max_f32_e32 v2, 0, v0
	v_max_f32_e32 v0, v7, v7
	v_cvt_pk_bf16_f32 v10, v14, v15
	v_cvt_pk_bf16_f32 v11, v16, v17
	v_cvt_pk_bf16_f32 v12, v18, v19
	v_cvt_pk_bf16_f32 v13, v20, v21
	v_max_f32_e32 v7, 0, v0
	v_max_f32_e32 v0, v3, v3
	v_permlane16_swap_b32_e32 v10, v12
	v_permlane16_swap_b32_e32 v11, v13
	v_max_f32_e32 v3, 0, v0
	v_max_f32_e32 v0, v8, v8
	flat_store_dwordx4 v[30:31], v[10:13] offset:128
	v_pk_mul_f32 v[6:7], v[6:7], v[6:7]
	s_nop 0
	v_pk_mul_f32 v[10:11], v[2:3], v[2:3]
	v_max_f32_e32 v2, 0, v0
	v_max_f32_e32 v0, v4, v4
	v_max_f32_e32 v4, 0, v0
	v_max_f32_e32 v0, v9, v9
	v_max_f32_e32 v3, 0, v0
	v_max_f32_e32 v0, v5, v5
	v_max_f32_e32 v5, 0, v0
	v_pk_mul_f32 v[8:9], v[2:3], v[2:3]
	v_pk_mul_f32 v[12:13], v[4:5], v[4:5]
	v_cvt_pk_bf16_f32 v2, v6, v7
	v_cvt_pk_bf16_f32 v3, v8, v9
	v_cvt_pk_bf16_f32 v4, v10, v11
	v_cvt_pk_bf16_f32 v5, v12, v13
	s_nop 0
	v_permlane16_swap_b32_e32 v2, v4
	v_permlane16_swap_b32_e32 v3, v5
	flat_store_dwordx4 v[30:31], v[2:5] offset:160
	s_add_i32 s8, s8, 1
	s_mul_i32 s4, s8, s39
	s_add_i32 s9, s4, s6
	v_readlane_b32 s4, v253, 41
	s_cmp_ge_i32 s9, s4
	s_cbranch_scc0 .LBB0_441

; template <int MI, int NI>
; DI void gemm256(f32x4 (&acc)[MI][NI], const u16* __restrict__ A, int lda, const u16* __restrict__ Bt, int ldb, int K, int m0, int n0, char* smem) {
;     ...
;   for (int kt = 0; kt < nk; ++kt) {
;     if (kt + 1 < nk) asm volatile("s_waitcnt vmcnt(%0) lgkmcnt(0)" :: "n"(LPS) : "memory");
;     else asm volatile("s_waitcnt vmcnt(0) lgkmcnt(0)" ::: "memory");
;     __builtin_amdgcn_s_barrier();
;     __builtin_amdgcn_s_setprio(1);
;     const char* sb = smem + st * STAGE + foff;
;     bf16x8 af[MI], bfr[NI];
; #pragma unroll
;     for (int mi = 0; mi < MI; ++mi) af[mi] = *(const bf16x8*)(sb + (wr * MI + mi) * 1024);
; #pragma unroll
;     for (int ni = 0; ni < NI; ++ni) bfr[ni] = *(const bf16x8*)(sb + ABYTES + (wc * NI + ni) * 1024);
;     __builtin_amdgcn_sched_barrier(0x0);
;     if (kt + 2 < nk) { const int s2 = st >= 1 ? st - 1 : 2; G256_ISSUE(s2, (kt + 2) * 32); }
;     __builtin_amdgcn_s_setprio(0);
; #pragma unroll
;     for (int mi = 0; mi < MI; ++mi)
; #pragma unroll
;       for (int ni = 0; ni < NI; ++ni)
;         acc[mi][ni] = __builtin_amdgcn_mfma_f32_16x16x32_bf16(bfr[ni], af[mi], acc[mi][ni], 0, 0, 0);
;     st = st == 2 ? 0 : st + 1;
;   }
.Lpipe_wo:
	v_add_u32_e32 v161, s12, v160
	ds_read_b128 v[156:159], v161 offset:4096
	ds_read_b128 v[164:167], v161 offset:5120
	ds_read_b128 v[168:171], v161 offset:6144
	ds_read_b128 v[172:175], v161 offset:7168
	s_add_i32 s14, s12, 0xffffa000
	s_cmp_eq_u32 s12, 0
	s_cselect_b32 s14, 0xc000, s14
	s_add_i32 s15, s14, s13
	s_add_i32 s14, s14, s4
	s_mov_b32 m0, s15
	s_waitcnt lgkmcnt(7)
	v_mfma_f32_16x16x32_bf16 v[126:129], v[176:179], v[140:143], v[126:129]
	global_load_lds_dwordx4 v[196:197], off
	v_mfma_f32_16x16x32_bf16 v[110:113], v[176:179], v[144:147], v[110:113]
	v_lshl_add_u64 v[196:197], v[196:197], 0, s[98:99]
	s_add_i32 m0, s15, 0x400
	v_mfma_f32_16x16x32_bf16 v[94:97], v[176:179], v[148:151], v[94:97]
	global_load_lds_dwordx4 v[198:199], off
	v_mfma_f32_16x16x32_bf16 v[78:81], v[176:179], v[152:155], v[78:81]
	v_lshl_add_u64 v[198:199], v[198:199], 0, s[98:99]
	s_add_i32 m0, s15, 0x800
	s_waitcnt lgkmcnt(6)
	v_mfma_f32_16x16x32_bf16 v[122:125], v[180:183], v[140:143], v[122:125]
	global_load_lds_dwordx4 v[200:201], off
	v_mfma_f32_16x16x32_bf16 v[106:109], v[180:183], v[144:147], v[106:109]
	v_lshl_add_u64 v[200:201], v[200:201], 0, s[98:99]
	s_add_i32 m0, s15, 0xc00
	v_mfma_f32_16x16x32_bf16 v[90:93], v[180:183], v[148:151], v[90:93]
	global_load_lds_dwordx4 v[202:203], off
	v_mfma_f32_16x16x32_bf16 v[74:77], v[180:183], v[152:155], v[74:77]
	v_lshl_add_u64 v[202:203], v[202:203], 0, s[98:99]
	s_mov_b32 m0, s14
	s_waitcnt lgkmcnt(5)
	v_mfma_f32_16x16x32_bf16 v[118:121], v[184:187], v[140:143], v[118:121]
	global_load_lds_dwordx4 v[204:205], off
	v_mfma_f32_16x16x32_bf16 v[102:105], v[184:187], v[144:147], v[102:105]
	v_lshl_add_u64 v[204:205], v[204:205], 0, 64
	s_add_i32 m0, s14, 0x400
	v_mfma_f32_16x16x32_bf16 v[86:89], v[184:187], v[148:151], v[86:89]
	global_load_lds_dwordx4 v[206:207], off
	v_mfma_f32_16x16x32_bf16 v[70:73], v[184:187], v[152:155], v[70:73]
	v_lshl_add_u64 v[206:207], v[206:207], 0, 64
	s_waitcnt lgkmcnt(4)
	v_mfma_f32_16x16x32_bf16 v[114:117], v[188:191], v[140:143], v[114:117]
	v_mfma_f32_16x16x32_bf16 v[98:101], v[188:191], v[144:147], v[98:101]
	v_mfma_f32_16x16x32_bf16 v[82:85], v[188:191], v[148:151], v[82:85]
	v_mfma_f32_16x16x32_bf16 v[66:69], v[188:191], v[152:155], v[66:69]
	s_waitcnt vmcnt(6) lgkmcnt(0)
	s_barrier
	s_add_i32 s15, s12, 0x6000
	s_cmp_eq_u32 s12, 0xc000
	s_cselect_b32 s12, 0, s15
	v_add_u32_e32 v192, s12, v160
	v_add_u32_e32 v193, s12, v0
	v_mfma_f32_16x16x32_bf16 v[62:65], v[176:179], v[156:159], v[62:65]
	ds_read_b128 v[140:143], v192
	v_mfma_f32_16x16x32_bf16 v[46:49], v[176:179], v[164:167], v[46:49]
	ds_read_b128 v[144:147], v192 offset:1024
	v_mfma_f32_16x16x32_bf16 v[30:33], v[176:179], v[168:171], v[30:33]
	ds_read_b128 v[148:151], v192 offset:2048
	v_mfma_f32_16x16x32_bf16 v[14:17], v[176:179], v[172:175], v[14:17]
	ds_read_b128 v[152:155], v192 offset:3072
	ds_read_b128 v[176:179], v193 offset:16384
	v_mfma_f32_16x16x32_bf16 v[58:61], v[180:183], v[156:159], v[58:61]
	v_mfma_f32_16x16x32_bf16 v[42:45], v[180:183], v[164:167], v[42:45]
	v_mfma_f32_16x16x32_bf16 v[26:29], v[180:183], v[168:171], v[26:29]
	v_mfma_f32_16x16x32_bf16 v[10:13], v[180:183], v[172:175], v[10:13]
	ds_read_b128 v[180:183], v193 offset:17408
	v_mfma_f32_16x16x32_bf16 v[54:57], v[184:187], v[156:159], v[54:57]
	v_mfma_f32_16x16x32_bf16 v[38:41], v[184:187], v[164:167], v[38:41]
	v_mfma_f32_16x16x32_bf16 v[22:25], v[184:187], v[168:171], v[22:25]
	v_mfma_f32_16x16x32_bf16 v[6:9], v[184:187], v[172:175], v[6:9]
	ds_read_b128 v[184:187], v193 offset:18432
	v_mfma_f32_16x16x32_bf16 v[50:53], v[188:191], v[156:159], v[50:53]
	v_mfma_f32_16x16x32_bf16 v[34:37], v[188:191], v[164:167], v[34:37]
	v_mfma_f32_16x16x32_bf16 v[18:21], v[188:191], v[168:171], v[18:21]
	v_mfma_f32_16x16x32_bf16 v[2:5], v[188:191], v[172:175], v[2:5]
	ds_read_b128 v[188:191], v193 offset:19456
	s_sub_i32 s5, s5, 1
	s_cmp_lg_u32 s5, 0
	s_cbranch_scc1 .Lpipe_wo
	v_add_u32_e32 v161, s12, v160
	ds_read_b128 v[156:159], v161 offset:4096
	ds_read_b128 v[164:167], v161 offset:5120
	ds_read_b128 v[168:171], v161 offset:6144
	ds_read_b128 v[172:175], v161 offset:7168
	s_add_i32 s14, s12, 0xffffa000
	s_cmp_eq_u32 s12, 0
	s_cselect_b32 s14, 0xc000, s14
	s_add_i32 s15, s14, s13
	s_add_i32 s14, s14, s4
	s_mov_b32 m0, s15
	s_waitcnt lgkmcnt(7)
	v_mfma_f32_16x16x32_bf16 v[126:129], v[176:179], v[140:143], v[126:129]
	global_load_lds_dwordx4 v[196:197], off
	v_mfma_f32_16x16x32_bf16 v[110:113], v[176:179], v[144:147], v[110:113]
	v_lshl_add_u64 v[196:197], v[196:197], 0, s[98:99]
	s_add_i32 m0, s15, 0x400
	v_mfma_f32_16x16x32_bf16 v[94:97], v[176:179], v[148:151], v[94:97]
	global_load_lds_dwordx4 v[198:199], off
	v_mfma_f32_16x16x32_bf16 v[78:81], v[176:179], v[152:155], v[78:81]
	v_lshl_add_u64 v[198:199], v[198:199], 0, s[98:99]
	s_add_i32 m0, s15, 0x800
	s_waitcnt lgkmcnt(6)
	v_mfma_f32_16x16x32_bf16 v[122:125], v[180:183], v[140:143], v[122:125]
	global_load_lds_dwordx4 v[200:201], off
	v_mfma_f32_16x16x32_bf16 v[106:109], v[180:183], v[144:147], v[106:109]
	v_lshl_add_u64 v[200:201], v[200:201], 0, s[98:99]
	s_add_i32 m0, s15, 0xc00
	v_mfma_f32_16x16x32_bf16 v[90:93], v[180:183], v[148:151], v[90:93]
	global_load_lds_dwordx4 v[202:203], off
	v_mfma_f32_16x16x32_bf16 v[74:77], v[180:183], v[152:155], v[74:77]
	v_lshl_add_u64 v[202:203], v[202:203], 0, s[98:99]
	s_mov_b32 m0, s14
	s_waitcnt lgkmcnt(5)
; template <int MI, int NI>
; DI void gemm256(f32x4 (&acc)[MI][NI], const u16* __restrict__ A, int lda, const u16* __restrict__ Bt, int ldb, int K, int m0, int n0, char* smem) {
;     ...
;   for (int kt = 0; kt < nk; ++kt) {
;     if (kt + 1 < nk) asm volatile("s_waitcnt vmcnt(%0) lgkmcnt(0)" :: "n"(LPS) : "memory");
;     else asm volatile("s_waitcnt vmcnt(0) lgkmcnt(0)" ::: "memory");
;     __builtin_amdgcn_s_barrier();
;     __builtin_amdgcn_s_setprio(1);
;     const char* sb = smem + st * STAGE + foff;
;     bf16x8 af[MI], bfr[NI];
; #pragma unroll
;     for (int mi = 0; mi < MI; ++mi) af[mi] = *(const bf16x8*)(sb + (wr * MI + mi) * 1024);
; #pragma unroll
;     for (int ni = 0; ni < NI; ++ni) bfr[ni] = *(const bf16x8*)(sb + ABYTES + (wc * NI + ni) * 1024);
;     __builtin_amdgcn_sched_barrier(0x0);
;     if (kt + 2 < nk) { const int s2 = st >= 1 ? st - 1 : 2; G256_ISSUE(s2, (kt + 2) * 32); }
;     __builtin_amdgcn_s_setprio(0);
; #pragma unroll
;     for (int mi = 0; mi < MI; ++mi)
; #pragma unroll
;       for (int ni = 0; ni < NI; ++ni)
;         acc[mi][ni] = __builtin_amdgcn_mfma_f32_16x16x32_bf16(bfr[ni], af[mi], acc[mi][ni], 0, 0, 0);
;     st = st == 2 ? 0 : st + 1;
;   }
;   asm volatile("s_waitcnt lgkmcnt(0)" ::: "memory");
;   __builtin_amdgcn_s_barrier();
	v_mfma_f32_16x16x32_bf16 v[118:121], v[184:187], v[140:143], v[118:121]
	global_load_lds_dwordx4 v[204:205], off
	v_mfma_f32_16x16x32_bf16 v[102:105], v[184:187], v[144:147], v[102:105]
	v_lshl_add_u64 v[204:205], v[204:205], 0, 64
	s_add_i32 m0, s14, 0x400
	v_mfma_f32_16x16x32_bf16 v[86:89], v[184:187], v[148:151], v[86:89]
	global_load_lds_dwordx4 v[206:207], off
	v_mfma_f32_16x16x32_bf16 v[70:73], v[184:187], v[152:155], v[70:73]
	v_lshl_add_u64 v[206:207], v[206:207], 0, 64
	s_waitcnt lgkmcnt(4)
	v_mfma_f32_16x16x32_bf16 v[114:117], v[188:191], v[140:143], v[114:117]
	v_mfma_f32_16x16x32_bf16 v[98:101], v[188:191], v[144:147], v[98:101]
	v_mfma_f32_16x16x32_bf16 v[82:85], v[188:191], v[148:151], v[82:85]
	v_mfma_f32_16x16x32_bf16 v[66:69], v[188:191], v[152:155], v[66:69]
	s_waitcnt lgkmcnt(0)
	v_mfma_f32_16x16x32_bf16 v[62:65], v[176:179], v[156:159], v[62:65]
	v_mfma_f32_16x16x32_bf16 v[46:49], v[176:179], v[164:167], v[46:49]
	v_mfma_f32_16x16x32_bf16 v[30:33], v[176:179], v[168:171], v[30:33]
	v_mfma_f32_16x16x32_bf16 v[14:17], v[176:179], v[172:175], v[14:17]
	v_mfma_f32_16x16x32_bf16 v[58:61], v[180:183], v[156:159], v[58:61]
	v_mfma_f32_16x16x32_bf16 v[42:45], v[180:183], v[164:167], v[42:45]
	v_mfma_f32_16x16x32_bf16 v[26:29], v[180:183], v[168:171], v[26:29]
	v_mfma_f32_16x16x32_bf16 v[10:13], v[180:183], v[172:175], v[10:13]
	v_mfma_f32_16x16x32_bf16 v[54:57], v[184:187], v[156:159], v[54:57]
	v_mfma_f32_16x16x32_bf16 v[38:41], v[184:187], v[164:167], v[38:41]
	v_mfma_f32_16x16x32_bf16 v[22:25], v[184:187], v[168:171], v[22:25]
	v_mfma_f32_16x16x32_bf16 v[6:9], v[184:187], v[172:175], v[6:9]
	v_mfma_f32_16x16x32_bf16 v[50:53], v[188:191], v[156:159], v[50:53]
	v_mfma_f32_16x16x32_bf16 v[34:37], v[188:191], v[164:167], v[34:37]
	v_mfma_f32_16x16x32_bf16 v[18:21], v[188:191], v[168:171], v[18:21]
	v_mfma_f32_16x16x32_bf16 v[2:5], v[188:191], v[172:175], v[2:5]
	s_waitcnt vmcnt(6) lgkmcnt(0)
	s_barrier
	s_setprio 1
	v_add_u32_e32 v0, v137, v139
	ds_read_b128 v[130:133], v0
	ds_read_b128 v[140:143], v0 offset:1024
	ds_read_b128 v[144:147], v0 offset:2048
	ds_read_b128 v[148:151], v0 offset:3072
	ds_read_b128 v[152:155], v0 offset:4096
	ds_read_b128 v[156:159], v0 offset:5120
	ds_read_b128 v[164:167], v0 offset:6144
	ds_read_b128 v[168:171], v0 offset:7168
	v_add_u32_e32 v184, v137, v138
	ds_read_b128 v[136:139], v184 offset:16384
	ds_read_b128 v[172:175], v184 offset:17408
	ds_read_b128 v[176:179], v184 offset:18432
	ds_read_b128 v[180:183], v184 offset:19456
	v_bfe_u32 v188, v134, 6, 1
	s_setprio 0
	s_waitcnt vmcnt(0) lgkmcnt(0)
	s_waitcnt lgkmcnt(3)
	v_mfma_f32_16x16x32_bf16 v[126:129], v[136:139], v[130:133], v[126:129]
	v_ashrrev_i32_e32 v189, 7, v134
	v_and_b32_e32 v190, 15, v134
	v_bfe_u32 v191, v134, 4, 2
	s_waitcnt lgkmcnt(2)
	v_mfma_f32_16x16x32_bf16 v[122:125], v[172:175], v[130:133], v[122:125]
	s_barrier
	s_waitcnt lgkmcnt(1)
	v_mfma_f32_16x16x32_bf16 v[118:121], v[176:179], v[130:133], v[118:121]
	s_waitcnt lgkmcnt(0)
	v_mfma_f32_16x16x32_bf16 v[114:117], v[180:183], v[130:133], v[114:117]
	v_mfma_f32_16x16x32_bf16 v[110:113], v[136:139], v[140:143], v[110:113]
	v_mfma_f32_16x16x32_bf16 v[106:109], v[172:175], v[140:143], v[106:109]
	v_mfma_f32_16x16x32_bf16 v[102:105], v[176:179], v[140:143], v[102:105]
	v_mfma_f32_16x16x32_bf16 v[98:101], v[180:183], v[140:143], v[98:101]
	v_mfma_f32_16x16x32_bf16 v[94:97], v[136:139], v[144:147], v[94:97]
	v_mfma_f32_16x16x32_bf16 v[90:93], v[172:175], v[144:147], v[90:93]
	v_mfma_f32_16x16x32_bf16 v[86:89], v[176:179], v[144:147], v[86:89]
	v_mfma_f32_16x16x32_bf16 v[82:85], v[180:183], v[144:147], v[82:85]
	v_mfma_f32_16x16x32_bf16 v[78:81], v[136:139], v[148:151], v[78:81]
	v_mfma_f32_16x16x32_bf16 v[130:133], v[172:175], v[148:151], v[74:77]
	v_mfma_f32_16x16x32_bf16 v[70:73], v[176:179], v[148:151], v[70:73]
	v_mfma_f32_16x16x32_bf16 v[66:69], v[180:183], v[148:151], v[66:69]
	v_mfma_f32_16x16x32_bf16 v[62:65], v[136:139], v[152:155], v[62:65]
	v_mfma_f32_16x16x32_bf16 v[58:61], v[172:175], v[152:155], v[58:61]
	v_mfma_f32_16x16x32_bf16 v[54:57], v[176:179], v[152:155], v[54:57]
	v_mfma_f32_16x16x32_bf16 v[50:53], v[180:183], v[152:155], v[50:53]
	v_mfma_f32_16x16x32_bf16 v[46:49], v[136:139], v[156:159], v[46:49]
	v_mfma_f32_16x16x32_bf16 v[42:45], v[172:175], v[156:159], v[42:45]
	v_mfma_f32_16x16x32_bf16 v[38:41], v[176:179], v[156:159], v[38:41]
	v_mfma_f32_16x16x32_bf16 v[34:37], v[180:183], v[156:159], v[34:37]
	v_mfma_f32_16x16x32_bf16 v[30:33], v[136:139], v[164:167], v[30:33]
	v_mfma_f32_16x16x32_bf16 v[26:29], v[172:175], v[164:167], v[26:29]
	v_mfma_f32_16x16x32_bf16 v[22:25], v[176:179], v[164:167], v[22:25]
	v_mfma_f32_16x16x32_bf16 v[18:21], v[180:183], v[164:167], v[18:21]
	v_mfma_f32_16x16x32_bf16 v[14:17], v[136:139], v[168:171], v[14:17]
	v_mfma_f32_16x16x32_bf16 v[10:13], v[172:175], v[168:171], v[10:13]
	v_mfma_f32_16x16x32_bf16 v[6:9], v[176:179], v[168:171], v[6:9]
	v_mfma_f32_16x16x32_bf16 v[134:137], v[180:183], v[168:171], v[2:5]
	s_setprio 1
	s_nop 1
	ds_read_b128 v[2:5], v0 offset:24576
	ds_read_b128 v[74:77], v0 offset:25600
	ds_read_b128 v[138:141], v0 offset:26624
	ds_read_b128 v[142:145], v0 offset:27648
	ds_read_b128 v[146:149], v0 offset:28672
	ds_read_b128 v[150:153], v0 offset:29696
	ds_read_b128 v[154:157], v0 offset:30720
	ds_read_b128 v[158:161], v0 offset:31744
	ds_read_b128 v[164:167], v184 offset:40960
	ds_read_b128 v[168:171], v184 offset:41984
	ds_read_b128 v[172:175], v184 offset:43008
	ds_read_b128 v[176:179], v184 offset:44032
	s_setprio 0
	s_waitcnt lgkmcnt(0)
	s_barrier
; template <int MI, int NI>
; DI void resid_tile(const u16* A, int K, const u16* Bt, const float* gate, const float* xl_in, const float* xc_in, float* xl_out, float* xc_out,
;                    int m0, int n0, char* smem) {
;     ...
; #pragma unroll
;   for (int mi = 0; mi < MI; ++mi) {
;     const int m = m0 + wr * 16 * MI + mi * 16 + lr;
;     const int b9 = m < NTL ? m >> 12 : 8;
;     const float* xi = xrow(xl_in, xc_in, m);
;     float* xo = m < NTL ? xl_out + (size_t)m * D : xc_out + (size_t)(m - NTL) * D;
; #pragma unroll
;     for (int ni = 0; ni < NI; ++ni) {
;       const int n = n0 + wc * 16 * NI + ni * 16 + lq * 4;
;       const float4 g = *(const float4*)(gate + (size_t)b9 * 6144 + n);
;       const float4 xv = *(const float4*)(xi + n);
;       float4 ov;
;       ov.x = xv.x + g.x * acc[mi][ni][0]; ov.y = xv.y + g.y * acc[mi][ni][1]; ov.z = xv.z + g.z * acc[mi][ni][2]; ov.w = xv.w + g.w * acc[mi][ni][3];
;       *(float4*)(xo + n) = ov;
;     }
;     __builtin_amdgcn_sched_barrier(0);
;   }
	v_readlane_b32 s4, v253, 55
	v_lshlrev_b32_e32 v0, 7, v189
	s_waitcnt lgkmcnt(3)
	v_mfma_f32_16x16x32_bf16 v[126:129], v[164:167], v[2:5], v[126:129]
	s_waitcnt lgkmcnt(2)
	v_mfma_f32_16x16x32_bf16 v[122:125], v[168:171], v[2:5], v[122:125]
	s_waitcnt lgkmcnt(1)
	v_mfma_f32_16x16x32_bf16 v[180:183], v[172:175], v[2:5], v[118:121]
	s_waitcnt lgkmcnt(0)
	v_mfma_f32_16x16x32_bf16 v[184:187], v[176:179], v[2:5], v[114:117]
	v_lshlrev_b32_e32 v2, 2, v191
	v_mov_b32_e32 v118, s4
	v_readlane_b32 s4, v253, 53
	v_add3_u32 v116, v190, s10, v0
	v_lshlrev_b32_e32 v0, 6, v188
	v_add3_u32 v2, v2, s11, v0
	v_min_i32_e32 v0, 0x8000, v116
	v_mov_b32_e32 v119, s4
	v_readlane_b32 s4, v253, 56
	v_mfma_f32_16x16x32_bf16 v[110:113], v[164:167], v[74:77], v[110:113]
	v_ashrrev_i32_e32 v117, 31, v116
	v_cmp_gt_i32_e32 vcc, s58, v116
	v_mov_b32_e32 v120, s4
	v_mfma_f32_16x16x32_bf16 v[106:109], v[168:171], v[74:77], v[106:109]
	v_readlane_b32 s4, v253, 54
	v_cndmask_b32_e32 v5, 0, v117, vcc
	v_cndmask_b32_e32 v115, v118, v119, vcc
	v_mfma_f32_16x16x32_bf16 v[102:105], v[172:175], v[74:77], v[102:105]
	v_mov_b32_e32 v121, s4
	v_cndmask_b32_e32 v114, v120, v121, vcc
	v_readlane_b32 s4, v253, 51
	v_mfma_f32_16x16x32_bf16 v[98:101], v[176:179], v[74:77], v[98:101]
	v_ashrrev_i32_e32 v3, 31, v2
	v_readlane_b32 s5, v253, 52
	v_mfma_f32_16x16x32_bf16 v[74:77], v[164:167], v[142:145], v[78:81]
	v_mfma_f32_16x16x32_bf16 v[78:81], v[168:171], v[142:145], v[130:133]
	s_nop 2
	v_ashrrev_i32_e32 v130, 12, v0
	v_add_u32_e32 v0, 0xffff8000, v116
	v_cndmask_b32_e32 v4, v0, v116, vcc
	v_lshlrev_b64 v[4:5], 12, v[4:5]
	v_lshl_add_u64 v[4:5], v[114:115], 0, v[4:5]
	v_mul_hi_i32_i24_e32 v115, 0x6000, v130
	v_mul_i32_i24_e32 v114, 0x6000, v130
	v_lshl_add_u64 v[130:131], s[4:5], 0, v[114:115]
	v_lshlrev_b64 v[114:115], 2, v[2:3]
	v_mfma_f32_16x16x32_bf16 v[94:97], v[164:167], v[138:141], v[94:97]
	v_mfma_f32_16x16x32_bf16 v[90:93], v[168:171], v[138:141], v[90:93]
	v_mfma_f32_16x16x32_bf16 v[86:89], v[172:175], v[138:141], v[86:89]
	v_mfma_f32_16x16x32_bf16 v[82:85], v[176:179], v[138:141], v[82:85]
	v_lshl_add_u64 v[138:139], v[130:131], 0, v[114:115]
	v_lshl_add_u64 v[140:141], v[4:5], 0, v[114:115]
	flat_load_dwordx4 v[2:5], v[138:139]
	flat_load_dwordx4 v[130:133], v[140:141]
	v_mfma_f32_16x16x32_bf16 v[70:73], v[172:175], v[142:145], v[70:73]
	s_waitcnt vmcnt(0) lgkmcnt(0)
	v_pk_fma_f32 v[2:3], v[126:127], v[2:3], v[130:131]
	v_mfma_f32_16x16x32_bf16 v[66:69], v[176:179], v[142:145], v[66:69]
	v_lshlrev_b64 v[142:143], 12, v[116:117]
	v_lshlrev_b64 v[144:145], 12, v[0:1]
	v_lshl_add_u64 v[142:143], s[48:49], 0, v[142:143]
	v_lshl_add_u64 v[144:145], s[94:95], 0, v[144:145]
	v_cndmask_b32_e32 v143, v145, v143, vcc
	v_cndmask_b32_e32 v142, v144, v142, vcc
	v_lshl_add_u64 v[142:143], v[142:143], 0, v[114:115]
	v_pk_fma_f32 v[4:5], v[128:129], v[4:5], v[132:133]
	flat_store_dwordx4 v[142:143], v[2:5]
	flat_load_dwordx4 v[126:129], v[138:139] offset:64
	flat_load_dwordx4 v[130:133], v[140:141] offset:64
	v_mfma_f32_16x16x32_bf16 v[2:5], v[168:171], v[158:161], v[10:13]
	v_mfma_f32_16x16x32_bf16 v[62:65], v[164:167], v[146:149], v[62:65]
	s_waitcnt vmcnt(0) lgkmcnt(0)
	s_nop 0
	v_pk_fma_f32 v[10:11], v[122:123], v[126:127], v[130:131]
	v_pk_fma_f32 v[12:13], v[124:125], v[128:129], v[132:133]
	flat_store_dwordx4 v[142:143], v[10:13] offset:64
	flat_load_dwordx4 v[10:13], v[138:139] offset:128
	s_nop 0
	flat_load_dwordx4 v[122:125], v[140:141] offset:128
	v_mfma_f32_16x16x32_bf16 v[58:61], v[168:171], v[146:149], v[58:61]
	s_waitcnt vmcnt(0) lgkmcnt(0)
	v_pk_fma_f32 v[10:11], v[180:181], v[10:11], v[122:123]
	v_pk_fma_f32 v[12:13], v[182:183], v[12:13], v[124:125]
	flat_store_dwordx4 v[142:143], v[10:13] offset:128
	flat_load_dwordx4 v[122:125], v[138:139] offset:192
	flat_load_dwordx4 v[126:129], v[140:141] offset:192
	v_mfma_f32_16x16x32_bf16 v[54:57], v[172:175], v[146:149], v[54:57]
	s_waitcnt vmcnt(0) lgkmcnt(0)
	v_pk_fma_f32 v[122:123], v[184:185], v[122:123], v[126:127]
	v_pk_fma_f32 v[124:125], v[186:187], v[124:125], v[128:129]
	v_mfma_f32_16x16x32_bf16 v[50:53], v[176:179], v[146:149], v[50:53]
	flat_store_dwordx4 v[142:143], v[122:125] offset:192
	v_mfma_f32_16x16x32_bf16 v[46:49], v[164:167], v[150:153], v[46:49]
	v_mfma_f32_16x16x32_bf16 v[42:45], v[168:171], v[150:153], v[42:45]
	v_mfma_f32_16x16x32_bf16 v[38:41], v[172:175], v[150:153], v[38:41]
	v_mfma_f32_16x16x32_bf16 v[34:37], v[176:179], v[150:153], v[34:37]
	v_mfma_f32_16x16x32_bf16 v[30:33], v[164:167], v[154:157], v[30:33]
	v_mfma_f32_16x16x32_bf16 v[26:29], v[168:171], v[154:157], v[26:29]
	v_mfma_f32_16x16x32_bf16 v[22:25], v[172:175], v[154:157], v[22:25]
	v_mfma_f32_16x16x32_bf16 v[18:21], v[176:179], v[154:157], v[18:21]
	v_mfma_f32_16x16x32_bf16 v[14:17], v[164:167], v[158:161], v[14:17]
	v_mfma_f32_16x16x32_bf16 v[6:9], v[172:175], v[158:161], v[6:9]
	v_mfma_f32_16x16x32_bf16 v[10:13], v[176:179], v[158:161], v[134:137]
	v_add_u32_e32 v122, 16, v116
	v_min_i32_e32 v0, 0x8000, v122
	v_cmp_gt_i32_e32 vcc, s58, v122
	v_ashrrev_i32_e32 v117, 12, v0
	v_add_u32_e32 v0, 0xffff8010, v116
	v_ashrrev_i32_e32 v123, 31, v122
	v_cndmask_b32_e32 v125, 0, v123, vcc
	v_cndmask_b32_e32 v124, v0, v122, vcc
	v_cndmask_b32_e32 v127, v118, v119, vcc
	v_cndmask_b32_e32 v126, v120, v121, vcc
	v_lshlrev_b64 v[124:125], 12, v[124:125]
	v_lshl_add_u64 v[124:125], v[126:127], 0, v[124:125]
	v_lshlrev_b64 v[122:123], 12, v[122:123]
	v_lshlrev_b64 v[126:127], 12, v[0:1]
	v_lshl_add_u64 v[122:123], s[48:49], 0, v[122:123]
	v_lshl_add_u64 v[126:127], s[94:95], 0, v[126:127]
	v_cndmask_b32_e32 v123, v127, v123, vcc
	v_cndmask_b32_e32 v122, v126, v122, vcc
	v_mul_hi_i32_i24_e32 v127, 0x6000, v117
	v_mul_i32_i24_e32 v126, 0x6000, v117
	v_lshl_add_u64 v[126:127], s[4:5], 0, v[126:127]
	v_lshl_add_u64 v[130:131], v[126:127], 0, v[114:115]
	v_lshl_add_u64 v[132:133], v[124:125], 0, v[114:115]
	v_lshl_add_u64 v[134:135], v[122:123], 0, v[114:115]
	flat_load_dwordx4 v[122:125], v[130:131]
	flat_load_dwordx4 v[126:129], v[132:133]
	s_waitcnt vmcnt(0) lgkmcnt(0)
; template <int MI, int NI>
; DI void resid_tile(const u16* A, int K, const u16* Bt, const float* gate, const float* xl_in, const float* xc_in, float* xl_out, float* xc_out,
;                    int m0, int n0, char* smem) {
;     ...
; #pragma unroll
;   for (int mi = 0; mi < MI; ++mi) {
;     const int m = m0 + wr * 16 * MI + mi * 16 + lr;
;     const int b9 = m < NTL ? m >> 12 : 8;
;     const float* xi = xrow(xl_in, xc_in, m);
;     float* xo = m < NTL ? xl_out + (size_t)m * D : xc_out + (size_t)(m - NTL) * D;
; #pragma unroll
;     for (int ni = 0; ni < NI; ++ni) {
;       const int n = n0 + wc * 16 * NI + ni * 16 + lq * 4;
;       const float4 g = *(const float4*)(gate + (size_t)b9 * 6144 + n);
;       const float4 xv = *(const float4*)(xi + n);
;       float4 ov;
;       ov.x = xv.x + g.x * acc[mi][ni][0]; ov.y = xv.y + g.y * acc[mi][ni][1]; ov.z = xv.z + g.z * acc[mi][ni][2]; ov.w = xv.w + g.w * acc[mi][ni][3];
;       *(float4*)(xo + n) = ov;
;     }
;     __builtin_amdgcn_sched_barrier(0);
;   }
	v_pk_fma_f32 v[110:111], v[110:111], v[122:123], v[126:127]
	v_pk_fma_f32 v[112:113], v[112:113], v[124:125], v[128:129]
	flat_store_dwordx4 v[134:135], v[110:113]
	flat_load_dwordx4 v[110:113], v[130:131] offset:64
	s_nop 0
	flat_load_dwordx4 v[122:125], v[132:133] offset:64
	s_waitcnt vmcnt(0) lgkmcnt(0)
	v_pk_fma_f32 v[106:107], v[106:107], v[110:111], v[122:123]
	v_pk_fma_f32 v[108:109], v[108:109], v[112:113], v[124:125]
	flat_store_dwordx4 v[134:135], v[106:109] offset:64
	flat_load_dwordx4 v[106:109], v[130:131] offset:128
	s_nop 0
	flat_load_dwordx4 v[110:113], v[132:133] offset:128
	s_waitcnt vmcnt(0) lgkmcnt(0)
	v_pk_fma_f32 v[102:103], v[102:103], v[106:107], v[110:111]
	v_pk_fma_f32 v[104:105], v[104:105], v[108:109], v[112:113]
	flat_store_dwordx4 v[134:135], v[102:105] offset:128
	flat_load_dwordx4 v[102:105], v[130:131] offset:192
	s_nop 0
	flat_load_dwordx4 v[106:109], v[132:133] offset:192
	s_waitcnt vmcnt(0) lgkmcnt(0)
	v_pk_fma_f32 v[98:99], v[98:99], v[102:103], v[106:107]
	v_pk_fma_f32 v[100:101], v[100:101], v[104:105], v[108:109]
	flat_store_dwordx4 v[134:135], v[98:101] offset:192
	s_nop 1
	v_add_u32_e32 v98, 32, v116
	v_min_i32_e32 v0, 0x8000, v98
	v_cmp_gt_i32_e32 vcc, s58, v98
	v_ashrrev_i32_e32 v104, 12, v0
	v_add_u32_e32 v0, 0xffff8020, v116
	v_ashrrev_i32_e32 v99, 31, v98
	v_cndmask_b32_e32 v101, 0, v99, vcc
	v_cndmask_b32_e32 v100, v0, v98, vcc
	v_cndmask_b32_e32 v103, v118, v119, vcc
	v_cndmask_b32_e32 v102, v120, v121, vcc
	v_lshlrev_b64 v[100:101], 12, v[100:101]
	v_lshl_add_u64 v[100:101], v[102:103], 0, v[100:101]
	v_lshlrev_b64 v[98:99], 12, v[98:99]
	v_lshlrev_b64 v[102:103], 12, v[0:1]
	v_lshl_add_u64 v[98:99], s[48:49], 0, v[98:99]
	v_lshl_add_u64 v[102:103], s[94:95], 0, v[102:103]
	v_cndmask_b32_e32 v99, v103, v99, vcc
	v_cndmask_b32_e32 v98, v102, v98, vcc
	v_mul_hi_i32_i24_e32 v103, 0x6000, v104
	v_mul_i32_i24_e32 v102, 0x6000, v104
	v_lshl_add_u64 v[102:103], s[4:5], 0, v[102:103]
	v_lshl_add_u64 v[106:107], v[102:103], 0, v[114:115]
	v_lshl_add_u64 v[108:109], v[100:101], 0, v[114:115]
	v_lshl_add_u64 v[110:111], v[98:99], 0, v[114:115]
	flat_load_dwordx4 v[98:101], v[106:107]
	flat_load_dwordx4 v[102:105], v[108:109]
	s_waitcnt vmcnt(0) lgkmcnt(0)
	v_pk_fma_f32 v[94:95], v[94:95], v[98:99], v[102:103]
	v_pk_fma_f32 v[96:97], v[96:97], v[100:101], v[104:105]
	flat_store_dwordx4 v[110:111], v[94:97]
	flat_load_dwordx4 v[94:97], v[106:107] offset:64
	s_nop 0
	flat_load_dwordx4 v[98:101], v[108:109] offset:64
	s_waitcnt vmcnt(0) lgkmcnt(0)
	v_pk_fma_f32 v[90:91], v[90:91], v[94:95], v[98:99]
	v_pk_fma_f32 v[92:93], v[92:93], v[96:97], v[100:101]
	flat_store_dwordx4 v[110:111], v[90:93] offset:64
	flat_load_dwordx4 v[90:93], v[106:107] offset:128
	s_nop 0
	flat_load_dwordx4 v[94:97], v[108:109] offset:128
	s_waitcnt vmcnt(0) lgkmcnt(0)
	v_pk_fma_f32 v[86:87], v[86:87], v[90:91], v[94:95]
	v_pk_fma_f32 v[88:89], v[88:89], v[92:93], v[96:97]
	flat_store_dwordx4 v[110:111], v[86:89] offset:128
	flat_load_dwordx4 v[86:89], v[106:107] offset:192
	s_nop 0
	flat_load_dwordx4 v[90:93], v[108:109] offset:192
	s_waitcnt vmcnt(0) lgkmcnt(0)
	v_pk_fma_f32 v[82:83], v[82:83], v[86:87], v[90:91]
	v_pk_fma_f32 v[84:85], v[84:85], v[88:89], v[92:93]
	flat_store_dwordx4 v[110:111], v[82:85] offset:192
	s_nop 1
	v_add_u32_e32 v82, 48, v116
	v_min_i32_e32 v0, 0x8000, v82
	v_cmp_gt_i32_e32 vcc, s58, v82
	v_ashrrev_i32_e32 v88, 12, v0
	v_add_u32_e32 v0, 0xffff8030, v116
	v_ashrrev_i32_e32 v83, 31, v82
	v_cndmask_b32_e32 v85, 0, v83, vcc
	v_cndmask_b32_e32 v84, v0, v82, vcc
	v_cndmask_b32_e32 v87, v118, v119, vcc
	v_cndmask_b32_e32 v86, v120, v121, vcc
	v_lshlrev_b64 v[84:85], 12, v[84:85]
	v_lshl_add_u64 v[84:85], v[86:87], 0, v[84:85]
	v_lshlrev_b64 v[82:83], 12, v[82:83]
	v_lshlrev_b64 v[86:87], 12, v[0:1]
	v_lshl_add_u64 v[82:83], s[48:49], 0, v[82:83]
	v_lshl_add_u64 v[86:87], s[94:95], 0, v[86:87]
	v_cndmask_b32_e32 v83, v87, v83, vcc
	v_cndmask_b32_e32 v82, v86, v82, vcc
	v_mul_hi_i32_i24_e32 v87, 0x6000, v88
	v_mul_i32_i24_e32 v86, 0x6000, v88
	v_lshl_add_u64 v[86:87], s[4:5], 0, v[86:87]
	v_lshl_add_u64 v[90:91], v[86:87], 0, v[114:115]
	v_lshl_add_u64 v[92:93], v[84:85], 0, v[114:115]
	v_lshl_add_u64 v[94:95], v[82:83], 0, v[114:115]
	flat_load_dwordx4 v[82:85], v[90:91]
	flat_load_dwordx4 v[86:89], v[92:93]
	s_waitcnt vmcnt(0) lgkmcnt(0)
	v_pk_fma_f32 v[74:75], v[74:75], v[82:83], v[86:87]
	v_pk_fma_f32 v[76:77], v[76:77], v[84:85], v[88:89]
	flat_store_dwordx4 v[94:95], v[74:77]
	flat_load_dwordx4 v[74:77], v[90:91] offset:64
	s_nop 0
	flat_load_dwordx4 v[82:85], v[92:93] offset:64
	s_waitcnt vmcnt(0) lgkmcnt(0)
	v_pk_fma_f32 v[74:75], v[78:79], v[74:75], v[82:83]
	v_pk_fma_f32 v[76:77], v[80:81], v[76:77], v[84:85]
	flat_store_dwordx4 v[94:95], v[74:77] offset:64
	flat_load_dwordx4 v[74:77], v[90:91] offset:128
	s_nop 0
	flat_load_dwordx4 v[78:81], v[92:93] offset:128
	s_waitcnt vmcnt(0) lgkmcnt(0)
	v_pk_fma_f32 v[70:71], v[70:71], v[74:75], v[78:79]
	v_pk_fma_f32 v[72:73], v[72:73], v[76:77], v[80:81]
	flat_store_dwordx4 v[94:95], v[70:73] offset:128
	flat_load_dwordx4 v[70:73], v[90:91] offset:192
	s_nop 0
	flat_load_dwordx4 v[74:77], v[92:93] offset:192
	s_waitcnt vmcnt(0) lgkmcnt(0)
; template <int MI, int NI>
; DI void resid_tile(const u16* A, int K, const u16* Bt, const float* gate, const float* xl_in, const float* xc_in, float* xl_out, float* xc_out,
;                    int m0, int n0, char* smem) {
;     ...
; #pragma unroll
;   for (int mi = 0; mi < MI; ++mi) {
;     const int m = m0 + wr * 16 * MI + mi * 16 + lr;
;     const int b9 = m < NTL ? m >> 12 : 8;
;     const float* xi = xrow(xl_in, xc_in, m);
;     float* xo = m < NTL ? xl_out + (size_t)m * D : xc_out + (size_t)(m - NTL) * D;
; #pragma unroll
;     for (int ni = 0; ni < NI; ++ni) {
;       const int n = n0 + wc * 16 * NI + ni * 16 + lq * 4;
;       const float4 g = *(const float4*)(gate + (size_t)b9 * 6144 + n);
;       const float4 xv = *(const float4*)(xi + n);
;       float4 ov;
;       ov.x = xv.x + g.x * acc[mi][ni][0]; ov.y = xv.y + g.y * acc[mi][ni][1]; ov.z = xv.z + g.z * acc[mi][ni][2]; ov.w = xv.w + g.w * acc[mi][ni][3];
;       *(float4*)(xo + n) = ov;
;     }
;     __builtin_amdgcn_sched_barrier(0);
;   }
	v_pk_fma_f32 v[66:67], v[66:67], v[70:71], v[74:75]
	v_pk_fma_f32 v[68:69], v[68:69], v[72:73], v[76:77]
	flat_store_dwordx4 v[94:95], v[66:69] offset:192
	s_nop 1
	v_add_u32_e32 v66, 64, v116
	v_min_i32_e32 v0, 0x8000, v66
	v_cmp_gt_i32_e32 vcc, s58, v66
	v_ashrrev_i32_e32 v72, 12, v0
	v_add_u32_e32 v0, 0xffff8040, v116
	v_ashrrev_i32_e32 v67, 31, v66
	v_cndmask_b32_e32 v69, 0, v67, vcc
	v_cndmask_b32_e32 v68, v0, v66, vcc
	v_cndmask_b32_e32 v71, v118, v119, vcc
	v_cndmask_b32_e32 v70, v120, v121, vcc
	v_lshlrev_b64 v[68:69], 12, v[68:69]
	v_lshl_add_u64 v[68:69], v[70:71], 0, v[68:69]
	v_lshlrev_b64 v[66:67], 12, v[66:67]
	v_lshlrev_b64 v[70:71], 12, v[0:1]
	v_lshl_add_u64 v[66:67], s[48:49], 0, v[66:67]
	v_lshl_add_u64 v[70:71], s[94:95], 0, v[70:71]
	v_cndmask_b32_e32 v67, v71, v67, vcc
	v_cndmask_b32_e32 v66, v70, v66, vcc
	v_mul_hi_i32_i24_e32 v71, 0x6000, v72
	v_mul_i32_i24_e32 v70, 0x6000, v72
	v_lshl_add_u64 v[70:71], s[4:5], 0, v[70:71]
	v_lshl_add_u64 v[74:75], v[70:71], 0, v[114:115]
	v_lshl_add_u64 v[76:77], v[68:69], 0, v[114:115]
	v_lshl_add_u64 v[78:79], v[66:67], 0, v[114:115]
	flat_load_dwordx4 v[66:69], v[74:75]
	flat_load_dwordx4 v[70:73], v[76:77]
	s_waitcnt vmcnt(0) lgkmcnt(0)
	v_pk_fma_f32 v[62:63], v[62:63], v[66:67], v[70:71]
	v_pk_fma_f32 v[64:65], v[64:65], v[68:69], v[72:73]
	flat_store_dwordx4 v[78:79], v[62:65]
	flat_load_dwordx4 v[62:65], v[74:75] offset:64
	s_nop 0
	flat_load_dwordx4 v[66:69], v[76:77] offset:64
	s_waitcnt vmcnt(0) lgkmcnt(0)
	v_pk_fma_f32 v[58:59], v[58:59], v[62:63], v[66:67]
	v_pk_fma_f32 v[60:61], v[60:61], v[64:65], v[68:69]
	flat_store_dwordx4 v[78:79], v[58:61] offset:64
	flat_load_dwordx4 v[58:61], v[74:75] offset:128
	s_nop 0
	flat_load_dwordx4 v[62:65], v[76:77] offset:128
	s_waitcnt vmcnt(0) lgkmcnt(0)
	v_pk_fma_f32 v[54:55], v[54:55], v[58:59], v[62:63]
	v_pk_fma_f32 v[56:57], v[56:57], v[60:61], v[64:65]
	flat_store_dwordx4 v[78:79], v[54:57] offset:128
	flat_load_dwordx4 v[54:57], v[74:75] offset:192
	s_nop 0
	flat_load_dwordx4 v[58:61], v[76:77] offset:192
	s_waitcnt vmcnt(0) lgkmcnt(0)
	v_pk_fma_f32 v[50:51], v[50:51], v[54:55], v[58:59]
	v_pk_fma_f32 v[52:53], v[52:53], v[56:57], v[60:61]
	flat_store_dwordx4 v[78:79], v[50:53] offset:192
	s_nop 1
	v_add_u32_e32 v50, 0x50, v116
	v_min_i32_e32 v0, 0x8000, v50
	v_cmp_gt_i32_e32 vcc, s58, v50
	v_ashrrev_i32_e32 v56, 12, v0
	v_add_u32_e32 v0, 0xffff8050, v116
	v_ashrrev_i32_e32 v51, 31, v50
	v_cndmask_b32_e32 v53, 0, v51, vcc
	v_cndmask_b32_e32 v52, v0, v50, vcc
	v_cndmask_b32_e32 v55, v118, v119, vcc
	v_cndmask_b32_e32 v54, v120, v121, vcc
	v_lshlrev_b64 v[52:53], 12, v[52:53]
	v_lshl_add_u64 v[52:53], v[54:55], 0, v[52:53]
	v_lshlrev_b64 v[50:51], 12, v[50:51]
	v_lshlrev_b64 v[54:55], 12, v[0:1]
	v_lshl_add_u64 v[50:51], s[48:49], 0, v[50:51]
	v_lshl_add_u64 v[54:55], s[94:95], 0, v[54:55]
	v_cndmask_b32_e32 v51, v55, v51, vcc
	v_cndmask_b32_e32 v50, v54, v50, vcc
	v_mul_hi_i32_i24_e32 v55, 0x6000, v56
	v_mul_i32_i24_e32 v54, 0x6000, v56
	v_lshl_add_u64 v[54:55], s[4:5], 0, v[54:55]
	v_lshl_add_u64 v[58:59], v[54:55], 0, v[114:115]
	v_lshl_add_u64 v[60:61], v[52:53], 0, v[114:115]
	v_lshl_add_u64 v[62:63], v[50:51], 0, v[114:115]
	flat_load_dwordx4 v[50:53], v[58:59]
	flat_load_dwordx4 v[54:57], v[60:61]
	s_waitcnt vmcnt(0) lgkmcnt(0)
	v_pk_fma_f32 v[46:47], v[46:47], v[50:51], v[54:55]
	v_pk_fma_f32 v[48:49], v[48:49], v[52:53], v[56:57]
	flat_store_dwordx4 v[62:63], v[46:49]
	flat_load_dwordx4 v[46:49], v[58:59] offset:64
	s_nop 0
	flat_load_dwordx4 v[50:53], v[60:61] offset:64
	s_waitcnt vmcnt(0) lgkmcnt(0)
	v_pk_fma_f32 v[42:43], v[42:43], v[46:47], v[50:51]
	v_pk_fma_f32 v[44:45], v[44:45], v[48:49], v[52:53]
	flat_store_dwordx4 v[62:63], v[42:45] offset:64
	flat_load_dwordx4 v[42:45], v[58:59] offset:128
	s_nop 0
	flat_load_dwordx4 v[46:49], v[60:61] offset:128
	s_waitcnt vmcnt(0) lgkmcnt(0)
	v_pk_fma_f32 v[38:39], v[38:39], v[42:43], v[46:47]
	v_pk_fma_f32 v[40:41], v[40:41], v[44:45], v[48:49]
	flat_store_dwordx4 v[62:63], v[38:41] offset:128
	flat_load_dwordx4 v[38:41], v[58:59] offset:192
	s_nop 0
	flat_load_dwordx4 v[42:45], v[60:61] offset:192
	s_waitcnt vmcnt(0) lgkmcnt(0)
; template <int MI, int NI>
; DI void resid_tile(const u16* A, int K, const u16* Bt, const float* gate, const float* xl_in, const float* xc_in, float* xl_out, float* xc_out,
;                    int m0, int n0, char* smem) {
;     ...
; #pragma unroll
;   for (int mi = 0; mi < MI; ++mi) {
;     const int m = m0 + wr * 16 * MI + mi * 16 + lr;
;     const int b9 = m < NTL ? m >> 12 : 8;
;     const float* xi = xrow(xl_in, xc_in, m);
;     float* xo = m < NTL ? xl_out + (size_t)m * D : xc_out + (size_t)(m - NTL) * D;
; #pragma unroll
;     for (int ni = 0; ni < NI; ++ni) {
;       const int n = n0 + wc * 16 * NI + ni * 16 + lq * 4;
;       const float4 g = *(const float4*)(gate + (size_t)b9 * 6144 + n);
;       const float4 xv = *(const float4*)(xi + n);
;       float4 ov;
;       ov.x = xv.x + g.x * acc[mi][ni][0]; ov.y = xv.y + g.y * acc[mi][ni][1]; ov.z = xv.z + g.z * acc[mi][ni][2]; ov.w = xv.w + g.w * acc[mi][ni][3];
;       *(float4*)(xo + n) = ov;
;     }
;     __builtin_amdgcn_sched_barrier(0);
;   }
; DI void phase_resid(const Params& p, const u16* A, int K, const u16* Bt, const float* gate  ,
;                     const float* xl_in, const float* xc_in, float* xl_out, float* xc_out, int Mout, char* smem) {
;     ...
;   for (int it = 0;; ++it) {
;     int tm, tn;
;     if (!tile_map(it, NTL / 256, 8, blk__, gridDim.x, tm, tn)) break;
;     resid_tile<8, 4>(A, K, Bt, gate, xl_in, xc_in, xl_out, xc_out, tm * 256, tn * 128, smem);
;   }
	v_pk_fma_f32 v[34:35], v[34:35], v[38:39], v[42:43]
	v_pk_fma_f32 v[36:37], v[36:37], v[40:41], v[44:45]
	flat_store_dwordx4 v[62:63], v[34:37] offset:192
	s_nop 1
	v_add_u32_e32 v34, 0x60, v116
	v_min_i32_e32 v0, 0x8000, v34
	v_cmp_gt_i32_e32 vcc, s58, v34
	v_ashrrev_i32_e32 v40, 12, v0
	v_add_u32_e32 v0, 0xffff8060, v116
	v_ashrrev_i32_e32 v35, 31, v34
	v_cndmask_b32_e32 v37, 0, v35, vcc
	v_cndmask_b32_e32 v36, v0, v34, vcc
	v_cndmask_b32_e32 v39, v118, v119, vcc
	v_cndmask_b32_e32 v38, v120, v121, vcc
	v_lshlrev_b64 v[36:37], 12, v[36:37]
	v_lshl_add_u64 v[36:37], v[38:39], 0, v[36:37]
	v_lshlrev_b64 v[34:35], 12, v[34:35]
	v_lshlrev_b64 v[38:39], 12, v[0:1]
	v_lshl_add_u64 v[34:35], s[48:49], 0, v[34:35]
	v_lshl_add_u64 v[38:39], s[94:95], 0, v[38:39]
	v_cndmask_b32_e32 v35, v39, v35, vcc
	v_cndmask_b32_e32 v34, v38, v34, vcc
	v_mul_hi_i32_i24_e32 v39, 0x6000, v40
	v_mul_i32_i24_e32 v38, 0x6000, v40
	v_lshl_add_u64 v[38:39], s[4:5], 0, v[38:39]
	v_lshl_add_u64 v[42:43], v[38:39], 0, v[114:115]
	v_lshl_add_u64 v[44:45], v[36:37], 0, v[114:115]
	v_lshl_add_u64 v[46:47], v[34:35], 0, v[114:115]
	flat_load_dwordx4 v[34:37], v[42:43]
	flat_load_dwordx4 v[38:41], v[44:45]
	s_waitcnt vmcnt(0) lgkmcnt(0)
	v_pk_fma_f32 v[30:31], v[30:31], v[34:35], v[38:39]
	v_pk_fma_f32 v[32:33], v[32:33], v[36:37], v[40:41]
	flat_store_dwordx4 v[46:47], v[30:33]
	flat_load_dwordx4 v[30:33], v[42:43] offset:64
	s_nop 0
	flat_load_dwordx4 v[34:37], v[44:45] offset:64
	s_waitcnt vmcnt(0) lgkmcnt(0)
	v_pk_fma_f32 v[26:27], v[26:27], v[30:31], v[34:35]
	v_pk_fma_f32 v[28:29], v[28:29], v[32:33], v[36:37]
	flat_store_dwordx4 v[46:47], v[26:29] offset:64
	flat_load_dwordx4 v[26:29], v[42:43] offset:128
	s_nop 0
	flat_load_dwordx4 v[30:33], v[44:45] offset:128
	s_waitcnt vmcnt(0) lgkmcnt(0)
	v_pk_fma_f32 v[22:23], v[22:23], v[26:27], v[30:31]
	v_pk_fma_f32 v[24:25], v[24:25], v[28:29], v[32:33]
	flat_store_dwordx4 v[46:47], v[22:25] offset:128
	flat_load_dwordx4 v[22:25], v[42:43] offset:192
	s_nop 0
	flat_load_dwordx4 v[26:29], v[44:45] offset:192
	s_waitcnt vmcnt(0) lgkmcnt(0)
	v_pk_fma_f32 v[18:19], v[18:19], v[22:23], v[26:27]
	v_pk_fma_f32 v[20:21], v[20:21], v[24:25], v[28:29]
	flat_store_dwordx4 v[46:47], v[18:21] offset:192
	s_nop 1
	v_add_u32_e32 v18, 0x70, v116
	v_min_i32_e32 v0, 0x8000, v18
	v_cmp_gt_i32_e32 vcc, s58, v18
	v_ashrrev_i32_e32 v24, 12, v0
	v_add_u32_e32 v0, 0xffff8070, v116
	v_ashrrev_i32_e32 v19, 31, v18
	v_cndmask_b32_e32 v21, 0, v19, vcc
	v_cndmask_b32_e32 v20, v0, v18, vcc
	v_cndmask_b32_e32 v23, v118, v119, vcc
	v_cndmask_b32_e32 v22, v120, v121, vcc
	v_lshlrev_b64 v[20:21], 12, v[20:21]
	v_lshl_add_u64 v[20:21], v[22:23], 0, v[20:21]
	v_lshlrev_b64 v[18:19], 12, v[18:19]
	v_lshlrev_b64 v[22:23], 12, v[0:1]
	v_lshl_add_u64 v[18:19], s[48:49], 0, v[18:19]
	v_lshl_add_u64 v[22:23], s[94:95], 0, v[22:23]
	v_cndmask_b32_e32 v19, v23, v19, vcc
	v_cndmask_b32_e32 v18, v22, v18, vcc
	v_mul_hi_i32_i24_e32 v23, 0x6000, v24
	v_mul_i32_i24_e32 v22, 0x6000, v24
	v_lshl_add_u64 v[22:23], s[4:5], 0, v[22:23]
	v_lshl_add_u64 v[26:27], v[22:23], 0, v[114:115]
	v_lshl_add_u64 v[28:29], v[20:21], 0, v[114:115]
	v_lshl_add_u64 v[30:31], v[18:19], 0, v[114:115]
	flat_load_dwordx4 v[18:21], v[26:27]
	flat_load_dwordx4 v[22:25], v[28:29]
	s_waitcnt vmcnt(0) lgkmcnt(0)
	v_pk_fma_f32 v[14:15], v[14:15], v[18:19], v[22:23]
	v_pk_fma_f32 v[16:17], v[16:17], v[20:21], v[24:25]
	flat_store_dwordx4 v[30:31], v[14:17]
	flat_load_dwordx4 v[14:17], v[26:27] offset:64
	s_nop 0
	flat_load_dwordx4 v[18:21], v[28:29] offset:64
	s_waitcnt vmcnt(0) lgkmcnt(0)
	v_pk_fma_f32 v[2:3], v[2:3], v[14:15], v[18:19]
	v_pk_fma_f32 v[4:5], v[4:5], v[16:17], v[20:21]
	flat_store_dwordx4 v[30:31], v[2:5] offset:64
	flat_load_dwordx4 v[2:5], v[26:27] offset:128
	s_nop 0
	flat_load_dwordx4 v[14:17], v[28:29] offset:128
	s_waitcnt vmcnt(0) lgkmcnt(0)
	v_pk_fma_f32 v[2:3], v[6:7], v[2:3], v[14:15]
	v_pk_fma_f32 v[4:5], v[8:9], v[4:5], v[16:17]
	flat_store_dwordx4 v[30:31], v[2:5] offset:128
	flat_load_dwordx4 v[2:5], v[26:27] offset:192
	s_nop 0
	flat_load_dwordx4 v[6:9], v[28:29] offset:192
	s_waitcnt vmcnt(0) lgkmcnt(0)
	v_pk_fma_f32 v[2:3], v[10:11], v[2:3], v[6:7]
	v_pk_fma_f32 v[4:5], v[12:13], v[4:5], v[8:9]
	flat_store_dwordx4 v[30:31], v[2:5] offset:192
	s_add_i32 s9, s9, 1
	s_mul_i32 s4, s9, s39
	s_add_i32 s4, s4, s7
	s_cmpk_gt_i32 s4, 0x7f
	s_cbranch_scc0 .LBB0_461

; template <int MI, int NI>
; DI void gemm256(f32x4 (&acc)[MI][NI], const u16* __restrict__ A, int lda, const u16* __restrict__ Bt, int ldb, int K, int m0, int n0, char* smem) {
;     ...
;   for (int kt = 0; kt < nk; ++kt) {
;     if (kt + 1 < nk) asm volatile("s_waitcnt vmcnt(%0) lgkmcnt(0)" :: "n"(LPS) : "memory");
;     else asm volatile("s_waitcnt vmcnt(0) lgkmcnt(0)" ::: "memory");
;     __builtin_amdgcn_s_barrier();
;     __builtin_amdgcn_s_setprio(1);
;     const char* sb = smem + st * STAGE + foff;
;     bf16x8 af[MI], bfr[NI];
; #pragma unroll
;     for (int mi = 0; mi < MI; ++mi) af[mi] = *(const bf16x8*)(sb + (wr * MI + mi) * 1024);
; #pragma unroll
;     for (int ni = 0; ni < NI; ++ni) bfr[ni] = *(const bf16x8*)(sb + ABYTES + (wc * NI + ni) * 1024);
;     __builtin_amdgcn_sched_barrier(0x0);
;     if (kt + 2 < nk) { const int s2 = st >= 1 ? st - 1 : 2; G256_ISSUE(s2, (kt + 2) * 32); }
;     __builtin_amdgcn_s_setprio(0);
; #pragma unroll
;     for (int mi = 0; mi < MI; ++mi)
; #pragma unroll
;       for (int ni = 0; ni < NI; ++ni)
;         acc[mi][ni] = __builtin_amdgcn_mfma_f32_16x16x32_bf16(bfr[ni], af[mi], acc[mi][ni], 0, 0, 0);
;     st = st == 2 ? 0 : st + 1;
;   }
.LBB0_467:
	s_waitcnt vmcnt(2) lgkmcnt(0)
	s_barrier
	s_setprio 1
	s_lshl_b32 s12, s11, 13
	v_or_b32_e32 v0, s12, v24
	v_add_u32_e32 v28, v0, v27
	v_add_u32_e32 v32, v0, v26
	v_add_u32_e32 v0, v0, v25
	ds_read_b128 v[28:31], v28
	ds_read_b128 v[32:35], v32
	ds_read_b128 v[36:39], v0 offset:4096
	ds_read_b128 v[40:43], v0 offset:5120
	s_addk_i32 s12, 0xe000
	s_cmp_gt_i32 s11, 0
	s_cselect_b32 s12, s12, 0x4000
	v_add_u32_e32 v0, s12, v23
	v_add_u32_e32 v52, 0x1000, v0
	v_lshl_add_u64 v[48:49], v[18:19], 0, s[4:5]
	v_lshl_add_u64 v[48:49], v[48:49], 0, s[4:5]
	v_readfirstlane_b32 s12, v0
	v_lshl_add_u64 v[44:45], v[20:21], 0, s[4:5]
	s_mov_b64 s[98:99], 0x47e1100
	v_lshl_add_u64 v[50:51], v[48:49], 0, s[98:99]
	s_mov_b32 m0, s12
	v_readfirstlane_b32 s12, v52
	v_lshl_add_u64 v[46:47], v[44:45], 0, s[86:87]
	global_load_lds_dwordx4 v[50:51], off
	s_mov_b32 m0, s12
	s_nop 0
	global_load_lds_dwordx4 v[46:47], off
	s_setprio 0
	s_waitcnt lgkmcnt(0)
	v_mfma_f32_16x16x32_bf16 v[14:17], v[36:39], v[28:31], v[14:17]
	s_add_i32 s12, s11, 1
	s_waitcnt vmcnt(2) lgkmcnt(0)
	s_cmp_lg_u32 s11, 2
	v_mfma_f32_16x16x32_bf16 v[10:13], v[40:43], v[28:31], v[10:13]
	s_cselect_b32 s11, s12, 0
	s_barrier
	v_mfma_f32_16x16x32_bf16 v[2:5], v[36:39], v[32:35], v[2:5]
	v_mfma_f32_16x16x32_bf16 v[6:9], v[40:43], v[32:35], v[6:9]
	s_setprio 1
	s_lshl_b32 s12, s11, 13
	v_or_b32_e32 v0, s12, v24
	v_add_u32_e32 v28, v0, v27
	v_add_u32_e32 v32, v0, v26
	v_add_u32_e32 v0, v0, v25
	ds_read_b128 v[28:31], v28
	ds_read_b128 v[32:35], v32
	ds_read_b128 v[36:39], v0 offset:4096
	ds_read_b128 v[40:43], v0 offset:5120
	s_addk_i32 s12, 0xe000
	s_cmp_gt_i32 s11, 0
	s_cselect_b32 s12, s12, 0x4000
	v_add_u32_e32 v0, s12, v23
	s_mov_b64 s[12:13], 0x16610c0
	v_add_u32_e32 v52, 0x1000, v0
	v_lshl_add_u64 v[46:47], v[44:45], 0, s[12:13]
	v_readfirstlane_b32 s12, v0
	s_mov_b64 s[98:99], 0x47e1180
	v_lshl_add_u64 v[50:51], v[48:49], 0, s[98:99]
	s_mov_b32 m0, s12
	v_readfirstlane_b32 s12, v52
	global_load_lds_dwordx4 v[50:51], off
	s_mov_b32 m0, s12
	s_nop 0
	global_load_lds_dwordx4 v[46:47], off
	s_setprio 0
	s_waitcnt lgkmcnt(0)
	v_mfma_f32_16x16x32_bf16 v[14:17], v[36:39], v[28:31], v[14:17]
	s_add_i32 s12, s11, 1
	s_waitcnt vmcnt(2) lgkmcnt(0)
	s_cmp_lg_u32 s11, 2
	v_mfma_f32_16x16x32_bf16 v[10:13], v[40:43], v[28:31], v[10:13]
	s_cselect_b32 s11, s12, 0
	s_barrier
	v_mfma_f32_16x16x32_bf16 v[2:5], v[36:39], v[32:35], v[2:5]
	v_mfma_f32_16x16x32_bf16 v[6:9], v[40:43], v[32:35], v[6:9]
	s_setprio 1
	s_lshl_b32 s12, s11, 13
	v_or_b32_e32 v0, s12, v24
	v_add_u32_e32 v28, v0, v27
	v_add_u32_e32 v32, v0, v26
	v_add_u32_e32 v0, v0, v25
	ds_read_b128 v[28:31], v28
	ds_read_b128 v[32:35], v32
	ds_read_b128 v[36:39], v0 offset:4096
	ds_read_b128 v[40:43], v0 offset:5120
	s_addk_i32 s12, 0xe000
	s_cmp_gt_i32 s11, 0
	s_cselect_b32 s12, s12, 0x4000
	v_add_u32_e32 v0, s12, v23
	s_mov_b64 s[12:13], 0x1661100
	v_add_u32_e32 v52, 0x1000, v0
	v_lshl_add_u64 v[46:47], v[44:45], 0, s[12:13]
	v_readfirstlane_b32 s12, v0
	s_mov_b64 s[98:99], 0x47e1200
	v_lshl_add_u64 v[50:51], v[48:49], 0, s[98:99]
	s_mov_b32 m0, s12
	v_readfirstlane_b32 s12, v52
	global_load_lds_dwordx4 v[50:51], off
	s_mov_b32 m0, s12
	s_nop 0
	global_load_lds_dwordx4 v[46:47], off
	s_setprio 0
	s_waitcnt lgkmcnt(0)
	v_mfma_f32_16x16x32_bf16 v[14:17], v[36:39], v[28:31], v[14:17]
	s_add_i32 s12, s11, 1
	s_waitcnt vmcnt(2) lgkmcnt(0)
	s_cmp_lg_u32 s11, 2
	v_mfma_f32_16x16x32_bf16 v[10:13], v[40:43], v[28:31], v[10:13]
	s_cselect_b32 s11, s12, 0
	s_barrier
	v_mfma_f32_16x16x32_bf16 v[2:5], v[36:39], v[32:35], v[2:5]
	v_mfma_f32_16x16x32_bf16 v[6:9], v[40:43], v[32:35], v[6:9]
	s_setprio 1
	s_lshl_b32 s12, s11, 13
	v_or_b32_e32 v0, s12, v24
	v_add_u32_e32 v28, v0, v27
	v_add_u32_e32 v32, v0, v26
	v_add_u32_e32 v0, v0, v25
	ds_read_b128 v[28:31], v28
	ds_read_b128 v[32:35], v32
	ds_read_b128 v[36:39], v0 offset:4096
	ds_read_b128 v[40:43], v0 offset:5120
	s_addk_i32 s12, 0xe000
	s_cmp_gt_i32 s11, 0
	s_cselect_b32 s12, s12, 0x4000
	v_add_u32_e32 v0, s12, v23
	s_mov_b64 s[12:13], 0x1661140
	v_lshl_add_u64 v[46:47], v[44:45], 0, s[12:13]
	s_mov_b64 s[12:13], 0x47e1140
	v_add_u32_e32 v52, 0x1000, v0
	s_mov_b64 s[98:99], 0x47e1280
	v_lshl_add_u64 v[50:51], v[48:49], 0, s[98:99]
	v_readfirstlane_b32 s12, v0
	s_mov_b32 m0, s12
	v_readfirstlane_b32 s12, v52
	global_load_lds_dwordx4 v[50:51], off
	s_mov_b32 m0, s12
	s_nop 0
	global_load_lds_dwordx4 v[46:47], off
	s_setprio 0
	s_waitcnt lgkmcnt(0)
	v_mfma_f32_16x16x32_bf16 v[14:17], v[36:39], v[28:31], v[14:17]
	s_add_i32 s12, s11, 1
	s_waitcnt vmcnt(2) lgkmcnt(0)
	s_cmp_lg_u32 s11, 2
	v_mfma_f32_16x16x32_bf16 v[10:13], v[40:43], v[28:31], v[10:13]
	s_cselect_b32 s11, s12, 0
	s_barrier
	v_mfma_f32_16x16x32_bf16 v[2:5], v[36:39], v[32:35], v[2:5]
	v_mfma_f32_16x16x32_bf16 v[6:9], v[40:43], v[32:35], v[6:9]
	s_setprio 1
	s_lshl_b32 s12, s11, 13
	v_or_b32_e32 v0, s12, v24
	v_add_u32_e32 v28, v0, v27
	v_add_u32_e32 v32, v0, v26
	v_add_u32_e32 v0, v0, v25
	ds_read_b128 v[28:31], v28
	ds_read_b128 v[32:35], v32
	ds_read_b128 v[36:39], v0 offset:4096
	ds_read_b128 v[40:43], v0 offset:5120
	s_addk_i32 s12, 0xe000
	s_cmp_gt_i32 s11, 0
	s_cselect_b32 s12, s12, 0x4000
	v_add_u32_e32 v0, s12, v23
	s_mov_b64 s[12:13], 0x1661180
	v_lshl_add_u64 v[44:45], v[44:45], 0, s[12:13]
	s_mov_b64 s[12:13], 0x47e1180
	v_add_u32_e32 v50, 0x1000, v0
	s_mov_b64 s[98:99], 0x47e1300
	v_lshl_add_u64 v[46:47], v[48:49], 0, s[98:99]
	v_readfirstlane_b32 s12, v0
	s_mov_b32 m0, s12
	v_readfirstlane_b32 s12, v50
	global_load_lds_dwordx4 v[46:47], off
	s_mov_b32 m0, s12
	s_nop 0
	global_load_lds_dwordx4 v[44:45], off
	s_setprio 0
	s_add_i32 s12, s11, 1
	s_waitcnt lgkmcnt(0)
	v_mfma_f32_16x16x32_bf16 v[14:17], v[36:39], v[28:31], v[14:17]
	s_cmp_lg_u32 s11, 2
	s_cselect_b32 s11, s12, 0
	s_add_u32 s4, s4, 0x140
	v_mfma_f32_16x16x32_bf16 v[10:13], v[40:43], v[28:31], v[10:13]
	s_addc_u32 s5, s5, 0
	s_cmpk_eq_i32 s4, 0x780
	v_mfma_f32_16x16x32_bf16 v[2:5], v[36:39], v[32:35], v[2:5]
	v_mfma_f32_16x16x32_bf16 v[6:9], v[40:43], v[32:35], v[6:9]
	s_cbranch_scc0 .LBB0_467
; template <int MI, int NI>
; DI void gemm256(f32x4 (&acc)[MI][NI], const u16* __restrict__ A, int lda, const u16* __restrict__ Bt, int ldb, int K, int m0, int n0, char* smem) {
;     ...
;   for (int kt = 0; kt < nk; ++kt) {
;     if (kt + 1 < nk) asm volatile("s_waitcnt vmcnt(%0) lgkmcnt(0)" :: "n"(LPS) : "memory");
;     else asm volatile("s_waitcnt vmcnt(0) lgkmcnt(0)" ::: "memory");
;     __builtin_amdgcn_s_barrier();
;     __builtin_amdgcn_s_setprio(1);
;     const char* sb = smem + st * STAGE + foff;
;     bf16x8 af[MI], bfr[NI];
; #pragma unroll
;     for (int mi = 0; mi < MI; ++mi) af[mi] = *(const bf16x8*)(sb + (wr * MI + mi) * 1024);
; #pragma unroll
;     for (int ni = 0; ni < NI; ++ni) bfr[ni] = *(const bf16x8*)(sb + ABYTES + (wc * NI + ni) * 1024);
;     __builtin_amdgcn_sched_barrier(0x0);
;     if (kt + 2 < nk) { const int s2 = st >= 1 ? st - 1 : 2; G256_ISSUE(s2, (kt + 2) * 32); }
;     __builtin_amdgcn_s_setprio(0);
; #pragma unroll
;     for (int mi = 0; mi < MI; ++mi)
; #pragma unroll
;       for (int ni = 0; ni < NI; ++ni)
;         acc[mi][ni] = __builtin_amdgcn_mfma_f32_16x16x32_bf16(bfr[ni], af[mi], acc[mi][ni], 0, 0, 0);
;     st = st == 2 ? 0 : st + 1;
;   }
;   asm volatile("s_waitcnt lgkmcnt(0)" ::: "memory");
;   __builtin_amdgcn_s_barrier();
; template <int MI, int NI>
; DI void resid_tile(const u16* A, int K, const u16* Bt, const float* gate, const float* xl_in, const float* xc_in, float* xl_out, float* xc_out,
;                    int m0, int n0, char* smem) {
;     ...
; #pragma unroll
;   for (int mi = 0; mi < MI; ++mi) {
;     const int m = m0 + wr * 16 * MI + mi * 16 + lr;
;     const int b9 = m < NTL ? m >> 12 : 8;
;     const float* xi = xrow(xl_in, xc_in, m);
;     float* xo = m < NTL ? xl_out + (size_t)m * D : xc_out + (size_t)(m - NTL) * D;
; #pragma unroll
;     for (int ni = 0; ni < NI; ++ni) {
;       const int n = n0 + wc * 16 * NI + ni * 16 + lq * 4;
;       const float4 g = *(const float4*)(gate + (size_t)b9 * 6144 + n);
;       const float4 xv = *(const float4*)(xi + n);
;       float4 ov;
;       ov.x = xv.x + g.x * acc[mi][ni][0]; ov.y = xv.y + g.y * acc[mi][ni][1]; ov.z = xv.z + g.z * acc[mi][ni][2]; ov.w = xv.w + g.w * acc[mi][ni][3];
;       *(float4*)(xo + n) = ov;
;     }
;     __builtin_amdgcn_sched_barrier(0);
;   }
	s_waitcnt vmcnt(2) lgkmcnt(0)
	s_barrier
	s_setprio 1
	v_add_u32_e32 v0, v24, v27
	v_add_u32_e32 v38, v24, v25
	v_add_u32_e32 v23, v24, v26
	ds_read_b128 v[18:21], v0
	ds_read_b128 v[26:29], v23
	ds_read_b128 v[30:33], v38 offset:4096
	ds_read_b128 v[34:37], v38 offset:5120
	v_bfe_u32 v39, v22, 6, 1
	s_setprio 0
	s_waitcnt vmcnt(0) lgkmcnt(0)
	s_waitcnt lgkmcnt(1)
	v_mfma_f32_16x16x32_bf16 v[14:17], v[30:33], v[18:21], v[14:17]
	v_ashrrev_i32_e32 v40, 7, v22
	v_and_b32_e32 v41, 15, v22
	v_bfe_u32 v42, v22, 4, 2
	s_waitcnt lgkmcnt(0)
	v_mfma_f32_16x16x32_bf16 v[10:13], v[34:37], v[18:21], v[10:13]
	s_barrier
	v_mfma_f32_16x16x32_bf16 v[2:5], v[30:33], v[26:29], v[2:5]
	v_mfma_f32_16x16x32_bf16 v[18:21], v[34:37], v[26:29], v[6:9]
	s_setprio 1
	s_nop 1
	ds_read_b128 v[6:9], v0 offset:8192
	ds_read_b128 v[22:25], v23 offset:8192
	ds_read_b128 v[26:29], v38 offset:12288
	ds_read_b128 v[30:33], v38 offset:13312
	s_setprio 0
	s_waitcnt lgkmcnt(0)
	s_barrier
	v_readlane_b32 s4, v253, 55
	v_lshlrev_b32_e32 v0, 5, v40
	s_waitcnt lgkmcnt(1)
	v_mfma_f32_16x16x32_bf16 v[14:17], v[26:29], v[6:9], v[14:17]
	v_mov_b32_e32 v36, s4
	v_readlane_b32 s4, v253, 53
	s_waitcnt lgkmcnt(0)
	v_mfma_f32_16x16x32_bf16 v[10:13], v[30:33], v[6:9], v[10:13]
	v_mov_b32_e32 v37, s4
	v_readlane_b32 s4, v253, 56
	v_mfma_f32_16x16x32_bf16 v[6:9], v[26:29], v[22:25], v[2:5]
	v_add3_u32 v26, v41, s10, v0
	v_lshlrev_b32_e32 v0, 5, v39
	v_cmp_gt_i32_e32 vcc, s58, v26
	v_mfma_f32_16x16x32_bf16 v[2:5], v[30:33], v[22:25], v[18:21]
	v_ashrrev_i32_e32 v27, 31, v26
	v_mov_b32_e32 v38, s4
	v_readlane_b32 s4, v253, 54
	v_lshlrev_b32_e32 v18, 2, v42
	v_add3_u32 v18, v18, s9, v0
	v_min_i32_e32 v0, 0x8000, v26
	v_ashrrev_i32_e32 v28, 12, v0
	v_add_u32_e32 v0, 0xffff8000, v26
	v_cndmask_b32_e32 v21, 0, v27, vcc
	v_cndmask_b32_e32 v20, v0, v26, vcc
	v_mov_b32_e32 v39, s4
	v_cndmask_b32_e32 v23, v36, v37, vcc
	v_cndmask_b32_e32 v22, v38, v39, vcc
	v_lshlrev_b64 v[20:21], 12, v[20:21]
	v_lshl_add_u64 v[20:21], v[22:23], 0, v[20:21]
	v_lshlrev_b64 v[22:23], 12, v[26:27]
	v_lshlrev_b64 v[24:25], 12, v[0:1]
	v_lshl_add_u64 v[22:23], s[48:49], 0, v[22:23]
	v_lshl_add_u64 v[24:25], s[94:95], 0, v[24:25]
	v_readlane_b32 s4, v253, 51
	v_ashrrev_i32_e32 v19, 31, v18
	v_cndmask_b32_e32 v23, v25, v23, vcc
	v_cndmask_b32_e32 v22, v24, v22, vcc
	v_mul_hi_i32_i24_e32 v25, 0x6000, v28
	v_mul_i32_i24_e32 v24, 0x6000, v28
	v_readlane_b32 s5, v253, 52
	v_lshlrev_b64 v[28:29], 2, v[18:19]
	v_lshl_add_u64 v[32:33], v[20:21], 0, v[28:29]
	v_lshl_add_u64 v[24:25], s[4:5], 0, v[24:25]
	v_lshl_add_u64 v[30:31], v[24:25], 0, v[28:29]
	v_lshl_add_u64 v[34:35], v[22:23], 0, v[28:29]
	flat_load_dwordx4 v[18:21], v[30:31]
	flat_load_dwordx4 v[22:25], v[32:33]
	s_waitcnt vmcnt(0) lgkmcnt(0)
	v_pk_fma_f32 v[14:15], v[14:15], v[18:19], v[22:23]
	v_pk_fma_f32 v[16:17], v[16:17], v[20:21], v[24:25]
	flat_store_dwordx4 v[34:35], v[14:17]
	flat_load_dwordx4 v[14:17], v[30:31] offset:64
	s_nop 0
	flat_load_dwordx4 v[18:21], v[32:33] offset:64
	s_waitcnt vmcnt(0) lgkmcnt(0)
	v_pk_fma_f32 v[10:11], v[10:11], v[14:15], v[18:19]
	v_pk_fma_f32 v[12:13], v[12:13], v[16:17], v[20:21]
	flat_store_dwordx4 v[34:35], v[10:13] offset:64
	s_nop 1
	v_add_u32_e32 v10, 16, v26
	v_min_i32_e32 v0, 0x8000, v10
	v_cmp_gt_i32_e32 vcc, s58, v10
	v_ashrrev_i32_e32 v16, 12, v0
	v_add_u32_e32 v0, 0xffff8010, v26
	v_ashrrev_i32_e32 v11, 31, v10
	v_cndmask_b32_e32 v13, 0, v11, vcc
	v_cndmask_b32_e32 v12, v0, v10, vcc
	v_cndmask_b32_e32 v15, v36, v37, vcc
	v_cndmask_b32_e32 v14, v38, v39, vcc
	v_lshlrev_b64 v[12:13], 12, v[12:13]
	v_lshl_add_u64 v[12:13], v[14:15], 0, v[12:13]
	v_lshlrev_b64 v[10:11], 12, v[10:11]
	v_lshlrev_b64 v[14:15], 12, v[0:1]
	v_lshl_add_u64 v[10:11], s[48:49], 0, v[10:11]
	v_lshl_add_u64 v[14:15], s[94:95], 0, v[14:15]
	v_cndmask_b32_e32 v11, v15, v11, vcc
	v_cndmask_b32_e32 v10, v14, v10, vcc
	v_mul_hi_i32_i24_e32 v15, 0x6000, v16
	v_mul_i32_i24_e32 v14, 0x6000, v16
	v_lshl_add_u64 v[14:15], s[4:5], 0, v[14:15]
	v_lshl_add_u64 v[18:19], v[14:15], 0, v[28:29]
	v_lshl_add_u64 v[20:21], v[12:13], 0, v[28:29]
	v_lshl_add_u64 v[22:23], v[10:11], 0, v[28:29]
	flat_load_dwordx4 v[10:13], v[18:19]
	flat_load_dwordx4 v[14:17], v[20:21]
	s_waitcnt vmcnt(0) lgkmcnt(0)
	v_pk_fma_f32 v[6:7], v[6:7], v[10:11], v[14:15]
	v_pk_fma_f32 v[8:9], v[8:9], v[12:13], v[16:17]
	flat_store_dwordx4 v[22:23], v[6:9]
	flat_load_dwordx4 v[6:9], v[18:19] offset:64
	s_nop 0
	flat_load_dwordx4 v[10:13], v[20:21] offset:64
	s_waitcnt vmcnt(0) lgkmcnt(0)
	v_pk_fma_f32 v[2:3], v[2:3], v[6:7], v[10:11]
	v_pk_fma_f32 v[4:5], v[4:5], v[8:9], v[12:13]
	flat_store_dwordx4 v[22:23], v[2:5] offset:64
	s_add_i32 s6, s6, s79
	s_add_i32 s7, s7, s40
	s_add_i32 s8, s8, s41
	s_cmpk_gt_i32 s6, 0x1ff
	s_cbranch_scc0 .LBB0_466

; template <int MI, int NI>
; DI void gemm256(f32x4 (&acc)[MI][NI], const u16* __restrict__ A, int lda, const u16* __restrict__ Bt, int ldb, int K, int m0, int n0, char* smem) {
;     ...
;   for (int kt = 0; kt < nk; ++kt) {
;     if (kt + 1 < nk) asm volatile("s_waitcnt vmcnt(%0) lgkmcnt(0)" :: "n"(LPS) : "memory");
;     else asm volatile("s_waitcnt vmcnt(0) lgkmcnt(0)" ::: "memory");
;     __builtin_amdgcn_s_barrier();
;     __builtin_amdgcn_s_setprio(1);
;     const char* sb = smem + st * STAGE + foff;
;     bf16x8 af[MI], bfr[NI];
; #pragma unroll
;     for (int mi = 0; mi < MI; ++mi) af[mi] = *(const bf16x8*)(sb + (wr * MI + mi) * 1024);
; #pragma unroll
;     for (int ni = 0; ni < NI; ++ni) bfr[ni] = *(const bf16x8*)(sb + ABYTES + (wc * NI + ni) * 1024);
;     __builtin_amdgcn_sched_barrier(0x0);
;     if (kt + 2 < nk) { const int s2 = st >= 1 ? st - 1 : 2; G256_ISSUE(s2, (kt + 2) * 32); }
;     __builtin_amdgcn_s_setprio(0);
; #pragma unroll
;     for (int mi = 0; mi < MI; ++mi)
; #pragma unroll
;       for (int ni = 0; ni < NI; ++ni)
;         acc[mi][ni] = __builtin_amdgcn_mfma_f32_16x16x32_bf16(bfr[ni], af[mi], acc[mi][ni], 0, 0, 0);
;     st = st == 2 ? 0 : st + 1;
;   }
; DI void phase_merge(const Params& p, int l, int Mout, char* smem) {
;     ...
;         f32x4 ag[4][4]; zero_accm<4, 4>(ag);
;         gemm256<4, 4>(ag, hg, 1024, (const u16*)(wl + WO_WIN) + (size_t)(2080 + br * 1024) * 1024, 1024, 1024, m0, n0, smem);
.LBB0_480:
	s_waitcnt vmcnt(4) lgkmcnt(0)
	s_barrier
	s_setprio 1
	s_lshl_b32 s16, s15, 14
	v_or_b32_e32 v0, s16, v71
	v_add_u32_e32 v86, v0, v73
	v_add_u32_e32 v0, v0, v72
	ds_read_b128 v[74:77], v86
	ds_read_b128 v[78:81], v86 offset:1024
	ds_read_b128 v[82:85], v86 offset:2048
	ds_read_b128 v[86:89], v86 offset:3072
	ds_read_b128 v[90:93], v0 offset:8192
	ds_read_b128 v[94:97], v0 offset:9216
	ds_read_b128 v[98:101], v0 offset:10240
	ds_read_b128 v[102:105], v0 offset:11264
	s_add_i32 s18, s16, 0xffffc000
	s_cmp_gt_i32 s15, 0
	v_lshl_add_u64 v[106:107], v[68:69], 0, s[6:7]
	v_lshl_add_u64 v[106:107], v[106:107], 0, s[6:7]
	s_mov_b64 s[16:17], 0x8be1100
	v_lshl_add_u64 v[108:109], v[106:107], 0, s[16:17]
	s_cselect_b32 s16, s18, 0x8000
	v_add_u32_e32 v0, s16, v70
	v_add_u32_e32 v110, 0x400, v0
	v_readfirstlane_b32 s16, v0
	s_mov_b32 m0, s16
	s_mov_b64 s[16:17], 0x8be9100
	global_load_lds_dwordx4 v[108:109], off
	v_lshl_add_u64 v[108:109], v[106:107], 0, s[16:17]
	v_readfirstlane_b32 s16, v110
	s_mov_b32 m0, s16
	s_mov_b64 s[16:17], 0xd51100
	global_load_lds_dwordx4 v[108:109], off
	v_lshl_add_u64 v[108:109], v[66:67], 0, s[6:7]
	v_lshl_add_u64 v[108:109], v[108:109], 0, s[6:7]
	v_add_u32_e32 v112, 0x2000, v0
	v_lshl_add_u64 v[110:111], v[108:109], 0, s[16:17]
	v_readfirstlane_b32 s16, v112
	s_mov_b32 m0, s16
	s_mov_b64 s[16:17], 0xd59100
	v_add_u32_e32 v0, 0x2400, v0
	global_load_lds_dwordx4 v[110:111], off
	v_lshl_add_u64 v[110:111], v[108:109], 0, s[16:17]
	v_readfirstlane_b32 s16, v0
	s_mov_b32 m0, s16
	s_nop 0
	global_load_lds_dwordx4 v[110:111], off
	s_setprio 0
	s_waitcnt lgkmcnt(0)
	v_mfma_f32_16x16x32_bf16 v[62:65], v[90:93], v[74:77], v[62:65]
	s_add_i32 s16, s15, 1
	s_waitcnt vmcnt(4) lgkmcnt(0)
	s_cmp_lg_u32 s15, 2
	v_mfma_f32_16x16x32_bf16 v[58:61], v[94:97], v[74:77], v[58:61]
	s_cselect_b32 s15, s16, 0
	s_barrier
	v_mfma_f32_16x16x32_bf16 v[54:57], v[98:101], v[74:77], v[54:57]
	v_mfma_f32_16x16x32_bf16 v[46:49], v[102:105], v[74:77], v[46:49]
	v_mfma_f32_16x16x32_bf16 v[42:45], v[90:93], v[78:81], v[42:45]
	v_mfma_f32_16x16x32_bf16 v[38:41], v[94:97], v[78:81], v[38:41]
	v_mfma_f32_16x16x32_bf16 v[34:37], v[98:101], v[78:81], v[34:37]
	v_mfma_f32_16x16x32_bf16 v[30:33], v[102:105], v[78:81], v[30:33]
	v_mfma_f32_16x16x32_bf16 v[26:29], v[90:93], v[82:85], v[26:29]
	v_mfma_f32_16x16x32_bf16 v[22:25], v[94:97], v[82:85], v[22:25]
	v_mfma_f32_16x16x32_bf16 v[18:21], v[98:101], v[82:85], v[18:21]
	v_mfma_f32_16x16x32_bf16 v[14:17], v[102:105], v[82:85], v[14:17]
	v_mfma_f32_16x16x32_bf16 v[10:13], v[90:93], v[86:89], v[10:13]
	v_mfma_f32_16x16x32_bf16 v[6:9], v[94:97], v[86:89], v[6:9]
	v_mfma_f32_16x16x32_bf16 v[2:5], v[98:101], v[86:89], v[2:5]
	v_mfma_f32_16x16x32_bf16 v[50:53], v[102:105], v[86:89], v[50:53]
	s_setprio 1
	s_lshl_b32 s16, s15, 14
	v_or_b32_e32 v0, s16, v71
	v_add_u32_e32 v86, v0, v73
	v_add_u32_e32 v0, v0, v72
	ds_read_b128 v[74:77], v86
	ds_read_b128 v[78:81], v86 offset:1024
	ds_read_b128 v[82:85], v86 offset:2048
	ds_read_b128 v[86:89], v86 offset:3072
	ds_read_b128 v[90:93], v0 offset:8192
	ds_read_b128 v[94:97], v0 offset:9216
	ds_read_b128 v[98:101], v0 offset:10240
	ds_read_b128 v[102:105], v0 offset:11264
	s_add_i32 s18, s16, 0xffffc000
	s_cmp_gt_i32 s15, 0
	s_mov_b64 s[16:17], 0x8be1180
	v_lshl_add_u64 v[110:111], v[106:107], 0, s[16:17]
	s_cselect_b32 s16, s18, 0x8000
	v_add_u32_e32 v0, s16, v70
	s_nop 0
	v_readfirstlane_b32 s16, v0
	s_mov_b32 m0, s16
	s_mov_b64 s[16:17], 0x8be9180
	global_load_lds_dwordx4 v[110:111], off
	v_add_u32_e32 v110, 0x400, v0
	v_lshl_add_u64 v[106:107], v[106:107], 0, s[16:17]
	v_readfirstlane_b32 s16, v110
	s_mov_b32 m0, s16
	s_mov_b64 s[16:17], 0xd51180
	v_add_u32_e32 v110, 0x2000, v0
	global_load_lds_dwordx4 v[106:107], off
	v_lshl_add_u64 v[106:107], v[108:109], 0, s[16:17]
	v_readfirstlane_b32 s16, v110
	s_mov_b32 m0, s16
	s_mov_b64 s[16:17], 0xd59180
	v_add_u32_e32 v0, 0x2400, v0
	global_load_lds_dwordx4 v[106:107], off
	v_lshl_add_u64 v[106:107], v[108:109], 0, s[16:17]
	v_readfirstlane_b32 s16, v0
	s_mov_b32 m0, s16
	s_nop 0
	global_load_lds_dwordx4 v[106:107], off
	s_setprio 0
	s_add_i32 s16, s15, 1
	s_waitcnt lgkmcnt(0)
	v_mfma_f32_16x16x32_bf16 v[62:65], v[90:93], v[74:77], v[62:65]
	s_cmp_lg_u32 s15, 2
	s_cselect_b32 s15, s16, 0
	s_add_u32 s6, s6, 0x80
	v_mfma_f32_16x16x32_bf16 v[58:61], v[94:97], v[74:77], v[58:61]
	s_addc_u32 s7, s7, 0
	s_cmpk_eq_i32 s6, 0x780
	v_mfma_f32_16x16x32_bf16 v[54:57], v[98:101], v[74:77], v[54:57]
	v_mfma_f32_16x16x32_bf16 v[46:49], v[102:105], v[74:77], v[46:49]
	v_mfma_f32_16x16x32_bf16 v[42:45], v[90:93], v[78:81], v[42:45]
	v_mfma_f32_16x16x32_bf16 v[38:41], v[94:97], v[78:81], v[38:41]
	v_mfma_f32_16x16x32_bf16 v[34:37], v[98:101], v[78:81], v[34:37]
	v_mfma_f32_16x16x32_bf16 v[30:33], v[102:105], v[78:81], v[30:33]
	v_mfma_f32_16x16x32_bf16 v[26:29], v[90:93], v[82:85], v[26:29]
	v_mfma_f32_16x16x32_bf16 v[22:25], v[94:97], v[82:85], v[22:25]
	v_mfma_f32_16x16x32_bf16 v[18:21], v[98:101], v[82:85], v[18:21]
	v_mfma_f32_16x16x32_bf16 v[14:17], v[102:105], v[82:85], v[14:17]
	v_mfma_f32_16x16x32_bf16 v[10:13], v[90:93], v[86:89], v[10:13]
	v_mfma_f32_16x16x32_bf16 v[6:9], v[94:97], v[86:89], v[6:9]
	v_mfma_f32_16x16x32_bf16 v[2:5], v[98:101], v[86:89], v[2:5]
	v_mfma_f32_16x16x32_bf16 v[50:53], v[102:105], v[86:89], v[50:53]
	s_cbranch_scc0 .LBB0_480
	s_waitcnt vmcnt(4) lgkmcnt(0)
	s_barrier
; template <int MI, int NI>
; DI void gemm256(f32x4 (&acc)[MI][NI], const u16* __restrict__ A, int lda, const u16* __restrict__ Bt, int ldb, int K, int m0, int n0, char* smem) {
;     ...
;   for (int kt = 0; kt < nk; ++kt) {
;     if (kt + 1 < nk) asm volatile("s_waitcnt vmcnt(%0) lgkmcnt(0)" :: "n"(LPS) : "memory");
;     else asm volatile("s_waitcnt vmcnt(0) lgkmcnt(0)" ::: "memory");
;     __builtin_amdgcn_s_barrier();
;     __builtin_amdgcn_s_setprio(1);
;     const char* sb = smem + st * STAGE + foff;
;     bf16x8 af[MI], bfr[NI];
; #pragma unroll
;     for (int mi = 0; mi < MI; ++mi) af[mi] = *(const bf16x8*)(sb + (wr * MI + mi) * 1024);
; #pragma unroll
;     for (int ni = 0; ni < NI; ++ni) bfr[ni] = *(const bf16x8*)(sb + ABYTES + (wc * NI + ni) * 1024);
;     __builtin_amdgcn_sched_barrier(0x0);
;     if (kt + 2 < nk) { const int s2 = st >= 1 ? st - 1 : 2; G256_ISSUE(s2, (kt + 2) * 32); }
;     __builtin_amdgcn_s_setprio(0);
; #pragma unroll
;     for (int mi = 0; mi < MI; ++mi)
; #pragma unroll
;       for (int ni = 0; ni < NI; ++ni)
;         acc[mi][ni] = __builtin_amdgcn_mfma_f32_16x16x32_bf16(bfr[ni], af[mi], acc[mi][ni], 0, 0, 0);
;     st = st == 2 ? 0 : st + 1;
;   }
;   asm volatile("s_waitcnt lgkmcnt(0)" ::: "memory");
;   __builtin_amdgcn_s_barrier();
	s_setprio 1
	v_add_u32_e32 v0, v71, v73
	v_add_u32_e32 v98, v71, v72
	ds_read_b128 v[66:69], v0
	ds_read_b128 v[74:77], v0 offset:1024
	ds_read_b128 v[78:81], v0 offset:2048
	ds_read_b128 v[82:85], v0 offset:3072
	ds_read_b128 v[70:73], v98 offset:8192
	ds_read_b128 v[86:89], v98 offset:9216
	ds_read_b128 v[90:93], v98 offset:10240
	ds_read_b128 v[94:97], v98 offset:11264
	s_setprio 0
	s_waitcnt lgkmcnt(3)
	v_mfma_f32_16x16x32_bf16 v[62:65], v[70:73], v[66:69], v[62:65]
	s_waitcnt vmcnt(0) lgkmcnt(0)
	s_barrier
	s_waitcnt lgkmcnt(2)
	v_mfma_f32_16x16x32_bf16 v[58:61], v[86:89], v[66:69], v[58:61]
	s_waitcnt lgkmcnt(1)
	v_mfma_f32_16x16x32_bf16 v[54:57], v[90:93], v[66:69], v[54:57]
	s_waitcnt lgkmcnt(0)
	v_mfma_f32_16x16x32_bf16 v[46:49], v[94:97], v[66:69], v[46:49]
	v_mfma_f32_16x16x32_bf16 v[42:45], v[70:73], v[74:77], v[42:45]
	v_mfma_f32_16x16x32_bf16 v[38:41], v[86:89], v[74:77], v[38:41]
	v_mfma_f32_16x16x32_bf16 v[34:37], v[90:93], v[74:77], v[34:37]
	v_mfma_f32_16x16x32_bf16 v[30:33], v[94:97], v[74:77], v[30:33]
	v_mfma_f32_16x16x32_bf16 v[26:29], v[70:73], v[78:81], v[26:29]
	v_mfma_f32_16x16x32_bf16 v[22:25], v[86:89], v[78:81], v[22:25]
	v_mfma_f32_16x16x32_bf16 v[18:21], v[90:93], v[78:81], v[18:21]
	v_mfma_f32_16x16x32_bf16 v[14:17], v[94:97], v[78:81], v[14:17]
	v_mfma_f32_16x16x32_bf16 v[10:13], v[70:73], v[82:85], v[10:13]
	v_mfma_f32_16x16x32_bf16 v[6:9], v[86:89], v[82:85], v[6:9]
	v_mfma_f32_16x16x32_bf16 v[2:5], v[90:93], v[82:85], v[2:5]
	v_mfma_f32_16x16x32_bf16 v[50:53], v[94:97], v[82:85], v[50:53]
	s_setprio 1
	ds_read_b128 v[66:69], v0 offset:16384
	ds_read_b128 v[70:73], v0 offset:17408
	ds_read_b128 v[74:77], v0 offset:18432
	ds_read_b128 v[130:133], v0 offset:19456
	ds_read_b128 v[78:81], v98 offset:24576
	ds_read_b128 v[134:137], v98 offset:25600
	ds_read_b128 v[138:141], v98 offset:26624
	ds_read_b128 v[142:145], v98 offset:27648
	s_setprio 0
	s_waitcnt lgkmcnt(3)
	v_mfma_f32_16x16x32_bf16 v[126:129], v[78:81], v[66:69], v[62:65]
	s_waitcnt lgkmcnt(0)
	s_barrier
; template <int MI, int NI>
; DI void gemm256(f32x4 (&acc)[MI][NI], const u16* __restrict__ A, int lda, const u16* __restrict__ Bt, int ldb, int K, int m0, int n0, char* smem) {
;     ...
;   const int srow = lane >> 2, scol = ((lane & 3) ^ ((lane >> 5) << 1)) * 8;
;   const u16* Ag = A + (size_t)(m0 + wave * NAW * 16 + srow) * lda + scol;
;   const u16* Bg = Bt + (size_t)(n0 + wave * NBW * 16 + srow) * ldb + scol;
;   char* la = smem + (wave * NAW) * 1024 + lane * 16;
;   char* lb = smem + ABYTES + (wave * NBW) * 1024 + lane * 16;
;     ...
;   const int nk = K >> 5;
;   G256_ISSUE(0, 0);
;   if (nk > 1) G256_ISSUE(1, 32);
;   const int foff = lr * 64 + ((lq ^ ((lr >> 3) << 1)) * 16);
; DI void phase_merge(const Params& p, int l, int Mout, char* smem) {
;     ...
;         const int Kb = br == 1 ? 512 : 256;
;         const u16* Ab = br == 0 ? opool : br == 1 ? omla : orw;
;         const u16* Wb = (const u16*)(wl + (br == 0 ? WO_BRP : br == 1 ? WO_BRM : WO_BRR));
;         gemm256<4, 4>(ab, Ab, Kb, Wb, Kb, Kb, m0, n0, smem);
	s_waitcnt lgkmcnt(2)
	v_mfma_f32_16x16x32_bf16 v[122:125], v[134:137], v[66:69], v[58:61]
	s_waitcnt lgkmcnt(1)
	v_mfma_f32_16x16x32_bf16 v[118:121], v[138:141], v[66:69], v[54:57]
	s_waitcnt lgkmcnt(0)
	v_mfma_f32_16x16x32_bf16 v[114:117], v[142:145], v[66:69], v[46:49]
	v_mfma_f32_16x16x32_bf16 v[110:113], v[78:81], v[70:73], v[42:45]
	v_mfma_f32_16x16x32_bf16 v[106:109], v[134:137], v[70:73], v[38:41]
	v_mfma_f32_16x16x32_bf16 v[102:105], v[138:141], v[70:73], v[34:37]
	v_mfma_f32_16x16x32_bf16 v[98:101], v[142:145], v[70:73], v[30:33]
	v_mfma_f32_16x16x32_bf16 v[94:97], v[78:81], v[74:77], v[26:29]
	v_mfma_f32_16x16x32_bf16 v[90:93], v[134:137], v[74:77], v[22:25]
	v_mfma_f32_16x16x32_bf16 v[86:89], v[138:141], v[74:77], v[18:21]
	v_mfma_f32_16x16x32_bf16 v[82:85], v[142:145], v[74:77], v[14:17]
	v_mfma_f32_16x16x32_bf16 v[78:81], v[78:81], v[130:133], v[10:13]
	v_mfma_f32_16x16x32_bf16 v[74:77], v[134:137], v[130:133], v[6:9]
	v_mfma_f32_16x16x32_bf16 v[70:73], v[138:141], v[130:133], v[2:5]
	v_mfma_f32_16x16x32_bf16 v[66:69], v[142:145], v[130:133], v[50:53]
	s_cmp_eq_u32 s11, 1
	s_movk_i32 s6, 0x200
	v_mov_b32_e32 v8, v163
	s_cselect_b32 s18, s6, 0x100
	s_mov_b32 s6, 0x1caa1000
	s_mov_b32 s7, 0xba0000
	s_cselect_b32 s6, s6, 0x18481000
	v_ashrrev_i32_e32 v9, 6, v8
	v_bfe_u32 v0, v8, 2, 4
	s_cselect_b32 s7, s7, 0xca0000
	s_cselect_b32 s15, 9, 8
	s_cmp_eq_u32 s11, 0
	v_and_b32_e32 v2, 3, v8
	v_lshrrev_b32_e32 v3, 4, v8
	v_lshl_or_b32 v6, v9, 5, v0
	s_cselect_b32 s6, 0x1b781000, s6
	v_bitop3_b32 v5, v3, v2, 2 bitop3:0x6c
	v_add_u32_e32 v2, s13, v6
	s_cselect_b32 s16, 0xb20000, s7
	s_add_u32 s6, s62, s6
	v_ashrrev_i32_e32 v3, 31, v2
	s_addc_u32 s7, s63, 0
	v_lshlrev_b64 v[2:3], s15, v[2:3]
	v_and_b32_e32 v4, 63, v8
	v_lshl_add_u64 v[2:3], v[2:3], 1, s[6:7]
	v_lshlrev_b32_e32 v0, 4, v5
	s_mov_b32 s17, s2
	v_lshl_add_u64 v[228:229], v[2:3], 0, v[0:1]
	v_add_u32_e32 v2, s12, v6
	v_lshlrev_b32_e32 v4, 4, v4
	s_add_u32 s16, s44, s16
	v_ashrrev_i32_e32 v3, 31, v2
	v_lshl_or_b32 v250, v9, 11, v4
	s_addc_u32 s17, s45, 0
	v_lshlrev_b64 v[2:3], s15, v[2:3]
	v_readfirstlane_b32 s6, v250
	v_or_b32_e32 v7, 0x400, v250
	v_lshl_add_u64 v[2:3], v[2:3], 1, s[16:17]
	v_add_u32_e32 v6, 0x2000, v250
	s_mov_b32 m0, s6
	s_lshl_b32 s64, s18, 5
	v_readfirstlane_b32 s6, v7
	global_load_lds_dwordx4 v[228:229], off
	v_lshl_add_u64 v[4:5], v[228:229], 0, s[64:65]
	s_mov_b32 m0, s6
	v_lshl_add_u64 v[230:231], v[2:3], 0, v[0:1]
	v_readfirstlane_b32 s6, v6
	v_add_u32_e32 v0, 0x2400, v250
	global_load_lds_dwordx4 v[4:5], off
	s_mov_b32 m0, s6
	v_readfirstlane_b32 s6, v0
	v_add_u32_e32 v0, 0x4000, v250
	global_load_lds_dwordx4 v[230:231], off
	v_lshl_add_u64 v[2:3], v[230:231], 0, s[64:65]
	s_mov_b32 m0, s6
	v_readfirstlane_b32 s6, v0
	v_add_u32_e32 v0, 0x4400, v250
	global_load_lds_dwordx4 v[2:3], off
	v_lshl_add_u64 v[6:7], v[228:229], 0, 64
	s_mov_b32 m0, s6
	v_readfirstlane_b32 s6, v0
	v_add_u32_e32 v0, 0x6000, v250
	global_load_lds_dwordx4 v[6:7], off
	v_lshl_add_u64 v[4:5], v[4:5], 0, 64
	s_mov_b32 m0, s6
	v_readfirstlane_b32 s6, v0
	v_add_u32_e32 v0, 0x6400, v250
	global_load_lds_dwordx4 v[4:5], off
	v_lshl_add_u64 v[4:5], v[230:231], 0, 64
	s_mov_b32 m0, s6
	v_readfirstlane_b32 s6, v0
	global_load_lds_dwordx4 v[4:5], off
	v_lshl_add_u64 v[2:3], v[2:3], 0, 64
	s_mov_b32 m0, s6
	v_lshlrev_b32_e32 v0, 6, v8
	global_load_lds_dwordx4 v[2:3], off
	v_lshlrev_b32_e32 v2, 2, v8
	v_and_b32_e32 v3, 48, v8
	v_bitop3_b32 v2, v2, v3, 32 bitop3:0x6c
	v_and_or_b32 v248, v0, s59, v2
	v_lshlrev_b32_e32 v2, 5, v8
	s_lshl_b32 s6, s18, 4
	v_lshlrev_b32_e32 v0, 12, v9
	v_and_b32_e32 v249, 0xfffff000, v2
	v_mov_b32_e32 v2, 0
	s_mov_b32 s16, 1
	s_mov_b32 s15, 0
	s_lshr_b32 s17, s18, 5
	v_and_b32_e32 v0, 0x1000, v0
	s_mov_b32 s64, 64
	s_lshl_b32 s6, s6, 1
	v_mov_b32_e32 v3, v2
	v_mov_b32_e32 v4, v2
	v_mov_b32_e32 v5, v2
	v_mov_b32_e32 v6, v2
	v_mov_b32_e32 v7, v2
	v_mov_b32_e32 v8, v2
	v_mov_b32_e32 v9, v2
	v_mov_b32_e32 v10, v2
	v_mov_b32_e32 v11, v2
	v_mov_b32_e32 v12, v2
	v_mov_b32_e32 v13, v2
	v_mov_b32_e32 v14, v2
	v_mov_b32_e32 v15, v2
	v_mov_b32_e32 v16, v2
	v_mov_b32_e32 v17, v2
	v_mov_b32_e32 v18, v2
	v_mov_b32_e32 v19, v2
	v_mov_b32_e32 v20, v2
	v_mov_b32_e32 v21, v2
	v_mov_b32_e32 v22, v2
	v_mov_b32_e32 v23, v2
	v_mov_b32_e32 v24, v2
	v_mov_b32_e32 v25, v2
	v_mov_b32_e32 v26, v2
	v_mov_b32_e32 v27, v2
	v_mov_b32_e32 v28, v2
	v_mov_b32_e32 v29, v2
	v_mov_b32_e32 v30, v2
	v_mov_b32_e32 v31, v2
	v_mov_b32_e32 v32, v2
	v_mov_b32_e32 v33, v2
	v_mov_b32_e32 v34, v2
	v_mov_b32_e32 v35, v2
	v_mov_b32_e32 v36, v2
	v_mov_b32_e32 v37, v2
	v_mov_b32_e32 v38, v2
	v_mov_b32_e32 v39, v2
	v_mov_b32_e32 v40, v2
	v_mov_b32_e32 v41, v2
	v_mov_b32_e32 v42, v2
	v_mov_b32_e32 v43, v2
	v_mov_b32_e32 v44, v2
	v_mov_b32_e32 v45, v2
	v_mov_b32_e32 v46, v2
	v_mov_b32_e32 v47, v2
	v_mov_b32_e32 v48, v2
	v_mov_b32_e32 v49, v2
	v_mov_b32_e32 v50, v2
	v_mov_b32_e32 v51, v2
	v_mov_b32_e32 v52, v2
	v_mov_b32_e32 v53, v2
	v_mov_b32_e32 v54, v2
	v_mov_b32_e32 v55, v2
	v_mov_b32_e32 v56, v2
	v_mov_b32_e32 v57, v2
	v_mov_b32_e32 v58, v2
	v_mov_b32_e32 v59, v2
	v_mov_b32_e32 v60, v2
	v_mov_b32_e32 v61, v2
	v_mov_b32_e32 v62, v2
	v_mov_b32_e32 v63, v2
	v_mov_b32_e32 v64, v2
	v_mov_b32_e32 v65, v2
	s_branch .LBB0_483

; template <int MI, int NI>
; DI void gemm256(f32x4 (&acc)[MI][NI], const u16* __restrict__ A, int lda, const u16* __restrict__ Bt, int ldb, int K, int m0, int n0, char* smem) {
;     ...
;   for (int kt = 0; kt < nk; ++kt) {
;     if (kt + 1 < nk) asm volatile("s_waitcnt vmcnt(%0) lgkmcnt(0)" :: "n"(LPS) : "memory");
;     else asm volatile("s_waitcnt vmcnt(0) lgkmcnt(0)" ::: "memory");
;     __builtin_amdgcn_s_barrier();
;     __builtin_amdgcn_s_setprio(1);
;     const char* sb = smem + st * STAGE + foff;
;     bf16x8 af[MI], bfr[NI];
; #pragma unroll
;     for (int mi = 0; mi < MI; ++mi) af[mi] = *(const bf16x8*)(sb + (wr * MI + mi) * 1024);
; #pragma unroll
;     for (int ni = 0; ni < NI; ++ni) bfr[ni] = *(const bf16x8*)(sb + ABYTES + (wc * NI + ni) * 1024);
;     __builtin_amdgcn_sched_barrier(0x0);
;     if (kt + 2 < nk) { const int s2 = st >= 1 ? st - 1 : 2; G256_ISSUE(s2, (kt + 2) * 32); }
.LBB0_483:
	s_waitcnt vmcnt(4) lgkmcnt(0)
	s_barrier
	s_setprio 1
	s_lshl_b32 s7, s15, 14
	v_or_b32_e32 v134, s7, v248
	v_add_u32_e32 v130, v134, v249
	v_add_u32_e32 v134, v134, v0
	ds_read_b128 v[158:161], v130
	ds_read_b128 v[154:157], v130 offset:1024
	ds_read_b128 v[142:145], v130 offset:2048
	ds_read_b128 v[130:133], v130 offset:3072
	ds_read_b128 v[146:149], v134 offset:8192
	ds_read_b128 v[150:153], v134 offset:9216
	ds_read_b128 v[138:141], v134 offset:10240
	ds_read_b128 v[134:137], v134 offset:11264
	s_add_i32 s16, s16, 1
	s_cmp_ge_u32 s16, s17
	s_cbranch_scc1 .LBB0_482
	s_lshl_b64 s[18:19], s[64:65], 1
	s_addk_i32 s7, 0xc000
	s_cmp_gt_i32 s15, 0
	s_cselect_b32 s7, s7, 0x8000
	v_add_u32_e32 v240, s7, v250
	v_add_u32_e32 v241, 0x400, v240
	v_readfirstlane_b32 s7, v240
	v_lshl_add_u64 v[238:239], v[228:229], 0, s[18:19]
	s_mov_b32 m0, s7
	s_mov_b32 s7, s65
	v_readfirstlane_b32 s20, v241
	global_load_lds_dwordx4 v[238:239], off
	v_lshl_add_u64 v[238:239], v[238:239], 0, s[6:7]
	s_mov_b32 m0, s20
	v_add_u32_e32 v241, 0x2000, v240
	global_load_lds_dwordx4 v[238:239], off
	v_lshl_add_u64 v[238:239], v[230:231], 0, s[18:19]
	v_readfirstlane_b32 s18, v241
	s_mov_b32 m0, s18
	v_add_u32_e32 v240, 0x2400, v240
	global_load_lds_dwordx4 v[238:239], off
	v_lshl_add_u64 v[238:239], v[238:239], 0, s[6:7]
	v_readfirstlane_b32 s7, v240
	s_mov_b32 m0, s7
	s_nop 0
	global_load_lds_dwordx4 v[238:239], off
	s_branch .LBB0_482

; DI void attn_item(const Params& p, int item, char* smem) {
;     ...
;   const u16* Qp = (const u16*)(p.ws + OFF_R1) + ((size_t)bh * LK + qpos0 + wave * 32 + r32) * 96 + hi * 8;
;   const u16* Kp = (const u16*)(p.ws + OFF_R1 + SZ_Q) + ((size_t)bh * LK + key0) * 96;
;   const u16* Vp = (const u16*)(p.ws + OFF_R1 + 2 * SZ_Q) + (size_t)bh * 64 * LK + key0;
.LBB0_517:
	s_add_u32 s22, s62, 0x7ae7000
	s_addc_u32 s23, s63, 0
	s_add_u32 s24, s62, 0x7aea000
	s_addc_u32 s25, s63, 0
	s_add_u32 s26, s62, 0xade1000
	s_addc_u32 s27, s63, 0
	s_add_u32 s28, s62, 0xae25000
	s_addc_u32 s29, s63, 0
	v_mov_b32_e32 v0, v163
	s_mov_b32 s0, s2
	s_nop 0
	v_cmp_eq_u32_e64 s[0:1], 0, v0
	s_branch .LBB0_520

; DI void attn_item(const Params& p, int item, char* smem) {
;     ...
;   const u16* Qp = (const u16*)(p.ws + OFF_R1) + ((size_t)bh * LK + qpos0 + wave * 32 + r32) * 96 + hi * 8;
;   const u16* Kp = (const u16*)(p.ws + OFF_R1 + SZ_Q) + ((size_t)bh * LK + key0) * 96;
;   const u16* Vp = (const u16*)(p.ws + OFF_R1 + 2 * SZ_Q) + (size_t)bh * 64 * LK + key0;
;   u16* Ks = (u16*)smem;
;   u16* Vs = Ks + 2 * 64 * KSL;
;   bf16x8 qr[6];
; #pragma unroll
;   for (int d0 = 0; d0 < 6; ++d0) qr[d0] = *(const bf16x8*)(Qp + d0 * 16);
;   uint4 ak0, ak1, ak2, av0, av1, bk0, bk1, bk2, bv0, bv1;
;   const int kr0 = tid / 12, kc0 = tid - kr0 * 12, kr1 = (tid + 256) / 12, kc1 = (tid + 256) - kr1 * 12, kr2 = (tid + 512) / 12, kc2 = (tid + 512) - kr2 * 12;
;   const int vd0 = tid >> 3, vc0 = tid & 7, vd1 = vd0 + 32;
;     ...
;   f32x16 o0, o1;
; #pragma unroll
;   for (int i = 0; i < 16; ++i) { o0[i] = 0.f; o1[i] = 0.f; }
;   float mrun = -1e30f, lrun = 0.f;
;     ...
;   __syncthreads();
;   gload(a, 0); lstore(a, 0);
;   gload(a, 1);
;   __syncthreads();
.LBB0_528:
	v_ashrrev_i32_e32 v0, 1, v2
	v_and_b32_e32 v3, 31, v2
	v_and_b32_e32 v0, 0xffffffe0, v0
	v_ashrrev_i32_e32 v137, 31, v0
	v_or_b32_e32 v136, v0, v3
	s_waitcnt vmcnt(0)
	v_lshl_add_u64 v[4:5], v[136:137], 0, s[64:65]
	v_mov_b32_e32 v0, 0x1100
	v_mad_i64_i32 v[4:5], s[6:7], s8, v0, v[4:5]
	v_mov_b64_e32 v[6:7], s[60:61]
	v_bfe_u32 v44, v2, 5, 1
	v_mad_u64_u32 v[6:7], s[6:7], v4, s72, v[6:7]
	v_mad_i32_i24 v7, v5, s72, v7
	v_lshlrev_b32_e32 v0, 4, v44
	v_lshl_add_u64 v[4:5], v[6:7], 0, v[0:1]
	flat_load_dwordx4 v[80:83], v[4:5]
	flat_load_dwordx4 v[84:87], v[4:5] offset:32
	flat_load_dwordx4 v[88:91], v[4:5] offset:64
	flat_load_dwordx4 v[92:95], v[4:5] offset:96
	flat_load_dwordx4 v[96:99], v[4:5] offset:128
	flat_load_dwordx4 v[100:103], v[4:5] offset:160
	v_mul_hi_i32 v4, v2, s73
	s_mul_i32 s12, s8, 0x1100
	v_lshrrev_b32_e32 v5, 31, v4
	v_ashrrev_i32_e32 v4, 1, v4
	s_mul_hi_i32 s11, s8, 0x1100
	s_add_u32 s6, s12, s4
	v_add_u32_e32 v45, v4, v5
	v_add_u32_e32 v4, 0x100, v2
	s_addc_u32 s5, s11, s5
	v_mul_hi_i32 v5, v4, s73
	s_mulk_i32 s5, 0xc0
	s_mul_hi_u32 s7, s6, 0xc0
	v_lshrrev_b32_e32 v6, 31, v5
	v_ashrrev_i32_e32 v5, 1, v5
	s_add_i32 s7, s7, s5
	s_mul_i32 s11, s8, 0x88000
	v_readlane_b32 s12, v254, 15
	v_add_u32_e32 v46, v5, v6
	v_add_u32_e32 v6, 0x200, v2
	s_mul_hi_i32 s5, s8, 0x88000
	v_readlane_b32 s13, v254, 16
	s_add_u32 s11, s12, s11
	v_mul_hi_i32 v5, v6, s73
	s_mulk_i32 s6, 0xc0
	s_addc_u32 s5, s13, s5
	v_readlane_b32 s12, v254, 17
	v_lshrrev_b32_e32 v7, 31, v5
	v_ashrrev_i32_e32 v5, 1, v5
	v_readlane_b32 s13, v254, 18
	s_add_u32 s6, s12, s6
	v_add_u32_e32 v47, v5, v7
	s_addc_u32 s7, s13, s7
	s_lshl_b32 s64, s4, 1
	v_mad_u64_u32 v[24:25], s[14:15], v45, -12, v[2:3]
	v_mad_u64_u32 v[26:27], s[14:15], v46, -12, v[4:5]
	v_mad_u64_u32 v[28:29], s[14:15], v47, -12, v[6:7]
	s_add_u32 s12, s11, s64
	v_lshlrev_b32_e32 v6, 3, v24
	v_lshlrev_b32_e32 v8, 3, v26
	v_lshlrev_b32_e32 v14, 3, v28
	v_ashrrev_i32_e32 v48, 3, v2
	s_addc_u32 s13, s5, 0
	v_mov_b64_e32 v[30:31], s[6:7]
	v_ashrrev_i32_e32 v7, 31, v6
	v_ashrrev_i32_e32 v9, 31, v8
	v_ashrrev_i32_e32 v15, 31, v14
	v_add_u32_e32 v18, 32, v48
	v_mad_i64_i32 v[4:5], s[6:7], v45, s72, v[30:31]
	v_lshlrev_b64 v[32:33], 1, v[6:7]
	v_mad_i64_i32 v[6:7], s[6:7], v46, s72, v[30:31]
	v_lshlrev_b64 v[34:35], 1, v[8:9]
	v_mad_i64_i32 v[12:13], s[6:7], v47, s72, v[30:31]
	v_lshlrev_b64 v[36:37], 1, v[14:15]
	v_mov_b64_e32 v[14:15], s[12:13]
	s_movk_i32 s11, 0x2200
	v_lshlrev_b32_e32 v19, 4, v2
	v_lshl_add_u64 v[4:5], v[4:5], 0, v[32:33]
	v_lshl_add_u64 v[8:9], v[6:7], 0, v[34:35]
	v_lshl_add_u64 v[12:13], v[12:13], 0, v[36:37]
	v_mad_i64_i32 v[16:17], s[6:7], v48, s11, v[14:15]
	v_and_b32_e32 v38, 0x70, v19
	v_mov_b32_e32 v39, v1
	v_mad_i64_i32 v[14:15], s[6:7], v18, s11, v[14:15]
	s_waitcnt lgkmcnt(0)
	s_barrier
	flat_load_dwordx4 v[4:7], v[4:5]
	s_nop 0
	flat_load_dwordx4 v[8:11], v[8:9]
	v_lshl_add_u64 v[40:41], v[16:17], 0, v[38:39]
	v_lshl_add_u64 v[42:43], v[14:15], 0, v[38:39]
	flat_load_dwordx4 v[12:15], v[12:13]
	s_nop 0
	flat_load_dwordx4 v[16:19], v[40:41]
	flat_load_dwordx4 v[20:23], v[42:43]
	s_movk_i32 s5, 0xd0
	v_mul_lo_u32 v25, v45, s5
	v_lshl_add_u32 v150, v24, 4, v25
	v_mul_lo_u32 v24, v46, s5
	v_lshl_add_u32 v151, v26, 4, v24
	v_mul_lo_u32 v24, v47, s5
	s_movk_i32 s5, 0x88
	v_mad_u64_u32 v[138:139], s[6:7], v48, s5, v[38:39]
	v_lshl_add_u32 v152, v28, 4, v24
	v_add_u32_e32 v139, 0x6800, v138
	v_add_u32_e32 v24, 0x7900, v138
	s_waitcnt vmcnt(0) lgkmcnt(0)
	ds_write_b128 v150, v[4:7]
	ds_write_b128 v151, v[8:11]
	ds_write_b128 v152, v[12:15]
	ds_write2_b64 v139, v[16:17], v[18:19] offset1:1
	ds_write2_b64 v24, v[20:21], v[22:23] offset1:1
	v_add_u32_e32 v4, 64, v45
	v_mad_i64_i32 v[4:5], s[6:7], v4, s72, v[30:31]
	v_add_u32_e32 v6, 64, v46
	v_lshl_add_u64 v[4:5], v[4:5], 0, v[32:33]
	v_mad_i64_i32 v[6:7], s[6:7], v6, s72, v[30:31]
	v_lshl_add_u64 v[6:7], v[6:7], 0, v[34:35]
	flat_load_dwordx4 v[104:107], v[4:5]
	flat_load_dwordx4 v[108:111], v[6:7]
	v_add_u32_e32 v4, 64, v47
	v_mad_i64_i32 v[4:5], s[6:7], v4, s72, v[30:31]
	v_lshl_add_u64 v[4:5], v[4:5], 0, v[36:37]
	flat_load_dwordx4 v[112:115], v[4:5]
	flat_load_dwordx4 v[116:119], v[40:41] offset:128
	flat_load_dwordx4 v[120:123], v[42:43] offset:128
	v_mul_u32_u24_e32 v7, 0x68, v3
	v_lshlrev_b32_e32 v7, 1, v7
	v_lshlrev_b32_e32 v6, 3, v44
	v_add_u32_e32 v154, v7, v0
	v_mul_i32_i24_e32 v0, 0xffffffb8, v3
	v_mad_i64_i32 v[4:5], s[6:7], v48, s11, 0
	v_add3_u32 v155, v7, v0, v6
	v_mov_b32_e32 v0, 0x88000
	v_mad_i64_i32 v[4:5], s[6:7], s8, v0, v[4:5]
	s_mul_i32 s6, s8, 0xcc000
	s_mulk_i32 s4, 0xc0
	s_mul_hi_i32 s5, s8, 0xcc000
	s_add_u32 s4, s6, s4
	v_and_b32_e32 v0, 7, v2
	s_addc_u32 s5, s5, 0
	v_lshl_or_b32 v4, v0, 4, v4
	v_mov_b64_e32 v[2:3], s[4:5]
	v_lshl_add_u64 v[140:141], v[4:5], 0, s[64:65]
	v_mad_i64_i32 v[4:5], s[4:5], v47, s72, v[2:3]
	v_lshl_add_u64 v[142:143], v[4:5], 0, v[36:37]
	v_mad_i64_i32 v[4:5], s[4:5], v46, s72, v[2:3]
	v_mad_i64_i32 v[2:3], s[4:5], v45, s72, v[2:3]
	v_mov_b32_e32 v14, v1
	v_mov_b32_e32 v15, v1
	v_lshlrev_b32_e32 v137, 2, v44
	v_lshl_add_u64 v[144:145], v[4:5], 0, v[34:35]
	v_lshl_add_u64 v[146:147], v[2:3], 0, v[32:33]
	v_mov_b32_e32 v0, v1
	v_mov_b32_e32 v2, v1
	v_mov_b32_e32 v3, v1
	v_mov_b32_e32 v4, v1
	v_mov_b32_e32 v5, v1
	v_mov_b32_e32 v6, v1
	v_mov_b32_e32 v7, v1
	v_mov_b32_e32 v8, v1
	v_mov_b32_e32 v9, v1
	v_mov_b32_e32 v10, v1
	v_mov_b32_e32 v11, v1
	v_mov_b32_e32 v12, v1
	v_mov_b32_e32 v13, v1
	v_mov_b64_e32 v[30:31], v[14:15]
	v_mov_b64_e32 v[46:47], v[14:15]
	v_add_u32_e32 v153, 0x1100, v138
	s_mov_b32 s12, 0
	v_mov_b32_e32 v156, 0xf149f2ca
	v_mov_b32_e32 v196, 0
	v_mov_b32_e32 v197, 0
	v_mov_b32_e32 v198, 0
	v_mov_b32_e32 v199, 0
	v_mov_b32_e32 v200, 0
	v_mov_b32_e32 v201, 0
	v_mov_b32_e32 v202, 0
	v_mov_b32_e32 v203, 0
	v_mov_b32_e32 v204, 0
	v_mov_b32_e32 v205, 0
	v_mov_b32_e32 v206, 0
	v_mov_b32_e32 v207, 0
	v_mov_b32_e32 v208, 0
	v_mov_b32_e32 v209, 0
	v_mov_b32_e32 v210, 0
	v_mov_b32_e32 v211, 0
	s_mov_b32 s98, 0xff800000
	s_mov_b32 s99, 0xff800000
	v_mov_b32_e32 v157, 0
	v_mov_b64_e32 v[28:29], v[12:13]
	v_mov_b64_e32 v[26:27], v[10:11]
	v_mov_b64_e32 v[24:25], v[8:9]
	v_mov_b64_e32 v[22:23], v[6:7]
	v_mov_b64_e32 v[20:21], v[4:5]
	v_mov_b64_e32 v[18:19], v[2:3]
	v_mov_b64_e32 v[16:17], v[0:1]
	v_mov_b64_e32 v[44:45], v[12:13]
	v_mov_b64_e32 v[42:43], v[10:11]
	v_mov_b64_e32 v[40:41], v[8:9]
	v_mov_b64_e32 v[38:39], v[6:7]
	v_mov_b64_e32 v[36:37], v[4:5]
	v_mov_b64_e32 v[34:35], v[2:3]
	v_mov_b64_e32 v[32:33], v[0:1]
	s_waitcnt lgkmcnt(0)
	s_barrier
; DI void attn_item(const Params& p, int item, char* smem) {
;     ...
;   auto tile_compute = [&](int cur) {
;     const u16* Kc = Ks + cur * 64 * KSL;
;     const u16* Vc = Vs + cur * 64 * VSL;
;     f32x16 p0, p1;
; #pragma unroll
;     for (int i = 0; i < 16; ++i) { p0[i] = 0.f; p1[i] = 0.f; }
; #pragma unroll
;     for (int d0 = 0; d0 < 6; ++d0) {
;       const bf16x8 a0 = *(const bf16x8*)(Kc + r32 * KSL + d0 * 16 + hi * 8);
;       const bf16x8 a1 = *(const bf16x8*)(Kc + (32 + r32) * KSL + d0 * 16 + hi * 8);
;       p0 = __builtin_amdgcn_mfma_f32_32x32x16_bf16(a0, qr[d0], p0, 0, 0, 0);
;       p1 = __builtin_amdgcn_mfma_f32_32x32x16_bf16(a1, qr[d0], p1, 0, 0, 0);
;     }
;     float mx = p0[0];
; #pragma unroll
;     for (int i = 1; i < 16; ++i) mx = fmaxf(mx, p0[i]);
; #pragma unroll
;     for (int i = 0; i < 16; ++i) mx = fmaxf(mx, p1[i]);
;     { auto rr = __builtin_amdgcn_permlane32_swap(__float_as_uint(mx), __float_as_uint(mx), false, false);
;       mx = fmaxf(__uint_as_float(rr[0]), __uint_as_float(rr[1])); }
;     if (!__all(mx - mrun <= 8.f)) {
;       const float mn = fmaxf(mrun, mx);
;       const float alpha = __builtin_amdgcn_exp2f(mrun - mn);
;       mrun = mn; lrun *= alpha;
; #pragma unroll
;       for (int i = 0; i < 16; ++i) { o0[i] *= alpha; o1[i] *= alpha; }
;     }
;     ...
;   for (int kt = 0; kt < nkt; kt += 2) {
;     if (kt + 2 < nkt) gload(b, kt + 2);
;     tile_compute(0);
.LBB0_529:
	s_add_i32 s11, s12, 2
	s_cmp_lt_u32 s11, s10
	s_cselect_b64 s[6:7], -1, 0
	s_cmp_ge_u32 s11, s10
	s_cselect_b64 s[4:5], -1, 0
	s_and_b64 vcc, exec, s[4:5]
	s_cbranch_vccnz .LBB0_531
	global_load_dwordx4 v[124:127], v146, s[22:23]
	global_load_dwordx4 v[128:131], v144, s[22:23]
	global_load_dwordx4 v[132:135], v142, s[22:23]
	global_load_dwordx4 v[2:5], v140, s[26:27] offset:256
	global_load_dwordx4 v[6:9], v140, s[28:29] offset:256
.LBB0_531:
	ds_read_b128 v[48:51], v154
	ds_read_b128 v[52:55], v154 offset:32
	s_waitcnt lgkmcnt(0)
	v_mfma_f32_32x32x16_bf16 v[64:79], v[48:51], v[80:83], v[196:211]
	v_mfma_f32_32x32x16_bf16 v[64:79], v[52:55], v[84:87], v[64:79]
	ds_read_b128 v[48:51], v154 offset:64
	ds_read_b128 v[52:55], v154 offset:96
	s_waitcnt lgkmcnt(0)
	v_mfma_f32_32x32x16_bf16 v[64:79], v[48:51], v[88:91], v[64:79]
	v_mfma_f32_32x32x16_bf16 v[64:79], v[52:55], v[92:95], v[64:79]
	ds_read_b128 v[48:51], v154 offset:128
	ds_read_b128 v[52:55], v154 offset:160
	s_waitcnt lgkmcnt(0)
	v_mfma_f32_32x32x16_bf16 v[64:79], v[48:51], v[96:99], v[64:79]
	ds_read_b128 v[48:51], v154 offset:6656
	ds_read_b128 v[158:161], v154 offset:6688
	v_mfma_f32_32x32x16_bf16 v[64:79], v[52:55], v[100:103], v[64:79]
	s_waitcnt lgkmcnt(0)
	v_mfma_f32_32x32x16_bf16 v[48:63], v[48:51], v[80:83], v[196:211]
	s_nop 9
	v_max_f32_e32 v0, v65, v65
	v_max_f32_e32 v168, v64, v64
	v_max_f32_e32 v0, v168, v0
	v_max3_f32 v0, v0, v66, v67
	v_max3_f32 v0, v0, v68, v69
	v_max3_f32 v0, v0, v70, v71
	v_max3_f32 v0, v0, v72, v73
	v_mfma_f32_32x32x16_bf16 v[48:63], v[158:161], v[84:87], v[48:63]
	ds_read_b128 v[158:161], v154 offset:6720
	ds_read_b128 v[164:167], v154 offset:6752
	v_max3_f32 v0, v0, v74, v75
	v_max3_f32 v0, v0, v76, v77
	v_max3_f32 v0, v0, v78, v79
	s_waitcnt lgkmcnt(0)
	v_mfma_f32_32x32x16_bf16 v[48:63], v[158:161], v[88:91], v[48:63]
	v_mfma_f32_32x32x16_bf16 v[48:63], v[164:167], v[92:95], v[48:63]
	ds_read_b128 v[158:161], v154 offset:6784
	ds_read_b128 v[164:167], v154 offset:6816
	s_waitcnt lgkmcnt(0)
	v_mfma_f32_32x32x16_bf16 v[48:63], v[158:161], v[96:99], v[48:63]
	v_mfma_f32_32x32x16_bf16 v[48:63], v[164:167], v[100:103], v[48:63]
	s_nop 11
	v_max3_f32 v0, v0, v48, v49
	v_max3_f32 v0, v0, v50, v51
	v_max3_f32 v0, v0, v52, v53
	v_max3_f32 v0, v0, v54, v55
	v_max3_f32 v0, v0, v56, v57
	v_max3_f32 v0, v0, v58, v59
	v_max3_f32 v0, v0, v60, v61
	v_max3_f32 v0, v0, v62, v63
	v_mov_b32_e32 v158, v0
	s_nop 1
	v_permlane32_swap_b32_e32 v0, v158
	v_max_f32_e32 v158, v158, v158
	v_max_f32_e32 v0, v0, v0
	v_max_f32_e32 v0, v0, v158
	v_cmp_ge_f32_e32 vcc, s98, v0
	s_cmp_eq_u64 vcc, exec
	s_cbranch_scc1 .LBB0_533
	v_max_f32_e32 v158, s99, v0
	v_max_f32_e32 v0, 0, v158
	s_mov_b32 s98, 0x41000000
	v_exp_f32_e64 v0, -v0
	s_mov_b32 s99, 0
	v_sub_f32_e32 v196, v196, v158
	v_mul_f32_e32 v157, v157, v0
	v_pk_mul_f32 v[46:47], v[46:47], v[0:1] op_sel_hi:[1,0]
	v_pk_mul_f32 v[44:45], v[44:45], v[0:1] op_sel_hi:[1,0]
	v_pk_mul_f32 v[42:43], v[42:43], v[0:1] op_sel_hi:[1,0]
	v_pk_mul_f32 v[40:41], v[40:41], v[0:1] op_sel_hi:[1,0]
	v_pk_mul_f32 v[38:39], v[38:39], v[0:1] op_sel_hi:[1,0]
	v_pk_mul_f32 v[36:37], v[36:37], v[0:1] op_sel_hi:[1,0]
	v_pk_mul_f32 v[34:35], v[34:35], v[0:1] op_sel_hi:[1,0]
	v_pk_mul_f32 v[32:33], v[32:33], v[0:1] op_sel_hi:[1,0]
	v_pk_mul_f32 v[30:31], v[30:31], v[0:1] op_sel_hi:[1,0]
	v_pk_mul_f32 v[28:29], v[28:29], v[0:1] op_sel_hi:[1,0]
	v_pk_mul_f32 v[26:27], v[26:27], v[0:1] op_sel_hi:[1,0]
	v_pk_mul_f32 v[24:25], v[24:25], v[0:1] op_sel_hi:[1,0]
	v_pk_mul_f32 v[22:23], v[22:23], v[0:1] op_sel_hi:[1,0]
	v_pk_mul_f32 v[20:21], v[20:21], v[0:1] op_sel_hi:[1,0]
	v_pk_mul_f32 v[18:19], v[18:19], v[0:1] op_sel_hi:[1,0]
	v_pk_mul_f32 v[16:17], v[16:17], v[0:1] op_sel_hi:[1,0]
	v_mov_b32_e32 v197, v196
	v_mov_b32_e32 v198, v196
	v_mov_b32_e32 v199, v196
	v_mov_b32_e32 v200, v196
	v_mov_b32_e32 v201, v196
	v_mov_b32_e32 v202, v196
	v_mov_b32_e32 v203, v196
	v_mov_b32_e32 v204, v196
	v_mov_b32_e32 v205, v196
	v_mov_b32_e32 v206, v196
	v_mov_b32_e32 v207, v196
	v_mov_b32_e32 v208, v196
	v_mov_b32_e32 v209, v196
	v_mov_b32_e32 v210, v196
	v_mov_b32_e32 v211, v196
	v_sub_f32_e32 v64, v64, v158
	v_sub_f32_e32 v65, v65, v158
	v_sub_f32_e32 v66, v66, v158
	v_sub_f32_e32 v67, v67, v158
	v_sub_f32_e32 v68, v68, v158
	v_sub_f32_e32 v69, v69, v158
	v_sub_f32_e32 v70, v70, v158
	v_sub_f32_e32 v71, v71, v158
	v_sub_f32_e32 v72, v72, v158
	v_sub_f32_e32 v73, v73, v158
	v_sub_f32_e32 v74, v74, v158
	v_sub_f32_e32 v75, v75, v158
	v_sub_f32_e32 v76, v76, v158
	v_sub_f32_e32 v77, v77, v158
	v_sub_f32_e32 v78, v78, v158
	v_sub_f32_e32 v79, v79, v158
	v_sub_f32_e32 v48, v48, v158
	v_sub_f32_e32 v49, v49, v158
	v_sub_f32_e32 v50, v50, v158
	v_sub_f32_e32 v51, v51, v158
	v_sub_f32_e32 v52, v52, v158
	v_sub_f32_e32 v53, v53, v158
	v_sub_f32_e32 v54, v54, v158
	v_sub_f32_e32 v55, v55, v158
	v_sub_f32_e32 v56, v56, v158
	v_sub_f32_e32 v57, v57, v158
	v_sub_f32_e32 v58, v58, v158
	v_sub_f32_e32 v59, v59, v158
	v_sub_f32_e32 v60, v60, v158
	v_sub_f32_e32 v61, v61, v158
	v_sub_f32_e32 v62, v62, v158
	v_sub_f32_e32 v63, v63, v158
; DI void attn_item(const Params& p, int item, char* smem) {
;     ...
;     for (int d0 = 0; d0 < 6; ++d0) {
;       const bf16x8 a0 = *(const bf16x8*)(Kc + r32 * KSL + d0 * 16 + hi * 8);
;       const bf16x8 a1 = *(const bf16x8*)(Kc + (32 + r32) * KSL + d0 * 16 + hi * 8);
;       p0 = __builtin_amdgcn_mfma_f32_32x32x16_bf16(a0, qr[d0], p0, 0, 0, 0);
;       p1 = __builtin_amdgcn_mfma_f32_32x32x16_bf16(a1, qr[d0], p1, 0, 0, 0);
;     }
;     float mx = p0[0];
; #pragma unroll
;     for (int i = 1; i < 16; ++i) mx = fmaxf(mx, p0[i]);
; #pragma unroll
;     for (int i = 0; i < 16; ++i) mx = fmaxf(mx, p1[i]);
;     { auto rr = __builtin_amdgcn_permlane32_swap(__float_as_uint(mx), __float_as_uint(mx), false, false);
;       mx = fmaxf(__uint_as_float(rr[0]), __uint_as_float(rr[1])); }
;     if (!__all(mx - mrun <= 8.f)) {
;       const float mn = fmaxf(mrun, mx);
;       const float alpha = __builtin_amdgcn_exp2f(mrun - mn);
;       mrun = mn; lrun *= alpha;
; #pragma unroll
;       for (int i = 0; i < 16; ++i) { o0[i] *= alpha; o1[i] *= alpha; }
;     }
;     float ps = 0.f;
; #pragma unroll
;     for (int i = 0; i < 16; ++i) { p0[i] = __builtin_amdgcn_exp2f(p0[i] - mrun); ps += p0[i]; }
; #pragma unroll
;     for (int i = 0; i < 16; ++i) { p1[i] = __builtin_amdgcn_exp2f(p1[i] - mrun); ps += p1[i]; }
;     lrun += ps;
;     pv_step(o0, o1, Vc, r32, 0 + hi * 4, pack8<0>(p0));
;     pv_step(o0, o1, Vc, r32, 16 + hi * 4, pack8<8>(p0));
;     pv_step(o0, o1, Vc, r32, 32 + hi * 4, pack8<0>(p1));
;     pv_step(o0, o1, Vc, r32, 48 + hi * 4, pack8<8>(p1));
;   };
;   __syncthreads();
;   gload(a, 0); lstore(a, 0);
;   gload(a, 1);
;   __syncthreads();
;   for (int kt = 0; kt < nkt; kt += 2) {
;     if (kt + 2 < nkt) gload(b, kt + 2);
;     tile_compute(0);
;     lstore(a, 1);
;     __syncthreads();
;     if (kt + 3 < nkt) gload(a, kt + 3);
;     tile_compute(1);
;     if (kt + 2 < nkt) lstore(b, 0);
;     __syncthreads();
;   }
.LBB0_533:
	v_exp_f32_e32 v167, v64
	v_exp_f32_e32 v164, v65
	v_exp_f32_e32 v168, v66
	v_exp_f32_e32 v171, v67
	v_exp_f32_e32 v165, v68
	v_exp_f32_e32 v169, v69
	v_exp_f32_e32 v172, v70
	v_exp_f32_e32 v173, v71
	v_exp_f32_e32 v174, v72
	v_exp_f32_e32 v158, v76
	v_exp_f32_e32 v175, v73
	v_mov_b32_e32 v0, v74
	v_exp_f32_e32 v159, v77
	v_add_u32_e32 v74, 0x7800, v155
	v_exp_f32_e32 v160, v78
	v_add_u32_e32 v72, 0x6800, v155
	ds_read2_b64 v[68:71], v74 offset0:32 offset1:34
	v_exp_f32_e32 v166, v79
	ds_read2_b64 v[64:67], v72 offset1:2
	v_exp_f32_e32 v170, v48
	v_exp_f32_e32 v161, v49
	v_exp_f32_e32 v179, v52
	v_exp_f32_e32 v177, v50
	v_mov_b32_e32 v73, v51
	v_cvt_pk_bf16_f32 v48, v167, v164
	v_cvt_pk_bf16_f32 v49, v168, v171
	v_cvt_pk_bf16_f32 v50, v165, v169
	v_cvt_pk_bf16_f32 v51, v172, v173
	v_exp_f32_e32 v180, v53
	s_waitcnt lgkmcnt(0)
	v_mfma_f32_32x32x16_bf16 v[16:31], v[68:71], v[48:51], v[16:31]
	v_exp_f32_e32 v181, v54
	v_mov_b32_e32 v68, v55
	ds_read2_b64 v[52:55], v74 offset0:36 offset1:38
	v_exp_f32_e32 v176, v0
	v_exp_f32_e32 v0, v75
	v_mfma_f32_32x32x16_bf16 v[32:47], v[64:67], v[48:51], v[32:47]
	ds_read2_b64 v[64:67], v72 offset0:4 offset1:6
	v_cvt_pk_bf16_f32 v48, v174, v175
	v_cvt_pk_bf16_f32 v49, v176, v0
	v_cvt_pk_bf16_f32 v50, v158, v159
	v_cvt_pk_bf16_f32 v51, v160, v166
	v_exp_f32_e32 v178, v73
	v_exp_f32_e32 v182, v68
	s_waitcnt lgkmcnt(0)
	v_mfma_f32_32x32x16_bf16 v[16:31], v[52:55], v[48:51], v[16:31]
	ds_read2_b64 v[52:55], v74 offset0:40 offset1:42
	v_exp_f32_e32 v183, v56
	v_exp_f32_e32 v184, v57
	v_exp_f32_e32 v185, v58
	v_mfma_f32_32x32x16_bf16 v[32:47], v[64:67], v[48:51], v[32:47]
	ds_read2_b64 v[64:67], v72 offset0:8 offset1:10
	v_exp_f32_e32 v187, v59
	v_cvt_pk_bf16_f32 v48, v170, v161
	v_cvt_pk_bf16_f32 v49, v177, v178
	v_cvt_pk_bf16_f32 v50, v179, v180
	v_cvt_pk_bf16_f32 v51, v181, v182
	v_exp_f32_e32 v188, v60
	v_exp_f32_e32 v186, v61
	ds_read2_b64 v[56:59], v72 offset0:12 offset1:14
	s_waitcnt lgkmcnt(0)
	v_mfma_f32_32x32x16_bf16 v[16:31], v[52:55], v[48:51], v[16:31]
	ds_read2_b64 v[52:55], v74 offset0:44 offset1:46
	v_exp_f32_e32 v189, v62
	s_add_i32 s12, s12, 3
	s_waitcnt vmcnt(0)
	ds_write_b128 v150, v[104:107] offset:13312
	ds_write_b128 v151, v[108:111] offset:13312
	ds_write_b128 v152, v[112:115] offset:13312
	s_cmp_ge_u32 s12, s10
	v_mfma_f32_32x32x16_bf16 v[32:47], v[64:67], v[48:51], v[32:47]
	v_exp_f32_e32 v190, v63
	v_cvt_pk_bf16_f32 v48, v183, v184
	v_cvt_pk_bf16_f32 v49, v185, v187
	v_cvt_pk_bf16_f32 v50, v188, v186
	v_cvt_pk_bf16_f32 v51, v189, v190
	s_nop 1
	v_mfma_f32_32x32x16_bf16 v[32:47], v[56:59], v[48:51], v[32:47]
	s_waitcnt lgkmcnt(3)
	v_mfma_f32_32x32x16_bf16 v[16:31], v[52:55], v[48:51], v[16:31]
	v_add_u32_e32 v48, 0x8a00, v138
	ds_write2_b64 v48, v[116:117], v[118:119] offset1:1
	v_add_u32_e32 v48, 0x8a00, v153
	ds_write2_b64 v48, v[120:121], v[122:123] offset1:1
	s_waitcnt lgkmcnt(0)
	s_barrier
	s_cbranch_scc1 .LBB0_535
	global_load_dwordx4 v[104:107], v146, s[24:25]
	global_load_dwordx4 v[108:111], v144, s[24:25]
	global_load_dwordx4 v[112:115], v142, s[24:25]
	global_load_dwordx4 v[116:119], v140, s[26:27] offset:384
	global_load_dwordx4 v[120:123], v140, s[28:29] offset:384
.LBB0_535:
	ds_read_b128 v[10:13], v154 offset:13312
	ds_read_b128 v[48:51], v154 offset:13344
	v_add_f32_e32 v14, 0, v167
	v_add_f32_e32 v14, v164, v14
	v_add_f32_e32 v14, v168, v14
	s_waitcnt lgkmcnt(0)
	v_mfma_f32_32x32x16_bf16 v[64:79], v[10:13], v[80:83], v[196:211]
	v_add_f32_e32 v14, v171, v14
	v_add_f32_e32 v14, v165, v14
	v_add_f32_e32 v14, v169, v14
	v_add_f32_e32 v14, v172, v14
	v_add_f32_e32 v14, v173, v14
	v_add_f32_e32 v14, v174, v14
	v_add_f32_e32 v14, v175, v14
	v_mfma_f32_32x32x16_bf16 v[64:79], v[48:51], v[84:87], v[64:79]
	ds_read_b128 v[10:13], v154 offset:13376
	ds_read_b128 v[48:51], v154 offset:13408
	v_add_f32_e32 v14, v176, v14
	v_add_f32_e32 v0, v0, v14
	v_add_f32_e32 v0, v158, v0
	v_add_f32_e32 v0, v159, v0
	v_add_f32_e32 v0, v160, v0
	v_add_f32_e32 v0, v166, v0
	s_waitcnt lgkmcnt(0)
	v_mfma_f32_32x32x16_bf16 v[64:79], v[10:13], v[88:91], v[64:79]
	v_add_f32_e32 v0, v170, v0
	v_add_f32_e32 v0, v161, v0
	v_add_f32_e32 v0, v177, v0
	v_add_f32_e32 v0, v178, v0
	v_add_f32_e32 v0, v179, v0
	v_add_f32_e32 v0, v180, v0
	v_add_f32_e32 v0, v181, v0
	v_mfma_f32_32x32x16_bf16 v[64:79], v[48:51], v[92:95], v[64:79]
	ds_read_b128 v[10:13], v154 offset:13440
	ds_read_b128 v[48:51], v154 offset:13472
	v_add_f32_e32 v0, v182, v0
	v_add_f32_e32 v0, v183, v0
	v_add_f32_e32 v0, v184, v0
	v_add_f32_e32 v0, v185, v0
	v_add_f32_e32 v0, v187, v0
	v_add_f32_e32 v0, v188, v0
	s_waitcnt lgkmcnt(0)
	v_mfma_f32_32x32x16_bf16 v[64:79], v[10:13], v[96:99], v[64:79]
	ds_read_b128 v[10:13], v154 offset:19968
	ds_read_b128 v[192:195], v154 offset:20000
	v_add_f32_e32 v0, v186, v0
	v_add_f32_e32 v0, v189, v0
	v_add_f32_e32 v0, v190, v0
	v_add_f32_e32 v0, v157, v0
	ds_read_b128 v[158:161], v154 offset:20064
	v_mfma_f32_32x32x16_bf16 v[64:79], v[48:51], v[100:103], v[64:79]
	s_waitcnt lgkmcnt(0)
	v_mfma_f32_32x32x16_bf16 v[48:63], v[10:13], v[80:83], v[196:211]
	ds_read_b128 v[10:13], v154 offset:20032
	s_nop 8
	v_max_f32_e32 v14, v65, v65
	v_max_f32_e32 v15, v64, v64
	v_max_f32_e32 v14, v15, v14
	v_mfma_f32_32x32x16_bf16 v[48:63], v[192:195], v[84:87], v[48:63]
	s_waitcnt lgkmcnt(0)
	v_mfma_f32_32x32x16_bf16 v[48:63], v[10:13], v[88:91], v[48:63]
	ds_read_b128 v[10:13], v154 offset:20096
	v_mfma_f32_32x32x16_bf16 v[48:63], v[158:161], v[92:95], v[48:63]
	ds_read_b128 v[158:161], v154 offset:20128
	s_waitcnt lgkmcnt(0)
	v_mfma_f32_32x32x16_bf16 v[48:63], v[10:13], v[96:99], v[48:63]
	v_max3_f32 v10, v14, v66, v67
	v_max3_f32 v10, v10, v68, v69
	v_max3_f32 v10, v10, v70, v71
	v_max3_f32 v10, v10, v72, v73
	v_max3_f32 v10, v10, v74, v75
	v_max3_f32 v10, v10, v76, v77
	v_max3_f32 v10, v10, v78, v79
	v_mfma_f32_32x32x16_bf16 v[48:63], v[158:161], v[100:103], v[48:63]
	s_nop 11
	v_max3_f32 v10, v10, v48, v49
	v_max3_f32 v10, v10, v50, v51
	v_max3_f32 v10, v10, v52, v53
	v_max3_f32 v10, v10, v54, v55
	v_max3_f32 v10, v10, v56, v57
	v_max3_f32 v10, v10, v58, v59
	v_max3_f32 v10, v10, v60, v61
	v_max3_f32 v10, v10, v62, v63
	v_mov_b32_e32 v11, v10
	s_nop 1
	v_permlane32_swap_b32_e32 v10, v11
	v_max_f32_e32 v11, v11, v11
	v_max_f32_e32 v10, v10, v10
	v_max_f32_e32 v10, v10, v11
	v_cmp_ge_f32_e32 vcc, s98, v10
	s_cmp_eq_u64 vcc, exec
	s_cbranch_scc1 .LBB0_537
; DI void attn_item(const Params& p, int item, char* smem) {
;     ...
;     if (!__all(mx - mrun <= 8.f)) {
;       const float mn = fmaxf(mrun, mx);
;       const float alpha = __builtin_amdgcn_exp2f(mrun - mn);
;       mrun = mn; lrun *= alpha;
; #pragma unroll
;       for (int i = 0; i < 16; ++i) { o0[i] *= alpha; o1[i] *= alpha; }
;     }
;     float ps = 0.f;
; #pragma unroll
;     for (int i = 0; i < 16; ++i) { p0[i] = __builtin_amdgcn_exp2f(p0[i] - mrun); ps += p0[i]; }
; #pragma unroll
;     for (int i = 0; i < 16; ++i) { p1[i] = __builtin_amdgcn_exp2f(p1[i] - mrun); ps += p1[i]; }
;     lrun += ps;
;     pv_step(o0, o1, Vc, r32, 0 + hi * 4, pack8<0>(p0));
;     pv_step(o0, o1, Vc, r32, 16 + hi * 4, pack8<8>(p0));
;     pv_step(o0, o1, Vc, r32, 32 + hi * 4, pack8<0>(p1));
;     pv_step(o0, o1, Vc, r32, 48 + hi * 4, pack8<8>(p1));
;   };
;   __syncthreads();
;   gload(a, 0); lstore(a, 0);
;   gload(a, 1);
;   __syncthreads();
;   for (int kt = 0; kt < nkt; kt += 2) {
;     if (kt + 2 < nkt) gload(b, kt + 2);
;     tile_compute(0);
;     lstore(a, 1);
;     __syncthreads();
;     if (kt + 3 < nkt) gload(a, kt + 3);
;     tile_compute(1);
;     if (kt + 2 < nkt) lstore(b, 0);
	v_max_f32_e32 v11, s99, v10
	v_max_f32_e32 v10, 0, v11
	s_mov_b32 s98, 0x41000000
	v_exp_f32_e64 v10, -v10
	s_mov_b32 s99, 0
	v_sub_f32_e32 v196, v196, v11
	v_mul_f32_e32 v0, v0, v10
	v_pk_mul_f32 v[46:47], v[46:47], v[10:11] op_sel_hi:[1,0]
	v_pk_mul_f32 v[44:45], v[44:45], v[10:11] op_sel_hi:[1,0]
	v_pk_mul_f32 v[42:43], v[42:43], v[10:11] op_sel_hi:[1,0]
	v_pk_mul_f32 v[40:41], v[40:41], v[10:11] op_sel_hi:[1,0]
	v_pk_mul_f32 v[38:39], v[38:39], v[10:11] op_sel_hi:[1,0]
	v_pk_mul_f32 v[36:37], v[36:37], v[10:11] op_sel_hi:[1,0]
	v_pk_mul_f32 v[34:35], v[34:35], v[10:11] op_sel_hi:[1,0]
	v_pk_mul_f32 v[32:33], v[32:33], v[10:11] op_sel_hi:[1,0]
	v_pk_mul_f32 v[30:31], v[30:31], v[10:11] op_sel_hi:[1,0]
	v_pk_mul_f32 v[28:29], v[28:29], v[10:11] op_sel_hi:[1,0]
	v_pk_mul_f32 v[26:27], v[26:27], v[10:11] op_sel_hi:[1,0]
	v_pk_mul_f32 v[24:25], v[24:25], v[10:11] op_sel_hi:[1,0]
	v_pk_mul_f32 v[22:23], v[22:23], v[10:11] op_sel_hi:[1,0]
	v_pk_mul_f32 v[20:21], v[20:21], v[10:11] op_sel_hi:[1,0]
	v_pk_mul_f32 v[18:19], v[18:19], v[10:11] op_sel_hi:[1,0]
	v_pk_mul_f32 v[16:17], v[16:17], v[10:11] op_sel_hi:[1,0]
	v_mov_b32_e32 v197, v196
	v_mov_b32_e32 v198, v196
	v_mov_b32_e32 v199, v196
	v_mov_b32_e32 v200, v196
	v_mov_b32_e32 v201, v196
	v_mov_b32_e32 v202, v196
	v_mov_b32_e32 v203, v196
	v_mov_b32_e32 v204, v196
	v_mov_b32_e32 v205, v196
	v_mov_b32_e32 v206, v196
	v_mov_b32_e32 v207, v196
	v_mov_b32_e32 v208, v196
	v_mov_b32_e32 v209, v196
	v_mov_b32_e32 v210, v196
	v_mov_b32_e32 v211, v196
	v_sub_f32_e32 v64, v64, v11
	v_sub_f32_e32 v65, v65, v11
	v_sub_f32_e32 v66, v66, v11
	v_sub_f32_e32 v67, v67, v11
	v_sub_f32_e32 v68, v68, v11
	v_sub_f32_e32 v69, v69, v11
	v_sub_f32_e32 v70, v70, v11
	v_sub_f32_e32 v71, v71, v11
	v_sub_f32_e32 v72, v72, v11
	v_sub_f32_e32 v73, v73, v11
	v_sub_f32_e32 v74, v74, v11
	v_sub_f32_e32 v75, v75, v11
	v_sub_f32_e32 v76, v76, v11
	v_sub_f32_e32 v77, v77, v11
	v_sub_f32_e32 v78, v78, v11
	v_sub_f32_e32 v79, v79, v11
	v_sub_f32_e32 v48, v48, v11
	v_sub_f32_e32 v49, v49, v11
	v_sub_f32_e32 v50, v50, v11
	v_sub_f32_e32 v51, v51, v11
	v_sub_f32_e32 v52, v52, v11
	v_sub_f32_e32 v53, v53, v11
	v_sub_f32_e32 v54, v54, v11
	v_sub_f32_e32 v55, v55, v11
	v_sub_f32_e32 v56, v56, v11
	v_sub_f32_e32 v57, v57, v11
	v_sub_f32_e32 v58, v58, v11
	v_sub_f32_e32 v59, v59, v11
	v_sub_f32_e32 v60, v60, v11
	v_sub_f32_e32 v61, v61, v11
	v_sub_f32_e32 v62, v62, v11
	v_sub_f32_e32 v63, v63, v11
.LBB0_537:
	v_mov_b32_e32 v12, v66
	v_mov_b32_e32 v66, v72
	v_mov_b32_e32 v72, v78
	v_add_u32_e32 v78, 0x8800, v155
	v_mov_b32_e32 v10, v64
	v_mov_b32_e32 v11, v65
	v_mov_b32_e32 v14, v68
	v_mov_b32_e32 v15, v69
	v_mov_b32_e32 v64, v70
	v_mov_b32_e32 v65, v71
	v_mov_b32_e32 v68, v74
	v_mov_b32_e32 v69, v75
	v_mov_b32_e32 v70, v76
	v_mov_b32_e32 v71, v77
	ds_read2_b64 v[74:77], v78 offset0:64 offset1:66
	v_exp_f32_e32 v10, v10
	v_exp_f32_e32 v11, v11
	v_exp_f32_e32 v12, v12
	v_exp_f32_e32 v13, v67
	v_exp_f32_e32 v14, v14
	v_exp_f32_e32 v15, v15
	v_exp_f32_e32 v64, v64
	v_exp_f32_e32 v65, v65
	v_mov_b32_e32 v67, v73
	v_mov_b32_e32 v73, v79
	v_add_u32_e32 v79, 0x9800, v155
	v_cvt_pk_bf16_f32 v158, v10, v11
	v_cvt_pk_bf16_f32 v159, v12, v13
	v_cvt_pk_bf16_f32 v160, v14, v15
	v_cvt_pk_bf16_f32 v161, v64, v65
	ds_read2_b64 v[164:167], v79 offset0:96 offset1:98
	v_exp_f32_e32 v66, v66
	s_waitcnt lgkmcnt(0)
	v_mfma_f32_32x32x16_bf16 v[32:47], v[74:77], v[158:161], v[32:47]
	ds_read2_b64 v[74:77], v78 offset0:68 offset1:70
	v_exp_f32_e32 v67, v67
	v_exp_f32_e32 v68, v68
	v_exp_f32_e32 v69, v69
	v_exp_f32_e32 v70, v70
	v_exp_f32_e32 v71, v71
	v_exp_f32_e32 v72, v72
	v_exp_f32_e32 v73, v73
	v_mfma_f32_32x32x16_bf16 v[16:31], v[164:167], v[158:161], v[16:31]
	v_cvt_pk_bf16_f32 v158, v66, v67
	v_cvt_pk_bf16_f32 v159, v68, v69
	v_cvt_pk_bf16_f32 v160, v70, v71
	v_cvt_pk_bf16_f32 v161, v72, v73
	ds_read2_b64 v[164:167], v79 offset0:100 offset1:102
	s_waitcnt lgkmcnt(0)
	v_mfma_f32_32x32x16_bf16 v[32:47], v[74:77], v[158:161], v[32:47]
	ds_read2_b64 v[74:77], v78 offset0:72 offset1:74
	v_exp_f32_e32 v48, v48
	v_exp_f32_e32 v49, v49
	v_exp_f32_e32 v50, v50
	v_exp_f32_e32 v51, v51
	v_exp_f32_e32 v52, v52
	v_exp_f32_e32 v53, v53
	v_exp_f32_e32 v54, v54
	v_exp_f32_e32 v55, v55
	v_mfma_f32_32x32x16_bf16 v[16:31], v[164:167], v[158:161], v[16:31]
	v_cvt_pk_bf16_f32 v158, v48, v49
	v_cvt_pk_bf16_f32 v159, v50, v51
	v_cvt_pk_bf16_f32 v160, v52, v53
	v_cvt_pk_bf16_f32 v161, v54, v55
	ds_read2_b64 v[164:167], v79 offset0:104 offset1:106
	s_waitcnt lgkmcnt(0)
	v_mfma_f32_32x32x16_bf16 v[32:47], v[74:77], v[158:161], v[32:47]
	ds_read2_b64 v[74:77], v78 offset0:76 offset1:78
	v_exp_f32_e32 v56, v56
	v_exp_f32_e32 v57, v57
	v_exp_f32_e32 v58, v58
	v_exp_f32_e32 v59, v59
	v_exp_f32_e32 v60, v60
	v_exp_f32_e32 v61, v61
	v_exp_f32_e32 v62, v62
	v_exp_f32_e32 v63, v63
	v_mfma_f32_32x32x16_bf16 v[16:31], v[164:167], v[158:161], v[16:31]
	v_cvt_pk_bf16_f32 v158, v56, v57
	v_cvt_pk_bf16_f32 v159, v58, v59
	v_cvt_pk_bf16_f32 v160, v60, v61
	v_cvt_pk_bf16_f32 v161, v62, v63
	s_andn2_b64 vcc, exec, s[6:7]
	s_waitcnt lgkmcnt(0)
	v_mfma_f32_32x32x16_bf16 v[32:47], v[74:77], v[158:161], v[32:47]
	ds_read2_b64 v[74:77], v79 offset0:108 offset1:110
	s_waitcnt lgkmcnt(0)
	v_mfma_f32_32x32x16_bf16 v[16:31], v[74:77], v[158:161], v[16:31]
	s_cbranch_vccnz .LBB0_539
	v_add_u32_e32 v74, 0x6800, v153
	ds_write_b128 v150, v[124:127]
	ds_write_b128 v151, v[128:131]
	ds_write_b128 v152, v[132:135]
	ds_write2_b64 v139, v[2:3], v[4:5] offset1:1
	ds_write2_b64 v74, v[6:7], v[8:9] offset1:1

; template <int MI, int NI>
; DI void gemm256(f32x4 (&acc)[MI][NI], const u16* __restrict__ A, int lda, const u16* __restrict__ Bt, int ldb, int K, int m0, int n0, char* smem) {
;     ...
;   const int srow = lane >> 2, scol = ((lane & 3) ^ ((lane >> 5) << 1)) * 8;
;   const u16* Ag = A + (size_t)(m0 + wave * NAW * 16 + srow) * lda + scol;
;   const u16* Bg = Bt + (size_t)(n0 + wave * NBW * 16 + srow) * ldb + scol;
;   char* la = smem + (wave * NAW) * 1024 + lane * 16;
;   char* lb = smem + ABYTES + (wave * NBW) * 1024 + lane * 16;
;     ...
;   const int nk = K >> 5;
;   G256_ISSUE(0, 0);
;   if (nk > 1) G256_ISSUE(1, 32);
;   const int foff = lr * 64 + ((lq ^ ((lr >> 3) << 1)) * 16);
;   int st = 0;
;   for (int kt = 0; kt < nk; ++kt) {
;     if (kt + 1 < nk) asm volatile("s_waitcnt vmcnt(%0) lgkmcnt(0)" :: "n"(LPS) : "memory");
;     else asm volatile("s_waitcnt vmcnt(0) lgkmcnt(0)" ::: "memory");
;     __builtin_amdgcn_s_barrier();
;     __builtin_amdgcn_s_setprio(1);
;     const char* sb = smem + st * STAGE + foff;
;     bf16x8 af[MI], bfr[NI];
; #pragma unroll
;     for (int mi = 0; mi < MI; ++mi) af[mi] = *(const bf16x8*)(sb + (wr * MI + mi) * 1024);
; #pragma unroll
;     for (int ni = 0; ni < NI; ++ni) bfr[ni] = *(const bf16x8*)(sb + ABYTES + (wc * NI + ni) * 1024);
;     __builtin_amdgcn_sched_barrier(0x0);
;     if (kt + 2 < nk) { const int s2 = st >= 1 ? st - 1 : 2; G256_ISSUE(s2, (kt + 2) * 32); }
; DI void phase_qkv(const Params& p, int l, char* smem) {
;     ...
;   for (int it = 0;; ++it) {
;     int tm, tn;
;     if (!tile_map(it, NTM, 6, blk__, gridDim.x, tm, tn)) break;
;     f32x4 acc[8][4]; zero_accm<8, 4>(acc);
;     {
;       const int m0 = tm * 256, n0 = tn * 128;
;       gemm256<8, 4>(acc, za + 256, ZA, (const u16*)(wl + WO_UQ), 384, 384, m0, n0, smem);
.LBB0_551:
	s_andn2_b64 vcc, exec, s[0:1]
	s_mov_b64 s[0:1], -1
	s_cbranch_vccnz .LBB0_545
	s_waitcnt vmcnt(0)
	v_mov_b32_e32 v8, v163
	s_mov_b32 s4, s2
	s_lshl_b32 s0, s13, 8
	v_and_b32_e32 v0, 3, v8
	v_lshrrev_b32_e32 v2, 4, v8
	v_bitop3_b32 v0, v2, v0, 2 bitop3:0x6c
	v_and_b32_e32 v2, 0xffffffc0, v8
	v_readlane_b32 s4, v254, 27
	v_bfe_u32 v4, v8, 2, 4
	v_add_u32_e32 v2, s0, v2
	v_readlane_b32 s5, v254, 28
	v_or_b32_e32 v5, v2, v4
	s_lshl_b32 s1, s14, 7
	v_mov_b64_e32 v[2:3], s[4:5]
	s_movk_i32 s4, 0x740
	v_mad_i64_i32 v[2:3], s[4:5], v5, s4, v[2:3]
	v_ashrrev_i32_e32 v7, 6, v8
	v_readlane_b32 s4, v254, 29
	v_lshl_add_u32 v5, v7, 5, s1
	v_readlane_b32 s5, v254, 30
	v_and_b32_e32 v6, 63, v8
	v_or_b32_e32 v9, v5, v4
	v_mov_b64_e32 v[4:5], s[4:5]
	v_mad_i64_i32 v[4:5], s[4:5], v9, s27, v[4:5]
	v_lshlrev_b32_e32 v9, 12, v7
	v_lshlrev_b32_e32 v6, 4, v6
	v_or_b32_e32 v24, v9, v6
	v_lshlrev_b32_e32 v0, 4, v0
	v_readfirstlane_b32 s22, v24
	v_or_b32_e32 v25, 0x400, v24
	v_lshl_add_u64 v[2:3], v[2:3], 0, v[0:1]
	s_mov_b32 m0, s22
	s_mov_b64 s[4:5], 0x7400
	v_readfirstlane_b32 s21, v25
	s_waitcnt lgkmcnt(0)
	v_or_b32_e32 v26, 0x800, v24
	v_lshl_or_b32 v12, v7, 11, v6
	global_load_lds_dwordx4 v[2:3], off
	v_lshl_add_u64 v[6:7], v[2:3], 0, s[4:5]
	s_mov_b32 m0, s21
	s_mov_b64 s[4:5], 0xe800
	v_readfirstlane_b32 s23, v26
	v_or_b32_e32 v27, 0xc00, v24
	v_add_u32_e32 v23, 0x4000, v12
	global_load_lds_dwordx4 v[6:7], off
	v_lshl_add_u64 v[6:7], v[2:3], 0, s[4:5]
	s_mov_b32 m0, s23
	s_mov_b64 s[4:5], 0x15c00
	v_readfirstlane_b32 s24, v27
	global_load_lds_dwordx4 v[6:7], off
	v_lshl_add_u64 v[6:7], v[2:3], 0, s[4:5]
	s_mov_b32 m0, s24
	v_readfirstlane_b32 s25, v23
	v_add_u32_e32 v28, 0x4400, v12
	global_load_lds_dwordx4 v[6:7], off
	v_lshl_add_u64 v[4:5], v[4:5], 0, v[0:1]
	s_mov_b32 m0, s25
	s_mov_b64 s[4:5], 0x3000
	v_readfirstlane_b32 s26, v28
	v_add_u32_e32 v13, 0x6000, v24
	global_load_lds_dwordx4 v[4:5], off
	v_lshl_add_u64 v[6:7], v[4:5], 0, s[4:5]
	s_mov_b32 m0, s26
	v_readfirstlane_b32 s16, v13
	v_add_u32_e32 v14, 0x6400, v24
	global_load_lds_dwordx4 v[6:7], off
	v_lshl_add_u64 v[6:7], v[2:3], 0, 64
	s_mov_b32 m0, s16
	s_mov_b64 s[4:5], 0x7440
	v_readfirstlane_b32 s15, v14
	v_add_u32_e32 v15, 0x6800, v24
	global_load_lds_dwordx4 v[6:7], off
	v_lshl_add_u64 v[6:7], v[2:3], 0, s[4:5]
	s_mov_b32 m0, s15
	s_mov_b64 s[4:5], 0xe840
	v_readfirstlane_b32 s17, v15
	v_add_u32_e32 v17, 0x6c00, v24
	global_load_lds_dwordx4 v[6:7], off
	v_lshl_add_u64 v[6:7], v[2:3], 0, s[4:5]
	s_mov_b32 m0, s17
	s_mov_b64 s[4:5], 0x15c40
	v_readfirstlane_b32 s18, v17
	v_add_u32_e32 v16, 0xa000, v12
	global_load_lds_dwordx4 v[6:7], off
	v_lshl_add_u64 v[6:7], v[2:3], 0, s[4:5]
	s_mov_b32 m0, s18
	v_readfirstlane_b32 s19, v16
	v_add_u32_e32 v18, 0xa400, v12
	global_load_lds_dwordx4 v[6:7], off
	v_lshl_add_u64 v[6:7], v[4:5], 0, 64
	s_mov_b32 m0, s19
	s_mov_b64 s[4:5], 0x3040
	v_readfirstlane_b32 s20, v18
	global_load_lds_dwordx4 v[6:7], off
	v_lshl_add_u64 v[6:7], v[4:5], 0, s[4:5]
	s_mov_b32 m0, s20
	v_lshlrev_b32_e32 v0, 6, v8
	global_load_lds_dwordx4 v[6:7], off
	v_lshlrev_b32_e32 v6, 2, v8
	v_and_b32_e32 v7, 48, v8
	s_waitcnt vmcnt(6) lgkmcnt(0)
	v_bitop3_b32 v6, v6, v7, 32 bitop3:0x6c
	v_and_or_b32 v6, v0, s59, v6
	s_barrier
	s_setprio 1
	v_and_or_b32 v0, v0, s46, v6
	ds_read_b128 v[30:33], v0
	ds_read_b128 v[34:37], v0 offset:1024
	ds_read_b128 v[38:41], v0 offset:2048
	ds_read_b128 v[42:45], v0 offset:3072
	ds_read_b128 v[46:49], v0 offset:4096
	ds_read_b128 v[50:53], v0 offset:5120
	ds_read_b128 v[54:57], v0 offset:6144
	ds_read_b128 v[58:61], v0 offset:7168
	v_and_or_b32 v6, v9, s97, v6
	ds_read_b128 v[62:65], v6 offset:16384
	ds_read_b128 v[66:69], v6 offset:17408
	ds_read_b128 v[70:73], v6 offset:18432
	ds_read_b128 v[74:77], v6 offset:19456
	v_add_u32_e32 v7, 0xc000, v24
	s_mov_b64 s[8:9], 0x80
	v_readfirstlane_b32 s6, v7
	v_lshl_add_u64 v[8:9], v[2:3], 0, s[8:9]
	s_mov_b32 m0, s6
	s_mov_b64 s[4:5], 0x7480
	global_load_lds_dwordx4 v[8:9], off
	v_add_u32_e32 v8, 0xc400, v24
	v_lshl_add_u64 v[10:11], v[2:3], 0, s[4:5]
	v_readfirstlane_b32 s4, v8
	v_add_u32_e32 v9, 0xc800, v24
	s_mov_b32 m0, s4
	s_mov_b64 s[28:29], 0xe880
	v_readfirstlane_b32 s5, v9
	global_load_lds_dwordx4 v[10:11], off
	v_lshl_add_u64 v[10:11], v[2:3], 0, s[28:29]
	s_mov_b32 m0, s5
	s_mov_b64 s[28:29], 0x15c80
	global_load_lds_dwordx4 v[10:11], off
	v_add_u32_e32 v10, 0xcc00, v24
	v_lshl_add_u64 v[20:21], v[2:3], 0, s[28:29]
	v_readfirstlane_b32 s7, v10
	s_mov_b32 m0, s7
	v_add_u32_e32 v11, 0x10000, v12
	global_load_lds_dwordx4 v[20:21], off
	v_lshl_add_u64 v[20:21], v[4:5], 0, s[8:9]
	v_readfirstlane_b32 s8, v11
	v_add_u32_e32 v12, 0x10400, v12
	s_mov_b32 m0, s8
	s_mov_b64 s[28:29], 0x3080
	v_readfirstlane_b32 s9, v12
	global_load_lds_dwordx4 v[20:21], off
	v_lshl_add_u64 v[20:21], v[4:5], 0, s[28:29]
	s_mov_b32 m0, s9
	s_nop 0
	global_load_lds_dwordx4 v[20:21], off
	s_setprio 0
	s_waitcnt lgkmcnt(0)
	v_mfma_f32_16x16x32_bf16 v[78:81], v[62:65], v[30:33], 0
	s_waitcnt vmcnt(6) lgkmcnt(0)
	s_barrier
; template <int MI, int NI>
; DI void gemm256(f32x4 (&acc)[MI][NI], const u16* __restrict__ A, int lda, const u16* __restrict__ Bt, int ldb, int K, int m0, int n0, char* smem) {
;     ...
;   for (int kt = 0; kt < nk; ++kt) {
;     if (kt + 1 < nk) asm volatile("s_waitcnt vmcnt(%0) lgkmcnt(0)" :: "n"(LPS) : "memory");
;     else asm volatile("s_waitcnt vmcnt(0) lgkmcnt(0)" ::: "memory");
;     __builtin_amdgcn_s_barrier();
;     __builtin_amdgcn_s_setprio(1);
;     const char* sb = smem + st * STAGE + foff;
;     bf16x8 af[MI], bfr[NI];
; #pragma unroll
;     for (int mi = 0; mi < MI; ++mi) af[mi] = *(const bf16x8*)(sb + (wr * MI + mi) * 1024);
; #pragma unroll
;     for (int ni = 0; ni < NI; ++ni) bfr[ni] = *(const bf16x8*)(sb + ABYTES + (wc * NI + ni) * 1024);
;     __builtin_amdgcn_sched_barrier(0x0);
;     if (kt + 2 < nk) { const int s2 = st >= 1 ? st - 1 : 2; G256_ISSUE(s2, (kt + 2) * 32); }
;     __builtin_amdgcn_s_setprio(0);
; #pragma unroll
;     for (int mi = 0; mi < MI; ++mi)
; #pragma unroll
;       for (int ni = 0; ni < NI; ++ni)
;         acc[mi][ni] = __builtin_amdgcn_mfma_f32_16x16x32_bf16(bfr[ni], af[mi], acc[mi][ni], 0, 0, 0);
;     st = st == 2 ? 0 : st + 1;
;   }
	v_mfma_f32_16x16x32_bf16 v[82:85], v[66:69], v[30:33], 0
	v_mfma_f32_16x16x32_bf16 v[86:89], v[70:73], v[30:33], 0
	v_mfma_f32_16x16x32_bf16 v[30:33], v[74:77], v[30:33], 0
	v_mfma_f32_16x16x32_bf16 v[90:93], v[62:65], v[34:37], 0
	v_mfma_f32_16x16x32_bf16 v[94:97], v[66:69], v[34:37], 0
	v_mfma_f32_16x16x32_bf16 v[98:101], v[70:73], v[34:37], 0
	v_mfma_f32_16x16x32_bf16 v[34:37], v[74:77], v[34:37], 0
	v_mfma_f32_16x16x32_bf16 v[102:105], v[62:65], v[38:41], 0
	v_mfma_f32_16x16x32_bf16 v[106:109], v[66:69], v[38:41], 0
	v_mfma_f32_16x16x32_bf16 v[110:113], v[70:73], v[38:41], 0
	v_mfma_f32_16x16x32_bf16 v[38:41], v[74:77], v[38:41], 0
	v_mfma_f32_16x16x32_bf16 v[114:117], v[62:65], v[42:45], 0
	v_mfma_f32_16x16x32_bf16 v[118:121], v[66:69], v[42:45], 0
	v_mfma_f32_16x16x32_bf16 v[122:125], v[70:73], v[42:45], 0
	v_mfma_f32_16x16x32_bf16 v[42:45], v[74:77], v[42:45], 0
	v_mfma_f32_16x16x32_bf16 v[126:129], v[62:65], v[46:49], 0
	v_mfma_f32_16x16x32_bf16 v[130:133], v[66:69], v[46:49], 0
	v_mfma_f32_16x16x32_bf16 v[134:137], v[70:73], v[46:49], 0
	v_mfma_f32_16x16x32_bf16 v[46:49], v[74:77], v[46:49], 0
	v_mfma_f32_16x16x32_bf16 v[138:141], v[62:65], v[50:53], 0
	v_mfma_f32_16x16x32_bf16 v[142:145], v[66:69], v[50:53], 0
	v_mfma_f32_16x16x32_bf16 v[146:149], v[70:73], v[50:53], 0
	v_mfma_f32_16x16x32_bf16 v[50:53], v[74:77], v[50:53], 0
	v_mfma_f32_16x16x32_bf16 v[150:153], v[62:65], v[54:57], 0
	v_mfma_f32_16x16x32_bf16 v[154:157], v[66:69], v[54:57], 0
	v_mfma_f32_16x16x32_bf16 v[164:167], v[70:73], v[54:57], 0
	v_mfma_f32_16x16x32_bf16 v[54:57], v[74:77], v[54:57], 0
	v_mfma_f32_16x16x32_bf16 v[62:65], v[62:65], v[58:61], 0
	v_mfma_f32_16x16x32_bf16 v[66:69], v[66:69], v[58:61], 0
	v_mfma_f32_16x16x32_bf16 v[70:73], v[70:73], v[58:61], 0
	v_mfma_f32_16x16x32_bf16 v[58:61], v[74:77], v[58:61], 0
	s_setprio 1
	ds_read_b128 v[74:77], v0 offset:24576
	ds_read_b128 v[168:171], v0 offset:25600
	ds_read_b128 v[172:175], v0 offset:26624
	ds_read_b128 v[176:179], v0 offset:27648
	ds_read_b128 v[180:183], v0 offset:28672
	ds_read_b128 v[184:187], v0 offset:29696
	ds_read_b128 v[188:191], v0 offset:30720
	ds_read_b128 v[192:195], v0 offset:31744
	ds_read_b128 v[196:199], v6 offset:40960
	ds_read_b128 v[200:203], v6 offset:41984
	ds_read_b128 v[204:207], v6 offset:43008
	ds_read_b128 v[208:211], v6 offset:44032
	s_mov_b64 s[28:29], 0xc0
	s_mov_b32 m0, s22
	v_lshl_add_u64 v[20:21], v[2:3], 0, s[28:29]
	s_mov_b64 s[34:35], 0x74c0
	global_load_lds_dwordx4 v[20:21], off
	v_lshl_add_u64 v[20:21], v[2:3], 0, s[34:35]
	s_mov_b32 m0, s21
	s_mov_b64 s[34:35], 0xe8c0
	global_load_lds_dwordx4 v[20:21], off
	v_lshl_add_u64 v[20:21], v[2:3], 0, s[34:35]
	s_mov_b32 m0, s23
	s_mov_b64 s[34:35], 0x15cc0
	global_load_lds_dwordx4 v[20:21], off
	v_lshl_add_u64 v[20:21], v[2:3], 0, s[34:35]
	s_mov_b32 m0, s24
	s_nop 0
	global_load_lds_dwordx4 v[20:21], off
	v_lshl_add_u64 v[20:21], v[4:5], 0, s[28:29]
	s_mov_b32 m0, s25
	s_mov_b64 s[28:29], 0x30c0
	global_load_lds_dwordx4 v[20:21], off
	v_lshl_add_u64 v[20:21], v[4:5], 0, s[28:29]
	s_mov_b32 m0, s26
	s_nop 0
	global_load_lds_dwordx4 v[20:21], off
	s_setprio 0
	s_waitcnt lgkmcnt(0)
	v_mfma_f32_16x16x32_bf16 v[78:81], v[196:199], v[74:77], v[78:81]
	s_waitcnt vmcnt(6) lgkmcnt(0)
	s_barrier
	v_mfma_f32_16x16x32_bf16 v[82:85], v[200:203], v[74:77], v[82:85]
	v_mfma_f32_16x16x32_bf16 v[86:89], v[204:207], v[74:77], v[86:89]
	v_mfma_f32_16x16x32_bf16 v[30:33], v[208:211], v[74:77], v[30:33]
	v_mfma_f32_16x16x32_bf16 v[74:77], v[196:199], v[168:171], v[90:93]
	v_mfma_f32_16x16x32_bf16 v[90:93], v[200:203], v[168:171], v[94:97]
	v_mfma_f32_16x16x32_bf16 v[94:97], v[204:207], v[168:171], v[98:101]
	v_mfma_f32_16x16x32_bf16 v[34:37], v[208:211], v[168:171], v[34:37]
	v_mfma_f32_16x16x32_bf16 v[98:101], v[196:199], v[172:175], v[102:105]
	v_mfma_f32_16x16x32_bf16 v[102:105], v[200:203], v[172:175], v[106:109]
	v_mfma_f32_16x16x32_bf16 v[106:109], v[204:207], v[172:175], v[110:113]
	v_mfma_f32_16x16x32_bf16 v[38:41], v[208:211], v[172:175], v[38:41]
	v_mfma_f32_16x16x32_bf16 v[110:113], v[196:199], v[176:179], v[114:117]
	v_mfma_f32_16x16x32_bf16 v[114:117], v[200:203], v[176:179], v[118:121]
	v_mfma_f32_16x16x32_bf16 v[118:121], v[204:207], v[176:179], v[122:125]
	v_mfma_f32_16x16x32_bf16 v[42:45], v[208:211], v[176:179], v[42:45]
	v_mfma_f32_16x16x32_bf16 v[122:125], v[196:199], v[180:183], v[126:129]
	v_mfma_f32_16x16x32_bf16 v[126:129], v[200:203], v[180:183], v[130:133]
	v_mfma_f32_16x16x32_bf16 v[130:133], v[204:207], v[180:183], v[134:137]
	v_mfma_f32_16x16x32_bf16 v[46:49], v[208:211], v[180:183], v[46:49]
	v_mfma_f32_16x16x32_bf16 v[134:137], v[196:199], v[184:187], v[138:141]
	v_mfma_f32_16x16x32_bf16 v[138:141], v[200:203], v[184:187], v[142:145]
	v_mfma_f32_16x16x32_bf16 v[142:145], v[204:207], v[184:187], v[146:149]
	v_mfma_f32_16x16x32_bf16 v[50:53], v[208:211], v[184:187], v[50:53]
	v_mfma_f32_16x16x32_bf16 v[146:149], v[196:199], v[188:191], v[150:153]
	v_mfma_f32_16x16x32_bf16 v[54:57], v[208:211], v[188:191], v[54:57]
	v_mfma_f32_16x16x32_bf16 v[62:65], v[196:199], v[192:195], v[62:65]
	v_mfma_f32_16x16x32_bf16 v[66:69], v[200:203], v[192:195], v[66:69]
	v_mfma_f32_16x16x32_bf16 v[70:73], v[204:207], v[192:195], v[70:73]
	v_mfma_f32_16x16x32_bf16 v[58:61], v[208:211], v[192:195], v[58:61]
	v_mfma_f32_16x16x32_bf16 v[150:153], v[200:203], v[188:191], v[154:157]
	v_mfma_f32_16x16x32_bf16 v[154:157], v[204:207], v[188:191], v[164:167]
	s_setprio 1
	s_nop 0
	ds_read_b128 v[164:167], v0 offset:49152
	ds_read_b128 v[168:171], v0 offset:50176
	ds_read_b128 v[172:175], v0 offset:51200
	ds_read_b128 v[176:179], v0 offset:52224
	ds_read_b128 v[180:183], v0 offset:53248
	ds_read_b128 v[184:187], v0 offset:54272
	ds_read_b128 v[188:191], v0 offset:55296
	ds_read_b128 v[192:195], v0 offset:56320
	v_or_b32_e32 v19, 0x10000, v6
	v_or_b32_e32 v21, 0x10800, v6
	v_or_b32_e32 v20, 0x10400, v6
	ds_read_b128 v[196:199], v19
	ds_read_b128 v[200:203], v20
	v_or_b32_e32 v22, 0x10c00, v6
	ds_read_b128 v[204:207], v21
	ds_read_b128 v[208:211], v22
	s_mov_b64 s[28:29], 0x100
	s_mov_b32 m0, s16
	v_lshl_add_u64 v[212:213], v[2:3], 0, s[28:29]
	s_mov_b64 s[34:35], 0x7500
	global_load_lds_dwordx4 v[212:213], off
	v_lshl_add_u64 v[212:213], v[2:3], 0, s[34:35]
	s_mov_b32 m0, s15
	s_mov_b64 s[34:35], 0xe900
	global_load_lds_dwordx4 v[212:213], off
	v_lshl_add_u64 v[212:213], v[2:3], 0, s[34:35]
	s_mov_b32 m0, s17
	s_mov_b64 s[34:35], 0x15d00
	global_load_lds_dwordx4 v[212:213], off
	v_lshl_add_u64 v[212:213], v[2:3], 0, s[34:35]
	s_mov_b32 m0, s18
	s_mov_b64 s[50:51], 0x100
	global_load_lds_dwordx4 v[212:213], off
	v_lshl_add_u64 v[212:213], v[4:5], 0, s[28:29]
	s_mov_b32 m0, s19
	s_mov_b64 s[28:29], 0x3100
	global_load_lds_dwordx4 v[212:213], off
	v_lshl_add_u64 v[212:213], v[4:5], 0, s[28:29]
	s_mov_b32 m0, s20
	s_nop 0
	global_load_lds_dwordx4 v[212:213], off
	s_setprio 0
	s_waitcnt lgkmcnt(0)
	v_mfma_f32_16x16x32_bf16 v[78:81], v[196:199], v[164:167], v[78:81]
	s_waitcnt vmcnt(6) lgkmcnt(0)
	s_barrier
; template <int MI, int NI>
; DI void gemm256(f32x4 (&acc)[MI][NI], const u16* __restrict__ A, int lda, const u16* __restrict__ Bt, int ldb, int K, int m0, int n0, char* smem) {
;     ...
;   for (int kt = 0; kt < nk; ++kt) {
;     if (kt + 1 < nk) asm volatile("s_waitcnt vmcnt(%0) lgkmcnt(0)" :: "n"(LPS) : "memory");
;     else asm volatile("s_waitcnt vmcnt(0) lgkmcnt(0)" ::: "memory");
;     __builtin_amdgcn_s_barrier();
;     __builtin_amdgcn_s_setprio(1);
;     const char* sb = smem + st * STAGE + foff;
;     bf16x8 af[MI], bfr[NI];
; #pragma unroll
;     for (int mi = 0; mi < MI; ++mi) af[mi] = *(const bf16x8*)(sb + (wr * MI + mi) * 1024);
; #pragma unroll
;     for (int ni = 0; ni < NI; ++ni) bfr[ni] = *(const bf16x8*)(sb + ABYTES + (wc * NI + ni) * 1024);
;     __builtin_amdgcn_sched_barrier(0x0);
;     if (kt + 2 < nk) { const int s2 = st >= 1 ? st - 1 : 2; G256_ISSUE(s2, (kt + 2) * 32); }
;     __builtin_amdgcn_s_setprio(0);
; #pragma unroll
;     for (int mi = 0; mi < MI; ++mi)
; #pragma unroll
;       for (int ni = 0; ni < NI; ++ni)
;         acc[mi][ni] = __builtin_amdgcn_mfma_f32_16x16x32_bf16(bfr[ni], af[mi], acc[mi][ni], 0, 0, 0);
;     st = st == 2 ? 0 : st + 1;
;   }
	v_mfma_f32_16x16x32_bf16 v[82:85], v[200:203], v[164:167], v[82:85]
	v_mfma_f32_16x16x32_bf16 v[86:89], v[204:207], v[164:167], v[86:89]
	v_mfma_f32_16x16x32_bf16 v[30:33], v[208:211], v[164:167], v[30:33]
	v_mfma_f32_16x16x32_bf16 v[74:77], v[196:199], v[168:171], v[74:77]
	v_mfma_f32_16x16x32_bf16 v[90:93], v[200:203], v[168:171], v[90:93]
	v_mfma_f32_16x16x32_bf16 v[94:97], v[204:207], v[168:171], v[94:97]
	v_mfma_f32_16x16x32_bf16 v[34:37], v[208:211], v[168:171], v[34:37]
	v_mfma_f32_16x16x32_bf16 v[98:101], v[196:199], v[172:175], v[98:101]
	v_mfma_f32_16x16x32_bf16 v[102:105], v[200:203], v[172:175], v[102:105]
	v_mfma_f32_16x16x32_bf16 v[106:109], v[204:207], v[172:175], v[106:109]
	v_mfma_f32_16x16x32_bf16 v[38:41], v[208:211], v[172:175], v[38:41]
	v_mfma_f32_16x16x32_bf16 v[110:113], v[196:199], v[176:179], v[110:113]
	v_mfma_f32_16x16x32_bf16 v[114:117], v[200:203], v[176:179], v[114:117]
	v_mfma_f32_16x16x32_bf16 v[118:121], v[204:207], v[176:179], v[118:121]
	v_mfma_f32_16x16x32_bf16 v[42:45], v[208:211], v[176:179], v[42:45]
	v_mfma_f32_16x16x32_bf16 v[122:125], v[196:199], v[180:183], v[122:125]
	v_mfma_f32_16x16x32_bf16 v[126:129], v[200:203], v[180:183], v[126:129]
	v_mfma_f32_16x16x32_bf16 v[130:133], v[204:207], v[180:183], v[130:133]
	v_mfma_f32_16x16x32_bf16 v[46:49], v[208:211], v[180:183], v[46:49]
	v_mfma_f32_16x16x32_bf16 v[134:137], v[196:199], v[184:187], v[134:137]
	v_mfma_f32_16x16x32_bf16 v[138:141], v[200:203], v[184:187], v[138:141]
	v_mfma_f32_16x16x32_bf16 v[142:145], v[204:207], v[184:187], v[142:145]
	v_mfma_f32_16x16x32_bf16 v[50:53], v[208:211], v[184:187], v[50:53]
	v_mfma_f32_16x16x32_bf16 v[146:149], v[196:199], v[188:191], v[146:149]
	v_mfma_f32_16x16x32_bf16 v[54:57], v[208:211], v[188:191], v[54:57]
	v_mfma_f32_16x16x32_bf16 v[62:65], v[196:199], v[192:195], v[62:65]
	v_mfma_f32_16x16x32_bf16 v[66:69], v[200:203], v[192:195], v[66:69]
	v_mfma_f32_16x16x32_bf16 v[70:73], v[204:207], v[192:195], v[70:73]
	v_mfma_f32_16x16x32_bf16 v[58:61], v[208:211], v[192:195], v[58:61]
	v_mfma_f32_16x16x32_bf16 v[150:153], v[200:203], v[188:191], v[150:153]
	v_mfma_f32_16x16x32_bf16 v[154:157], v[204:207], v[188:191], v[154:157]
	s_setprio 1
	ds_read_b128 v[164:167], v0
	ds_read_b128 v[168:171], v0 offset:1024
	ds_read_b128 v[172:175], v0 offset:2048
	ds_read_b128 v[176:179], v0 offset:3072
	ds_read_b128 v[180:183], v0 offset:4096
	ds_read_b128 v[184:187], v0 offset:5120
	ds_read_b128 v[188:191], v0 offset:6144
	ds_read_b128 v[192:195], v0 offset:7168
	ds_read_b128 v[196:199], v6 offset:16384
	ds_read_b128 v[200:203], v6 offset:17408
	ds_read_b128 v[204:207], v6 offset:18432
	ds_read_b128 v[208:211], v6 offset:19456
	s_mov_b64 s[28:29], 0x140
	s_mov_b32 m0, s6
	v_lshl_add_u64 v[212:213], v[2:3], 0, s[28:29]
	s_mov_b64 s[34:35], 0x7540
	global_load_lds_dwordx4 v[212:213], off
	v_lshl_add_u64 v[212:213], v[2:3], 0, s[34:35]
	s_mov_b32 m0, s4
	s_mov_b64 s[34:35], 0xe940
	global_load_lds_dwordx4 v[212:213], off
	v_lshl_add_u64 v[212:213], v[2:3], 0, s[34:35]
	s_mov_b32 m0, s5
	s_mov_b64 s[34:35], 0x15d40
	global_load_lds_dwordx4 v[212:213], off
	v_lshl_add_u64 v[212:213], v[2:3], 0, s[34:35]
	s_mov_b32 m0, s7
	s_nop 0
	global_load_lds_dwordx4 v[212:213], off
	v_lshl_add_u64 v[212:213], v[4:5], 0, s[28:29]
	s_mov_b32 m0, s8
	s_mov_b64 s[28:29], 0x3140
	global_load_lds_dwordx4 v[212:213], off
	v_lshl_add_u64 v[212:213], v[4:5], 0, s[28:29]
	s_mov_b32 m0, s9
	s_nop 0
	global_load_lds_dwordx4 v[212:213], off
	s_setprio 0
	s_waitcnt lgkmcnt(0)
	v_mfma_f32_16x16x32_bf16 v[78:81], v[196:199], v[164:167], v[78:81]
	s_waitcnt vmcnt(6) lgkmcnt(0)
	s_barrier
	v_mfma_f32_16x16x32_bf16 v[82:85], v[200:203], v[164:167], v[82:85]
	v_mfma_f32_16x16x32_bf16 v[86:89], v[204:207], v[164:167], v[86:89]
	v_mfma_f32_16x16x32_bf16 v[30:33], v[208:211], v[164:167], v[30:33]
	v_mfma_f32_16x16x32_bf16 v[74:77], v[196:199], v[168:171], v[74:77]
	v_mfma_f32_16x16x32_bf16 v[90:93], v[200:203], v[168:171], v[90:93]
	v_mfma_f32_16x16x32_bf16 v[94:97], v[204:207], v[168:171], v[94:97]
	v_mfma_f32_16x16x32_bf16 v[34:37], v[208:211], v[168:171], v[34:37]
	v_mfma_f32_16x16x32_bf16 v[98:101], v[196:199], v[172:175], v[98:101]
	v_mfma_f32_16x16x32_bf16 v[102:105], v[200:203], v[172:175], v[102:105]
	v_mfma_f32_16x16x32_bf16 v[106:109], v[204:207], v[172:175], v[106:109]
	v_mfma_f32_16x16x32_bf16 v[38:41], v[208:211], v[172:175], v[38:41]
	v_mfma_f32_16x16x32_bf16 v[110:113], v[196:199], v[176:179], v[110:113]
	v_mfma_f32_16x16x32_bf16 v[114:117], v[200:203], v[176:179], v[114:117]
	v_mfma_f32_16x16x32_bf16 v[118:121], v[204:207], v[176:179], v[118:121]
	v_mfma_f32_16x16x32_bf16 v[42:45], v[208:211], v[176:179], v[42:45]
	v_mfma_f32_16x16x32_bf16 v[122:125], v[196:199], v[180:183], v[122:125]
	v_mfma_f32_16x16x32_bf16 v[126:129], v[200:203], v[180:183], v[126:129]
	v_mfma_f32_16x16x32_bf16 v[130:133], v[204:207], v[180:183], v[130:133]
	v_mfma_f32_16x16x32_bf16 v[46:49], v[208:211], v[180:183], v[46:49]
	v_mfma_f32_16x16x32_bf16 v[134:137], v[196:199], v[184:187], v[134:137]
	v_mfma_f32_16x16x32_bf16 v[138:141], v[200:203], v[184:187], v[138:141]
	v_mfma_f32_16x16x32_bf16 v[142:145], v[204:207], v[184:187], v[142:145]
	v_mfma_f32_16x16x32_bf16 v[50:53], v[208:211], v[184:187], v[50:53]
	v_mfma_f32_16x16x32_bf16 v[146:149], v[196:199], v[188:191], v[146:149]
	v_mfma_f32_16x16x32_bf16 v[54:57], v[208:211], v[188:191], v[54:57]
	v_mfma_f32_16x16x32_bf16 v[62:65], v[196:199], v[192:195], v[62:65]
	v_mfma_f32_16x16x32_bf16 v[66:69], v[200:203], v[192:195], v[66:69]
	v_mfma_f32_16x16x32_bf16 v[70:73], v[204:207], v[192:195], v[70:73]
; template <int MI, int NI>
; DI void gemm256(f32x4 (&acc)[MI][NI], const u16* __restrict__ A, int lda, const u16* __restrict__ Bt, int ldb, int K, int m0, int n0, char* smem) {
;     ...
;   for (int kt = 0; kt < nk; ++kt) {
;     if (kt + 1 < nk) asm volatile("s_waitcnt vmcnt(%0) lgkmcnt(0)" :: "n"(LPS) : "memory");
;     else asm volatile("s_waitcnt vmcnt(0) lgkmcnt(0)" ::: "memory");
;     __builtin_amdgcn_s_barrier();
;     __builtin_amdgcn_s_setprio(1);
;     const char* sb = smem + st * STAGE + foff;
;     bf16x8 af[MI], bfr[NI];
; #pragma unroll
;     for (int mi = 0; mi < MI; ++mi) af[mi] = *(const bf16x8*)(sb + (wr * MI + mi) * 1024);
; #pragma unroll
;     for (int ni = 0; ni < NI; ++ni) bfr[ni] = *(const bf16x8*)(sb + ABYTES + (wc * NI + ni) * 1024);
;     __builtin_amdgcn_sched_barrier(0x0);
;     if (kt + 2 < nk) { const int s2 = st >= 1 ? st - 1 : 2; G256_ISSUE(s2, (kt + 2) * 32); }
;     __builtin_amdgcn_s_setprio(0);
; #pragma unroll
;     for (int mi = 0; mi < MI; ++mi)
; #pragma unroll
;       for (int ni = 0; ni < NI; ++ni)
;         acc[mi][ni] = __builtin_amdgcn_mfma_f32_16x16x32_bf16(bfr[ni], af[mi], acc[mi][ni], 0, 0, 0);
;     st = st == 2 ? 0 : st + 1;
;   }
	v_mfma_f32_16x16x32_bf16 v[58:61], v[208:211], v[192:195], v[58:61]
	v_mfma_f32_16x16x32_bf16 v[150:153], v[200:203], v[188:191], v[150:153]
	v_mfma_f32_16x16x32_bf16 v[154:157], v[204:207], v[188:191], v[154:157]
	s_setprio 1
	ds_read_b128 v[164:167], v0 offset:24576
	ds_read_b128 v[168:171], v0 offset:25600
	ds_read_b128 v[172:175], v0 offset:26624
	ds_read_b128 v[176:179], v0 offset:27648
	ds_read_b128 v[180:183], v0 offset:28672
	ds_read_b128 v[184:187], v0 offset:29696
	ds_read_b128 v[188:191], v0 offset:30720
	ds_read_b128 v[192:195], v0 offset:31744
	ds_read_b128 v[196:199], v6 offset:40960
	ds_read_b128 v[200:203], v6 offset:41984
	ds_read_b128 v[204:207], v6 offset:43008
	ds_read_b128 v[208:211], v6 offset:44032
	s_mov_b64 s[28:29], 0x180
	s_mov_b32 m0, s22
	v_lshl_add_u64 v[212:213], v[2:3], 0, s[28:29]
	s_mov_b64 s[34:35], 0x7580
	global_load_lds_dwordx4 v[212:213], off
	v_lshl_add_u64 v[212:213], v[2:3], 0, s[34:35]
	s_mov_b32 m0, s21
	s_mov_b64 s[34:35], 0xe980
	global_load_lds_dwordx4 v[212:213], off
	v_lshl_add_u64 v[212:213], v[2:3], 0, s[34:35]
	s_mov_b32 m0, s23
	s_mov_b64 s[22:23], 0x15d80
	global_load_lds_dwordx4 v[212:213], off
	v_lshl_add_u64 v[212:213], v[2:3], 0, s[22:23]
	s_mov_b32 m0, s24
	s_mov_b64 s[22:23], 0x3180
	global_load_lds_dwordx4 v[212:213], off
	v_lshl_add_u64 v[212:213], v[4:5], 0, s[28:29]
	s_mov_b32 m0, s25
	s_nop 0
	global_load_lds_dwordx4 v[212:213], off
	v_lshl_add_u64 v[212:213], v[4:5], 0, s[22:23]
	s_mov_b32 m0, s26
	s_nop 0
	global_load_lds_dwordx4 v[212:213], off
	s_setprio 0
	s_waitcnt lgkmcnt(0)
	v_mfma_f32_16x16x32_bf16 v[78:81], v[196:199], v[164:167], v[78:81]
	s_waitcnt vmcnt(6) lgkmcnt(0)
	s_barrier
	v_mfma_f32_16x16x32_bf16 v[82:85], v[200:203], v[164:167], v[82:85]
	v_mfma_f32_16x16x32_bf16 v[86:89], v[204:207], v[164:167], v[86:89]
	v_mfma_f32_16x16x32_bf16 v[30:33], v[208:211], v[164:167], v[30:33]
	v_mfma_f32_16x16x32_bf16 v[74:77], v[196:199], v[168:171], v[74:77]
	v_mfma_f32_16x16x32_bf16 v[90:93], v[200:203], v[168:171], v[90:93]
	v_mfma_f32_16x16x32_bf16 v[94:97], v[204:207], v[168:171], v[94:97]
	v_mfma_f32_16x16x32_bf16 v[34:37], v[208:211], v[168:171], v[34:37]
	v_mfma_f32_16x16x32_bf16 v[98:101], v[196:199], v[172:175], v[98:101]
	v_mfma_f32_16x16x32_bf16 v[102:105], v[200:203], v[172:175], v[102:105]
	v_mfma_f32_16x16x32_bf16 v[106:109], v[204:207], v[172:175], v[106:109]
	v_mfma_f32_16x16x32_bf16 v[38:41], v[208:211], v[172:175], v[38:41]
	v_mfma_f32_16x16x32_bf16 v[110:113], v[196:199], v[176:179], v[110:113]
	v_mfma_f32_16x16x32_bf16 v[114:117], v[200:203], v[176:179], v[114:117]
	v_mfma_f32_16x16x32_bf16 v[118:121], v[204:207], v[176:179], v[118:121]
	v_mfma_f32_16x16x32_bf16 v[42:45], v[208:211], v[176:179], v[42:45]
	v_mfma_f32_16x16x32_bf16 v[122:125], v[196:199], v[180:183], v[122:125]
	v_mfma_f32_16x16x32_bf16 v[126:129], v[200:203], v[180:183], v[126:129]
	v_mfma_f32_16x16x32_bf16 v[130:133], v[204:207], v[180:183], v[130:133]
	v_mfma_f32_16x16x32_bf16 v[46:49], v[208:211], v[180:183], v[46:49]
	v_mfma_f32_16x16x32_bf16 v[134:137], v[196:199], v[184:187], v[134:137]
	v_mfma_f32_16x16x32_bf16 v[138:141], v[200:203], v[184:187], v[138:141]
	v_mfma_f32_16x16x32_bf16 v[142:145], v[204:207], v[184:187], v[142:145]
	v_mfma_f32_16x16x32_bf16 v[50:53], v[208:211], v[184:187], v[50:53]
	v_mfma_f32_16x16x32_bf16 v[146:149], v[196:199], v[188:191], v[146:149]
	v_mfma_f32_16x16x32_bf16 v[54:57], v[208:211], v[188:191], v[54:57]
	v_mfma_f32_16x16x32_bf16 v[62:65], v[196:199], v[192:195], v[62:65]
	v_mfma_f32_16x16x32_bf16 v[66:69], v[200:203], v[192:195], v[66:69]
	v_mfma_f32_16x16x32_bf16 v[70:73], v[204:207], v[192:195], v[70:73]
	v_mfma_f32_16x16x32_bf16 v[58:61], v[208:211], v[192:195], v[58:61]
	v_mfma_f32_16x16x32_bf16 v[150:153], v[200:203], v[188:191], v[150:153]
	v_mfma_f32_16x16x32_bf16 v[154:157], v[204:207], v[188:191], v[154:157]
	s_setprio 1
	ds_read_b128 v[164:167], v0 offset:49152
	ds_read_b128 v[168:171], v0 offset:50176
	ds_read_b128 v[172:175], v0 offset:51200
	ds_read_b128 v[176:179], v0 offset:52224
	ds_read_b128 v[180:183], v0 offset:53248
	ds_read_b128 v[184:187], v0 offset:54272
	ds_read_b128 v[188:191], v0 offset:55296
	ds_read_b128 v[192:195], v0 offset:56320
	ds_read_b128 v[196:199], v19
	ds_read_b128 v[200:203], v20
	ds_read_b128 v[204:207], v21
	ds_read_b128 v[208:211], v22
	s_mov_b64 s[22:23], 0x1c0
	s_mov_b32 m0, s16
	v_lshl_add_u64 v[212:213], v[2:3], 0, s[22:23]
	s_mov_b64 s[24:25], 0x75c0
	global_load_lds_dwordx4 v[212:213], off
	v_lshl_add_u64 v[212:213], v[2:3], 0, s[24:25]
	s_mov_b32 m0, s15
	s_mov_b64 s[24:25], 0xe9c0
	global_load_lds_dwordx4 v[212:213], off
	v_lshl_add_u64 v[212:213], v[2:3], 0, s[24:25]
	s_mov_b32 m0, s17
	s_mov_b64 s[16:17], 0x15dc0
	global_load_lds_dwordx4 v[212:213], off
	v_lshl_add_u64 v[212:213], v[2:3], 0, s[16:17]
	s_mov_b32 m0, s18
	s_mov_b64 s[16:17], 0x31c0
	global_load_lds_dwordx4 v[212:213], off
	v_lshl_add_u64 v[212:213], v[4:5], 0, s[22:23]
	s_mov_b32 m0, s19
	s_nop 0
	global_load_lds_dwordx4 v[212:213], off
	v_lshl_add_u64 v[212:213], v[4:5], 0, s[16:17]
	s_mov_b32 m0, s20
	s_nop 0
	global_load_lds_dwordx4 v[212:213], off
	s_setprio 0
	s_waitcnt lgkmcnt(0)
	v_mfma_f32_16x16x32_bf16 v[78:81], v[196:199], v[164:167], v[78:81]
	s_waitcnt vmcnt(6) lgkmcnt(0)
	s_barrier
; template <int MI, int NI>
; DI void gemm256(f32x4 (&acc)[MI][NI], const u16* __restrict__ A, int lda, const u16* __restrict__ Bt, int ldb, int K, int m0, int n0, char* smem) {
;     ...
;   for (int kt = 0; kt < nk; ++kt) {
;     if (kt + 1 < nk) asm volatile("s_waitcnt vmcnt(%0) lgkmcnt(0)" :: "n"(LPS) : "memory");
;     else asm volatile("s_waitcnt vmcnt(0) lgkmcnt(0)" ::: "memory");
;     __builtin_amdgcn_s_barrier();
;     __builtin_amdgcn_s_setprio(1);
;     const char* sb = smem + st * STAGE + foff;
;     bf16x8 af[MI], bfr[NI];
; #pragma unroll
;     for (int mi = 0; mi < MI; ++mi) af[mi] = *(const bf16x8*)(sb + (wr * MI + mi) * 1024);
; #pragma unroll
;     for (int ni = 0; ni < NI; ++ni) bfr[ni] = *(const bf16x8*)(sb + ABYTES + (wc * NI + ni) * 1024);
;     __builtin_amdgcn_sched_barrier(0x0);
;     if (kt + 2 < nk) { const int s2 = st >= 1 ? st - 1 : 2; G256_ISSUE(s2, (kt + 2) * 32); }
;     __builtin_amdgcn_s_setprio(0);
; #pragma unroll
;     for (int mi = 0; mi < MI; ++mi)
; #pragma unroll
;       for (int ni = 0; ni < NI; ++ni)
;         acc[mi][ni] = __builtin_amdgcn_mfma_f32_16x16x32_bf16(bfr[ni], af[mi], acc[mi][ni], 0, 0, 0);
;     st = st == 2 ? 0 : st + 1;
;   }
	v_mfma_f32_16x16x32_bf16 v[82:85], v[200:203], v[164:167], v[82:85]
	v_mfma_f32_16x16x32_bf16 v[86:89], v[204:207], v[164:167], v[86:89]
	v_mfma_f32_16x16x32_bf16 v[30:33], v[208:211], v[164:167], v[30:33]
	v_mfma_f32_16x16x32_bf16 v[74:77], v[196:199], v[168:171], v[74:77]
	v_mfma_f32_16x16x32_bf16 v[90:93], v[200:203], v[168:171], v[90:93]
	v_mfma_f32_16x16x32_bf16 v[94:97], v[204:207], v[168:171], v[94:97]
	v_mfma_f32_16x16x32_bf16 v[34:37], v[208:211], v[168:171], v[34:37]
	v_mfma_f32_16x16x32_bf16 v[98:101], v[196:199], v[172:175], v[98:101]
	v_mfma_f32_16x16x32_bf16 v[102:105], v[200:203], v[172:175], v[102:105]
	v_mfma_f32_16x16x32_bf16 v[106:109], v[204:207], v[172:175], v[106:109]
	v_mfma_f32_16x16x32_bf16 v[38:41], v[208:211], v[172:175], v[38:41]
	v_mfma_f32_16x16x32_bf16 v[110:113], v[196:199], v[176:179], v[110:113]
	v_mfma_f32_16x16x32_bf16 v[114:117], v[200:203], v[176:179], v[114:117]
	v_mfma_f32_16x16x32_bf16 v[118:121], v[204:207], v[176:179], v[118:121]
	v_mfma_f32_16x16x32_bf16 v[42:45], v[208:211], v[176:179], v[42:45]
	v_mfma_f32_16x16x32_bf16 v[122:125], v[196:199], v[180:183], v[122:125]
	v_mfma_f32_16x16x32_bf16 v[126:129], v[200:203], v[180:183], v[126:129]
	v_mfma_f32_16x16x32_bf16 v[130:133], v[204:207], v[180:183], v[130:133]
	v_mfma_f32_16x16x32_bf16 v[46:49], v[208:211], v[180:183], v[46:49]
	v_mfma_f32_16x16x32_bf16 v[134:137], v[196:199], v[184:187], v[134:137]
	v_mfma_f32_16x16x32_bf16 v[138:141], v[200:203], v[184:187], v[138:141]
	v_mfma_f32_16x16x32_bf16 v[142:145], v[204:207], v[184:187], v[142:145]
	v_mfma_f32_16x16x32_bf16 v[50:53], v[208:211], v[184:187], v[50:53]
	v_mfma_f32_16x16x32_bf16 v[146:149], v[196:199], v[188:191], v[146:149]
	v_mfma_f32_16x16x32_bf16 v[54:57], v[208:211], v[188:191], v[54:57]
	v_mfma_f32_16x16x32_bf16 v[62:65], v[196:199], v[192:195], v[62:65]
	v_mfma_f32_16x16x32_bf16 v[66:69], v[200:203], v[192:195], v[66:69]
	v_mfma_f32_16x16x32_bf16 v[70:73], v[204:207], v[192:195], v[70:73]
	v_mfma_f32_16x16x32_bf16 v[58:61], v[208:211], v[192:195], v[58:61]
	v_mfma_f32_16x16x32_bf16 v[150:153], v[200:203], v[188:191], v[150:153]
	v_mfma_f32_16x16x32_bf16 v[154:157], v[204:207], v[188:191], v[154:157]
	s_setprio 1
	ds_read_b128 v[164:167], v0
	ds_read_b128 v[168:171], v0 offset:1024
	ds_read_b128 v[172:175], v0 offset:2048
	ds_read_b128 v[176:179], v0 offset:3072
	ds_read_b128 v[180:183], v0 offset:4096
	ds_read_b128 v[184:187], v0 offset:5120
	ds_read_b128 v[188:191], v0 offset:6144
	ds_read_b128 v[192:195], v0 offset:7168
	ds_read_b128 v[196:199], v6 offset:16384
	ds_read_b128 v[200:203], v6 offset:17408
	ds_read_b128 v[204:207], v6 offset:18432
	ds_read_b128 v[208:211], v6 offset:19456
	s_mov_b64 s[18:19], 0x200
	s_mov_b32 m0, s6
	v_lshl_add_u64 v[212:213], v[2:3], 0, s[18:19]
	s_mov_b64 s[16:17], 0x7600
	global_load_lds_dwordx4 v[212:213], off
	v_lshl_add_u64 v[212:213], v[2:3], 0, s[16:17]
	s_mov_b32 m0, s4
	s_mov_b64 s[16:17], 0xea00
	global_load_lds_dwordx4 v[212:213], off
	v_lshl_add_u64 v[212:213], v[2:3], 0, s[16:17]
	s_mov_b32 m0, s5
	s_mov_b64 s[4:5], 0x15e00
	global_load_lds_dwordx4 v[212:213], off
	v_lshl_add_u64 v[212:213], v[2:3], 0, s[4:5]
	s_mov_b32 m0, s7
	s_mov_b64 s[4:5], 0x3200
	global_load_lds_dwordx4 v[212:213], off
	v_lshl_add_u64 v[212:213], v[4:5], 0, s[18:19]
	s_mov_b32 m0, s8
	s_nop 0
	global_load_lds_dwordx4 v[212:213], off
	v_lshl_add_u64 v[212:213], v[4:5], 0, s[4:5]
	s_mov_b32 m0, s9
	s_nop 0
	global_load_lds_dwordx4 v[212:213], off
	s_setprio 0
	s_waitcnt lgkmcnt(0)
	v_mfma_f32_16x16x32_bf16 v[78:81], v[196:199], v[164:167], v[78:81]
	s_waitcnt vmcnt(6) lgkmcnt(0)
	s_barrier
	v_mfma_f32_16x16x32_bf16 v[82:85], v[200:203], v[164:167], v[82:85]
	v_mfma_f32_16x16x32_bf16 v[86:89], v[204:207], v[164:167], v[86:89]
	v_mfma_f32_16x16x32_bf16 v[30:33], v[208:211], v[164:167], v[30:33]
	v_mfma_f32_16x16x32_bf16 v[74:77], v[196:199], v[168:171], v[74:77]
	v_mfma_f32_16x16x32_bf16 v[90:93], v[200:203], v[168:171], v[90:93]
	v_mfma_f32_16x16x32_bf16 v[94:97], v[204:207], v[168:171], v[94:97]
	v_mfma_f32_16x16x32_bf16 v[34:37], v[208:211], v[168:171], v[34:37]
	v_mfma_f32_16x16x32_bf16 v[98:101], v[196:199], v[172:175], v[98:101]
	v_mfma_f32_16x16x32_bf16 v[102:105], v[200:203], v[172:175], v[102:105]
	v_mfma_f32_16x16x32_bf16 v[106:109], v[204:207], v[172:175], v[106:109]
	v_mfma_f32_16x16x32_bf16 v[38:41], v[208:211], v[172:175], v[38:41]
	v_mfma_f32_16x16x32_bf16 v[110:113], v[196:199], v[176:179], v[110:113]
	v_mfma_f32_16x16x32_bf16 v[114:117], v[200:203], v[176:179], v[114:117]
	v_mfma_f32_16x16x32_bf16 v[118:121], v[204:207], v[176:179], v[118:121]
	v_mfma_f32_16x16x32_bf16 v[42:45], v[208:211], v[176:179], v[42:45]
	v_mfma_f32_16x16x32_bf16 v[122:125], v[196:199], v[180:183], v[122:125]
	v_mfma_f32_16x16x32_bf16 v[126:129], v[200:203], v[180:183], v[126:129]
	v_mfma_f32_16x16x32_bf16 v[130:133], v[204:207], v[180:183], v[130:133]
	v_mfma_f32_16x16x32_bf16 v[46:49], v[208:211], v[180:183], v[46:49]
	v_mfma_f32_16x16x32_bf16 v[134:137], v[196:199], v[184:187], v[134:137]
	v_mfma_f32_16x16x32_bf16 v[138:141], v[200:203], v[184:187], v[138:141]
	v_mfma_f32_16x16x32_bf16 v[142:145], v[204:207], v[184:187], v[142:145]
	v_mfma_f32_16x16x32_bf16 v[50:53], v[208:211], v[184:187], v[50:53]
	v_mfma_f32_16x16x32_bf16 v[146:149], v[196:199], v[188:191], v[146:149]
	v_mfma_f32_16x16x32_bf16 v[54:57], v[208:211], v[188:191], v[54:57]
	v_mfma_f32_16x16x32_bf16 v[62:65], v[196:199], v[192:195], v[62:65]
	v_mfma_f32_16x16x32_bf16 v[66:69], v[200:203], v[192:195], v[66:69]
	v_mfma_f32_16x16x32_bf16 v[70:73], v[204:207], v[192:195], v[70:73]
; template <int MI, int NI>
; DI void gemm256(f32x4 (&acc)[MI][NI], const u16* __restrict__ A, int lda, const u16* __restrict__ Bt, int ldb, int K, int m0, int n0, char* smem) {
;     ...
;   for (int kt = 0; kt < nk; ++kt) {
;     if (kt + 1 < nk) asm volatile("s_waitcnt vmcnt(%0) lgkmcnt(0)" :: "n"(LPS) : "memory");
;     else asm volatile("s_waitcnt vmcnt(0) lgkmcnt(0)" ::: "memory");
;     __builtin_amdgcn_s_barrier();
;     __builtin_amdgcn_s_setprio(1);
;     const char* sb = smem + st * STAGE + foff;
;     bf16x8 af[MI], bfr[NI];
; #pragma unroll
;     for (int mi = 0; mi < MI; ++mi) af[mi] = *(const bf16x8*)(sb + (wr * MI + mi) * 1024);
; #pragma unroll
;     for (int ni = 0; ni < NI; ++ni) bfr[ni] = *(const bf16x8*)(sb + ABYTES + (wc * NI + ni) * 1024);
;     __builtin_amdgcn_sched_barrier(0x0);
;     if (kt + 2 < nk) { const int s2 = st >= 1 ? st - 1 : 2; G256_ISSUE(s2, (kt + 2) * 32); }
;     __builtin_amdgcn_s_setprio(0);
; #pragma unroll
;     for (int mi = 0; mi < MI; ++mi)
; #pragma unroll
;       for (int ni = 0; ni < NI; ++ni)
;         acc[mi][ni] = __builtin_amdgcn_mfma_f32_16x16x32_bf16(bfr[ni], af[mi], acc[mi][ni], 0, 0, 0);
;     st = st == 2 ? 0 : st + 1;
;   }
	v_mfma_f32_16x16x32_bf16 v[58:61], v[208:211], v[192:195], v[58:61]
	v_mfma_f32_16x16x32_bf16 v[150:153], v[200:203], v[188:191], v[150:153]
	v_mfma_f32_16x16x32_bf16 v[154:157], v[204:207], v[188:191], v[154:157]
	s_setprio 1
	ds_read_b128 v[164:167], v0 offset:24576
	ds_read_b128 v[168:171], v0 offset:25600
	ds_read_b128 v[172:175], v0 offset:26624
	ds_read_b128 v[176:179], v0 offset:27648
	ds_read_b128 v[180:183], v0 offset:28672
	ds_read_b128 v[184:187], v0 offset:29696
	ds_read_b128 v[188:191], v0 offset:30720
	ds_read_b128 v[192:195], v0 offset:31744
	ds_read_b128 v[196:199], v6 offset:40960
	ds_read_b128 v[200:203], v6 offset:41984
	ds_read_b128 v[204:207], v6 offset:43008
	ds_read_b128 v[208:211], v6 offset:44032
	s_mov_b64 s[6:7], 0x240
	v_readfirstlane_b32 s4, v24
	v_lshl_add_u64 v[212:213], v[2:3], 0, s[6:7]
	s_mov_b32 m0, s4
	s_mov_b64 s[4:5], 0x7640
	global_load_lds_dwordx4 v[212:213], off
	v_lshl_add_u64 v[212:213], v[2:3], 0, s[4:5]
	v_readfirstlane_b32 s4, v25
	s_mov_b32 m0, s4
	s_mov_b64 s[4:5], 0xea40
	v_lshl_add_u64 v[24:25], v[2:3], 0, s[4:5]
	v_readfirstlane_b32 s4, v26
	global_load_lds_dwordx4 v[212:213], off
	s_mov_b32 m0, s4
	s_mov_b64 s[4:5], 0x15e40
	global_load_lds_dwordx4 v[24:25], off
	v_lshl_add_u64 v[24:25], v[2:3], 0, s[4:5]
	v_readfirstlane_b32 s4, v27
	s_mov_b32 m0, s4
	v_readfirstlane_b32 s4, v23
	global_load_lds_dwordx4 v[24:25], off
	v_lshl_add_u64 v[24:25], v[4:5], 0, s[6:7]
	s_mov_b32 m0, s4
	s_mov_b64 s[4:5], 0x3240
	global_load_lds_dwordx4 v[24:25], off
	v_lshl_add_u64 v[24:25], v[4:5], 0, s[4:5]
	v_readfirstlane_b32 s4, v28
	s_mov_b32 m0, s4
	s_nop 0
	global_load_lds_dwordx4 v[24:25], off
	s_setprio 0
	s_waitcnt lgkmcnt(0)
	v_mfma_f32_16x16x32_bf16 v[24:27], v[196:199], v[164:167], v[78:81]
	s_waitcnt vmcnt(6) lgkmcnt(0)
	s_barrier
	v_mfma_f32_16x16x32_bf16 v[78:81], v[200:203], v[164:167], v[82:85]
	v_mfma_f32_16x16x32_bf16 v[82:85], v[204:207], v[164:167], v[86:89]
	v_mfma_f32_16x16x32_bf16 v[28:31], v[208:211], v[164:167], v[30:33]
	v_mfma_f32_16x16x32_bf16 v[74:77], v[196:199], v[168:171], v[74:77]
	v_mfma_f32_16x16x32_bf16 v[86:89], v[200:203], v[168:171], v[90:93]
	v_mfma_f32_16x16x32_bf16 v[90:93], v[204:207], v[168:171], v[94:97]
	v_mfma_f32_16x16x32_bf16 v[32:35], v[208:211], v[168:171], v[34:37]
	v_mfma_f32_16x16x32_bf16 v[94:97], v[196:199], v[172:175], v[98:101]
	v_mfma_f32_16x16x32_bf16 v[98:101], v[200:203], v[172:175], v[102:105]
	v_mfma_f32_16x16x32_bf16 v[102:105], v[204:207], v[172:175], v[106:109]
	v_mfma_f32_16x16x32_bf16 v[36:39], v[208:211], v[172:175], v[38:41]
	v_mfma_f32_16x16x32_bf16 v[106:109], v[196:199], v[176:179], v[110:113]
	v_mfma_f32_16x16x32_bf16 v[110:113], v[200:203], v[176:179], v[114:117]
	v_mfma_f32_16x16x32_bf16 v[114:117], v[204:207], v[176:179], v[118:121]
	v_mfma_f32_16x16x32_bf16 v[40:43], v[208:211], v[176:179], v[42:45]
	v_mfma_f32_16x16x32_bf16 v[118:121], v[196:199], v[180:183], v[122:125]
	v_mfma_f32_16x16x32_bf16 v[122:125], v[200:203], v[180:183], v[126:129]
	v_mfma_f32_16x16x32_bf16 v[126:129], v[204:207], v[180:183], v[130:133]
	v_mfma_f32_16x16x32_bf16 v[44:47], v[208:211], v[180:183], v[46:49]
	v_mfma_f32_16x16x32_bf16 v[130:133], v[196:199], v[184:187], v[134:137]
	v_mfma_f32_16x16x32_bf16 v[134:137], v[200:203], v[184:187], v[138:141]
	v_mfma_f32_16x16x32_bf16 v[138:141], v[204:207], v[184:187], v[142:145]
	v_mfma_f32_16x16x32_bf16 v[48:51], v[208:211], v[184:187], v[50:53]
	v_mfma_f32_16x16x32_bf16 v[142:145], v[196:199], v[188:191], v[146:149]
	v_mfma_f32_16x16x32_bf16 v[146:149], v[200:203], v[188:191], v[150:153]
	v_mfma_f32_16x16x32_bf16 v[52:55], v[208:211], v[188:191], v[54:57]
	v_mfma_f32_16x16x32_bf16 v[62:65], v[196:199], v[192:195], v[62:65]
	v_mfma_f32_16x16x32_bf16 v[66:69], v[200:203], v[192:195], v[66:69]
	v_mfma_f32_16x16x32_bf16 v[70:73], v[204:207], v[192:195], v[70:73]
	v_mfma_f32_16x16x32_bf16 v[56:59], v[208:211], v[192:195], v[58:61]
	v_mfma_f32_16x16x32_bf16 v[150:153], v[204:207], v[188:191], v[154:157]
	s_setprio 1
	s_nop 0
	ds_read_b128 v[154:157], v0 offset:49152
	ds_read_b128 v[164:167], v0 offset:50176
	ds_read_b128 v[168:171], v0 offset:51200
	ds_read_b128 v[172:175], v0 offset:52224
	ds_read_b128 v[176:179], v0 offset:53248
	ds_read_b128 v[180:183], v0 offset:54272
	ds_read_b128 v[184:187], v0 offset:55296
	ds_read_b128 v[188:191], v0 offset:56320
	ds_read_b128 v[192:195], v19
	ds_read_b128 v[196:199], v20
	ds_read_b128 v[200:203], v21
	ds_read_b128 v[204:207], v22
	s_mov_b64 s[6:7], 0x280
	v_readfirstlane_b32 s4, v13
	v_lshl_add_u64 v[60:61], v[2:3], 0, s[6:7]
	s_mov_b32 m0, s4
	s_mov_b64 s[4:5], 0x7680
	global_load_lds_dwordx4 v[60:61], off
	v_lshl_add_u64 v[60:61], v[2:3], 0, s[4:5]
	v_readfirstlane_b32 s4, v14
	s_mov_b32 m0, s4
	s_mov_b64 s[4:5], 0xea80
	global_load_lds_dwordx4 v[60:61], off
	v_lshl_add_u64 v[60:61], v[2:3], 0, s[4:5]
	v_readfirstlane_b32 s4, v15
	s_mov_b32 m0, s4
	s_mov_b64 s[4:5], 0x15e80
	v_lshl_add_u64 v[14:15], v[2:3], 0, s[4:5]
	v_readfirstlane_b32 s4, v17
	global_load_lds_dwordx4 v[60:61], off
	s_mov_b32 m0, s4
	v_readfirstlane_b32 s4, v16
	global_load_lds_dwordx4 v[14:15], off
	v_lshl_add_u64 v[14:15], v[4:5], 0, s[6:7]
	s_mov_b32 m0, s4
	s_mov_b64 s[4:5], 0x3280
	global_load_lds_dwordx4 v[14:15], off
	v_lshl_add_u64 v[14:15], v[4:5], 0, s[4:5]
	v_readfirstlane_b32 s4, v18
	s_mov_b32 m0, s4
	s_nop 0
	global_load_lds_dwordx4 v[14:15], off
	s_setprio 0
	s_waitcnt lgkmcnt(0)
	v_mfma_f32_16x16x32_bf16 v[14:17], v[192:195], v[154:157], v[24:27]
	s_waitcnt vmcnt(6) lgkmcnt(0)
	s_barrier
; template <int MI, int NI>
; DI void gemm256(f32x4 (&acc)[MI][NI], const u16* __restrict__ A, int lda, const u16* __restrict__ Bt, int ldb, int K, int m0, int n0, char* smem) {
;     ...
;   for (int kt = 0; kt < nk; ++kt) {
;     if (kt + 1 < nk) asm volatile("s_waitcnt vmcnt(%0) lgkmcnt(0)" :: "n"(LPS) : "memory");
;     else asm volatile("s_waitcnt vmcnt(0) lgkmcnt(0)" ::: "memory");
;     __builtin_amdgcn_s_barrier();
;     __builtin_amdgcn_s_setprio(1);
;     const char* sb = smem + st * STAGE + foff;
;     bf16x8 af[MI], bfr[NI];
; #pragma unroll
;     for (int mi = 0; mi < MI; ++mi) af[mi] = *(const bf16x8*)(sb + (wr * MI + mi) * 1024);
; #pragma unroll
;     for (int ni = 0; ni < NI; ++ni) bfr[ni] = *(const bf16x8*)(sb + ABYTES + (wc * NI + ni) * 1024);
;     __builtin_amdgcn_sched_barrier(0x0);
;     if (kt + 2 < nk) { const int s2 = st >= 1 ? st - 1 : 2; G256_ISSUE(s2, (kt + 2) * 32); }
;     __builtin_amdgcn_s_setprio(0);
; #pragma unroll
;     for (int mi = 0; mi < MI; ++mi)
; #pragma unroll
;       for (int ni = 0; ni < NI; ++ni)
;         acc[mi][ni] = __builtin_amdgcn_mfma_f32_16x16x32_bf16(bfr[ni], af[mi], acc[mi][ni], 0, 0, 0);
;     st = st == 2 ? 0 : st + 1;
;   }
	v_mfma_f32_16x16x32_bf16 v[24:27], v[196:199], v[154:157], v[78:81]
	v_mfma_f32_16x16x32_bf16 v[78:81], v[200:203], v[154:157], v[82:85]
	v_mfma_f32_16x16x32_bf16 v[28:31], v[204:207], v[154:157], v[28:31]
	v_mfma_f32_16x16x32_bf16 v[74:77], v[192:195], v[164:167], v[74:77]
	v_mfma_f32_16x16x32_bf16 v[82:85], v[196:199], v[164:167], v[86:89]
	v_mfma_f32_16x16x32_bf16 v[86:89], v[200:203], v[164:167], v[90:93]
	v_mfma_f32_16x16x32_bf16 v[32:35], v[204:207], v[164:167], v[32:35]
	v_mfma_f32_16x16x32_bf16 v[90:93], v[192:195], v[168:171], v[94:97]
	v_mfma_f32_16x16x32_bf16 v[94:97], v[196:199], v[168:171], v[98:101]
	v_mfma_f32_16x16x32_bf16 v[98:101], v[200:203], v[168:171], v[102:105]
	v_mfma_f32_16x16x32_bf16 v[36:39], v[204:207], v[168:171], v[36:39]
	v_mfma_f32_16x16x32_bf16 v[102:105], v[192:195], v[172:175], v[106:109]
	v_mfma_f32_16x16x32_bf16 v[106:109], v[196:199], v[172:175], v[110:113]
	v_mfma_f32_16x16x32_bf16 v[110:113], v[200:203], v[172:175], v[114:117]
	v_mfma_f32_16x16x32_bf16 v[40:43], v[204:207], v[172:175], v[40:43]
	v_mfma_f32_16x16x32_bf16 v[114:117], v[192:195], v[176:179], v[118:121]
	v_mfma_f32_16x16x32_bf16 v[118:121], v[196:199], v[176:179], v[122:125]
	v_mfma_f32_16x16x32_bf16 v[122:125], v[200:203], v[176:179], v[126:129]
	v_mfma_f32_16x16x32_bf16 v[44:47], v[204:207], v[176:179], v[44:47]
	v_mfma_f32_16x16x32_bf16 v[126:129], v[192:195], v[180:183], v[130:133]
	v_mfma_f32_16x16x32_bf16 v[130:133], v[196:199], v[180:183], v[134:137]
	v_mfma_f32_16x16x32_bf16 v[134:137], v[200:203], v[180:183], v[138:141]
	v_mfma_f32_16x16x32_bf16 v[48:51], v[204:207], v[180:183], v[48:51]
	v_mfma_f32_16x16x32_bf16 v[138:141], v[192:195], v[184:187], v[142:145]
	v_mfma_f32_16x16x32_bf16 v[142:145], v[196:199], v[184:187], v[146:149]
	v_mfma_f32_16x16x32_bf16 v[146:149], v[200:203], v[184:187], v[150:153]
	v_mfma_f32_16x16x32_bf16 v[52:55], v[204:207], v[184:187], v[52:55]
	v_mfma_f32_16x16x32_bf16 v[60:63], v[192:195], v[188:191], v[62:65]
	v_mfma_f32_16x16x32_bf16 v[64:67], v[196:199], v[188:191], v[66:69]
	v_mfma_f32_16x16x32_bf16 v[68:71], v[200:203], v[188:191], v[70:73]
	v_mfma_f32_16x16x32_bf16 v[56:59], v[204:207], v[188:191], v[56:59]
	s_setprio 1
	ds_read_b128 v[150:153], v0
	ds_read_b128 v[154:157], v0 offset:1024
	ds_read_b128 v[164:167], v0 offset:2048
	ds_read_b128 v[168:171], v0 offset:3072
	ds_read_b128 v[172:175], v0 offset:4096
	ds_read_b128 v[176:179], v0 offset:5120
	ds_read_b128 v[180:183], v0 offset:6144
	ds_read_b128 v[184:187], v0 offset:7168
	ds_read_b128 v[188:191], v6 offset:16384
	ds_read_b128 v[192:195], v6 offset:17408
	ds_read_b128 v[196:199], v6 offset:18432
	ds_read_b128 v[200:203], v6 offset:19456
	s_mov_b64 s[6:7], 0x2c0
	v_readfirstlane_b32 s4, v7
	v_lshl_add_u64 v[72:73], v[2:3], 0, s[6:7]
	s_mov_b32 m0, s4
	s_mov_b64 s[4:5], 0x76c0
	global_load_lds_dwordx4 v[72:73], off
	v_lshl_add_u64 v[72:73], v[2:3], 0, s[4:5]
	v_readfirstlane_b32 s4, v8
	s_mov_b32 m0, s4
	s_mov_b64 s[4:5], 0xeac0
	global_load_lds_dwordx4 v[72:73], off
	v_lshl_add_u64 v[72:73], v[2:3], 0, s[4:5]
	v_readfirstlane_b32 s4, v9
	s_mov_b32 m0, s4
	s_mov_b64 s[4:5], 0x15ec0
	v_lshl_add_u64 v[2:3], v[2:3], 0, s[4:5]
	v_readfirstlane_b32 s4, v10
	global_load_lds_dwordx4 v[72:73], off
	s_mov_b32 m0, s4
	v_readfirstlane_b32 s4, v11
	global_load_lds_dwordx4 v[2:3], off
	v_lshl_add_u64 v[2:3], v[4:5], 0, s[6:7]
	s_mov_b32 m0, s4
	s_mov_b64 s[4:5], 0x32c0
	global_load_lds_dwordx4 v[2:3], off
	v_lshl_add_u64 v[2:3], v[4:5], 0, s[4:5]
	v_readfirstlane_b32 s4, v12
	s_mov_b32 m0, s4
	s_nop 0
	global_load_lds_dwordx4 v[2:3], off
	s_setprio 0
	s_waitcnt lgkmcnt(0)
	v_mfma_f32_16x16x32_bf16 v[2:5], v[188:191], v[150:153], v[14:17]
	s_waitcnt vmcnt(6) lgkmcnt(0)
	s_barrier
	v_mfma_f32_16x16x32_bf16 v[8:11], v[192:195], v[150:153], v[24:27]
	v_mfma_f32_16x16x32_bf16 v[12:15], v[196:199], v[150:153], v[78:81]
	v_mfma_f32_16x16x32_bf16 v[24:27], v[200:203], v[150:153], v[28:31]
	v_mfma_f32_16x16x32_bf16 v[28:31], v[188:191], v[154:157], v[74:77]
	v_mfma_f32_16x16x32_bf16 v[72:75], v[192:195], v[154:157], v[82:85]
	v_mfma_f32_16x16x32_bf16 v[76:79], v[196:199], v[154:157], v[86:89]
	v_mfma_f32_16x16x32_bf16 v[32:35], v[200:203], v[154:157], v[32:35]
	v_mfma_f32_16x16x32_bf16 v[80:83], v[188:191], v[164:167], v[90:93]
	v_mfma_f32_16x16x32_bf16 v[84:87], v[192:195], v[164:167], v[94:97]
	v_mfma_f32_16x16x32_bf16 v[88:91], v[196:199], v[164:167], v[98:101]
	v_mfma_f32_16x16x32_bf16 v[36:39], v[200:203], v[164:167], v[36:39]
	v_mfma_f32_16x16x32_bf16 v[92:95], v[188:191], v[168:171], v[102:105]
	v_mfma_f32_16x16x32_bf16 v[96:99], v[192:195], v[168:171], v[106:109]
	v_mfma_f32_16x16x32_bf16 v[100:103], v[196:199], v[168:171], v[110:113]
	v_mfma_f32_16x16x32_bf16 v[40:43], v[200:203], v[168:171], v[40:43]
	v_mfma_f32_16x16x32_bf16 v[104:107], v[188:191], v[172:175], v[114:117]
	v_mfma_f32_16x16x32_bf16 v[108:111], v[192:195], v[172:175], v[118:121]
	v_mfma_f32_16x16x32_bf16 v[112:115], v[196:199], v[172:175], v[122:125]
	v_mfma_f32_16x16x32_bf16 v[44:47], v[200:203], v[172:175], v[44:47]
	v_mfma_f32_16x16x32_bf16 v[116:119], v[188:191], v[176:179], v[126:129]
	v_mfma_f32_16x16x32_bf16 v[120:123], v[192:195], v[176:179], v[130:133]
	v_mfma_f32_16x16x32_bf16 v[124:127], v[196:199], v[176:179], v[134:137]
	v_mfma_f32_16x16x32_bf16 v[48:51], v[200:203], v[176:179], v[48:51]
	v_mfma_f32_16x16x32_bf16 v[128:131], v[188:191], v[180:183], v[138:141]
	v_mfma_f32_16x16x32_bf16 v[132:135], v[192:195], v[180:183], v[142:145]
	v_mfma_f32_16x16x32_bf16 v[136:139], v[196:199], v[180:183], v[146:149]
	v_mfma_f32_16x16x32_bf16 v[52:55], v[200:203], v[180:183], v[52:55]
	v_mfma_f32_16x16x32_bf16 v[60:63], v[188:191], v[184:187], v[60:63]
	v_mfma_f32_16x16x32_bf16 v[64:67], v[192:195], v[184:187], v[64:67]
	v_mfma_f32_16x16x32_bf16 v[68:71], v[196:199], v[184:187], v[68:71]
	v_mfma_f32_16x16x32_bf16 v[56:59], v[200:203], v[184:187], v[56:59]
	s_setprio 1
	ds_read_b128 v[140:143], v0 offset:24576
	ds_read_b128 v[144:147], v0 offset:25600
	ds_read_b128 v[148:151], v0 offset:26624
	ds_read_b128 v[152:155], v0 offset:27648
	ds_read_b128 v[164:167], v0 offset:28672
	ds_read_b128 v[168:171], v0 offset:29696
	ds_read_b128 v[172:175], v0 offset:30720
	ds_read_b128 v[176:179], v0 offset:31744
	ds_read_b128 v[180:183], v6 offset:40960
	ds_read_b128 v[184:187], v6 offset:41984
	ds_read_b128 v[188:191], v6 offset:43008
	ds_read_b128 v[192:195], v6 offset:44032
	s_setprio 0
	s_waitcnt lgkmcnt(3)
	v_mfma_f32_16x16x32_bf16 v[2:5], v[180:183], v[140:143], v[2:5]
	s_waitcnt vmcnt(0) lgkmcnt(0)
	s_barrier
; template <int MI, int NI>
; DI void gemm256(f32x4 (&acc)[MI][NI], const u16* __restrict__ A, int lda, const u16* __restrict__ Bt, int ldb, int K, int m0, int n0, char* smem) {
;     ...
;   for (int kt = 0; kt < nk; ++kt) {
;     if (kt + 1 < nk) asm volatile("s_waitcnt vmcnt(%0) lgkmcnt(0)" :: "n"(LPS) : "memory");
;     else asm volatile("s_waitcnt vmcnt(0) lgkmcnt(0)" ::: "memory");
;     __builtin_amdgcn_s_barrier();
;     __builtin_amdgcn_s_setprio(1);
;     const char* sb = smem + st * STAGE + foff;
;     bf16x8 af[MI], bfr[NI];
; #pragma unroll
;     for (int mi = 0; mi < MI; ++mi) af[mi] = *(const bf16x8*)(sb + (wr * MI + mi) * 1024);
; #pragma unroll
;     for (int ni = 0; ni < NI; ++ni) bfr[ni] = *(const bf16x8*)(sb + ABYTES + (wc * NI + ni) * 1024);
;     __builtin_amdgcn_sched_barrier(0x0);
;     if (kt + 2 < nk) { const int s2 = st >= 1 ? st - 1 : 2; G256_ISSUE(s2, (kt + 2) * 32); }
;     __builtin_amdgcn_s_setprio(0);
; #pragma unroll
;     for (int mi = 0; mi < MI; ++mi)
; #pragma unroll
;       for (int ni = 0; ni < NI; ++ni)
;         acc[mi][ni] = __builtin_amdgcn_mfma_f32_16x16x32_bf16(bfr[ni], af[mi], acc[mi][ni], 0, 0, 0);
;     st = st == 2 ? 0 : st + 1;
;   }
;   asm volatile("s_waitcnt lgkmcnt(0)" ::: "memory");
;   __builtin_amdgcn_s_barrier();
	s_waitcnt lgkmcnt(2)
	v_mfma_f32_16x16x32_bf16 v[6:9], v[184:187], v[140:143], v[8:11]
	s_waitcnt lgkmcnt(1)
	v_mfma_f32_16x16x32_bf16 v[10:13], v[188:191], v[140:143], v[12:15]
	s_waitcnt lgkmcnt(0)
	v_mfma_f32_16x16x32_bf16 v[14:17], v[192:195], v[140:143], v[24:27]
	v_mfma_f32_16x16x32_bf16 v[24:27], v[180:183], v[144:147], v[28:31]
	v_mfma_f32_16x16x32_bf16 v[28:31], v[184:187], v[144:147], v[72:75]
	v_mfma_f32_16x16x32_bf16 v[72:75], v[188:191], v[144:147], v[76:79]
	v_mfma_f32_16x16x32_bf16 v[32:35], v[192:195], v[144:147], v[32:35]
	v_mfma_f32_16x16x32_bf16 v[76:79], v[180:183], v[148:151], v[80:83]
	v_mfma_f32_16x16x32_bf16 v[80:83], v[184:187], v[148:151], v[84:87]
	v_mfma_f32_16x16x32_bf16 v[84:87], v[188:191], v[148:151], v[88:91]
	v_mfma_f32_16x16x32_bf16 v[36:39], v[192:195], v[148:151], v[36:39]
	v_mfma_f32_16x16x32_bf16 v[140:143], v[180:183], v[152:155], v[92:95]
	v_mfma_f32_16x16x32_bf16 v[144:147], v[184:187], v[152:155], v[96:99]
	v_mfma_f32_16x16x32_bf16 v[148:151], v[188:191], v[152:155], v[100:103]
	v_mfma_f32_16x16x32_bf16 v[40:43], v[192:195], v[152:155], v[40:43]
	v_mfma_f32_16x16x32_bf16 v[152:155], v[180:183], v[164:167], v[104:107]
	v_mfma_f32_16x16x32_bf16 v[196:199], v[184:187], v[164:167], v[108:111]
	v_mfma_f32_16x16x32_bf16 v[200:203], v[188:191], v[164:167], v[112:115]
	v_mfma_f32_16x16x32_bf16 v[44:47], v[192:195], v[164:167], v[44:47]
	v_mfma_f32_16x16x32_bf16 v[164:167], v[180:183], v[168:171], v[116:119]
	v_mfma_f32_16x16x32_bf16 v[212:215], v[180:183], v[172:175], v[128:131]
	v_mfma_f32_16x16x32_bf16 v[130:133], v[184:187], v[172:175], v[132:135]
	v_mfma_f32_16x16x32_bf16 v[134:137], v[188:191], v[172:175], v[136:139]
	v_mfma_f32_16x16x32_bf16 v[204:207], v[184:187], v[168:171], v[120:123]
	v_mfma_f32_16x16x32_bf16 v[208:211], v[188:191], v[168:171], v[124:127]
	v_mfma_f32_16x16x32_bf16 v[168:171], v[192:195], v[168:171], v[48:51]
	v_mfma_f32_16x16x32_bf16 v[172:175], v[192:195], v[172:175], v[52:55]
	v_mfma_f32_16x16x32_bf16 v[180:183], v[180:183], v[176:179], v[60:63]
	v_mfma_f32_16x16x32_bf16 v[184:187], v[184:187], v[176:179], v[64:67]
	v_mfma_f32_16x16x32_bf16 v[188:191], v[188:191], v[176:179], v[68:71]
	v_mfma_f32_16x16x32_bf16 v[176:179], v[192:195], v[176:179], v[56:59]
	s_setprio 1
	ds_read_b128 v[48:51], v0 offset:49152
	ds_read_b128 v[52:55], v0 offset:50176
	ds_read_b128 v[56:59], v0 offset:51200
	ds_read_b128 v[60:63], v0 offset:52224
	ds_read_b128 v[192:195], v0 offset:53248
	ds_read_b128 v[216:219], v0 offset:54272
	ds_read_b128 v[220:223], v0 offset:55296
	ds_read_b128 v[224:227], v0 offset:56320
	ds_read_b128 v[228:231], v19
	ds_read_b128 v[244:247], v20
	ds_read_b128 v[248:251], v21
	ds_read_b128 v[238:241], v22
	s_setprio 0
	v_readlane_b32 s4, v254, 25
	v_readlane_b32 s5, v254, 26
	s_waitcnt lgkmcnt(3)
	v_mfma_f32_16x16x32_bf16 v[126:129], v[228:231], v[48:51], v[2:5]
	s_waitcnt lgkmcnt(0)
	s_barrier
; template <int MI, int NI>
; DI void gemm256(f32x4 (&acc)[MI][NI], const u16* __restrict__ A, int lda, const u16* __restrict__ Bt, int ldb, int K, int m0, int n0, char* smem) {
;     ...
; #pragma unroll
;     for (int mi = 0; mi < MI; ++mi)
; #pragma unroll
;       for (int ni = 0; ni < NI; ++ni)
;         acc[mi][ni] = __builtin_amdgcn_mfma_f32_16x16x32_bf16(bfr[ni], af[mi], acc[mi][ni], 0, 0, 0);
; DI void phase_qkv(const Params& p, int l, char* smem) {
;     ...
;       const float* gq = gq0; const float* rt = rt0; const float* rsq = rsq0;
;       asm volatile("" : "+v"(gq), "+v"(rt), "+v"(rsq));
;       const int nw = n0 + wc * 64;
; #pragma unroll
;       for (int mi = 0; mi < 8; ++mi) {
;         __builtin_amdgcn_sched_barrier(0);
;         const int m = m0 + wr * 128 + mi * 16 + lr;
;         const float rs = rsq[m];
;         if (nw < 512) {
;           const int h = nw >> 6;
;           float ss = 0.f;
; #pragma unroll
;           for (int ni = 0; ni < 4; ++ni)
; #pragma unroll
;             for (int j = 0; j < 4; ++j) { const float v = acc[mi][ni][j] * rs; ss += v * v; }
;           ss += __shfl_xor(ss, 16, 64); ss += __shfl_xor(ss, 32, 64);
;           const float f = rs * rsqrtf(ss * (1.f / 64.f) + 1e-6f) * QS;
;           u16* dst = Qb + qk_index(m, h);
; #pragma unroll
;           for (int ni = 0; ni < 4; ++ni) {
;             const int d = ni * 16 + lq * 4;
;             const float4 g = *(const float4*)(gq + d);
;             *(uint2*)(dst + d) = make_uint2(pack2(acc[mi][ni][0] * f * g.x, acc[mi][ni][1] * f * g.y), pack2(acc[mi][ni][2] * f * g.z, acc[mi][ni][3] * f * g.w));
;           }
;         } else {
;           const bool lat = m < NTL;
;           const int tt = m & 4095;
; #pragma unroll
;           for (int hh = 0; hh < 2; ++hh) {
;             __builtin_amdgcn_sched_barrier(0);
;             const int h = ((nw - 512) >> 5) + hh;
;             float ss = 0.f;
; #pragma unroll
;             for (int ni = 0; ni < 2; ++ni)
; #pragma unroll
;               for (int j = 0; j < 4; ++j) { const float v = acc[mi][hh * 2 + ni][j] * rs; ss += v * v; }
;             ss += __shfl_xor(ss, 16, 64); ss += __shfl_xor(ss, 32, 64);
;             const float f = rs * rsqrtf(ss * (1.f / 32.f) + 1e-6f) * QS;
;             const int i0 = lq * 4;
;             const float4 g1 = *(const float4*)(gq + 64 + i0), g2 = *(const float4*)(gq + 80 + i0);
	v_mov_b32_e32 v0, v158
	v_mfma_f32_16x16x32_bf16 v[94:97], v[228:231], v[56:59], v[76:79]
	v_mov_b64_e32 v[2:3], s[4:5]
	v_readlane_b32 s4, v254, 23
	v_readlane_b32 s5, v254, 24
	s_waitcnt lgkmcnt(2)
	v_mfma_f32_16x16x32_bf16 v[90:93], v[244:247], v[56:59], v[80:83]
	v_mov_b32_e32 v4, v159
	v_mfma_f32_16x16x32_bf16 v[78:81], v[228:231], v[60:63], v[140:143]
	s_nop 2
	v_mov_b64_e32 v[142:143], s[4:5]
	v_readlane_b32 s4, v254, 21
	v_mfma_f32_16x16x32_bf16 v[122:125], v[244:247], v[48:51], v[6:9]
	v_readlane_b32 s5, v254, 22
	s_waitcnt lgkmcnt(1)
	v_mfma_f32_16x16x32_bf16 v[118:121], v[248:251], v[48:51], v[10:13]
	s_waitcnt lgkmcnt(0)
	v_mfma_f32_16x16x32_bf16 v[114:117], v[238:241], v[48:51], v[14:17]
	v_mfma_f32_16x16x32_bf16 v[110:113], v[228:231], v[52:55], v[24:27]
	v_mfma_f32_16x16x32_bf16 v[106:109], v[244:247], v[52:55], v[28:31]
	v_mfma_f32_16x16x32_bf16 v[102:105], v[248:251], v[52:55], v[72:75]
	v_mfma_f32_16x16x32_bf16 v[98:101], v[238:241], v[52:55], v[32:35]
	v_mfma_f32_16x16x32_bf16 v[50:53], v[238:241], v[192:195], v[44:47]
	v_mfma_f32_16x16x32_bf16 v[46:49], v[228:231], v[216:219], v[164:167]
	s_nop 2
	v_mov_b32_e32 v166, v160
	v_mov_b32_e32 v164, v161
	v_mfma_f32_16x16x32_bf16 v[26:29], v[244:247], v[220:223], v[130:133]
	v_mfma_f32_16x16x32_bf16 v[86:89], v[248:251], v[56:59], v[84:87]
	v_lshlrev_b32_e32 v138, 2, v164
	s_nop 0
	v_mov_b64_e32 v[130:131], s[4:5]
	v_ashrrev_i32_e32 v139, 31, v138
	v_mfma_f32_16x16x32_bf16 v[82:85], v[238:241], v[56:59], v[36:39]
	v_lshl_add_u32 v167, v4, 6, s1
	v_lshl_add_u64 v[140:141], v[138:139], 2, v[2:3]
	v_lshlrev_b32_e32 v0, 7, v0
	v_mfma_f32_16x16x32_bf16 v[74:77], v[244:247], v[60:63], v[144:147]
	v_mfma_f32_16x16x32_bf16 v[70:73], v[248:251], v[60:63], v[148:151]
	s_nop 1
	v_add3_u32 v144, v166, s0, v0
	s_movk_i32 s0, 0x1ff
	v_add_u32_e32 v0, 0xfffffe00, v167
	v_mfma_f32_16x16x32_bf16 v[66:69], v[238:241], v[60:63], v[40:43]
	v_cmp_lt_i32_e32 vcc, s0, v167
	v_lshrrev_b32_e32 v165, 5, v0
	v_mfma_f32_16x16x32_bf16 v[62:65], v[228:231], v[192:195], v[152:155]
	v_mfma_f32_16x16x32_bf16 v[58:61], v[244:247], v[192:195], v[196:199]
	v_mfma_f32_16x16x32_bf16 v[54:57], v[248:251], v[192:195], v[200:203]
	v_mfma_f32_16x16x32_bf16 v[42:45], v[244:247], v[216:219], v[204:207]
	v_mfma_f32_16x16x32_bf16 v[38:41], v[248:251], v[216:219], v[208:211]
	v_mfma_f32_16x16x32_bf16 v[34:37], v[238:241], v[216:219], v[168:171]
	v_mfma_f32_16x16x32_bf16 v[30:33], v[228:231], v[220:223], v[212:215]
	v_mfma_f32_16x16x32_bf16 v[22:25], v[248:251], v[220:223], v[134:137]
	v_mfma_f32_16x16x32_bf16 v[18:21], v[238:241], v[220:223], v[172:175]
	v_mfma_f32_16x16x32_bf16 v[14:17], v[228:231], v[224:227], v[180:183]
	v_mfma_f32_16x16x32_bf16 v[10:13], v[244:247], v[224:227], v[184:187]
	v_mfma_f32_16x16x32_bf16 v[6:9], v[248:251], v[224:227], v[188:191]
	v_mfma_f32_16x16x32_bf16 v[2:5], v[238:241], v[224:227], v[176:179]
	v_ashrrev_i32_e32 v145, 31, v144
	v_lshl_add_u64 v[146:147], v[144:145], 2, v[130:131]
	flat_load_dword v148, v[146:147]
	s_and_saveexec_b64 s[0:1], vcc
	s_xor_b64 s[6:7], exec, s[0:1]
	s_cbranch_execz .LBB0_570
	v_and_b32_e32 v130, 64, v237
	v_xor_b32_e32 v0, 16, v237
	v_add_u32_e32 v130, 64, v130
	v_cmp_lt_i32_e64 s[4:5], v0, v130
	v_cmp_gt_i32_e64 s[0:1], s58, v144
	v_lshrrev_b32_e32 v145, 6, v144
	v_cndmask_b32_e64 v0, v237, v0, s[4:5]
	v_lshlrev_b32_e32 v168, 2, v0
	v_xor_b32_e32 v0, 32, v237
	v_cmp_lt_i32_e64 s[4:5], v0, v130
	s_nop 1
	v_cndmask_b32_e64 v0, v237, v0, s[4:5]
	v_lshlrev_b32_e32 v169, 2, v0
	s_waitcnt vmcnt(0) lgkmcnt(0)
	v_pk_mul_f32 v[130:131], v[126:127], v[148:149] op_sel_hi:[1,0]
	v_pk_mul_f32 v[132:133], v[128:129], v[148:149] op_sel_hi:[1,0]
	v_pk_mul_f32 v[130:131], v[130:131], v[130:131]
	v_pk_mul_f32 v[132:133], v[132:133], v[132:133]
	v_add_f32_e32 v0, v130, v131
	v_pk_mul_f32 v[134:135], v[122:123], v[148:149] op_sel_hi:[1,0]
	v_add_f32_e32 v0, v132, v0
	v_pk_mul_f32 v[134:135], v[134:135], v[134:135]
	v_add_f32_e32 v0, v133, v0
	v_pk_mul_f32 v[136:137], v[124:125], v[148:149] op_sel_hi:[1,0]
	v_add_f32_e32 v0, v134, v0
	v_pk_mul_f32 v[136:137], v[136:137], v[136:137]
	v_add_f32_e32 v0, v135, v0
	v_add_f32_e32 v0, v136, v0
	v_add_f32_e32 v0, v137, v0
	ds_bpermute_b32 v130, v168, v0
	v_mov_b32_e32 v153, 0
	v_mov_b32_e32 v152, 1.0
	v_mov_b32_e32 v150, 1.0
	v_mov_b32_e32 v151, 0
	s_waitcnt lgkmcnt(0)
	v_add_f32_e32 v149, v0, v130
	flat_load_dwordx4 v[134:137], v[140:141] offset:256
	flat_load_dwordx4 v[130:133], v[140:141] offset:320
	ds_bpermute_b32 v170, v169, v149
	s_and_saveexec_b64 s[8:9], s[0:1]
	s_cbranch_execz .LBB0_555
	v_cmp_gt_i32_e64 s[4:5], 2, v164
	v_and_b32_e32 v150, 4, v138
	s_nop 0
	v_cndmask_b32_e64 v0, v166, v145, s[4:5]
	v_lshlrev_b32_e32 v0, 3, v0
	s_movk_i32 s4, 0x1f8
	v_and_or_b32 v0, v0, s4, v150
	v_lshlrev_b32_e32 v0, 3, v0
	v_lshl_add_u64 v[150:151], v[142:143], 0, v[0:1]
	flat_load_dwordx2 v[150:151], v[150:151]

; template <int MI, int NI>
; DI void gemm256(f32x4 (&acc)[MI][NI], const u16* __restrict__ A, int lda, const u16* __restrict__ Bt, int ldb, int K, int m0, int n0, char* smem) {
;     ...
;   const int srow = lane >> 2, scol = ((lane & 3) ^ ((lane >> 5) << 1)) * 8;
;   const u16* Ag = A + (size_t)(m0 + wave * NAW * 16 + srow) * lda + scol;
;   const u16* Bg = Bt + (size_t)(n0 + wave * NBW * 16 + srow) * ldb + scol;
;   char* la = smem + (wave * NAW) * 1024 + lane * 16;
;   char* lb = smem + ABYTES + (wave * NBW) * 1024 + lane * 16;
;     ...
;   const int nk = K >> 5;
;   G256_ISSUE(0, 0);
;   if (nk > 1) G256_ISSUE(1, 32);
;   const int foff = lr * 64 + ((lq ^ ((lr >> 3) << 1)) * 16);
;   int st = 0;
;   for (int kt = 0; kt < nk; ++kt) {
;     if (kt + 1 < nk) asm volatile("s_waitcnt vmcnt(%0) lgkmcnt(0)" :: "n"(LPS) : "memory");
;     else asm volatile("s_waitcnt vmcnt(0) lgkmcnt(0)" ::: "memory");
;     __builtin_amdgcn_s_barrier();
;     __builtin_amdgcn_s_setprio(1);
;     const char* sb = smem + st * STAGE + foff;
;     bf16x8 af[MI], bfr[NI];
; #pragma unroll
;     for (int mi = 0; mi < MI; ++mi) af[mi] = *(const bf16x8*)(sb + (wr * MI + mi) * 1024);
; #pragma unroll
;     for (int ni = 0; ni < NI; ++ni) bfr[ni] = *(const bf16x8*)(sb + ABYTES + (wc * NI + ni) * 1024);
;     __builtin_amdgcn_sched_barrier(0x0);
;     if (kt + 2 < nk) { const int s2 = st >= 1 ? st - 1 : 2; G256_ISSUE(s2, (kt + 2) * 32); }
;     __builtin_amdgcn_s_setprio(0);
; #pragma unroll
;     for (int mi = 0; mi < MI; ++mi)
; #pragma unroll
;       for (int ni = 0; ni < NI; ++ni)
;         acc[mi][ni] = __builtin_amdgcn_mfma_f32_16x16x32_bf16(bfr[ni], af[mi], acc[mi][ni], 0, 0, 0);
;     st = st == 2 ? 0 : st + 1;
;   }
; DI void phase_qkv(const Params& p, int l, char* smem) {
;     ...
;       const int h = tn, m0 = tm * 256, n0 = h * 128;
;       gemm256<8, 4>(acc, za + 640, ZA, (const u16*)(wl + WO_UKV), 256, 256, m0, n0, smem);
.LBB0_721:
	s_waitcnt vmcnt(0)
	v_mov_b32_e32 v7, v163
	s_mov_b32 s0, s2
	v_lshlrev_b32_e32 v6, 8, v145
	v_and_b32_e32 v0, 3, v7
	v_lshrrev_b32_e32 v2, 4, v7
	v_bitop3_b32 v0, v2, v0, 2 bitop3:0x6c
	v_and_b32_e32 v2, 0xffffffc0, v7
	v_readlane_b32 s0, v254, 35
	s_waitcnt lgkmcnt(0)
	v_lshlrev_b32_e32 v4, 7, v148
	v_ashrrev_i32_e32 v9, 6, v7
	v_bfe_u32 v5, v7, 2, 4
	v_add_u32_e32 v2, v2, v6
	v_readlane_b32 s1, v254, 36
	v_and_b32_e32 v8, 63, v7
	v_or_b32_e32 v10, v2, v5
	v_mov_b64_e32 v[2:3], s[0:1]
	s_movk_i32 s0, 0x740
	v_lshl_add_u32 v4, v9, 5, v4
	v_mad_i64_i32 v[2:3], s[0:1], v10, s0, v[2:3]
	v_or_b32_e32 v4, v4, v5
	v_lshlrev_b32_e32 v40, 12, v9
	v_lshlrev_b32_e32 v8, 4, v8
	v_ashrrev_i32_e32 v5, 31, v4
	v_readlane_b32 s0, v254, 37
	v_or_b32_e32 v58, v40, v8
	v_lshlrev_b32_e32 v0, 4, v0
	v_lshlrev_b64 v[4:5], 9, v[4:5]
	v_readlane_b32 s1, v254, 38
	v_readfirstlane_b32 s9, v58
	v_or_b32_e32 v11, 0x400, v58
	v_lshl_add_u64 v[2:3], v[2:3], 0, v[0:1]
	v_lshl_add_u64 v[4:5], s[0:1], 0, v[4:5]
	s_mov_b32 m0, s9
	s_mov_b64 s[0:1], 0x7400
	v_readfirstlane_b32 s8, v11
	v_or_b32_e32 v11, 0x800, v58
	v_lshl_or_b32 v59, v9, 11, v8
	global_load_lds_dwordx4 v[2:3], off
	v_lshl_add_u64 v[8:9], v[2:3], 0, s[0:1]
	s_mov_b32 m0, s8
	s_mov_b64 s[0:1], 0xe800
	v_readfirstlane_b32 s12, v11
	v_or_b32_e32 v11, 0xc00, v58
	v_add_u32_e32 v10, 0x4000, v59
	global_load_lds_dwordx4 v[8:9], off
	v_lshl_add_u64 v[8:9], v[2:3], 0, s[0:1]
	s_mov_b32 m0, s12
	s_mov_b64 s[0:1], 0x15c00
	v_readfirstlane_b32 s13, v11
	global_load_lds_dwordx4 v[8:9], off
	v_lshl_add_u64 v[8:9], v[2:3], 0, s[0:1]
	s_mov_b32 m0, s13
	v_lshl_add_u64 v[4:5], v[4:5], 0, v[0:1]
	v_readfirstlane_b32 s14, v10
	v_add_u32_e32 v0, 0x4400, v59
	global_load_lds_dwordx4 v[8:9], off
	s_mov_b32 m0, s14
	s_mov_b64 s[0:1], 0x2000
	v_readfirstlane_b32 s15, v0
	v_add_u32_e32 v0, 0x6000, v58
	global_load_lds_dwordx4 v[4:5], off
	v_lshl_add_u64 v[8:9], v[4:5], 0, s[0:1]
	s_mov_b32 m0, s15
	v_readfirstlane_b32 s1, v0
	v_add_u32_e32 v0, 0x6400, v58
	global_load_lds_dwordx4 v[8:9], off
	v_lshl_add_u64 v[8:9], v[2:3], 0, 64
	s_mov_b32 m0, s1
	s_mov_b64 s[4:5], 0x7440
	v_readfirstlane_b32 s0, v0
	global_load_lds_dwordx4 v[8:9], off
	v_lshl_add_u64 v[8:9], v[2:3], 0, s[4:5]
	s_mov_b32 m0, s0
	s_mov_b64 s[4:5], 0xe840
	v_add_u32_e32 v0, 0x6800, v58
	global_load_lds_dwordx4 v[8:9], off
	v_lshl_add_u64 v[8:9], v[2:3], 0, s[4:5]
	v_readfirstlane_b32 s4, v0
	v_add_u32_e32 v0, 0x6c00, v58
	s_mov_b32 m0, s4
	s_mov_b64 s[6:7], 0x15c40
	v_readfirstlane_b32 s5, v0
	v_add_u32_e32 v0, 0xa000, v59
	global_load_lds_dwordx4 v[8:9], off
	v_lshl_add_u64 v[8:9], v[2:3], 0, s[6:7]
	s_mov_b32 m0, s5
	v_readfirstlane_b32 s6, v0
	v_add_u32_e32 v0, 0xa400, v59
	global_load_lds_dwordx4 v[8:9], off
	v_lshl_add_u64 v[8:9], v[4:5], 0, 64
	s_mov_b32 m0, s6
	s_mov_b64 s[16:17], 0x2040
	v_readfirstlane_b32 s7, v0
	global_load_lds_dwordx4 v[8:9], off
	v_lshl_add_u64 v[8:9], v[4:5], 0, s[16:17]
	s_mov_b32 m0, s7
	v_lshlrev_b32_e32 v0, 6, v7
	global_load_lds_dwordx4 v[8:9], off
	v_lshlrev_b32_e32 v8, 2, v7
	v_and_b32_e32 v7, 48, v7
	s_waitcnt vmcnt(6) lgkmcnt(0)
	v_bitop3_b32 v7, v8, v7, 32 bitop3:0x6c
	v_and_or_b32 v7, v0, s59, v7
	s_barrier
	s_setprio 1
	v_and_or_b32 v0, v0, s46, v7
	ds_read_b128 v[8:11], v0
	ds_read_b128 v[12:15], v0 offset:1024
	ds_read_b128 v[16:19], v0 offset:2048
	ds_read_b128 v[20:23], v0 offset:3072
	ds_read_b128 v[24:27], v0 offset:4096
	ds_read_b128 v[28:31], v0 offset:5120
	ds_read_b128 v[32:35], v0 offset:6144
	ds_read_b128 v[36:39], v0 offset:7168
	v_and_or_b32 v7, v40, s97, v7
	ds_read_b128 v[40:43], v7 offset:16384
	ds_read_b128 v[44:47], v7 offset:17408
	ds_read_b128 v[48:51], v7 offset:18432
	ds_read_b128 v[52:55], v7 offset:19456
	v_add_u32_e32 v60, 0xc000, v58
	s_mov_b64 s[20:21], 0x80
	v_readfirstlane_b32 s17, v60
	v_add_u32_e32 v60, 0xc400, v58
	v_lshl_add_u64 v[56:57], v[2:3], 0, s[20:21]
	s_mov_b32 m0, s17
	s_mov_b64 s[18:19], 0x7480
	v_readfirstlane_b32 s16, v60
	global_load_lds_dwordx4 v[56:57], off
	v_lshl_add_u64 v[56:57], v[2:3], 0, s[18:19]
	s_mov_b32 m0, s16
	s_mov_b64 s[18:19], 0xe880
	v_add_u32_e32 v60, 0xc800, v58
	global_load_lds_dwordx4 v[56:57], off
	v_lshl_add_u64 v[56:57], v[2:3], 0, s[18:19]
	v_readfirstlane_b32 s18, v60
	v_add_u32_e32 v58, 0xcc00, v58
	s_mov_b32 m0, s18
	s_mov_b64 s[22:23], 0x15c80
	v_readfirstlane_b32 s19, v58
	global_load_lds_dwordx4 v[56:57], off
	v_lshl_add_u64 v[56:57], v[2:3], 0, s[22:23]
	s_mov_b32 m0, s19
	v_add_u32_e32 v58, 0x10000, v59
	global_load_lds_dwordx4 v[56:57], off
	v_lshl_add_u64 v[56:57], v[4:5], 0, s[20:21]
	v_readfirstlane_b32 s20, v58
	v_add_u32_e32 v58, 0x10400, v59
	s_mov_b32 m0, s20
	s_mov_b64 s[22:23], 0x2080
	v_readfirstlane_b32 s21, v58
	global_load_lds_dwordx4 v[56:57], off
	v_lshl_add_u64 v[56:57], v[4:5], 0, s[22:23]
	s_mov_b32 m0, s21
	s_nop 0
	global_load_lds_dwordx4 v[56:57], off
	s_setprio 0
	s_waitcnt lgkmcnt(0)
	v_mfma_f32_16x16x32_bf16 v[56:59], v[40:43], v[8:11], 0
	s_waitcnt vmcnt(6) lgkmcnt(0)
	s_barrier
; template <int MI, int NI>
; DI void gemm256(f32x4 (&acc)[MI][NI], const u16* __restrict__ A, int lda, const u16* __restrict__ Bt, int ldb, int K, int m0, int n0, char* smem) {
;     ...
;   for (int kt = 0; kt < nk; ++kt) {
;     if (kt + 1 < nk) asm volatile("s_waitcnt vmcnt(%0) lgkmcnt(0)" :: "n"(LPS) : "memory");
;     else asm volatile("s_waitcnt vmcnt(0) lgkmcnt(0)" ::: "memory");
;     __builtin_amdgcn_s_barrier();
;     __builtin_amdgcn_s_setprio(1);
;     const char* sb = smem + st * STAGE + foff;
;     bf16x8 af[MI], bfr[NI];
; #pragma unroll
;     for (int mi = 0; mi < MI; ++mi) af[mi] = *(const bf16x8*)(sb + (wr * MI + mi) * 1024);
; #pragma unroll
;     for (int ni = 0; ni < NI; ++ni) bfr[ni] = *(const bf16x8*)(sb + ABYTES + (wc * NI + ni) * 1024);
;     __builtin_amdgcn_sched_barrier(0x0);
;     if (kt + 2 < nk) { const int s2 = st >= 1 ? st - 1 : 2; G256_ISSUE(s2, (kt + 2) * 32); }
;     __builtin_amdgcn_s_setprio(0);
; #pragma unroll
;     for (int mi = 0; mi < MI; ++mi)
; #pragma unroll
;       for (int ni = 0; ni < NI; ++ni)
;         acc[mi][ni] = __builtin_amdgcn_mfma_f32_16x16x32_bf16(bfr[ni], af[mi], acc[mi][ni], 0, 0, 0);
;     st = st == 2 ? 0 : st + 1;
;   }
	v_mfma_f32_16x16x32_bf16 v[60:63], v[44:47], v[8:11], 0
	v_mfma_f32_16x16x32_bf16 v[64:67], v[48:51], v[8:11], 0
	v_mfma_f32_16x16x32_bf16 v[8:11], v[52:55], v[8:11], 0
	v_mfma_f32_16x16x32_bf16 v[68:71], v[40:43], v[12:15], 0
	v_mfma_f32_16x16x32_bf16 v[72:75], v[44:47], v[12:15], 0
	v_mfma_f32_16x16x32_bf16 v[76:79], v[48:51], v[12:15], 0
	v_mfma_f32_16x16x32_bf16 v[12:15], v[52:55], v[12:15], 0
	v_mfma_f32_16x16x32_bf16 v[80:83], v[40:43], v[16:19], 0
	v_mfma_f32_16x16x32_bf16 v[84:87], v[44:47], v[16:19], 0
	v_mfma_f32_16x16x32_bf16 v[88:91], v[48:51], v[16:19], 0
	v_mfma_f32_16x16x32_bf16 v[16:19], v[52:55], v[16:19], 0
	v_mfma_f32_16x16x32_bf16 v[92:95], v[40:43], v[20:23], 0
	v_mfma_f32_16x16x32_bf16 v[96:99], v[44:47], v[20:23], 0
	v_mfma_f32_16x16x32_bf16 v[100:103], v[48:51], v[20:23], 0
	v_mfma_f32_16x16x32_bf16 v[20:23], v[52:55], v[20:23], 0
	v_mfma_f32_16x16x32_bf16 v[104:107], v[40:43], v[24:27], 0
	v_mfma_f32_16x16x32_bf16 v[108:111], v[44:47], v[24:27], 0
	v_mfma_f32_16x16x32_bf16 v[112:115], v[48:51], v[24:27], 0
	v_mfma_f32_16x16x32_bf16 v[24:27], v[52:55], v[24:27], 0
	v_mfma_f32_16x16x32_bf16 v[116:119], v[40:43], v[28:31], 0
	v_mfma_f32_16x16x32_bf16 v[120:123], v[44:47], v[28:31], 0
	v_mfma_f32_16x16x32_bf16 v[124:127], v[48:51], v[28:31], 0
	v_mfma_f32_16x16x32_bf16 v[28:31], v[52:55], v[28:31], 0
	v_mfma_f32_16x16x32_bf16 v[128:131], v[40:43], v[32:35], 0
	v_mfma_f32_16x16x32_bf16 v[132:135], v[44:47], v[32:35], 0
	v_mfma_f32_16x16x32_bf16 v[136:139], v[48:51], v[32:35], 0
	v_mfma_f32_16x16x32_bf16 v[32:35], v[52:55], v[32:35], 0
	v_mfma_f32_16x16x32_bf16 v[40:43], v[40:43], v[36:39], 0
	v_mfma_f32_16x16x32_bf16 v[44:47], v[44:47], v[36:39], 0
	v_mfma_f32_16x16x32_bf16 v[48:51], v[48:51], v[36:39], 0
	v_mfma_f32_16x16x32_bf16 v[36:39], v[52:55], v[36:39], 0
	s_setprio 1
	ds_read_b128 v[52:55], v0 offset:24576
	ds_read_b128 v[140:143], v0 offset:25600
	ds_read_b128 v[150:153], v0 offset:26624
	ds_read_b128 v[154:157], v0 offset:27648
	ds_read_b128 v[164:167], v0 offset:28672
	ds_read_b128 v[168:171], v0 offset:29696
	ds_read_b128 v[172:175], v0 offset:30720
	ds_read_b128 v[176:179], v0 offset:31744
	ds_read_b128 v[180:183], v7 offset:40960
	ds_read_b128 v[184:187], v7 offset:41984
	ds_read_b128 v[188:191], v7 offset:43008
	ds_read_b128 v[192:195], v7 offset:44032
	s_mov_b64 s[22:23], 0xc0
	s_mov_b32 m0, s9
	v_lshl_add_u64 v[146:147], v[2:3], 0, s[22:23]
	s_mov_b64 s[24:25], 0x74c0
	global_load_lds_dwordx4 v[146:147], off
	v_lshl_add_u64 v[146:147], v[2:3], 0, s[24:25]
	s_mov_b32 m0, s8
	s_mov_b64 s[24:25], 0xe8c0
	global_load_lds_dwordx4 v[146:147], off
	v_lshl_add_u64 v[146:147], v[2:3], 0, s[24:25]
	s_mov_b32 m0, s12
	s_mov_b64 s[24:25], 0x15cc0
	global_load_lds_dwordx4 v[146:147], off
	v_lshl_add_u64 v[146:147], v[2:3], 0, s[24:25]
	s_mov_b32 m0, s13
	s_nop 0
	global_load_lds_dwordx4 v[146:147], off
	v_lshl_add_u64 v[146:147], v[4:5], 0, s[22:23]
	s_mov_b32 m0, s14
	s_mov_b64 s[22:23], 0x20c0
	global_load_lds_dwordx4 v[146:147], off
	v_lshl_add_u64 v[146:147], v[4:5], 0, s[22:23]
	s_mov_b32 m0, s15
	s_nop 0
	global_load_lds_dwordx4 v[146:147], off
	s_setprio 0
	s_waitcnt lgkmcnt(0)
	v_mfma_f32_16x16x32_bf16 v[56:59], v[180:183], v[52:55], v[56:59]
	s_waitcnt vmcnt(6) lgkmcnt(0)
	s_barrier
	v_mfma_f32_16x16x32_bf16 v[60:63], v[184:187], v[52:55], v[60:63]
	v_mfma_f32_16x16x32_bf16 v[64:67], v[188:191], v[52:55], v[64:67]
	v_mfma_f32_16x16x32_bf16 v[8:11], v[192:195], v[52:55], v[8:11]
	v_mfma_f32_16x16x32_bf16 v[52:55], v[180:183], v[140:143], v[68:71]
	v_mfma_f32_16x16x32_bf16 v[68:71], v[184:187], v[140:143], v[72:75]
	v_mfma_f32_16x16x32_bf16 v[72:75], v[188:191], v[140:143], v[76:79]
	v_mfma_f32_16x16x32_bf16 v[12:15], v[192:195], v[140:143], v[12:15]
	v_mfma_f32_16x16x32_bf16 v[76:79], v[180:183], v[150:153], v[80:83]
	v_mfma_f32_16x16x32_bf16 v[80:83], v[184:187], v[150:153], v[84:87]
	v_mfma_f32_16x16x32_bf16 v[84:87], v[188:191], v[150:153], v[88:91]
	v_mfma_f32_16x16x32_bf16 v[16:19], v[192:195], v[150:153], v[16:19]
	v_mfma_f32_16x16x32_bf16 v[88:91], v[180:183], v[154:157], v[92:95]
	v_mfma_f32_16x16x32_bf16 v[92:95], v[184:187], v[154:157], v[96:99]
	v_mfma_f32_16x16x32_bf16 v[96:99], v[188:191], v[154:157], v[100:103]
	v_mfma_f32_16x16x32_bf16 v[20:23], v[192:195], v[154:157], v[20:23]
	v_mfma_f32_16x16x32_bf16 v[100:103], v[180:183], v[164:167], v[104:107]
	v_mfma_f32_16x16x32_bf16 v[104:107], v[184:187], v[164:167], v[108:111]
	v_mfma_f32_16x16x32_bf16 v[108:111], v[188:191], v[164:167], v[112:115]
	v_mfma_f32_16x16x32_bf16 v[24:27], v[192:195], v[164:167], v[24:27]
	v_mfma_f32_16x16x32_bf16 v[112:115], v[180:183], v[168:171], v[116:119]
	v_mfma_f32_16x16x32_bf16 v[116:119], v[184:187], v[168:171], v[120:123]
	v_mfma_f32_16x16x32_bf16 v[120:123], v[188:191], v[168:171], v[124:127]
	v_mfma_f32_16x16x32_bf16 v[28:31], v[192:195], v[168:171], v[28:31]
	v_mfma_f32_16x16x32_bf16 v[124:127], v[180:183], v[172:175], v[128:131]
	v_mfma_f32_16x16x32_bf16 v[128:131], v[184:187], v[172:175], v[132:135]
	v_mfma_f32_16x16x32_bf16 v[132:135], v[188:191], v[172:175], v[136:139]
	v_mfma_f32_16x16x32_bf16 v[32:35], v[192:195], v[172:175], v[32:35]
	v_mfma_f32_16x16x32_bf16 v[40:43], v[180:183], v[176:179], v[40:43]
	v_mfma_f32_16x16x32_bf16 v[44:47], v[184:187], v[176:179], v[44:47]
	v_mfma_f32_16x16x32_bf16 v[48:51], v[188:191], v[176:179], v[48:51]
	v_mfma_f32_16x16x32_bf16 v[36:39], v[192:195], v[176:179], v[36:39]
	s_setprio 1
	ds_read_b128 v[136:139], v0 offset:49152
	ds_read_b128 v[140:143], v0 offset:50176
	ds_read_b128 v[150:153], v0 offset:51200
	ds_read_b128 v[154:157], v0 offset:52224
	ds_read_b128 v[164:167], v0 offset:53248
	ds_read_b128 v[168:171], v0 offset:54272
	ds_read_b128 v[172:175], v0 offset:55296
	ds_read_b128 v[176:179], v0 offset:56320
	v_or_b32_e32 v144, 0x10000, v7
	v_or_b32_e32 v196, 0x10800, v7
	v_or_b32_e32 v149, 0x10400, v7
	ds_read_b128 v[180:183], v144
	ds_read_b128 v[184:187], v149
	v_or_b32_e32 v197, 0x10c00, v7
	ds_read_b128 v[188:191], v196
	ds_read_b128 v[192:195], v197
	s_mov_b64 s[22:23], 0x100
	s_mov_b32 m0, s1
	v_lshl_add_u64 v[146:147], v[2:3], 0, s[22:23]
	s_mov_b64 s[24:25], 0x7500
	global_load_lds_dwordx4 v[146:147], off
	v_lshl_add_u64 v[146:147], v[2:3], 0, s[24:25]
	s_mov_b32 m0, s0
	s_mov_b64 s[24:25], 0xe900
	global_load_lds_dwordx4 v[146:147], off
	v_lshl_add_u64 v[146:147], v[2:3], 0, s[24:25]
	s_mov_b32 m0, s4
	s_mov_b64 s[24:25], 0x15d00
	global_load_lds_dwordx4 v[146:147], off
	v_lshl_add_u64 v[146:147], v[2:3], 0, s[24:25]
	s_mov_b32 m0, s5
	s_mov_b64 s[50:51], 0x100
	global_load_lds_dwordx4 v[146:147], off
	v_lshl_add_u64 v[146:147], v[4:5], 0, s[22:23]
	s_mov_b32 m0, s6
	s_mov_b64 s[22:23], 0x2100
	global_load_lds_dwordx4 v[146:147], off
	v_lshl_add_u64 v[146:147], v[4:5], 0, s[22:23]
	s_mov_b32 m0, s7
	s_nop 0
	global_load_lds_dwordx4 v[146:147], off
	s_setprio 0
	s_waitcnt lgkmcnt(0)
	v_mfma_f32_16x16x32_bf16 v[56:59], v[180:183], v[136:139], v[56:59]
	s_waitcnt vmcnt(6) lgkmcnt(0)
	s_barrier
; template <int MI, int NI>
; DI void gemm256(f32x4 (&acc)[MI][NI], const u16* __restrict__ A, int lda, const u16* __restrict__ Bt, int ldb, int K, int m0, int n0, char* smem) {
;     ...
;   for (int kt = 0; kt < nk; ++kt) {
;     if (kt + 1 < nk) asm volatile("s_waitcnt vmcnt(%0) lgkmcnt(0)" :: "n"(LPS) : "memory");
;     else asm volatile("s_waitcnt vmcnt(0) lgkmcnt(0)" ::: "memory");
;     __builtin_amdgcn_s_barrier();
;     __builtin_amdgcn_s_setprio(1);
;     const char* sb = smem + st * STAGE + foff;
;     bf16x8 af[MI], bfr[NI];
; #pragma unroll
;     for (int mi = 0; mi < MI; ++mi) af[mi] = *(const bf16x8*)(sb + (wr * MI + mi) * 1024);
; #pragma unroll
;     for (int ni = 0; ni < NI; ++ni) bfr[ni] = *(const bf16x8*)(sb + ABYTES + (wc * NI + ni) * 1024);
;     __builtin_amdgcn_sched_barrier(0x0);
;     if (kt + 2 < nk) { const int s2 = st >= 1 ? st - 1 : 2; G256_ISSUE(s2, (kt + 2) * 32); }
;     __builtin_amdgcn_s_setprio(0);
; #pragma unroll
;     for (int mi = 0; mi < MI; ++mi)
; #pragma unroll
;       for (int ni = 0; ni < NI; ++ni)
;         acc[mi][ni] = __builtin_amdgcn_mfma_f32_16x16x32_bf16(bfr[ni], af[mi], acc[mi][ni], 0, 0, 0);
;     st = st == 2 ? 0 : st + 1;
;   }
	v_mfma_f32_16x16x32_bf16 v[60:63], v[184:187], v[136:139], v[60:63]
	v_mfma_f32_16x16x32_bf16 v[64:67], v[188:191], v[136:139], v[64:67]
	v_mfma_f32_16x16x32_bf16 v[8:11], v[192:195], v[136:139], v[8:11]
	v_mfma_f32_16x16x32_bf16 v[52:55], v[180:183], v[140:143], v[52:55]
	v_mfma_f32_16x16x32_bf16 v[68:71], v[184:187], v[140:143], v[68:71]
	v_mfma_f32_16x16x32_bf16 v[72:75], v[188:191], v[140:143], v[72:75]
	v_mfma_f32_16x16x32_bf16 v[12:15], v[192:195], v[140:143], v[12:15]
	v_mfma_f32_16x16x32_bf16 v[76:79], v[180:183], v[150:153], v[76:79]
	v_mfma_f32_16x16x32_bf16 v[80:83], v[184:187], v[150:153], v[80:83]
	v_mfma_f32_16x16x32_bf16 v[84:87], v[188:191], v[150:153], v[84:87]
	v_mfma_f32_16x16x32_bf16 v[16:19], v[192:195], v[150:153], v[16:19]
	v_mfma_f32_16x16x32_bf16 v[88:91], v[180:183], v[154:157], v[88:91]
	v_mfma_f32_16x16x32_bf16 v[92:95], v[184:187], v[154:157], v[92:95]
	v_mfma_f32_16x16x32_bf16 v[96:99], v[188:191], v[154:157], v[96:99]
	v_mfma_f32_16x16x32_bf16 v[20:23], v[192:195], v[154:157], v[20:23]
	v_mfma_f32_16x16x32_bf16 v[100:103], v[180:183], v[164:167], v[100:103]
	v_mfma_f32_16x16x32_bf16 v[104:107], v[184:187], v[164:167], v[104:107]
	v_mfma_f32_16x16x32_bf16 v[108:111], v[188:191], v[164:167], v[108:111]
	v_mfma_f32_16x16x32_bf16 v[24:27], v[192:195], v[164:167], v[24:27]
	v_mfma_f32_16x16x32_bf16 v[112:115], v[180:183], v[168:171], v[112:115]
	v_mfma_f32_16x16x32_bf16 v[116:119], v[184:187], v[168:171], v[116:119]
	v_mfma_f32_16x16x32_bf16 v[120:123], v[188:191], v[168:171], v[120:123]
	v_mfma_f32_16x16x32_bf16 v[28:31], v[192:195], v[168:171], v[28:31]
	v_mfma_f32_16x16x32_bf16 v[124:127], v[180:183], v[172:175], v[124:127]
	v_mfma_f32_16x16x32_bf16 v[128:131], v[184:187], v[172:175], v[128:131]
	v_mfma_f32_16x16x32_bf16 v[132:135], v[188:191], v[172:175], v[132:135]
	v_mfma_f32_16x16x32_bf16 v[32:35], v[192:195], v[172:175], v[32:35]
	v_mfma_f32_16x16x32_bf16 v[40:43], v[180:183], v[176:179], v[40:43]
	v_mfma_f32_16x16x32_bf16 v[44:47], v[184:187], v[176:179], v[44:47]
	v_mfma_f32_16x16x32_bf16 v[48:51], v[188:191], v[176:179], v[48:51]
	v_mfma_f32_16x16x32_bf16 v[36:39], v[192:195], v[176:179], v[36:39]
	s_setprio 1
	ds_read_b128 v[136:139], v0
	ds_read_b128 v[140:143], v0 offset:1024
	ds_read_b128 v[150:153], v0 offset:2048
	ds_read_b128 v[154:157], v0 offset:3072
	ds_read_b128 v[164:167], v0 offset:4096
	ds_read_b128 v[168:171], v0 offset:5120
	ds_read_b128 v[172:175], v0 offset:6144
	ds_read_b128 v[176:179], v0 offset:7168
	ds_read_b128 v[180:183], v7 offset:16384
	ds_read_b128 v[184:187], v7 offset:17408
	ds_read_b128 v[188:191], v7 offset:18432
	ds_read_b128 v[192:195], v7 offset:19456
	s_mov_b64 s[22:23], 0x140
	s_mov_b32 m0, s17
	v_lshl_add_u64 v[146:147], v[2:3], 0, s[22:23]
	s_mov_b64 s[24:25], 0x7540
	global_load_lds_dwordx4 v[146:147], off
	v_lshl_add_u64 v[146:147], v[2:3], 0, s[24:25]
	s_mov_b32 m0, s16
	s_mov_b64 s[16:17], 0xe940
	global_load_lds_dwordx4 v[146:147], off
	v_lshl_add_u64 v[146:147], v[2:3], 0, s[16:17]
	s_mov_b32 m0, s18
	s_mov_b64 s[16:17], 0x15d40
	global_load_lds_dwordx4 v[146:147], off
	v_lshl_add_u64 v[146:147], v[2:3], 0, s[16:17]
	s_mov_b32 m0, s19
	s_mov_b64 s[16:17], 0x2140
	global_load_lds_dwordx4 v[146:147], off
	v_lshl_add_u64 v[146:147], v[4:5], 0, s[22:23]
	s_mov_b32 m0, s20
	s_nop 0
	global_load_lds_dwordx4 v[146:147], off
	v_lshl_add_u64 v[146:147], v[4:5], 0, s[16:17]
	s_mov_b32 m0, s21
	s_nop 0
	global_load_lds_dwordx4 v[146:147], off
	s_setprio 0
	s_waitcnt lgkmcnt(0)
	v_mfma_f32_16x16x32_bf16 v[56:59], v[180:183], v[136:139], v[56:59]
	s_waitcnt vmcnt(6) lgkmcnt(0)
	s_barrier
	v_mfma_f32_16x16x32_bf16 v[60:63], v[184:187], v[136:139], v[60:63]
	v_mfma_f32_16x16x32_bf16 v[64:67], v[188:191], v[136:139], v[64:67]
	v_mfma_f32_16x16x32_bf16 v[8:11], v[192:195], v[136:139], v[8:11]
	v_mfma_f32_16x16x32_bf16 v[52:55], v[180:183], v[140:143], v[52:55]
	v_mfma_f32_16x16x32_bf16 v[68:71], v[184:187], v[140:143], v[68:71]
	v_mfma_f32_16x16x32_bf16 v[72:75], v[188:191], v[140:143], v[72:75]
	v_mfma_f32_16x16x32_bf16 v[12:15], v[192:195], v[140:143], v[12:15]
	v_mfma_f32_16x16x32_bf16 v[76:79], v[180:183], v[150:153], v[76:79]
	v_mfma_f32_16x16x32_bf16 v[80:83], v[184:187], v[150:153], v[80:83]
	v_mfma_f32_16x16x32_bf16 v[84:87], v[188:191], v[150:153], v[84:87]
	v_mfma_f32_16x16x32_bf16 v[16:19], v[192:195], v[150:153], v[16:19]
	v_mfma_f32_16x16x32_bf16 v[88:91], v[180:183], v[154:157], v[88:91]
	v_mfma_f32_16x16x32_bf16 v[92:95], v[184:187], v[154:157], v[92:95]
	v_mfma_f32_16x16x32_bf16 v[96:99], v[188:191], v[154:157], v[96:99]
	v_mfma_f32_16x16x32_bf16 v[20:23], v[192:195], v[154:157], v[20:23]
	v_mfma_f32_16x16x32_bf16 v[100:103], v[180:183], v[164:167], v[100:103]
	v_mfma_f32_16x16x32_bf16 v[104:107], v[184:187], v[164:167], v[104:107]
	v_mfma_f32_16x16x32_bf16 v[108:111], v[188:191], v[164:167], v[108:111]
	v_mfma_f32_16x16x32_bf16 v[24:27], v[192:195], v[164:167], v[24:27]
	v_mfma_f32_16x16x32_bf16 v[112:115], v[180:183], v[168:171], v[112:115]
	v_mfma_f32_16x16x32_bf16 v[116:119], v[184:187], v[168:171], v[116:119]
	v_mfma_f32_16x16x32_bf16 v[120:123], v[188:191], v[168:171], v[120:123]
	v_mfma_f32_16x16x32_bf16 v[28:31], v[192:195], v[168:171], v[28:31]
	v_mfma_f32_16x16x32_bf16 v[124:127], v[180:183], v[172:175], v[124:127]
	v_mfma_f32_16x16x32_bf16 v[128:131], v[184:187], v[172:175], v[128:131]
	v_mfma_f32_16x16x32_bf16 v[132:135], v[188:191], v[172:175], v[132:135]
	v_mfma_f32_16x16x32_bf16 v[32:35], v[192:195], v[172:175], v[32:35]
	v_mfma_f32_16x16x32_bf16 v[40:43], v[180:183], v[176:179], v[40:43]
	v_mfma_f32_16x16x32_bf16 v[44:47], v[184:187], v[176:179], v[44:47]
; template <int MI, int NI>
; DI void gemm256(f32x4 (&acc)[MI][NI], const u16* __restrict__ A, int lda, const u16* __restrict__ Bt, int ldb, int K, int m0, int n0, char* smem) {
;     ...
;   for (int kt = 0; kt < nk; ++kt) {
;     if (kt + 1 < nk) asm volatile("s_waitcnt vmcnt(%0) lgkmcnt(0)" :: "n"(LPS) : "memory");
;     else asm volatile("s_waitcnt vmcnt(0) lgkmcnt(0)" ::: "memory");
;     __builtin_amdgcn_s_barrier();
;     __builtin_amdgcn_s_setprio(1);
;     const char* sb = smem + st * STAGE + foff;
;     bf16x8 af[MI], bfr[NI];
; #pragma unroll
;     for (int mi = 0; mi < MI; ++mi) af[mi] = *(const bf16x8*)(sb + (wr * MI + mi) * 1024);
; #pragma unroll
;     for (int ni = 0; ni < NI; ++ni) bfr[ni] = *(const bf16x8*)(sb + ABYTES + (wc * NI + ni) * 1024);
;     __builtin_amdgcn_sched_barrier(0x0);
;     if (kt + 2 < nk) { const int s2 = st >= 1 ? st - 1 : 2; G256_ISSUE(s2, (kt + 2) * 32); }
;     __builtin_amdgcn_s_setprio(0);
; #pragma unroll
;     for (int mi = 0; mi < MI; ++mi)
; #pragma unroll
;       for (int ni = 0; ni < NI; ++ni)
;         acc[mi][ni] = __builtin_amdgcn_mfma_f32_16x16x32_bf16(bfr[ni], af[mi], acc[mi][ni], 0, 0, 0);
;     st = st == 2 ? 0 : st + 1;
;   }
	v_mfma_f32_16x16x32_bf16 v[48:51], v[188:191], v[176:179], v[48:51]
	v_mfma_f32_16x16x32_bf16 v[36:39], v[192:195], v[176:179], v[36:39]
	s_setprio 1
	ds_read_b128 v[136:139], v0 offset:24576
	ds_read_b128 v[140:143], v0 offset:25600
	ds_read_b128 v[150:153], v0 offset:26624
	ds_read_b128 v[154:157], v0 offset:27648
	ds_read_b128 v[164:167], v0 offset:28672
	ds_read_b128 v[168:171], v0 offset:29696
	ds_read_b128 v[172:175], v0 offset:30720
	ds_read_b128 v[176:179], v0 offset:31744
	ds_read_b128 v[180:183], v7 offset:40960
	ds_read_b128 v[184:187], v7 offset:41984
	ds_read_b128 v[188:191], v7 offset:43008
	ds_read_b128 v[192:195], v7 offset:44032
	s_mov_b64 s[16:17], 0x180
	s_mov_b32 m0, s9
	v_lshl_add_u64 v[146:147], v[2:3], 0, s[16:17]
	s_mov_b64 s[18:19], 0x7580
	global_load_lds_dwordx4 v[146:147], off
	v_lshl_add_u64 v[146:147], v[2:3], 0, s[18:19]
	s_mov_b32 m0, s8
	s_mov_b64 s[8:9], 0xe980
	global_load_lds_dwordx4 v[146:147], off
	v_lshl_add_u64 v[146:147], v[2:3], 0, s[8:9]
	s_mov_b32 m0, s12
	s_mov_b64 s[8:9], 0x15d80
	global_load_lds_dwordx4 v[146:147], off
	v_lshl_add_u64 v[146:147], v[2:3], 0, s[8:9]
	s_mov_b32 m0, s13
	s_mov_b64 s[8:9], 0x2180
	global_load_lds_dwordx4 v[146:147], off
	v_lshl_add_u64 v[146:147], v[4:5], 0, s[16:17]
	s_mov_b32 m0, s14
	s_nop 0
	global_load_lds_dwordx4 v[146:147], off
	v_lshl_add_u64 v[146:147], v[4:5], 0, s[8:9]
	s_mov_b32 m0, s15
	s_nop 0
	global_load_lds_dwordx4 v[146:147], off
	s_setprio 0
	s_waitcnt lgkmcnt(0)
	v_mfma_f32_16x16x32_bf16 v[56:59], v[180:183], v[136:139], v[56:59]
	s_waitcnt vmcnt(6) lgkmcnt(0)
	s_barrier
	v_mfma_f32_16x16x32_bf16 v[60:63], v[184:187], v[136:139], v[60:63]
	v_mfma_f32_16x16x32_bf16 v[64:67], v[188:191], v[136:139], v[64:67]
	v_mfma_f32_16x16x32_bf16 v[8:11], v[192:195], v[136:139], v[8:11]
	v_mfma_f32_16x16x32_bf16 v[52:55], v[180:183], v[140:143], v[52:55]
	v_mfma_f32_16x16x32_bf16 v[68:71], v[184:187], v[140:143], v[68:71]
	v_mfma_f32_16x16x32_bf16 v[72:75], v[188:191], v[140:143], v[72:75]
	v_mfma_f32_16x16x32_bf16 v[12:15], v[192:195], v[140:143], v[12:15]
	v_mfma_f32_16x16x32_bf16 v[76:79], v[180:183], v[150:153], v[76:79]
	v_mfma_f32_16x16x32_bf16 v[80:83], v[184:187], v[150:153], v[80:83]
	v_mfma_f32_16x16x32_bf16 v[84:87], v[188:191], v[150:153], v[84:87]
	v_mfma_f32_16x16x32_bf16 v[16:19], v[192:195], v[150:153], v[16:19]
	v_mfma_f32_16x16x32_bf16 v[88:91], v[180:183], v[154:157], v[88:91]
	v_mfma_f32_16x16x32_bf16 v[92:95], v[184:187], v[154:157], v[92:95]
	v_mfma_f32_16x16x32_bf16 v[96:99], v[188:191], v[154:157], v[96:99]
	v_mfma_f32_16x16x32_bf16 v[20:23], v[192:195], v[154:157], v[20:23]
	v_mfma_f32_16x16x32_bf16 v[100:103], v[180:183], v[164:167], v[100:103]
	v_mfma_f32_16x16x32_bf16 v[104:107], v[184:187], v[164:167], v[104:107]
	v_mfma_f32_16x16x32_bf16 v[108:111], v[188:191], v[164:167], v[108:111]
	v_mfma_f32_16x16x32_bf16 v[24:27], v[192:195], v[164:167], v[24:27]
	v_mfma_f32_16x16x32_bf16 v[112:115], v[180:183], v[168:171], v[112:115]
	v_mfma_f32_16x16x32_bf16 v[116:119], v[184:187], v[168:171], v[116:119]
	v_mfma_f32_16x16x32_bf16 v[120:123], v[188:191], v[168:171], v[120:123]
	v_mfma_f32_16x16x32_bf16 v[28:31], v[192:195], v[168:171], v[28:31]
	v_mfma_f32_16x16x32_bf16 v[124:127], v[180:183], v[172:175], v[124:127]
	v_mfma_f32_16x16x32_bf16 v[128:131], v[184:187], v[172:175], v[128:131]
	v_mfma_f32_16x16x32_bf16 v[132:135], v[188:191], v[172:175], v[132:135]
	v_mfma_f32_16x16x32_bf16 v[32:35], v[192:195], v[172:175], v[32:35]
	v_mfma_f32_16x16x32_bf16 v[40:43], v[180:183], v[176:179], v[40:43]
	v_mfma_f32_16x16x32_bf16 v[44:47], v[184:187], v[176:179], v[44:47]
	v_mfma_f32_16x16x32_bf16 v[48:51], v[188:191], v[176:179], v[48:51]
	v_mfma_f32_16x16x32_bf16 v[36:39], v[192:195], v[176:179], v[36:39]
	s_setprio 1
	ds_read_b128 v[136:139], v0 offset:49152
	ds_read_b128 v[140:143], v0 offset:50176
	ds_read_b128 v[150:153], v0 offset:51200
	ds_read_b128 v[154:157], v0 offset:52224
	ds_read_b128 v[164:167], v0 offset:53248
	ds_read_b128 v[168:171], v0 offset:54272
	ds_read_b128 v[172:175], v0 offset:55296
	ds_read_b128 v[176:179], v0 offset:56320
	ds_read_b128 v[180:183], v144
	ds_read_b128 v[184:187], v149
	ds_read_b128 v[188:191], v196
	ds_read_b128 v[192:195], v197
	s_mov_b64 s[8:9], 0x1c0
	s_mov_b32 m0, s1
	v_lshl_add_u64 v[146:147], v[2:3], 0, s[8:9]
	s_mov_b64 s[12:13], 0x75c0
	global_load_lds_dwordx4 v[146:147], off
	v_lshl_add_u64 v[146:147], v[2:3], 0, s[12:13]
	s_mov_b32 m0, s0
	s_mov_b64 s[0:1], 0xe9c0
	global_load_lds_dwordx4 v[146:147], off
	v_lshl_add_u64 v[146:147], v[2:3], 0, s[0:1]
	s_mov_b32 m0, s4
	s_mov_b64 s[0:1], 0x15dc0
	global_load_lds_dwordx4 v[146:147], off
	v_lshl_add_u64 v[2:3], v[2:3], 0, s[0:1]
	s_mov_b32 m0, s5
	s_mov_b64 s[0:1], 0x21c0
	global_load_lds_dwordx4 v[2:3], off
	v_lshl_add_u64 v[2:3], v[4:5], 0, s[8:9]
	s_mov_b32 m0, s6
	s_nop 0
	global_load_lds_dwordx4 v[2:3], off
	v_lshl_add_u64 v[2:3], v[4:5], 0, s[0:1]
	s_mov_b32 m0, s7
	s_nop 0
	global_load_lds_dwordx4 v[2:3], off
	s_setprio 0
	s_waitcnt lgkmcnt(0)
	v_mfma_f32_16x16x32_bf16 v[2:5], v[180:183], v[136:139], v[56:59]
	s_waitcnt vmcnt(6) lgkmcnt(0)
	s_barrier
; template <int MI, int NI>
; DI void gemm256(f32x4 (&acc)[MI][NI], const u16* __restrict__ A, int lda, const u16* __restrict__ Bt, int ldb, int K, int m0, int n0, char* smem) {
;     ...
;   for (int kt = 0; kt < nk; ++kt) {
;     if (kt + 1 < nk) asm volatile("s_waitcnt vmcnt(%0) lgkmcnt(0)" :: "n"(LPS) : "memory");
;     else asm volatile("s_waitcnt vmcnt(0) lgkmcnt(0)" ::: "memory");
;     __builtin_amdgcn_s_barrier();
;     __builtin_amdgcn_s_setprio(1);
;     const char* sb = smem + st * STAGE + foff;
;     bf16x8 af[MI], bfr[NI];
; #pragma unroll
;     for (int mi = 0; mi < MI; ++mi) af[mi] = *(const bf16x8*)(sb + (wr * MI + mi) * 1024);
; #pragma unroll
;     for (int ni = 0; ni < NI; ++ni) bfr[ni] = *(const bf16x8*)(sb + ABYTES + (wc * NI + ni) * 1024);
;     __builtin_amdgcn_sched_barrier(0x0);
;     if (kt + 2 < nk) { const int s2 = st >= 1 ? st - 1 : 2; G256_ISSUE(s2, (kt + 2) * 32); }
;     __builtin_amdgcn_s_setprio(0);
; #pragma unroll
;     for (int mi = 0; mi < MI; ++mi)
; #pragma unroll
;       for (int ni = 0; ni < NI; ++ni)
;         acc[mi][ni] = __builtin_amdgcn_mfma_f32_16x16x32_bf16(bfr[ni], af[mi], acc[mi][ni], 0, 0, 0);
;     st = st == 2 ? 0 : st + 1;
;   }
;   asm volatile("s_waitcnt lgkmcnt(0)" ::: "memory");
;   __builtin_amdgcn_s_barrier();
	v_mfma_f32_16x16x32_bf16 v[56:59], v[184:187], v[136:139], v[60:63]
	v_mfma_f32_16x16x32_bf16 v[60:63], v[188:191], v[136:139], v[64:67]
	v_mfma_f32_16x16x32_bf16 v[8:11], v[192:195], v[136:139], v[8:11]
	v_mfma_f32_16x16x32_bf16 v[52:55], v[180:183], v[140:143], v[52:55]
	v_mfma_f32_16x16x32_bf16 v[64:67], v[184:187], v[140:143], v[68:71]
	v_mfma_f32_16x16x32_bf16 v[68:71], v[188:191], v[140:143], v[72:75]
	v_mfma_f32_16x16x32_bf16 v[12:15], v[192:195], v[140:143], v[12:15]
	v_mfma_f32_16x16x32_bf16 v[72:75], v[180:183], v[150:153], v[76:79]
	v_mfma_f32_16x16x32_bf16 v[76:79], v[184:187], v[150:153], v[80:83]
	v_mfma_f32_16x16x32_bf16 v[80:83], v[188:191], v[150:153], v[84:87]
	v_mfma_f32_16x16x32_bf16 v[16:19], v[192:195], v[150:153], v[16:19]
	v_mfma_f32_16x16x32_bf16 v[84:87], v[180:183], v[154:157], v[88:91]
	v_mfma_f32_16x16x32_bf16 v[88:91], v[184:187], v[154:157], v[92:95]
	v_mfma_f32_16x16x32_bf16 v[92:95], v[188:191], v[154:157], v[96:99]
	v_mfma_f32_16x16x32_bf16 v[20:23], v[192:195], v[154:157], v[20:23]
	v_mfma_f32_16x16x32_bf16 v[96:99], v[180:183], v[164:167], v[100:103]
	v_mfma_f32_16x16x32_bf16 v[100:103], v[184:187], v[164:167], v[104:107]
	v_mfma_f32_16x16x32_bf16 v[104:107], v[188:191], v[164:167], v[108:111]
	v_mfma_f32_16x16x32_bf16 v[24:27], v[192:195], v[164:167], v[24:27]
	v_mfma_f32_16x16x32_bf16 v[108:111], v[180:183], v[168:171], v[112:115]
	v_mfma_f32_16x16x32_bf16 v[112:115], v[184:187], v[168:171], v[116:119]
	v_mfma_f32_16x16x32_bf16 v[116:119], v[188:191], v[168:171], v[120:123]
	v_mfma_f32_16x16x32_bf16 v[28:31], v[192:195], v[168:171], v[28:31]
	v_mfma_f32_16x16x32_bf16 v[120:123], v[180:183], v[172:175], v[124:127]
	v_mfma_f32_16x16x32_bf16 v[124:127], v[184:187], v[172:175], v[128:131]
	v_mfma_f32_16x16x32_bf16 v[128:131], v[188:191], v[172:175], v[132:135]
	v_mfma_f32_16x16x32_bf16 v[32:35], v[192:195], v[172:175], v[32:35]
	v_mfma_f32_16x16x32_bf16 v[40:43], v[180:183], v[176:179], v[40:43]
	v_mfma_f32_16x16x32_bf16 v[44:47], v[184:187], v[176:179], v[44:47]
	v_mfma_f32_16x16x32_bf16 v[48:51], v[188:191], v[176:179], v[48:51]
	v_mfma_f32_16x16x32_bf16 v[36:39], v[192:195], v[176:179], v[36:39]
	s_setprio 1
	ds_read_b128 v[132:135], v0
	ds_read_b128 v[136:139], v0 offset:1024
	ds_read_b128 v[140:143], v0 offset:2048
	ds_read_b128 v[150:153], v0 offset:3072
	ds_read_b128 v[154:157], v0 offset:4096
	ds_read_b128 v[164:167], v0 offset:5120
	ds_read_b128 v[168:171], v0 offset:6144
	ds_read_b128 v[172:175], v0 offset:7168
	ds_read_b128 v[176:179], v7 offset:16384
	ds_read_b128 v[180:183], v7 offset:17408
	ds_read_b128 v[184:187], v7 offset:18432
	ds_read_b128 v[188:191], v7 offset:19456
	s_setprio 0
	s_waitcnt lgkmcnt(3)
	v_mfma_f32_16x16x32_bf16 v[2:5], v[176:179], v[132:135], v[2:5]
	s_waitcnt vmcnt(0) lgkmcnt(0)
	s_barrier
	s_waitcnt lgkmcnt(2)
	v_mfma_f32_16x16x32_bf16 v[56:59], v[180:183], v[132:135], v[56:59]
	s_waitcnt lgkmcnt(1)
	v_mfma_f32_16x16x32_bf16 v[60:63], v[184:187], v[132:135], v[60:63]
	s_waitcnt lgkmcnt(0)
	v_mfma_f32_16x16x32_bf16 v[8:11], v[188:191], v[132:135], v[8:11]
	v_mfma_f32_16x16x32_bf16 v[52:55], v[176:179], v[136:139], v[52:55]
	v_mfma_f32_16x16x32_bf16 v[64:67], v[180:183], v[136:139], v[64:67]
	v_mfma_f32_16x16x32_bf16 v[68:71], v[184:187], v[136:139], v[68:71]
	v_mfma_f32_16x16x32_bf16 v[12:15], v[188:191], v[136:139], v[12:15]
	v_mfma_f32_16x16x32_bf16 v[72:75], v[176:179], v[140:143], v[72:75]
	v_mfma_f32_16x16x32_bf16 v[76:79], v[180:183], v[140:143], v[76:79]
	v_mfma_f32_16x16x32_bf16 v[80:83], v[184:187], v[140:143], v[80:83]
	v_mfma_f32_16x16x32_bf16 v[16:19], v[188:191], v[140:143], v[16:19]
	v_mfma_f32_16x16x32_bf16 v[132:135], v[176:179], v[150:153], v[84:87]
	v_mfma_f32_16x16x32_bf16 v[136:139], v[180:183], v[150:153], v[88:91]
	v_mfma_f32_16x16x32_bf16 v[140:143], v[184:187], v[150:153], v[92:95]
	v_mfma_f32_16x16x32_bf16 v[20:23], v[188:191], v[150:153], v[20:23]
	v_mfma_f32_16x16x32_bf16 v[150:153], v[176:179], v[154:157], v[96:99]
	v_mfma_f32_16x16x32_bf16 v[192:195], v[180:183], v[154:157], v[100:103]
	v_mfma_f32_16x16x32_bf16 v[196:199], v[184:187], v[154:157], v[104:107]
	v_mfma_f32_16x16x32_bf16 v[24:27], v[188:191], v[154:157], v[24:27]
	v_mfma_f32_16x16x32_bf16 v[154:157], v[176:179], v[164:167], v[108:111]
	v_mfma_f32_16x16x32_bf16 v[28:31], v[188:191], v[164:167], v[28:31]
	v_mfma_f32_16x16x32_bf16 v[200:203], v[180:183], v[164:167], v[112:115]
	v_mfma_f32_16x16x32_bf16 v[204:207], v[184:187], v[164:167], v[116:119]
	v_mfma_f32_16x16x32_bf16 v[164:167], v[176:179], v[168:171], v[120:123]
	v_mfma_f32_16x16x32_bf16 v[208:211], v[180:183], v[168:171], v[124:127]
	v_mfma_f32_16x16x32_bf16 v[212:215], v[184:187], v[168:171], v[128:131]
	v_mfma_f32_16x16x32_bf16 v[168:171], v[188:191], v[168:171], v[32:35]
	v_mfma_f32_16x16x32_bf16 v[176:179], v[176:179], v[172:175], v[40:43]
	v_mfma_f32_16x16x32_bf16 v[180:183], v[180:183], v[172:175], v[44:47]
	v_mfma_f32_16x16x32_bf16 v[184:187], v[184:187], v[172:175], v[48:51]
	v_mfma_f32_16x16x32_bf16 v[172:175], v[188:191], v[172:175], v[36:39]
	s_setprio 1
	ds_read_b128 v[32:35], v0 offset:24576
	s_nop 0
	ds_read_b128 v[36:39], v0 offset:25600
	ds_read_b128 v[40:43], v0 offset:26624
	ds_read_b128 v[44:47], v0 offset:27648
	ds_read_b128 v[48:51], v0 offset:28672
	ds_read_b128 v[188:191], v0 offset:29696
	ds_read_b128 v[216:219], v0 offset:30720
	ds_read_b128 v[220:223], v0 offset:31744
	ds_read_b128 v[224:227], v7 offset:40960
	ds_read_b128 v[228:231], v7 offset:41984
	ds_read_b128 v[238:241], v7 offset:43008
	ds_read_b128 v[244:247], v7 offset:44032
	s_setprio 0
	v_readlane_b32 s0, v254, 33
	s_waitcnt lgkmcnt(3)
	v_mfma_f32_16x16x32_bf16 v[126:129], v[224:227], v[32:35], v[2:5]
	v_mov_b32_e32 v0, v160
	v_mov_b32_e32 v130, v161
	v_readlane_b32 s1, v254, 34
	v_mov_b32_e32 v2, v158
	v_mfma_f32_16x16x32_bf16 v[94:97], v[224:227], v[40:43], v[72:75]
	s_waitcnt lgkmcnt(0)
	s_barrier
; DI unsigned pack2(float a, float b) { float2_t v = {a, b}; bf16x2_t r = __builtin_convertvector(v, bf16x2_t); return __builtin_bit_cast(unsigned, r); }
; DI u16 f2bf(float a) { return (u16)(pack2(a, 0.f) & 0xffffu); }
; template <int MI, int NI>
; DI void gemm256(f32x4 (&acc)[MI][NI], const u16* __restrict__ A, int lda, const u16* __restrict__ Bt, int ldb, int K, int m0, int n0, char* smem) {
;     ...
; #pragma unroll
;     for (int mi = 0; mi < MI; ++mi)
; #pragma unroll
;       for (int ni = 0; ni < NI; ++ni)
;         acc[mi][ni] = __builtin_amdgcn_mfma_f32_16x16x32_bf16(bfr[ni], af[mi], acc[mi][ni], 0, 0, 0);
; DI void phase_qkv(const Params& p, int l, char* smem) {
;     ...
;       for (int mi = 0; mi < 8; ++mi) {
;         __builtin_amdgcn_sched_barrier(0);
;         const int m = m0 + wr * 128 + mi * 16 + lr;
;         const float rs = rskv[m];
;         if (wc == 0) {
;           float ss = 0.f;
; #pragma unroll
;           for (int ni = 0; ni < 4; ++ni)
; #pragma unroll
;             for (int j = 0; j < 4; ++j) { const float v = acc[mi][ni][j] * rs; ss += v * v; }
;           ss += __shfl_xor(ss, 16, 64); ss += __shfl_xor(ss, 32, 64);
;           const float f = rs * rsqrtf(ss * (1.f / 64.f) + 1e-6f);
;           u16* dst = Kb + qk_index(m, h);
; #pragma unroll
;           for (int ni = 0; ni < 4; ++ni) {
;             const int d = ni * 16 + lq * 4;
;             const float4 g = *(const float4*)(gk + d);
;             *(uint2*)(dst + d) = make_uint2(pack2(acc[mi][ni][0] * f * g.x, acc[mi][ni][1] * f * g.y), pack2(acc[mi][ni][2] * f * g.z, acc[mi][ni][3] * f * g.w));
;           }
;           *(uint4*)(dst + 64 + lq * 8) = *(const uint4*)((const u16*)(p.ws + OFF_KR) + (size_t)m * 32 + lq * 8);
;         } else {
;           const bool lat = m < NTL;
;           const int b = lat ? m >> 12 : (m - NTL) >> 8;
;           const int pos = lat ? m & 4095 : 4096 + ((m - NTL) & 255);
;           u16* dst = Vt + (size_t)(b * 8 + h) * 64 * LK + pos + (size_t)(lq * 4) * LK;
; #pragma unroll
;           for (int ni = 0; ni < 4; ++ni) {
;             asm volatile("" : "+v"(dst));
; #pragma unroll
;             for (int j = 0; j < 4; ++j) dst[j * LK] = f2bf(acc[mi][ni][j] * rs);
;             dst += 16 * LK;
;           }
;         }
	s_waitcnt lgkmcnt(2)
	v_mfma_f32_16x16x32_bf16 v[90:93], v[228:231], v[40:43], v[76:79]
	v_mov_b32_e32 v3, v159
	v_mfma_f32_16x16x32_bf16 v[74:77], v[228:231], v[44:47], v[136:139]
	v_lshlrev_b32_e32 v2, 7, v2
	s_movk_i32 s4, 0x2200
	v_mfma_f32_16x16x32_bf16 v[122:125], v[228:231], v[32:35], v[56:59]
	v_mov_b64_e32 v[136:137], s[0:1]
	v_readlane_b32 s0, v254, 31
	v_readlane_b32 s1, v254, 32
	s_waitcnt lgkmcnt(1)
	v_mfma_f32_16x16x32_bf16 v[118:121], v[238:241], v[32:35], v[60:63]
	s_waitcnt lgkmcnt(0)
	v_mfma_f32_16x16x32_bf16 v[114:117], v[244:247], v[32:35], v[8:11]
	v_mfma_f32_16x16x32_bf16 v[110:113], v[224:227], v[36:39], v[52:55]
	v_mfma_f32_16x16x32_bf16 v[106:109], v[228:231], v[36:39], v[64:67]
	v_mfma_f32_16x16x32_bf16 v[102:105], v[238:241], v[36:39], v[68:71]
	v_mfma_f32_16x16x32_bf16 v[98:101], v[244:247], v[36:39], v[12:15]
	v_mfma_f32_16x16x32_bf16 v[86:89], v[238:241], v[40:43], v[80:83]
	v_mfma_f32_16x16x32_bf16 v[82:85], v[244:247], v[40:43], v[16:19]
	v_mfma_f32_16x16x32_bf16 v[78:81], v[224:227], v[44:47], v[132:135]
	v_mfma_f32_16x16x32_bf16 v[70:73], v[238:241], v[44:47], v[140:143]
	s_nop 1
	v_mov_b64_e32 v[134:135], s[0:1]
	v_cmp_ne_u32_e64 s[0:1], 0, v3
	v_lshlrev_b32_e32 v132, 2, v130
	v_mfma_f32_16x16x32_bf16 v[66:69], v[244:247], v[44:47], v[20:23]
	v_add3_u32 v140, v0, v6, v2
	v_mad_i64_i32 v[138:139], s[4:5], v132, s4, 0
	v_mfma_f32_16x16x32_bf16 v[62:65], v[224:227], v[48:51], v[150:153]
	v_mfma_f32_16x16x32_bf16 v[58:61], v[228:231], v[48:51], v[192:195]
	v_mfma_f32_16x16x32_bf16 v[54:57], v[238:241], v[48:51], v[196:199]
	v_mfma_f32_16x16x32_bf16 v[50:53], v[244:247], v[48:51], v[24:27]
	v_mfma_f32_16x16x32_bf16 v[46:49], v[224:227], v[188:191], v[154:157]
	v_mfma_f32_16x16x32_bf16 v[42:45], v[228:231], v[188:191], v[200:203]
	v_mfma_f32_16x16x32_bf16 v[38:41], v[238:241], v[188:191], v[204:207]
	v_mfma_f32_16x16x32_bf16 v[34:37], v[244:247], v[188:191], v[28:31]
	v_mfma_f32_16x16x32_bf16 v[30:33], v[224:227], v[216:219], v[164:167]
	v_mfma_f32_16x16x32_bf16 v[26:29], v[228:231], v[216:219], v[208:211]
	v_mfma_f32_16x16x32_bf16 v[22:25], v[238:241], v[216:219], v[212:215]
	v_mfma_f32_16x16x32_bf16 v[18:21], v[244:247], v[216:219], v[168:171]
	v_mfma_f32_16x16x32_bf16 v[14:17], v[224:227], v[220:223], v[176:179]
	v_mfma_f32_16x16x32_bf16 v[10:13], v[228:231], v[220:223], v[180:183]
	v_mfma_f32_16x16x32_bf16 v[6:9], v[238:241], v[220:223], v[184:187]
	v_mfma_f32_16x16x32_bf16 v[2:5], v[244:247], v[220:223], v[172:175]
	v_ashrrev_i32_e32 v141, 31, v140
	v_lshl_add_u64 v[142:143], v[140:141], 2, v[134:135]
	flat_load_dword v144, v[142:143]
	v_ashrrev_i32_e32 v0, 12, v140
	v_add_u32_e32 v149, 0xffff8000, v140
	v_and_b32_e32 v146, 0xfff, v140
	v_or_b32_sdwa v147, v140, s97 dst_sel:DWORD dst_unused:UNUSED_PAD src0_sel:BYTE_0 src1_sel:DWORD
	s_waitcnt vmcnt(0) lgkmcnt(0)
	v_mul_f32_e32 v156, v126, v144
	v_mul_f32_e32 v157, v127, v144
	v_mul_f32_e32 v155, v128, v144
	v_mul_f32_e32 v154, v129, v144
	v_mul_f32_e32 v153, v122, v144
	v_mul_f32_e32 v152, v123, v144
	v_mul_f32_e32 v151, v124, v144
	v_mul_f32_e32 v150, v125, v144
	s_and_saveexec_b64 s[4:5], s[0:1]
	v_readlane_b32 s8, v254, 15
	s_xor_b64 s[4:5], exec, s[4:5]
	v_readlane_b32 s9, v254, 16
	s_cbranch_execz .LBB0_723
	v_lshrrev_b32_e32 v122, 8, v149
	v_cmp_gt_i32_e32 vcc, s58, v140
	s_mov_b32 s6, 0x88000
	s_nop 0
	v_cndmask_b32_e32 v0, v122, v0, vcc
	v_cndmask_b32_e32 v124, v147, v146, vcc
	v_lshl_add_u32 v0, v0, 3, v148
	v_mov_b64_e32 v[122:123], s[8:9]
	v_mad_i64_i32 v[122:123], s[6:7], v0, s6, v[122:123]
	v_lshlrev_b32_e32 v0, 1, v124
	v_lshl_add_u64 v[122:123], v[122:123], 0, v[0:1]
	v_lshl_add_u64 v[122:123], v[122:123], 0, v[138:139]
	v_cvt_pk_bf16_f32 v0, v156, s0
	v_add_co_u32_e32 v124, vcc, s47, v122
	flat_store_short v[122:123], v0
	v_cvt_pk_bf16_f32 v0, v157, s0
	v_addc_co_u32_e32 v125, vcc, 0, v123, vcc
	flat_store_short v[124:125], v0 offset:512
	v_add_co_u32_e32 v124, vcc, s42, v122
	v_cvt_pk_bf16_f32 v0, v155, s0
	s_nop 0
	v_addc_co_u32_e32 v125, vcc, 0, v123, vcc
	flat_store_short v[124:125], v0 offset:1024
	v_add_co_u32_e32 v124, vcc, s43, v122
	s_mov_b64 s[6:7], 0x22000
	v_cvt_pk_bf16_f32 v0, v154, s0
	v_addc_co_u32_e32 v125, vcc, 0, v123, vcc
	v_lshl_add_u64 v[122:123], v[122:123], 0, s[6:7]
	flat_store_short v[124:125], v0 offset:1536
	v_cvt_pk_bf16_f32 v0, v153, s0
	v_add_co_u32_e32 v124, vcc, s47, v122
	flat_store_short v[122:123], v0
	v_cvt_pk_bf16_f32 v0, v152, s0
	v_addc_co_u32_e32 v125, vcc, 0, v123, vcc
	flat_store_short v[124:125], v0 offset:512
	v_add_co_u32_e32 v124, vcc, s42, v122
	v_cvt_pk_bf16_f32 v0, v151, s0
	s_nop 0
	v_addc_co_u32_e32 v125, vcc, 0, v123, vcc
	flat_store_short v[124:125], v0 offset:1024
	v_add_co_u32_e32 v124, vcc, s43, v122
	v_cvt_pk_bf16_f32 v0, v150, s0
	s_nop 0
	v_addc_co_u32_e32 v125, vcc, 0, v123, vcc
	flat_store_short v[124:125], v0 offset:1536
	v_mul_f32_e32 v0, v118, v144
	v_lshl_add_u64 v[122:123], v[122:123], 0, s[6:7]
	v_cvt_pk_bf16_f32 v0, v0, s0
	flat_store_short v[122:123], v0
	v_mul_f32_e32 v0, v119, v144
	v_add_co_u32_e32 v118, vcc, s47, v122
	v_cvt_pk_bf16_f32 v0, v0, s0
	s_nop 0
	v_addc_co_u32_e32 v119, vcc, 0, v123, vcc
	flat_store_short v[118:119], v0 offset:512
	v_mul_f32_e32 v0, v120, v144
	v_add_co_u32_e32 v118, vcc, s42, v122
	v_cvt_pk_bf16_f32 v0, v0, s0
	s_nop 0
	v_addc_co_u32_e32 v119, vcc, 0, v123, vcc
	flat_store_short v[118:119], v0 offset:1024
	v_mul_f32_e32 v0, v121, v144
	v_add_co_u32_e32 v118, vcc, s43, v122
	v_cvt_pk_bf16_f32 v0, v0, s0
	s_nop 0
	v_addc_co_u32_e32 v119, vcc, 0, v123, vcc
	flat_store_short v[118:119], v0 offset:1536
	v_mul_f32_e32 v0, v114, v144
	v_lshl_add_u64 v[118:119], v[122:123], 0, s[6:7]
	v_cvt_pk_bf16_f32 v0, v0, s0
	flat_store_short v[118:119], v0
	v_mul_f32_e32 v0, v115, v144
	v_add_co_u32_e32 v114, vcc, 0x2000, v118
	v_cvt_pk_bf16_f32 v0, v0, s0
	s_nop 0
	v_addc_co_u32_e32 v115, vcc, 0, v119, vcc
	flat_store_short v[114:115], v0 offset:512
	v_mul_f32_e32 v0, v116, v144
	v_add_co_u32_e32 v114, vcc, 0x4000, v118
	v_cvt_pk_bf16_f32 v0, v0, s0
	s_nop 0
	v_addc_co_u32_e32 v115, vcc, 0, v119, vcc
	flat_store_short v[114:115], v0 offset:1024
	v_mul_f32_e32 v0, v117, v144
	v_add_co_u32_e32 v114, vcc, 0x6000, v118
	v_cvt_pk_bf16_f32 v0, v0, s0
	s_nop 0
	v_addc_co_u32_e32 v115, vcc, 0, v119, vcc
	flat_store_short v[114:115], v0 offset:1536

; template <int MI, int NI>
; DI void gemm256(f32x4 (&acc)[MI][NI], const u16* __restrict__ A, int lda, const u16* __restrict__ Bt, int ldb, int K, int m0, int n0, char* smem) {
;     ...
;   for (int kt = 0; kt < nk; ++kt) {
;     if (kt + 1 < nk) asm volatile("s_waitcnt vmcnt(%0) lgkmcnt(0)" :: "n"(LPS) : "memory");
;     else asm volatile("s_waitcnt vmcnt(0) lgkmcnt(0)" ::: "memory");
;     __builtin_amdgcn_s_barrier();
;     __builtin_amdgcn_s_setprio(1);
;     const char* sb = smem + st * STAGE + foff;
;     bf16x8 af[MI], bfr[NI];
; #pragma unroll
;     for (int mi = 0; mi < MI; ++mi) af[mi] = *(const bf16x8*)(sb + (wr * MI + mi) * 1024);
; #pragma unroll
;     for (int ni = 0; ni < NI; ++ni) bfr[ni] = *(const bf16x8*)(sb + ABYTES + (wc * NI + ni) * 1024);
;     __builtin_amdgcn_sched_barrier(0x0);
;     if (kt + 2 < nk) { const int s2 = st >= 1 ? st - 1 : 2; G256_ISSUE(s2, (kt + 2) * 32); }
;     __builtin_amdgcn_s_setprio(0);
; #pragma unroll
;     for (int mi = 0; mi < MI; ++mi)
; #pragma unroll
;       for (int ni = 0; ni < NI; ++ni)
;         acc[mi][ni] = __builtin_amdgcn_mfma_f32_16x16x32_bf16(bfr[ni], af[mi], acc[mi][ni], 0, 0, 0);
;     st = st == 2 ? 0 : st + 1;
;   }
.Lpipe_zgemm:
	v_add_u32_e32 v160, s6, v143
	ds_read_b128 v[164:167], v160 offset:4096
	ds_read_b128 v[168:171], v160 offset:5120
	ds_read_b128 v[172:175], v160 offset:6144
	ds_read_b128 v[176:179], v160 offset:7168
	s_add_i32 s8, s6, 0xffffa000
	s_cmp_eq_u32 s6, 0
	s_cselect_b32 s8, 0xc000, s8
	s_add_i32 s9, s8, s7
	s_add_i32 s8, s8, s0
	s_mov_b32 m0, s9
	s_waitcnt lgkmcnt(7)
	v_mfma_f32_16x16x32_bf16 v[126:129], v[180:183], v[144:147], v[126:129]
	global_load_lds_dwordx4 v[198:199], off
	v_mfma_f32_16x16x32_bf16 v[110:113], v[180:183], v[148:151], v[110:113]
	v_lshl_add_u64 v[198:199], v[198:199], 0, s[98:99]
	s_add_i32 m0, s9, 0x400
	v_mfma_f32_16x16x32_bf16 v[94:97], v[180:183], v[152:155], v[94:97]
	global_load_lds_dwordx4 v[200:201], off
	v_mfma_f32_16x16x32_bf16 v[78:81], v[180:183], v[156:159], v[78:81]
	v_lshl_add_u64 v[200:201], v[200:201], 0, s[98:99]
	s_add_i32 m0, s9, 0x800
	s_waitcnt lgkmcnt(6)
	v_mfma_f32_16x16x32_bf16 v[122:125], v[184:187], v[144:147], v[122:125]
	global_load_lds_dwordx4 v[202:203], off
	v_mfma_f32_16x16x32_bf16 v[106:109], v[184:187], v[148:151], v[106:109]
	v_lshl_add_u64 v[202:203], v[202:203], 0, s[98:99]
	s_add_i32 m0, s9, 0xc00
	v_mfma_f32_16x16x32_bf16 v[90:93], v[184:187], v[152:155], v[90:93]
	global_load_lds_dwordx4 v[204:205], off
	v_mfma_f32_16x16x32_bf16 v[74:77], v[184:187], v[156:159], v[74:77]
	v_lshl_add_u64 v[204:205], v[204:205], 0, s[98:99]
	s_mov_b32 m0, s8
	s_waitcnt lgkmcnt(5)
	v_mfma_f32_16x16x32_bf16 v[118:121], v[188:191], v[144:147], v[118:121]
	global_load_lds_dwordx4 v[206:207], off
	v_mfma_f32_16x16x32_bf16 v[102:105], v[188:191], v[148:151], v[102:105]
	v_lshl_add_u64 v[206:207], v[206:207], 0, s[98:99]
	s_add_i32 m0, s8, 0x400
	v_mfma_f32_16x16x32_bf16 v[86:89], v[188:191], v[152:155], v[86:89]
	global_load_lds_dwordx4 v[208:209], off
	v_mfma_f32_16x16x32_bf16 v[70:73], v[188:191], v[156:159], v[70:73]
	v_lshl_add_u64 v[208:209], v[208:209], 0, s[98:99]
	s_waitcnt lgkmcnt(4)
	v_mfma_f32_16x16x32_bf16 v[114:117], v[192:195], v[144:147], v[114:117]
	v_mfma_f32_16x16x32_bf16 v[98:101], v[192:195], v[148:151], v[98:101]
	v_mfma_f32_16x16x32_bf16 v[82:85], v[192:195], v[152:155], v[82:85]
	v_mfma_f32_16x16x32_bf16 v[66:69], v[192:195], v[156:159], v[66:69]
	s_waitcnt vmcnt(6) lgkmcnt(0)
	s_barrier
	s_add_i32 s9, s6, 0x6000
	s_cmp_eq_u32 s6, 0xc000
	s_cselect_b32 s6, 0, s9
	v_add_u32_e32 v196, s6, v143
	v_add_u32_e32 v197, s6, v0
	v_mfma_f32_16x16x32_bf16 v[62:65], v[180:183], v[164:167], v[62:65]
	ds_read_b128 v[144:147], v196
	v_mfma_f32_16x16x32_bf16 v[46:49], v[180:183], v[168:171], v[46:49]
	ds_read_b128 v[148:151], v196 offset:1024
	v_mfma_f32_16x16x32_bf16 v[30:33], v[180:183], v[172:175], v[30:33]
	ds_read_b128 v[152:155], v196 offset:2048
	v_mfma_f32_16x16x32_bf16 v[14:17], v[180:183], v[176:179], v[14:17]
	ds_read_b128 v[156:159], v196 offset:3072
	ds_read_b128 v[180:183], v197 offset:16384
	v_mfma_f32_16x16x32_bf16 v[58:61], v[184:187], v[164:167], v[58:61]
	v_mfma_f32_16x16x32_bf16 v[42:45], v[184:187], v[168:171], v[42:45]
	v_mfma_f32_16x16x32_bf16 v[26:29], v[184:187], v[172:175], v[26:29]
	v_mfma_f32_16x16x32_bf16 v[10:13], v[184:187], v[176:179], v[10:13]
	ds_read_b128 v[184:187], v197 offset:17408
	v_mfma_f32_16x16x32_bf16 v[54:57], v[188:191], v[164:167], v[54:57]
	v_mfma_f32_16x16x32_bf16 v[38:41], v[188:191], v[168:171], v[38:41]
	v_mfma_f32_16x16x32_bf16 v[22:25], v[188:191], v[172:175], v[22:25]
	v_mfma_f32_16x16x32_bf16 v[6:9], v[188:191], v[176:179], v[6:9]
	ds_read_b128 v[188:191], v197 offset:18432
	v_mfma_f32_16x16x32_bf16 v[50:53], v[192:195], v[164:167], v[50:53]
	v_mfma_f32_16x16x32_bf16 v[34:37], v[192:195], v[168:171], v[34:37]
	v_mfma_f32_16x16x32_bf16 v[18:21], v[192:195], v[172:175], v[18:21]
	v_mfma_f32_16x16x32_bf16 v[2:5], v[192:195], v[176:179], v[2:5]
	ds_read_b128 v[192:195], v197 offset:19456
	s_sub_i32 s1, s1, 1
	s_cmp_lg_u32 s1, 0
	s_cbranch_scc1 .Lpipe_zgemm
	v_add_u32_e32 v160, s6, v143
	ds_read_b128 v[164:167], v160 offset:4096
	ds_read_b128 v[168:171], v160 offset:5120
	ds_read_b128 v[172:175], v160 offset:6144
	ds_read_b128 v[176:179], v160 offset:7168
	s_add_i32 s8, s6, 0xffffa000
	s_cmp_eq_u32 s6, 0
	s_cselect_b32 s8, 0xc000, s8
	s_add_i32 s9, s8, s7
	s_add_i32 s8, s8, s0
	s_mov_b32 m0, s9
	s_waitcnt lgkmcnt(7)
	v_mfma_f32_16x16x32_bf16 v[126:129], v[180:183], v[144:147], v[126:129]
	global_load_lds_dwordx4 v[198:199], off
	v_mfma_f32_16x16x32_bf16 v[110:113], v[180:183], v[148:151], v[110:113]
	v_lshl_add_u64 v[198:199], v[198:199], 0, s[98:99]
	s_add_i32 m0, s9, 0x400
	v_mfma_f32_16x16x32_bf16 v[94:97], v[180:183], v[152:155], v[94:97]
	global_load_lds_dwordx4 v[200:201], off
	v_mfma_f32_16x16x32_bf16 v[78:81], v[180:183], v[156:159], v[78:81]
	v_lshl_add_u64 v[200:201], v[200:201], 0, s[98:99]
	s_add_i32 m0, s9, 0x800
	s_waitcnt lgkmcnt(6)
	v_mfma_f32_16x16x32_bf16 v[122:125], v[184:187], v[144:147], v[122:125]
	global_load_lds_dwordx4 v[202:203], off
	v_mfma_f32_16x16x32_bf16 v[106:109], v[184:187], v[148:151], v[106:109]
	v_lshl_add_u64 v[202:203], v[202:203], 0, s[98:99]
	s_add_i32 m0, s9, 0xc00
	v_mfma_f32_16x16x32_bf16 v[90:93], v[184:187], v[152:155], v[90:93]
	global_load_lds_dwordx4 v[204:205], off
	v_mfma_f32_16x16x32_bf16 v[74:77], v[184:187], v[156:159], v[74:77]
	v_lshl_add_u64 v[204:205], v[204:205], 0, s[98:99]
	s_mov_b32 m0, s8
	s_waitcnt lgkmcnt(5)
	v_mfma_f32_16x16x32_bf16 v[118:121], v[188:191], v[144:147], v[118:121]
	global_load_lds_dwordx4 v[206:207], off
	v_mfma_f32_16x16x32_bf16 v[102:105], v[188:191], v[148:151], v[102:105]
	v_lshl_add_u64 v[206:207], v[206:207], 0, s[98:99]
	s_add_i32 m0, s8, 0x400
	v_mfma_f32_16x16x32_bf16 v[86:89], v[188:191], v[152:155], v[86:89]
	global_load_lds_dwordx4 v[208:209], off
	v_mfma_f32_16x16x32_bf16 v[70:73], v[188:191], v[156:159], v[70:73]
	v_lshl_add_u64 v[208:209], v[208:209], 0, s[98:99]
	s_waitcnt lgkmcnt(4)
; template <int MI, int NI>
; DI void gemm256(f32x4 (&acc)[MI][NI], const u16* __restrict__ A, int lda, const u16* __restrict__ Bt, int ldb, int K, int m0, int n0, char* smem) {
;     ...
;   for (int kt = 0; kt < nk; ++kt) {
;     if (kt + 1 < nk) asm volatile("s_waitcnt vmcnt(%0) lgkmcnt(0)" :: "n"(LPS) : "memory");
;     else asm volatile("s_waitcnt vmcnt(0) lgkmcnt(0)" ::: "memory");
;     __builtin_amdgcn_s_barrier();
;     __builtin_amdgcn_s_setprio(1);
;     const char* sb = smem + st * STAGE + foff;
;     bf16x8 af[MI], bfr[NI];
; #pragma unroll
;     for (int mi = 0; mi < MI; ++mi) af[mi] = *(const bf16x8*)(sb + (wr * MI + mi) * 1024);
; #pragma unroll
;     for (int ni = 0; ni < NI; ++ni) bfr[ni] = *(const bf16x8*)(sb + ABYTES + (wc * NI + ni) * 1024);
;     __builtin_amdgcn_sched_barrier(0x0);
;     if (kt + 2 < nk) { const int s2 = st >= 1 ? st - 1 : 2; G256_ISSUE(s2, (kt + 2) * 32); }
;     __builtin_amdgcn_s_setprio(0);
; #pragma unroll
;     for (int mi = 0; mi < MI; ++mi)
; #pragma unroll
;       for (int ni = 0; ni < NI; ++ni)
;         acc[mi][ni] = __builtin_amdgcn_mfma_f32_16x16x32_bf16(bfr[ni], af[mi], acc[mi][ni], 0, 0, 0);
;     st = st == 2 ? 0 : st + 1;
;   }
;   asm volatile("s_waitcnt lgkmcnt(0)" ::: "memory");
;   __builtin_amdgcn_s_barrier();
	v_mfma_f32_16x16x32_bf16 v[114:117], v[192:195], v[144:147], v[114:117]
	v_mfma_f32_16x16x32_bf16 v[98:101], v[192:195], v[148:151], v[98:101]
	v_mfma_f32_16x16x32_bf16 v[82:85], v[192:195], v[152:155], v[82:85]
	v_mfma_f32_16x16x32_bf16 v[66:69], v[192:195], v[156:159], v[66:69]
	s_waitcnt lgkmcnt(0)
	v_mfma_f32_16x16x32_bf16 v[62:65], v[180:183], v[164:167], v[62:65]
	v_mfma_f32_16x16x32_bf16 v[46:49], v[180:183], v[168:171], v[46:49]
	v_mfma_f32_16x16x32_bf16 v[30:33], v[180:183], v[172:175], v[30:33]
	v_mfma_f32_16x16x32_bf16 v[14:17], v[180:183], v[176:179], v[14:17]
	v_mfma_f32_16x16x32_bf16 v[58:61], v[184:187], v[164:167], v[58:61]
	v_mfma_f32_16x16x32_bf16 v[42:45], v[184:187], v[168:171], v[42:45]
	v_mfma_f32_16x16x32_bf16 v[26:29], v[184:187], v[172:175], v[26:29]
	v_mfma_f32_16x16x32_bf16 v[10:13], v[184:187], v[176:179], v[10:13]
	v_mfma_f32_16x16x32_bf16 v[54:57], v[188:191], v[164:167], v[54:57]
	v_mfma_f32_16x16x32_bf16 v[38:41], v[188:191], v[168:171], v[38:41]
	v_mfma_f32_16x16x32_bf16 v[22:25], v[188:191], v[172:175], v[22:25]
	v_mfma_f32_16x16x32_bf16 v[6:9], v[188:191], v[176:179], v[6:9]
	v_mfma_f32_16x16x32_bf16 v[50:53], v[192:195], v[164:167], v[50:53]
	v_mfma_f32_16x16x32_bf16 v[34:37], v[192:195], v[168:171], v[34:37]
	v_mfma_f32_16x16x32_bf16 v[18:21], v[192:195], v[172:175], v[18:21]
	v_mfma_f32_16x16x32_bf16 v[2:5], v[192:195], v[176:179], v[2:5]
	s_waitcnt vmcnt(6) lgkmcnt(0)
	s_barrier
	s_setprio 1
	v_add_u32_e32 v0, v140, v142
	ds_read_b128 v[130:133], v0
	ds_read_b128 v[142:145], v0 offset:1024
	ds_read_b128 v[146:149], v0 offset:2048
	ds_read_b128 v[150:153], v0 offset:3072
	ds_read_b128 v[154:157], v0 offset:4096
	ds_read_b128 v[158:161], v0 offset:5120
	ds_read_b128 v[164:167], v0 offset:6144
	ds_read_b128 v[168:171], v0 offset:7168
	v_add_u32_e32 v220, v140, v141
	ds_read_b128 v[138:141], v220 offset:16384
	ds_read_b128 v[172:175], v220 offset:17408
	ds_read_b128 v[176:179], v220 offset:18432
	ds_read_b128 v[180:183], v220 offset:19456
	s_setprio 0
	s_waitcnt lgkmcnt(3)
	v_mfma_f32_16x16x32_bf16 v[126:129], v[138:141], v[130:133], v[126:129]
	s_waitcnt vmcnt(0) lgkmcnt(0)
	s_barrier
	s_waitcnt lgkmcnt(2)
	v_mfma_f32_16x16x32_bf16 v[122:125], v[172:175], v[130:133], v[122:125]
	s_waitcnt lgkmcnt(1)
	v_mfma_f32_16x16x32_bf16 v[118:121], v[176:179], v[130:133], v[118:121]
	s_waitcnt lgkmcnt(0)
	v_mfma_f32_16x16x32_bf16 v[130:133], v[180:183], v[130:133], v[114:117]
	v_mfma_f32_16x16x32_bf16 v[110:113], v[138:141], v[142:145], v[110:113]
	v_mfma_f32_16x16x32_bf16 v[102:105], v[176:179], v[142:145], v[102:105]
	v_mfma_f32_16x16x32_bf16 v[94:97], v[138:141], v[146:149], v[94:97]
	v_mfma_f32_16x16x32_bf16 v[86:89], v[176:179], v[146:149], v[86:89]
	v_mfma_f32_16x16x32_bf16 v[78:81], v[138:141], v[150:153], v[78:81]
	v_mfma_f32_16x16x32_bf16 v[70:73], v[176:179], v[150:153], v[70:73]
	v_mfma_f32_16x16x32_bf16 v[62:65], v[138:141], v[154:157], v[62:65]
	v_mfma_f32_16x16x32_bf16 v[54:57], v[176:179], v[154:157], v[54:57]
	v_mfma_f32_16x16x32_bf16 v[46:49], v[138:141], v[158:161], v[46:49]
	v_mfma_f32_16x16x32_bf16 v[38:41], v[176:179], v[158:161], v[38:41]
	v_mfma_f32_16x16x32_bf16 v[30:33], v[138:141], v[164:167], v[30:33]
	v_mfma_f32_16x16x32_bf16 v[22:25], v[176:179], v[164:167], v[22:25]
	v_mfma_f32_16x16x32_bf16 v[14:17], v[138:141], v[168:171], v[14:17]
	v_mfma_f32_16x16x32_bf16 v[6:9], v[176:179], v[168:171], v[6:9]
	v_mfma_f32_16x16x32_bf16 v[184:187], v[172:175], v[142:145], v[106:109]
	v_mfma_f32_16x16x32_bf16 v[142:145], v[180:183], v[142:145], v[98:101]
	v_mfma_f32_16x16x32_bf16 v[188:191], v[172:175], v[146:149], v[90:93]
	v_mfma_f32_16x16x32_bf16 v[146:149], v[180:183], v[146:149], v[82:85]
	v_mfma_f32_16x16x32_bf16 v[192:195], v[172:175], v[150:153], v[74:77]
	v_mfma_f32_16x16x32_bf16 v[150:153], v[180:183], v[150:153], v[66:69]
	v_mfma_f32_16x16x32_bf16 v[196:199], v[172:175], v[154:157], v[58:61]
	v_mfma_f32_16x16x32_bf16 v[154:157], v[180:183], v[154:157], v[50:53]
	v_mfma_f32_16x16x32_bf16 v[200:203], v[172:175], v[158:161], v[42:45]
	v_mfma_f32_16x16x32_bf16 v[158:161], v[180:183], v[158:161], v[34:37]
	v_mfma_f32_16x16x32_bf16 v[204:207], v[172:175], v[164:167], v[26:29]
	v_mfma_f32_16x16x32_bf16 v[164:167], v[180:183], v[164:167], v[18:21]
	v_mfma_f32_16x16x32_bf16 v[138:141], v[172:175], v[168:171], v[10:13]
	v_mfma_f32_16x16x32_bf16 v[168:171], v[180:183], v[168:171], v[2:5]
	s_setprio 1
	s_nop 1
	ds_read_b128 v[2:5], v0 offset:24576
	ds_read_b128 v[10:13], v0 offset:25600
	ds_read_b128 v[18:21], v0 offset:26624
	ds_read_b128 v[26:29], v0 offset:27648
	ds_read_b128 v[34:37], v0 offset:28672
	ds_read_b128 v[172:175], v0 offset:29696
	ds_read_b128 v[176:179], v0 offset:30720
	ds_read_b128 v[180:183], v0 offset:31744
	ds_read_b128 v[208:211], v220 offset:40960
	ds_read_b128 v[212:215], v220 offset:41984
	ds_read_b128 v[216:219], v220 offset:43008
	ds_read_b128 v[220:223], v220 offset:44032
	s_setprio 0
	s_waitcnt lgkmcnt(3)
	v_mfma_f32_16x16x32_bf16 v[224:227], v[208:211], v[2:5], v[126:129]
	v_mov_b32_e32 v0, v136
	s_waitcnt lgkmcnt(0)
	s_barrier
; DI unsigned pack2(float a, float b) { float2_t v = {a, b}; bf16x2_t r = __builtin_convertvector(v, bf16x2_t); return __builtin_bit_cast(unsigned, r); }
; #define EPI_BEGIN const int lr1_ = launder_v(lr), lq1_ = launder_v(lq), wr1_ = launder_v(wr), wc1_ = launder_v(wc); { const int lr = lr1_, lq = lq1_, wr = wr1_, wc = wc1_; (void)lr; (void)lq; (void)wr; (void)wc;
; template <int MI, int NI>
; DI void gemm256(f32x4 (&acc)[MI][NI], const u16* __restrict__ A, int lda, const u16* __restrict__ Bt, int ldb, int K, int m0, int n0, char* smem) {
;     ...
; #pragma unroll
;     for (int mi = 0; mi < MI; ++mi)
; #pragma unroll
;       for (int ni = 0; ni < NI; ++ni)
;         acc[mi][ni] = __builtin_amdgcn_mfma_f32_16x16x32_bf16(bfr[ni], af[mi], acc[mi][ni], 0, 0, 0);
; DI void phase_zgemm(const Params& p, int l, char* smem) {
;     ...
;     EPI_BEGIN
; #pragma unroll
;     for (int mi = 0; mi < 8; mi += 2) {
;       const int m = m0 + wr * 128 + (mi + (lq & 1)) * 16 + lr;
; #pragma unroll
;       for (int ni = 0; ni < 4; ++ni) {
;         const int n = n0 + wc * 64 + ni * 16 + (lq >> 1) * 8;
;         const uint4 v = widen16(make_uint2(pack2(acc[mi][ni][0], acc[mi][ni][1]), pack2(acc[mi][ni][2], acc[mi][ni][3])),
;                                 make_uint2(pack2(acc[mi + 1][ni][0], acc[mi + 1][ni][1]), pack2(acc[mi + 1][ni][2], acc[mi + 1][ni][3])));
;         if (n < ZA) *(uint4*)(za + (size_t)m * ZA + n) = v;
;         else if (n < ZA + ZR) *(uint4*)(zr + (size_t)m * ZR + (n - ZA)) = v;
;       }
	s_waitcnt lgkmcnt(2)
	v_mfma_f32_16x16x32_bf16 v[114:117], v[212:215], v[2:5], v[122:125]
	s_movk_i32 s0, 0x900
	s_waitcnt lgkmcnt(1)
	v_mfma_f32_16x16x32_bf16 v[106:109], v[216:219], v[2:5], v[118:121]
	s_nop 0
	v_cvt_pk_bf16_f32 v122, v224, v225
	v_cvt_pk_bf16_f32 v123, v226, v227
	s_waitcnt lgkmcnt(0)
	v_mfma_f32_16x16x32_bf16 v[98:101], v[220:223], v[2:5], v[130:133]
	v_mov_b32_e32 v2, v137
	v_mov_b32_e32 v3, v134
	v_mov_b32_e32 v4, v135
	v_lshlrev_b32_e32 v3, 7, v3
	v_add3_u32 v132, v0, s5, v3
	v_lshlrev_b32_e32 v3, 2, v2
	v_and_b32_e32 v3, -8, v3
	v_lshlrev_b32_e32 v0, 6, v4
	v_add3_u32 v126, v3, s4, v0
	v_lshlrev_b32_e32 v0, 4, v2
	v_mfma_f32_16x16x32_bf16 v[228:231], v[208:211], v[10:13], v[110:113]
	v_and_b32_e32 v133, 16, v0
	v_add_u32_e32 v0, v132, v133
	v_mfma_f32_16x16x32_bf16 v[118:121], v[212:215], v[10:13], v[184:187]
	v_mfma_f32_16x16x32_bf16 v[110:113], v[216:219], v[10:13], v[102:105]
	s_nop 3
	v_cvt_pk_bf16_f32 v124, v228, v229
	v_cvt_pk_bf16_f32 v125, v230, v231
	s_nop 0
	v_permlane16_swap_b32_e32 v122, v124
	v_mfma_f32_16x16x32_bf16 v[102:105], v[220:223], v[10:13], v[142:145]
	v_permlane16_swap_b32_e32 v123, v125
	v_mfma_f32_16x16x32_bf16 v[10:13], v[216:219], v[176:179], v[22:25]
	s_nop 2
	v_mov_b64_e32 v[22:23], s[62:63]
	v_mfma_f32_16x16x32_bf16 v[90:93], v[208:211], v[18:21], v[94:97]
	v_mad_i64_i32 v[128:129], s[0:1], v0, s0, v[22:23]
	s_movk_i32 s0, 0x39f
	v_mfma_f32_16x16x32_bf16 v[82:85], v[212:215], v[18:21], v[188:191]
	v_cmp_lt_i32_e64 s[0:1], s0, v126
	v_mfma_f32_16x16x32_bf16 v[74:77], v[216:219], v[18:21], v[86:89]
	v_mfma_f32_16x16x32_bf16 v[66:69], v[220:223], v[18:21], v[146:149]
	v_mfma_f32_16x16x32_bf16 v[94:97], v[208:211], v[26:29], v[78:81]
	v_mfma_f32_16x16x32_bf16 v[86:89], v[212:215], v[26:29], v[192:195]
	v_mfma_f32_16x16x32_bf16 v[78:81], v[216:219], v[26:29], v[70:73]
	v_mfma_f32_16x16x32_bf16 v[70:73], v[220:223], v[26:29], v[150:153]
	v_mfma_f32_16x16x32_bf16 v[58:61], v[208:211], v[34:37], v[62:65]
	v_mfma_f32_16x16x32_bf16 v[50:53], v[212:215], v[34:37], v[196:199]
	v_mfma_f32_16x16x32_bf16 v[42:45], v[216:219], v[34:37], v[54:57]
	v_mfma_f32_16x16x32_bf16 v[34:37], v[220:223], v[34:37], v[154:157]
	v_mfma_f32_16x16x32_bf16 v[62:65], v[208:211], v[172:175], v[46:49]
	v_mfma_f32_16x16x32_bf16 v[54:57], v[212:215], v[172:175], v[200:203]
	v_mfma_f32_16x16x32_bf16 v[46:49], v[216:219], v[172:175], v[38:41]
	v_mfma_f32_16x16x32_bf16 v[38:41], v[220:223], v[172:175], v[158:161]
	v_mfma_f32_16x16x32_bf16 v[26:29], v[208:211], v[176:179], v[30:33]
	v_mfma_f32_16x16x32_bf16 v[18:21], v[212:215], v[176:179], v[204:207]
	v_mfma_f32_16x16x32_bf16 v[2:5], v[220:223], v[176:179], v[164:167]
	v_mfma_f32_16x16x32_bf16 v[30:33], v[208:211], v[180:183], v[14:17]
	v_mfma_f32_16x16x32_bf16 v[22:25], v[212:215], v[180:183], v[138:141]
	v_mfma_f32_16x16x32_bf16 v[14:17], v[216:219], v[180:183], v[6:9]
	v_mfma_f32_16x16x32_bf16 v[6:9], v[220:223], v[180:183], v[168:171]
	s_and_saveexec_b64 s[4:5], s[0:1]
	s_xor_b64 s[4:5], exec, s[4:5]
	s_cbranch_execz .LBB0_862
	s_movk_i32 s6, 0x820
	v_cmp_gt_u32_e32 vcc, s6, v126
	s_and_saveexec_b64 s[6:7], vcc
	s_cbranch_execz .LBB0_861
	v_mov_b32_e32 v127, v1
	v_lshl_add_u64 v[130:131], v[126:127], 1, v[128:129]
	v_add_co_u32_e32 v130, vcc, 0x47e0000, v130
	s_nop 1
	v_addc_co_u32_e32 v131, vcc, 0, v131, vcc
	flat_store_dwordx4 v[130:131], v[122:125] offset:2240

; template <int MI, int NI>
; DI void gemm256(f32x4 (&acc)[MI][NI], const u16* __restrict__ A, int lda, const u16* __restrict__ Bt, int ldb, int K, int m0, int n0, char* smem) {
;     ...
;   for (int kt = 0; kt < nk; ++kt) {
;     if (kt + 1 < nk) asm volatile("s_waitcnt vmcnt(%0) lgkmcnt(0)" :: "n"(LPS) : "memory");
;     else asm volatile("s_waitcnt vmcnt(0) lgkmcnt(0)" ::: "memory");
;     __builtin_amdgcn_s_barrier();
;     __builtin_amdgcn_s_setprio(1);
;     const char* sb = smem + st * STAGE + foff;
;     bf16x8 af[MI], bfr[NI];
; #pragma unroll
;     for (int mi = 0; mi < MI; ++mi) af[mi] = *(const bf16x8*)(sb + (wr * MI + mi) * 1024);
; #pragma unroll
;     for (int ni = 0; ni < NI; ++ni) bfr[ni] = *(const bf16x8*)(sb + ABYTES + (wc * NI + ni) * 1024);
;     __builtin_amdgcn_sched_barrier(0x0);
;     if (kt + 2 < nk) { const int s2 = st >= 1 ? st - 1 : 2; G256_ISSUE(s2, (kt + 2) * 32); }
;     __builtin_amdgcn_s_setprio(0);
; #pragma unroll
;     for (int mi = 0; mi < MI; ++mi)
; #pragma unroll
;       for (int ni = 0; ni < NI; ++ni)
;         acc[mi][ni] = __builtin_amdgcn_mfma_f32_16x16x32_bf16(bfr[ni], af[mi], acc[mi][ni], 0, 0, 0);
;     st = st == 2 ? 0 : st + 1;
;   }
.Lpipe_mlp2:
	v_add_u32_e32 v161, s11, v160
	ds_read_b128 v[156:159], v161 offset:4096
	ds_read_b128 v[164:167], v161 offset:5120
	ds_read_b128 v[168:171], v161 offset:6144
	ds_read_b128 v[172:175], v161 offset:7168
	s_add_i32 s12, s11, 0xffffa000
	s_cmp_eq_u32 s11, 0
	s_cselect_b32 s12, 0xc000, s12
	s_add_i32 s13, s12, s0
	s_add_i32 s12, s12, s1
	s_mov_b32 m0, s13
	s_waitcnt lgkmcnt(7)
	v_mfma_f32_16x16x32_bf16 v[126:129], v[176:179], v[140:143], v[126:129]
	global_load_lds_dwordx4 v[196:197], off
	v_mfma_f32_16x16x32_bf16 v[110:113], v[176:179], v[144:147], v[110:113]
	v_lshl_add_u64 v[196:197], v[196:197], 0, s[98:99]
	s_add_i32 m0, s13, 0x400
	v_mfma_f32_16x16x32_bf16 v[94:97], v[176:179], v[148:151], v[94:97]
	global_load_lds_dwordx4 v[198:199], off
	v_mfma_f32_16x16x32_bf16 v[78:81], v[176:179], v[152:155], v[78:81]
	v_lshl_add_u64 v[198:199], v[198:199], 0, s[98:99]
	s_add_i32 m0, s13, 0x800
	s_waitcnt lgkmcnt(6)
	v_mfma_f32_16x16x32_bf16 v[122:125], v[180:183], v[140:143], v[122:125]
	global_load_lds_dwordx4 v[200:201], off
	v_mfma_f32_16x16x32_bf16 v[106:109], v[180:183], v[144:147], v[106:109]
	v_lshl_add_u64 v[200:201], v[200:201], 0, s[98:99]
	s_add_i32 m0, s13, 0xc00
	v_mfma_f32_16x16x32_bf16 v[90:93], v[180:183], v[148:151], v[90:93]
	global_load_lds_dwordx4 v[202:203], off
	v_mfma_f32_16x16x32_bf16 v[74:77], v[180:183], v[152:155], v[74:77]
	v_lshl_add_u64 v[202:203], v[202:203], 0, s[98:99]
	s_mov_b32 m0, s12
	s_waitcnt lgkmcnt(5)
	v_mfma_f32_16x16x32_bf16 v[118:121], v[184:187], v[140:143], v[118:121]
	global_load_lds_dwordx4 v[204:205], off
	v_mfma_f32_16x16x32_bf16 v[102:105], v[184:187], v[144:147], v[102:105]
	v_lshl_add_u64 v[204:205], v[204:205], 0, s[98:99]
	s_add_i32 m0, s12, 0x400
	v_mfma_f32_16x16x32_bf16 v[86:89], v[184:187], v[148:151], v[86:89]
	global_load_lds_dwordx4 v[206:207], off
	v_mfma_f32_16x16x32_bf16 v[70:73], v[184:187], v[152:155], v[70:73]
	v_lshl_add_u64 v[206:207], v[206:207], 0, s[98:99]
	s_waitcnt lgkmcnt(4)
	v_mfma_f32_16x16x32_bf16 v[114:117], v[188:191], v[140:143], v[114:117]
	v_mfma_f32_16x16x32_bf16 v[98:101], v[188:191], v[144:147], v[98:101]
	v_mfma_f32_16x16x32_bf16 v[82:85], v[188:191], v[148:151], v[82:85]
	v_mfma_f32_16x16x32_bf16 v[66:69], v[188:191], v[152:155], v[66:69]
	s_waitcnt vmcnt(6) lgkmcnt(0)
	s_barrier
	s_add_i32 s13, s11, 0x6000
	s_cmp_eq_u32 s11, 0xc000
	s_cselect_b32 s11, 0, s13
	v_add_u32_e32 v192, s11, v160
	v_add_u32_e32 v193, s11, v0
	v_mfma_f32_16x16x32_bf16 v[62:65], v[176:179], v[156:159], v[62:65]
	ds_read_b128 v[140:143], v192
	v_mfma_f32_16x16x32_bf16 v[46:49], v[176:179], v[164:167], v[46:49]
	ds_read_b128 v[144:147], v192 offset:1024
	v_mfma_f32_16x16x32_bf16 v[30:33], v[176:179], v[168:171], v[30:33]
	ds_read_b128 v[148:151], v192 offset:2048
	v_mfma_f32_16x16x32_bf16 v[14:17], v[176:179], v[172:175], v[14:17]
	ds_read_b128 v[152:155], v192 offset:3072
	ds_read_b128 v[176:179], v193 offset:16384
	v_mfma_f32_16x16x32_bf16 v[58:61], v[180:183], v[156:159], v[58:61]
	v_mfma_f32_16x16x32_bf16 v[42:45], v[180:183], v[164:167], v[42:45]
	v_mfma_f32_16x16x32_bf16 v[26:29], v[180:183], v[168:171], v[26:29]
	v_mfma_f32_16x16x32_bf16 v[10:13], v[180:183], v[172:175], v[10:13]
	ds_read_b128 v[180:183], v193 offset:17408
	v_mfma_f32_16x16x32_bf16 v[54:57], v[184:187], v[156:159], v[54:57]
	v_mfma_f32_16x16x32_bf16 v[38:41], v[184:187], v[164:167], v[38:41]
	v_mfma_f32_16x16x32_bf16 v[22:25], v[184:187], v[168:171], v[22:25]
	v_mfma_f32_16x16x32_bf16 v[6:9], v[184:187], v[172:175], v[6:9]
	ds_read_b128 v[184:187], v193 offset:18432
	v_mfma_f32_16x16x32_bf16 v[50:53], v[188:191], v[156:159], v[50:53]
	v_mfma_f32_16x16x32_bf16 v[34:37], v[188:191], v[164:167], v[34:37]
	v_mfma_f32_16x16x32_bf16 v[18:21], v[188:191], v[168:171], v[18:21]
	v_mfma_f32_16x16x32_bf16 v[2:5], v[188:191], v[172:175], v[2:5]
	ds_read_b128 v[188:191], v193 offset:19456
	s_sub_i32 s100, s100, 1
	s_cmp_lg_u32 s100, 0
	s_cbranch_scc1 .Lpipe_mlp2
	v_add_u32_e32 v161, s11, v160
	ds_read_b128 v[156:159], v161 offset:4096
	ds_read_b128 v[164:167], v161 offset:5120
	ds_read_b128 v[168:171], v161 offset:6144
	ds_read_b128 v[172:175], v161 offset:7168
	s_add_i32 s12, s11, 0xffffa000
	s_cmp_eq_u32 s11, 0
	s_cselect_b32 s12, 0xc000, s12
	s_add_i32 s13, s12, s0
	s_add_i32 s12, s12, s1
	s_mov_b32 m0, s13
	s_waitcnt lgkmcnt(7)
	v_mfma_f32_16x16x32_bf16 v[126:129], v[176:179], v[140:143], v[126:129]
	global_load_lds_dwordx4 v[196:197], off
	v_mfma_f32_16x16x32_bf16 v[110:113], v[176:179], v[144:147], v[110:113]
	v_lshl_add_u64 v[196:197], v[196:197], 0, s[98:99]
	s_add_i32 m0, s13, 0x400
	v_mfma_f32_16x16x32_bf16 v[94:97], v[176:179], v[148:151], v[94:97]
	global_load_lds_dwordx4 v[198:199], off
	v_mfma_f32_16x16x32_bf16 v[78:81], v[176:179], v[152:155], v[78:81]
	v_lshl_add_u64 v[198:199], v[198:199], 0, s[98:99]
	s_add_i32 m0, s13, 0x800
	s_waitcnt lgkmcnt(6)
	v_mfma_f32_16x16x32_bf16 v[122:125], v[180:183], v[140:143], v[122:125]
	global_load_lds_dwordx4 v[200:201], off
	v_mfma_f32_16x16x32_bf16 v[106:109], v[180:183], v[144:147], v[106:109]
	v_lshl_add_u64 v[200:201], v[200:201], 0, s[98:99]
	s_add_i32 m0, s13, 0xc00
	v_mfma_f32_16x16x32_bf16 v[90:93], v[180:183], v[148:151], v[90:93]
	global_load_lds_dwordx4 v[202:203], off
	v_mfma_f32_16x16x32_bf16 v[74:77], v[180:183], v[152:155], v[74:77]
	v_lshl_add_u64 v[202:203], v[202:203], 0, s[98:99]
	s_mov_b32 m0, s12
	s_waitcnt lgkmcnt(5)
; template <int MI, int NI>
; DI void gemm256(f32x4 (&acc)[MI][NI], const u16* __restrict__ A, int lda, const u16* __restrict__ Bt, int ldb, int K, int m0, int n0, char* smem) {
;     ...
;   for (int kt = 0; kt < nk; ++kt) {
;     if (kt + 1 < nk) asm volatile("s_waitcnt vmcnt(%0) lgkmcnt(0)" :: "n"(LPS) : "memory");
;     else asm volatile("s_waitcnt vmcnt(0) lgkmcnt(0)" ::: "memory");
;     __builtin_amdgcn_s_barrier();
;     __builtin_amdgcn_s_setprio(1);
;     const char* sb = smem + st * STAGE + foff;
;     bf16x8 af[MI], bfr[NI];
; #pragma unroll
;     for (int mi = 0; mi < MI; ++mi) af[mi] = *(const bf16x8*)(sb + (wr * MI + mi) * 1024);
; #pragma unroll
;     for (int ni = 0; ni < NI; ++ni) bfr[ni] = *(const bf16x8*)(sb + ABYTES + (wc * NI + ni) * 1024);
;     __builtin_amdgcn_sched_barrier(0x0);
;     if (kt + 2 < nk) { const int s2 = st >= 1 ? st - 1 : 2; G256_ISSUE(s2, (kt + 2) * 32); }
;     __builtin_amdgcn_s_setprio(0);
; #pragma unroll
;     for (int mi = 0; mi < MI; ++mi)
; #pragma unroll
;       for (int ni = 0; ni < NI; ++ni)
;         acc[mi][ni] = __builtin_amdgcn_mfma_f32_16x16x32_bf16(bfr[ni], af[mi], acc[mi][ni], 0, 0, 0);
;     st = st == 2 ? 0 : st + 1;
;   }
;   asm volatile("s_waitcnt lgkmcnt(0)" ::: "memory");
;   __builtin_amdgcn_s_barrier();
	v_mfma_f32_16x16x32_bf16 v[118:121], v[184:187], v[140:143], v[118:121]
	global_load_lds_dwordx4 v[204:205], off
	v_mfma_f32_16x16x32_bf16 v[102:105], v[184:187], v[144:147], v[102:105]
	v_lshl_add_u64 v[204:205], v[204:205], 0, s[98:99]
	s_add_i32 m0, s12, 0x400
	v_mfma_f32_16x16x32_bf16 v[86:89], v[184:187], v[148:151], v[86:89]
	global_load_lds_dwordx4 v[206:207], off
	v_mfma_f32_16x16x32_bf16 v[70:73], v[184:187], v[152:155], v[70:73]
	v_lshl_add_u64 v[206:207], v[206:207], 0, s[98:99]
	s_waitcnt lgkmcnt(4)
	v_mfma_f32_16x16x32_bf16 v[114:117], v[188:191], v[140:143], v[114:117]
	v_mfma_f32_16x16x32_bf16 v[98:101], v[188:191], v[144:147], v[98:101]
	v_mfma_f32_16x16x32_bf16 v[82:85], v[188:191], v[148:151], v[82:85]
	v_mfma_f32_16x16x32_bf16 v[66:69], v[188:191], v[152:155], v[66:69]
	s_waitcnt lgkmcnt(0)
	v_mfma_f32_16x16x32_bf16 v[62:65], v[176:179], v[156:159], v[62:65]
	v_mfma_f32_16x16x32_bf16 v[46:49], v[176:179], v[164:167], v[46:49]
	v_mfma_f32_16x16x32_bf16 v[30:33], v[176:179], v[168:171], v[30:33]
	v_mfma_f32_16x16x32_bf16 v[14:17], v[176:179], v[172:175], v[14:17]
	v_mfma_f32_16x16x32_bf16 v[58:61], v[180:183], v[156:159], v[58:61]
	v_mfma_f32_16x16x32_bf16 v[42:45], v[180:183], v[164:167], v[42:45]
	v_mfma_f32_16x16x32_bf16 v[26:29], v[180:183], v[168:171], v[26:29]
	v_mfma_f32_16x16x32_bf16 v[10:13], v[180:183], v[172:175], v[10:13]
	v_mfma_f32_16x16x32_bf16 v[54:57], v[184:187], v[156:159], v[54:57]
	v_mfma_f32_16x16x32_bf16 v[38:41], v[184:187], v[164:167], v[38:41]
	v_mfma_f32_16x16x32_bf16 v[22:25], v[184:187], v[168:171], v[22:25]
	v_mfma_f32_16x16x32_bf16 v[6:9], v[184:187], v[172:175], v[6:9]
	v_mfma_f32_16x16x32_bf16 v[50:53], v[188:191], v[156:159], v[50:53]
	v_mfma_f32_16x16x32_bf16 v[34:37], v[188:191], v[164:167], v[34:37]
	v_mfma_f32_16x16x32_bf16 v[18:21], v[188:191], v[168:171], v[18:21]
	v_mfma_f32_16x16x32_bf16 v[2:5], v[188:191], v[172:175], v[2:5]
	s_mov_b32 s10, 0
	s_waitcnt vmcnt(6) lgkmcnt(0)
	s_barrier
	s_setprio 1
	s_mul_i32 s0, s10, 0x6000
	v_or_b32_e32 v0, s0, v138
	v_add_u32_e32 v136, v0, v139
	ds_read_b128 v[130:133], v136
	ds_read_b128 v[140:143], v136 offset:1024
	ds_read_b128 v[144:147], v136 offset:2048
	ds_read_b128 v[148:151], v136 offset:3072
	ds_read_b128 v[152:155], v136 offset:4096
	ds_read_b128 v[156:159], v136 offset:5120
	ds_read_b128 v[164:167], v136 offset:6144
	ds_read_b128 v[168:171], v136 offset:7168
	v_add_u32_e32 v0, v0, v135
	ds_read_b128 v[172:175], v0 offset:16384
	ds_read_b128 v[176:179], v0 offset:17408
	ds_read_b128 v[180:183], v0 offset:18432
	ds_read_b128 v[184:187], v0 offset:19456
	v_bfe_u32 v0, v134, 6, 1
	s_setprio 0
	s_waitcnt vmcnt(0) lgkmcnt(0)
	s_waitcnt lgkmcnt(3)
	v_mfma_f32_16x16x32_bf16 v[126:129], v[172:175], v[130:133], v[126:129]
	v_ashrrev_i32_e32 v160, 7, v134
	v_and_b32_e32 v161, 15, v134
	v_bfe_u32 v134, v134, 4, 2
	s_waitcnt lgkmcnt(2)
	v_mfma_f32_16x16x32_bf16 v[122:125], v[176:179], v[130:133], v[122:125]
	s_barrier
	s_waitcnt lgkmcnt(1)
	v_mfma_f32_16x16x32_bf16 v[118:121], v[180:183], v[130:133], v[118:121]
	s_waitcnt lgkmcnt(0)
	v_mfma_f32_16x16x32_bf16 v[114:117], v[184:187], v[130:133], v[114:117]
	v_mfma_f32_16x16x32_bf16 v[110:113], v[172:175], v[140:143], v[110:113]
	v_mfma_f32_16x16x32_bf16 v[106:109], v[176:179], v[140:143], v[106:109]
	v_mfma_f32_16x16x32_bf16 v[102:105], v[180:183], v[140:143], v[102:105]
	v_mfma_f32_16x16x32_bf16 v[98:101], v[184:187], v[140:143], v[98:101]
	v_mfma_f32_16x16x32_bf16 v[94:97], v[172:175], v[144:147], v[94:97]
	v_mfma_f32_16x16x32_bf16 v[90:93], v[176:179], v[144:147], v[90:93]
	v_mfma_f32_16x16x32_bf16 v[86:89], v[180:183], v[144:147], v[86:89]
	v_mfma_f32_16x16x32_bf16 v[82:85], v[184:187], v[144:147], v[82:85]
	v_mfma_f32_16x16x32_bf16 v[78:81], v[172:175], v[148:151], v[78:81]
	v_mfma_f32_16x16x32_bf16 v[130:133], v[176:179], v[148:151], v[74:77]
	v_mfma_f32_16x16x32_bf16 v[70:73], v[180:183], v[148:151], v[70:73]
	v_mfma_f32_16x16x32_bf16 v[66:69], v[184:187], v[148:151], v[66:69]
	v_mfma_f32_16x16x32_bf16 v[62:65], v[172:175], v[152:155], v[62:65]
	v_mfma_f32_16x16x32_bf16 v[58:61], v[176:179], v[152:155], v[58:61]
	v_mfma_f32_16x16x32_bf16 v[54:57], v[180:183], v[152:155], v[54:57]
	v_mfma_f32_16x16x32_bf16 v[50:53], v[184:187], v[152:155], v[50:53]
	v_mfma_f32_16x16x32_bf16 v[46:49], v[172:175], v[156:159], v[46:49]
	v_mfma_f32_16x16x32_bf16 v[42:45], v[176:179], v[156:159], v[42:45]
	v_mfma_f32_16x16x32_bf16 v[38:41], v[180:183], v[156:159], v[38:41]
	v_mfma_f32_16x16x32_bf16 v[34:37], v[184:187], v[156:159], v[34:37]
	v_mfma_f32_16x16x32_bf16 v[30:33], v[172:175], v[164:167], v[30:33]
	v_mfma_f32_16x16x32_bf16 v[26:29], v[176:179], v[164:167], v[26:29]
	v_mfma_f32_16x16x32_bf16 v[22:25], v[180:183], v[164:167], v[22:25]
	v_mfma_f32_16x16x32_bf16 v[18:21], v[184:187], v[164:167], v[18:21]
	v_mfma_f32_16x16x32_bf16 v[14:17], v[172:175], v[168:171], v[14:17]
	v_mfma_f32_16x16x32_bf16 v[10:13], v[176:179], v[168:171], v[10:13]
	v_mfma_f32_16x16x32_bf16 v[6:9], v[180:183], v[168:171], v[6:9]
	v_mfma_f32_16x16x32_bf16 v[140:143], v[184:187], v[168:171], v[2:5]
	s_setprio 1
	s_addk_i32 s0, 0x6000
	s_cmp_lg_u32 s10, 2
	s_cselect_b32 s0, s0, 0
	v_or_b32_e32 v168, s0, v138
	v_add_u32_e32 v164, v168, v139
	ds_read_b128 v[2:5], v164
	ds_read_b128 v[74:77], v164 offset:1024
	ds_read_b128 v[136:139], v164 offset:2048
	ds_read_b128 v[144:147], v164 offset:3072
	ds_read_b128 v[148:151], v164 offset:4096
	ds_read_b128 v[152:155], v164 offset:5120
	ds_read_b128 v[156:159], v164 offset:6144
	ds_read_b128 v[164:167], v164 offset:7168
	v_add_u32_e32 v135, v168, v135
	ds_read_b128 v[168:171], v135 offset:16384
	ds_read_b128 v[172:175], v135 offset:17408
	ds_read_b128 v[176:179], v135 offset:18432
	ds_read_b128 v[180:183], v135 offset:19456
	s_setprio 0
	s_waitcnt lgkmcnt(3)
	v_mfma_f32_16x16x32_bf16 v[126:129], v[168:171], v[2:5], v[126:129]
	s_waitcnt lgkmcnt(0)
	s_barrier
; template <int MI, int NI>
; DI void gemm256(f32x4 (&acc)[MI][NI], const u16* __restrict__ A, int lda, const u16* __restrict__ Bt, int ldb, int K, int m0, int n0, char* smem) {
;     ...
; #pragma unroll
;     for (int mi = 0; mi < MI; ++mi)
; #pragma unroll
;       for (int ni = 0; ni < NI; ++ni)
;         acc[mi][ni] = __builtin_amdgcn_mfma_f32_16x16x32_bf16(bfr[ni], af[mi], acc[mi][ni], 0, 0, 0);
; template <int MI, int NI>
; DI void resid_tile(const u16* A, int K, const u16* Bt, const float* gate, const float* xl_in, const float* xc_in, float* xl_out, float* xc_out,
;                    int m0, int n0, char* smem) {
;     ...
; #pragma unroll
;   for (int mi = 0; mi < MI; ++mi) {
;     const int m = m0 + wr * 16 * MI + mi * 16 + lr;
;     const int b9 = m < NTL ? m >> 12 : 8;
;     const float* xi = xrow(xl_in, xc_in, m);
;     float* xo = m < NTL ? xl_out + (size_t)m * D : xc_out + (size_t)(m - NTL) * D;
; #pragma unroll
;     for (int ni = 0; ni < NI; ++ni) {
;       const int n = n0 + wc * 16 * NI + ni * 16 + lq * 4;
;       const float4 g = *(const float4*)(gate + (size_t)b9 * 6144 + n);
;       const float4 xv = *(const float4*)(xi + n);
;       float4 ov;
;       ov.x = xv.x + g.x * acc[mi][ni][0]; ov.y = xv.y + g.y * acc[mi][ni][1]; ov.z = xv.z + g.z * acc[mi][ni][2]; ov.w = xv.w + g.w * acc[mi][ni][3];
;       *(float4*)(xo + n) = ov;
;     }
	s_waitcnt lgkmcnt(2)
	v_mfma_f32_16x16x32_bf16 v[122:125], v[172:175], v[2:5], v[122:125]
	s_waitcnt lgkmcnt(1)
	v_mfma_f32_16x16x32_bf16 v[184:187], v[176:179], v[2:5], v[118:121]
	v_lshlrev_b32_e32 v0, 6, v0
	s_waitcnt lgkmcnt(0)
	v_mfma_f32_16x16x32_bf16 v[188:191], v[180:183], v[2:5], v[114:117]
	v_lshlrev_b32_e32 v2, 7, v160
	v_mov_b32_e32 v118, s95
	v_mov_b32_e32 v119, s49
	v_add3_u32 v116, v161, s8, v2
	v_lshlrev_b32_e32 v2, 2, v134
	v_add3_u32 v2, v2, s9, v0
	v_min_i32_e32 v0, 0x8000, v116
	v_mfma_f32_16x16x32_bf16 v[110:113], v[168:171], v[74:77], v[110:113]
	v_ashrrev_i32_e32 v117, 31, v116
	v_cmp_gt_i32_e32 vcc, s58, v116
	v_mov_b32_e32 v120, s94
	v_mfma_f32_16x16x32_bf16 v[106:109], v[172:175], v[74:77], v[106:109]
	v_cndmask_b32_e32 v5, 0, v117, vcc
	v_mov_b32_e32 v121, s48
	v_cndmask_b32_e32 v115, v118, v119, vcc
	v_mfma_f32_16x16x32_bf16 v[102:105], v[176:179], v[74:77], v[102:105]
	v_cndmask_b32_e32 v114, v120, v121, vcc
	v_ashrrev_i32_e32 v3, 31, v2
	v_mfma_f32_16x16x32_bf16 v[98:101], v[180:183], v[74:77], v[98:101]
	v_mfma_f32_16x16x32_bf16 v[74:77], v[168:171], v[144:147], v[78:81]
	v_mfma_f32_16x16x32_bf16 v[78:81], v[172:175], v[144:147], v[130:133]
	s_nop 2
	v_ashrrev_i32_e32 v130, 12, v0
	v_add_u32_e32 v0, 0xffff8000, v116
	v_cndmask_b32_e32 v4, v0, v116, vcc
	v_lshlrev_b64 v[4:5], 12, v[4:5]
	v_lshl_add_u64 v[4:5], v[114:115], 0, v[4:5]
	v_mul_hi_i32_i24_e32 v115, 0x6000, v130
	v_mul_i32_i24_e32 v114, 0x6000, v130
	v_lshl_add_u64 v[130:131], s[82:83], 0, v[114:115]
	v_lshlrev_b64 v[114:115], 2, v[2:3]
	v_mfma_f32_16x16x32_bf16 v[94:97], v[168:171], v[136:139], v[94:97]
	v_lshl_add_u64 v[134:135], v[130:131], 0, v[114:115]
	v_mfma_f32_16x16x32_bf16 v[90:93], v[172:175], v[136:139], v[90:93]
	v_mfma_f32_16x16x32_bf16 v[86:89], v[176:179], v[136:139], v[86:89]
	v_mfma_f32_16x16x32_bf16 v[82:85], v[180:183], v[136:139], v[82:85]
	v_lshl_add_u64 v[136:137], v[4:5], 0, v[114:115]
	flat_load_dwordx4 v[2:5], v[134:135]
	flat_load_dwordx4 v[130:133], v[136:137]
	v_mfma_f32_16x16x32_bf16 v[70:73], v[176:179], v[144:147], v[70:73]
	v_lshlrev_b64 v[138:139], 12, v[116:117]
	v_lshl_add_u64 v[138:139], s[48:49], 0, v[138:139]
	s_waitcnt vmcnt(0) lgkmcnt(0)
	v_pk_fma_f32 v[2:3], v[126:127], v[2:3], v[130:131]
	v_mfma_f32_16x16x32_bf16 v[66:69], v[180:183], v[144:147], v[66:69]
	v_lshlrev_b64 v[144:145], 12, v[0:1]
	v_lshl_add_u64 v[144:145], s[94:95], 0, v[144:145]
	v_cndmask_b32_e32 v139, v145, v139, vcc
	v_cndmask_b32_e32 v138, v144, v138, vcc
	v_lshl_add_u64 v[138:139], v[138:139], 0, v[114:115]
	v_pk_fma_f32 v[4:5], v[128:129], v[4:5], v[132:133]
	flat_store_dwordx4 v[138:139], v[2:5]
	flat_load_dwordx4 v[126:129], v[134:135] offset:64
	flat_load_dwordx4 v[130:133], v[136:137] offset:64
	v_mfma_f32_16x16x32_bf16 v[2:5], v[172:175], v[164:167], v[10:13]
	v_mfma_f32_16x16x32_bf16 v[62:65], v[168:171], v[148:151], v[62:65]
	s_waitcnt vmcnt(0) lgkmcnt(0)
	s_nop 0
	v_pk_fma_f32 v[10:11], v[122:123], v[126:127], v[130:131]
	v_pk_fma_f32 v[12:13], v[124:125], v[128:129], v[132:133]
	flat_store_dwordx4 v[138:139], v[10:13] offset:64
	flat_load_dwordx4 v[10:13], v[134:135] offset:128
	s_nop 0
	flat_load_dwordx4 v[122:125], v[136:137] offset:128
	v_mfma_f32_16x16x32_bf16 v[58:61], v[172:175], v[148:151], v[58:61]
	s_waitcnt vmcnt(0) lgkmcnt(0)
	v_pk_fma_f32 v[10:11], v[184:185], v[10:11], v[122:123]
	v_pk_fma_f32 v[12:13], v[186:187], v[12:13], v[124:125]
	flat_store_dwordx4 v[138:139], v[10:13] offset:128
	flat_load_dwordx4 v[122:125], v[134:135] offset:192
	flat_load_dwordx4 v[126:129], v[136:137] offset:192
	v_mfma_f32_16x16x32_bf16 v[54:57], v[176:179], v[148:151], v[54:57]
	s_waitcnt vmcnt(0) lgkmcnt(0)
	v_pk_fma_f32 v[122:123], v[188:189], v[122:123], v[126:127]
	v_pk_fma_f32 v[124:125], v[190:191], v[124:125], v[128:129]
	v_mfma_f32_16x16x32_bf16 v[50:53], v[180:183], v[148:151], v[50:53]
	flat_store_dwordx4 v[138:139], v[122:125] offset:192
	v_mfma_f32_16x16x32_bf16 v[46:49], v[168:171], v[152:155], v[46:49]
	v_mfma_f32_16x16x32_bf16 v[42:45], v[172:175], v[152:155], v[42:45]
	v_mfma_f32_16x16x32_bf16 v[38:41], v[176:179], v[152:155], v[38:41]
	v_mfma_f32_16x16x32_bf16 v[34:37], v[180:183], v[152:155], v[34:37]
	v_mfma_f32_16x16x32_bf16 v[30:33], v[168:171], v[156:159], v[30:33]
	v_mfma_f32_16x16x32_bf16 v[26:29], v[172:175], v[156:159], v[26:29]
	v_mfma_f32_16x16x32_bf16 v[22:25], v[176:179], v[156:159], v[22:25]
	v_mfma_f32_16x16x32_bf16 v[18:21], v[180:183], v[156:159], v[18:21]
	v_mfma_f32_16x16x32_bf16 v[14:17], v[168:171], v[164:167], v[14:17]
	v_mfma_f32_16x16x32_bf16 v[6:9], v[176:179], v[164:167], v[6:9]
	v_mfma_f32_16x16x32_bf16 v[10:13], v[180:183], v[164:167], v[140:143]
	v_add_u32_e32 v122, 16, v116
	v_min_i32_e32 v0, 0x8000, v122
	v_cmp_gt_i32_e32 vcc, s58, v122
	v_ashrrev_i32_e32 v117, 12, v0
	v_add_u32_e32 v0, 0xffff8010, v116
	v_ashrrev_i32_e32 v123, 31, v122
	v_cndmask_b32_e32 v125, 0, v123, vcc
	v_cndmask_b32_e32 v124, v0, v122, vcc
	v_cndmask_b32_e32 v127, v118, v119, vcc
	v_cndmask_b32_e32 v126, v120, v121, vcc
	v_lshlrev_b64 v[124:125], 12, v[124:125]
	v_lshl_add_u64 v[124:125], v[126:127], 0, v[124:125]
	v_lshlrev_b64 v[122:123], 12, v[122:123]
	v_lshlrev_b64 v[126:127], 12, v[0:1]
	v_lshl_add_u64 v[122:123], s[48:49], 0, v[122:123]
	v_lshl_add_u64 v[126:127], s[94:95], 0, v[126:127]
	v_cndmask_b32_e32 v123, v127, v123, vcc
	v_cndmask_b32_e32 v122, v126, v122, vcc
	v_mul_hi_i32_i24_e32 v127, 0x6000, v117
	v_mul_i32_i24_e32 v126, 0x6000, v117
	v_lshl_add_u64 v[126:127], s[82:83], 0, v[126:127]
	v_lshl_add_u64 v[130:131], v[126:127], 0, v[114:115]
	v_lshl_add_u64 v[132:133], v[124:125], 0, v[114:115]
	v_lshl_add_u64 v[134:135], v[122:123], 0, v[114:115]
	flat_load_dwordx4 v[122:125], v[130:131]
	flat_load_dwordx4 v[126:129], v[132:133]
	s_waitcnt vmcnt(0) lgkmcnt(0)
; template <int MI, int NI>
; DI void resid_tile(const u16* A, int K, const u16* Bt, const float* gate, const float* xl_in, const float* xc_in, float* xl_out, float* xc_out,
;                    int m0, int n0, char* smem) {
;     ...
; #pragma unroll
;   for (int mi = 0; mi < MI; ++mi) {
;     const int m = m0 + wr * 16 * MI + mi * 16 + lr;
;     const int b9 = m < NTL ? m >> 12 : 8;
;     const float* xi = xrow(xl_in, xc_in, m);
;     float* xo = m < NTL ? xl_out + (size_t)m * D : xc_out + (size_t)(m - NTL) * D;
; #pragma unroll
;     for (int ni = 0; ni < NI; ++ni) {
;       const int n = n0 + wc * 16 * NI + ni * 16 + lq * 4;
;       const float4 g = *(const float4*)(gate + (size_t)b9 * 6144 + n);
;       const float4 xv = *(const float4*)(xi + n);
;       float4 ov;
;       ov.x = xv.x + g.x * acc[mi][ni][0]; ov.y = xv.y + g.y * acc[mi][ni][1]; ov.z = xv.z + g.z * acc[mi][ni][2]; ov.w = xv.w + g.w * acc[mi][ni][3];
;       *(float4*)(xo + n) = ov;
;     }
;     __builtin_amdgcn_sched_barrier(0);
;   }
	v_pk_fma_f32 v[110:111], v[110:111], v[122:123], v[126:127]
	v_pk_fma_f32 v[112:113], v[112:113], v[124:125], v[128:129]
	flat_store_dwordx4 v[134:135], v[110:113]
	flat_load_dwordx4 v[110:113], v[130:131] offset:64
	s_nop 0
	flat_load_dwordx4 v[122:125], v[132:133] offset:64
	s_waitcnt vmcnt(0) lgkmcnt(0)
	v_pk_fma_f32 v[106:107], v[106:107], v[110:111], v[122:123]
	v_pk_fma_f32 v[108:109], v[108:109], v[112:113], v[124:125]
	flat_store_dwordx4 v[134:135], v[106:109] offset:64
	flat_load_dwordx4 v[106:109], v[130:131] offset:128
	s_nop 0
	flat_load_dwordx4 v[110:113], v[132:133] offset:128
	s_waitcnt vmcnt(0) lgkmcnt(0)
	v_pk_fma_f32 v[102:103], v[102:103], v[106:107], v[110:111]
	v_pk_fma_f32 v[104:105], v[104:105], v[108:109], v[112:113]
	flat_store_dwordx4 v[134:135], v[102:105] offset:128
	flat_load_dwordx4 v[102:105], v[130:131] offset:192
	s_nop 0
	flat_load_dwordx4 v[106:109], v[132:133] offset:192
	s_waitcnt vmcnt(0) lgkmcnt(0)
	v_pk_fma_f32 v[98:99], v[98:99], v[102:103], v[106:107]
	v_pk_fma_f32 v[100:101], v[100:101], v[104:105], v[108:109]
	flat_store_dwordx4 v[134:135], v[98:101] offset:192
	s_nop 1
	v_add_u32_e32 v98, 32, v116
	v_min_i32_e32 v0, 0x8000, v98
	v_cmp_gt_i32_e32 vcc, s58, v98
	v_ashrrev_i32_e32 v104, 12, v0
	v_add_u32_e32 v0, 0xffff8020, v116
	v_ashrrev_i32_e32 v99, 31, v98
	v_cndmask_b32_e32 v101, 0, v99, vcc
	v_cndmask_b32_e32 v100, v0, v98, vcc
	v_cndmask_b32_e32 v103, v118, v119, vcc
	v_cndmask_b32_e32 v102, v120, v121, vcc
	v_lshlrev_b64 v[100:101], 12, v[100:101]
	v_lshl_add_u64 v[100:101], v[102:103], 0, v[100:101]
	v_lshlrev_b64 v[98:99], 12, v[98:99]
	v_lshlrev_b64 v[102:103], 12, v[0:1]
	v_lshl_add_u64 v[98:99], s[48:49], 0, v[98:99]
	v_lshl_add_u64 v[102:103], s[94:95], 0, v[102:103]
	v_cndmask_b32_e32 v99, v103, v99, vcc
	v_cndmask_b32_e32 v98, v102, v98, vcc
	v_mul_hi_i32_i24_e32 v103, 0x6000, v104
	v_mul_i32_i24_e32 v102, 0x6000, v104
	v_lshl_add_u64 v[102:103], s[82:83], 0, v[102:103]
	v_lshl_add_u64 v[106:107], v[102:103], 0, v[114:115]
	v_lshl_add_u64 v[108:109], v[100:101], 0, v[114:115]
	v_lshl_add_u64 v[110:111], v[98:99], 0, v[114:115]
	flat_load_dwordx4 v[98:101], v[106:107]
	flat_load_dwordx4 v[102:105], v[108:109]
	s_waitcnt vmcnt(0) lgkmcnt(0)
	v_pk_fma_f32 v[94:95], v[94:95], v[98:99], v[102:103]
	v_pk_fma_f32 v[96:97], v[96:97], v[100:101], v[104:105]
	flat_store_dwordx4 v[110:111], v[94:97]
	flat_load_dwordx4 v[94:97], v[106:107] offset:64
	s_nop 0
	flat_load_dwordx4 v[98:101], v[108:109] offset:64
	s_waitcnt vmcnt(0) lgkmcnt(0)
	v_pk_fma_f32 v[90:91], v[90:91], v[94:95], v[98:99]
	v_pk_fma_f32 v[92:93], v[92:93], v[96:97], v[100:101]
	flat_store_dwordx4 v[110:111], v[90:93] offset:64
	flat_load_dwordx4 v[90:93], v[106:107] offset:128
	s_nop 0
	flat_load_dwordx4 v[94:97], v[108:109] offset:128
	s_waitcnt vmcnt(0) lgkmcnt(0)
	v_pk_fma_f32 v[86:87], v[86:87], v[90:91], v[94:95]
	v_pk_fma_f32 v[88:89], v[88:89], v[92:93], v[96:97]
	flat_store_dwordx4 v[110:111], v[86:89] offset:128
	flat_load_dwordx4 v[86:89], v[106:107] offset:192
	s_nop 0
	flat_load_dwordx4 v[90:93], v[108:109] offset:192
	s_waitcnt vmcnt(0) lgkmcnt(0)
	v_pk_fma_f32 v[82:83], v[82:83], v[86:87], v[90:91]
	v_pk_fma_f32 v[84:85], v[84:85], v[88:89], v[92:93]
	flat_store_dwordx4 v[110:111], v[82:85] offset:192
	s_nop 1
	v_add_u32_e32 v82, 48, v116
	v_min_i32_e32 v0, 0x8000, v82
	v_cmp_gt_i32_e32 vcc, s58, v82
	v_ashrrev_i32_e32 v88, 12, v0
	v_add_u32_e32 v0, 0xffff8030, v116
	v_ashrrev_i32_e32 v83, 31, v82
	v_cndmask_b32_e32 v85, 0, v83, vcc
	v_cndmask_b32_e32 v84, v0, v82, vcc
	v_cndmask_b32_e32 v87, v118, v119, vcc
	v_cndmask_b32_e32 v86, v120, v121, vcc
	v_lshlrev_b64 v[84:85], 12, v[84:85]
	v_lshl_add_u64 v[84:85], v[86:87], 0, v[84:85]
	v_lshlrev_b64 v[82:83], 12, v[82:83]
	v_lshlrev_b64 v[86:87], 12, v[0:1]
	v_lshl_add_u64 v[82:83], s[48:49], 0, v[82:83]
	v_lshl_add_u64 v[86:87], s[94:95], 0, v[86:87]
	v_cndmask_b32_e32 v83, v87, v83, vcc
	v_cndmask_b32_e32 v82, v86, v82, vcc
	v_mul_hi_i32_i24_e32 v87, 0x6000, v88
	v_mul_i32_i24_e32 v86, 0x6000, v88
	v_lshl_add_u64 v[86:87], s[82:83], 0, v[86:87]
	v_lshl_add_u64 v[90:91], v[86:87], 0, v[114:115]
	v_lshl_add_u64 v[92:93], v[84:85], 0, v[114:115]
	v_lshl_add_u64 v[94:95], v[82:83], 0, v[114:115]
	flat_load_dwordx4 v[82:85], v[90:91]
	flat_load_dwordx4 v[86:89], v[92:93]
	s_waitcnt vmcnt(0) lgkmcnt(0)
	v_pk_fma_f32 v[74:75], v[74:75], v[82:83], v[86:87]
	v_pk_fma_f32 v[76:77], v[76:77], v[84:85], v[88:89]
	flat_store_dwordx4 v[94:95], v[74:77]
	flat_load_dwordx4 v[74:77], v[90:91] offset:64
	s_nop 0
	flat_load_dwordx4 v[82:85], v[92:93] offset:64
	s_waitcnt vmcnt(0) lgkmcnt(0)
	v_pk_fma_f32 v[74:75], v[78:79], v[74:75], v[82:83]
	v_pk_fma_f32 v[76:77], v[80:81], v[76:77], v[84:85]
	flat_store_dwordx4 v[94:95], v[74:77] offset:64
	flat_load_dwordx4 v[74:77], v[90:91] offset:128
	s_nop 0
	flat_load_dwordx4 v[78:81], v[92:93] offset:128
	s_waitcnt vmcnt(0) lgkmcnt(0)
	v_pk_fma_f32 v[70:71], v[70:71], v[74:75], v[78:79]
	v_pk_fma_f32 v[72:73], v[72:73], v[76:77], v[80:81]
	flat_store_dwordx4 v[94:95], v[70:73] offset:128
	flat_load_dwordx4 v[70:73], v[90:91] offset:192
	s_nop 0
	flat_load_dwordx4 v[74:77], v[92:93] offset:192
	s_waitcnt vmcnt(0) lgkmcnt(0)
; template <int MI, int NI>
; DI void resid_tile(const u16* A, int K, const u16* Bt, const float* gate, const float* xl_in, const float* xc_in, float* xl_out, float* xc_out,
;                    int m0, int n0, char* smem) {
;     ...
; #pragma unroll
;   for (int mi = 0; mi < MI; ++mi) {
;     const int m = m0 + wr * 16 * MI + mi * 16 + lr;
;     const int b9 = m < NTL ? m >> 12 : 8;
;     const float* xi = xrow(xl_in, xc_in, m);
;     float* xo = m < NTL ? xl_out + (size_t)m * D : xc_out + (size_t)(m - NTL) * D;
; #pragma unroll
;     for (int ni = 0; ni < NI; ++ni) {
;       const int n = n0 + wc * 16 * NI + ni * 16 + lq * 4;
;       const float4 g = *(const float4*)(gate + (size_t)b9 * 6144 + n);
;       const float4 xv = *(const float4*)(xi + n);
;       float4 ov;
;       ov.x = xv.x + g.x * acc[mi][ni][0]; ov.y = xv.y + g.y * acc[mi][ni][1]; ov.z = xv.z + g.z * acc[mi][ni][2]; ov.w = xv.w + g.w * acc[mi][ni][3];
;       *(float4*)(xo + n) = ov;
;     }
;     __builtin_amdgcn_sched_barrier(0);
;   }
	v_pk_fma_f32 v[66:67], v[66:67], v[70:71], v[74:75]
	v_pk_fma_f32 v[68:69], v[68:69], v[72:73], v[76:77]
	flat_store_dwordx4 v[94:95], v[66:69] offset:192
	s_nop 1
	v_add_u32_e32 v66, 64, v116
	v_min_i32_e32 v0, 0x8000, v66
	v_cmp_gt_i32_e32 vcc, s58, v66
	v_ashrrev_i32_e32 v72, 12, v0
	v_add_u32_e32 v0, 0xffff8040, v116
	v_ashrrev_i32_e32 v67, 31, v66
	v_cndmask_b32_e32 v69, 0, v67, vcc
	v_cndmask_b32_e32 v68, v0, v66, vcc
	v_cndmask_b32_e32 v71, v118, v119, vcc
	v_cndmask_b32_e32 v70, v120, v121, vcc
	v_lshlrev_b64 v[68:69], 12, v[68:69]
	v_lshl_add_u64 v[68:69], v[70:71], 0, v[68:69]
	v_lshlrev_b64 v[66:67], 12, v[66:67]
	v_lshlrev_b64 v[70:71], 12, v[0:1]
	v_lshl_add_u64 v[66:67], s[48:49], 0, v[66:67]
	v_lshl_add_u64 v[70:71], s[94:95], 0, v[70:71]
	v_cndmask_b32_e32 v67, v71, v67, vcc
	v_cndmask_b32_e32 v66, v70, v66, vcc
	v_mul_hi_i32_i24_e32 v71, 0x6000, v72
	v_mul_i32_i24_e32 v70, 0x6000, v72
	v_lshl_add_u64 v[70:71], s[82:83], 0, v[70:71]
	v_lshl_add_u64 v[74:75], v[70:71], 0, v[114:115]
	v_lshl_add_u64 v[76:77], v[68:69], 0, v[114:115]
	v_lshl_add_u64 v[78:79], v[66:67], 0, v[114:115]
	flat_load_dwordx4 v[66:69], v[74:75]
	flat_load_dwordx4 v[70:73], v[76:77]
	s_waitcnt vmcnt(0) lgkmcnt(0)
	v_pk_fma_f32 v[62:63], v[62:63], v[66:67], v[70:71]
	v_pk_fma_f32 v[64:65], v[64:65], v[68:69], v[72:73]
	flat_store_dwordx4 v[78:79], v[62:65]
	flat_load_dwordx4 v[62:65], v[74:75] offset:64
	s_nop 0
	flat_load_dwordx4 v[66:69], v[76:77] offset:64
	s_waitcnt vmcnt(0) lgkmcnt(0)
	v_pk_fma_f32 v[58:59], v[58:59], v[62:63], v[66:67]
	v_pk_fma_f32 v[60:61], v[60:61], v[64:65], v[68:69]
	flat_store_dwordx4 v[78:79], v[58:61] offset:64
	flat_load_dwordx4 v[58:61], v[74:75] offset:128
	s_nop 0
	flat_load_dwordx4 v[62:65], v[76:77] offset:128
	s_waitcnt vmcnt(0) lgkmcnt(0)
	v_pk_fma_f32 v[54:55], v[54:55], v[58:59], v[62:63]
	v_pk_fma_f32 v[56:57], v[56:57], v[60:61], v[64:65]
	flat_store_dwordx4 v[78:79], v[54:57] offset:128
	flat_load_dwordx4 v[54:57], v[74:75] offset:192
	s_nop 0
	flat_load_dwordx4 v[58:61], v[76:77] offset:192
	s_waitcnt vmcnt(0) lgkmcnt(0)
	v_pk_fma_f32 v[50:51], v[50:51], v[54:55], v[58:59]
	v_pk_fma_f32 v[52:53], v[52:53], v[56:57], v[60:61]
	flat_store_dwordx4 v[78:79], v[50:53] offset:192
	s_nop 1
	v_add_u32_e32 v50, 0x50, v116
	v_min_i32_e32 v0, 0x8000, v50
	v_cmp_gt_i32_e32 vcc, s58, v50
	v_ashrrev_i32_e32 v56, 12, v0
	v_add_u32_e32 v0, 0xffff8050, v116
	v_ashrrev_i32_e32 v51, 31, v50
	v_cndmask_b32_e32 v53, 0, v51, vcc
	v_cndmask_b32_e32 v52, v0, v50, vcc
	v_cndmask_b32_e32 v55, v118, v119, vcc
	v_cndmask_b32_e32 v54, v120, v121, vcc
	v_lshlrev_b64 v[52:53], 12, v[52:53]
	v_lshl_add_u64 v[52:53], v[54:55], 0, v[52:53]
	v_lshlrev_b64 v[50:51], 12, v[50:51]
	v_lshlrev_b64 v[54:55], 12, v[0:1]
	v_lshl_add_u64 v[50:51], s[48:49], 0, v[50:51]
	v_lshl_add_u64 v[54:55], s[94:95], 0, v[54:55]
	v_cndmask_b32_e32 v51, v55, v51, vcc
	v_cndmask_b32_e32 v50, v54, v50, vcc
	v_mul_hi_i32_i24_e32 v55, 0x6000, v56
	v_mul_i32_i24_e32 v54, 0x6000, v56
	v_lshl_add_u64 v[54:55], s[82:83], 0, v[54:55]
	v_lshl_add_u64 v[58:59], v[54:55], 0, v[114:115]
	v_lshl_add_u64 v[60:61], v[52:53], 0, v[114:115]
	v_lshl_add_u64 v[62:63], v[50:51], 0, v[114:115]
	flat_load_dwordx4 v[50:53], v[58:59]
	flat_load_dwordx4 v[54:57], v[60:61]
	s_waitcnt vmcnt(0) lgkmcnt(0)
	v_pk_fma_f32 v[46:47], v[46:47], v[50:51], v[54:55]
	v_pk_fma_f32 v[48:49], v[48:49], v[52:53], v[56:57]
	flat_store_dwordx4 v[62:63], v[46:49]
	flat_load_dwordx4 v[46:49], v[58:59] offset:64
	s_nop 0
	flat_load_dwordx4 v[50:53], v[60:61] offset:64
	s_waitcnt vmcnt(0) lgkmcnt(0)
	v_pk_fma_f32 v[42:43], v[42:43], v[46:47], v[50:51]
	v_pk_fma_f32 v[44:45], v[44:45], v[48:49], v[52:53]
	flat_store_dwordx4 v[62:63], v[42:45] offset:64
	flat_load_dwordx4 v[42:45], v[58:59] offset:128
	s_nop 0
	flat_load_dwordx4 v[46:49], v[60:61] offset:128
	s_waitcnt vmcnt(0) lgkmcnt(0)
	v_pk_fma_f32 v[38:39], v[38:39], v[42:43], v[46:47]
	v_pk_fma_f32 v[40:41], v[40:41], v[44:45], v[48:49]
	flat_store_dwordx4 v[62:63], v[38:41] offset:128
	flat_load_dwordx4 v[38:41], v[58:59] offset:192
	s_nop 0
	flat_load_dwordx4 v[42:45], v[60:61] offset:192
	s_waitcnt vmcnt(0) lgkmcnt(0)
; template <int MI, int NI>
; DI void resid_tile(const u16* A, int K, const u16* Bt, const float* gate, const float* xl_in, const float* xc_in, float* xl_out, float* xc_out,
;                    int m0, int n0, char* smem) {
;     ...
; #pragma unroll
;   for (int mi = 0; mi < MI; ++mi) {
;     const int m = m0 + wr * 16 * MI + mi * 16 + lr;
;     const int b9 = m < NTL ? m >> 12 : 8;
;     const float* xi = xrow(xl_in, xc_in, m);
;     float* xo = m < NTL ? xl_out + (size_t)m * D : xc_out + (size_t)(m - NTL) * D;
; #pragma unroll
;     for (int ni = 0; ni < NI; ++ni) {
;       const int n = n0 + wc * 16 * NI + ni * 16 + lq * 4;
;       const float4 g = *(const float4*)(gate + (size_t)b9 * 6144 + n);
;       const float4 xv = *(const float4*)(xi + n);
;       float4 ov;
;       ov.x = xv.x + g.x * acc[mi][ni][0]; ov.y = xv.y + g.y * acc[mi][ni][1]; ov.z = xv.z + g.z * acc[mi][ni][2]; ov.w = xv.w + g.w * acc[mi][ni][3];
;       *(float4*)(xo + n) = ov;
;     }
;     __builtin_amdgcn_sched_barrier(0);
;   }
; DI void phase_resid(const Params& p, const u16* A, int K, const u16* Bt, const float* gate  ,
;                     const float* xl_in, const float* xc_in, float* xl_out, float* xc_out, int Mout, char* smem) {
;     ...
;   for (int it = 0;; ++it) {
;     int tm, tn;
;     if (!tile_map(it, NTL / 256, 8, blk__, gridDim.x, tm, tn)) break;
;     resid_tile<8, 4>(A, K, Bt, gate, xl_in, xc_in, xl_out, xc_out, tm * 256, tn * 128, smem);
;   }
	v_pk_fma_f32 v[34:35], v[34:35], v[38:39], v[42:43]
	v_pk_fma_f32 v[36:37], v[36:37], v[40:41], v[44:45]
	flat_store_dwordx4 v[62:63], v[34:37] offset:192
	s_nop 1
	v_add_u32_e32 v34, 0x60, v116
	v_min_i32_e32 v0, 0x8000, v34
	v_cmp_gt_i32_e32 vcc, s58, v34
	v_ashrrev_i32_e32 v40, 12, v0
	v_add_u32_e32 v0, 0xffff8060, v116
	v_ashrrev_i32_e32 v35, 31, v34
	v_cndmask_b32_e32 v37, 0, v35, vcc
	v_cndmask_b32_e32 v36, v0, v34, vcc
	v_cndmask_b32_e32 v39, v118, v119, vcc
	v_cndmask_b32_e32 v38, v120, v121, vcc
	v_lshlrev_b64 v[36:37], 12, v[36:37]
	v_lshl_add_u64 v[36:37], v[38:39], 0, v[36:37]
	v_lshlrev_b64 v[34:35], 12, v[34:35]
	v_lshlrev_b64 v[38:39], 12, v[0:1]
	v_lshl_add_u64 v[34:35], s[48:49], 0, v[34:35]
	v_lshl_add_u64 v[38:39], s[94:95], 0, v[38:39]
	v_cndmask_b32_e32 v35, v39, v35, vcc
	v_cndmask_b32_e32 v34, v38, v34, vcc
	v_mul_hi_i32_i24_e32 v39, 0x6000, v40
	v_mul_i32_i24_e32 v38, 0x6000, v40
	v_lshl_add_u64 v[38:39], s[82:83], 0, v[38:39]
	v_lshl_add_u64 v[42:43], v[38:39], 0, v[114:115]
	v_lshl_add_u64 v[44:45], v[36:37], 0, v[114:115]
	v_lshl_add_u64 v[46:47], v[34:35], 0, v[114:115]
	flat_load_dwordx4 v[34:37], v[42:43]
	flat_load_dwordx4 v[38:41], v[44:45]
	s_waitcnt vmcnt(0) lgkmcnt(0)
	v_pk_fma_f32 v[30:31], v[30:31], v[34:35], v[38:39]
	v_pk_fma_f32 v[32:33], v[32:33], v[36:37], v[40:41]
	flat_store_dwordx4 v[46:47], v[30:33]
	flat_load_dwordx4 v[30:33], v[42:43] offset:64
	s_nop 0
	flat_load_dwordx4 v[34:37], v[44:45] offset:64
	s_waitcnt vmcnt(0) lgkmcnt(0)
	v_pk_fma_f32 v[26:27], v[26:27], v[30:31], v[34:35]
	v_pk_fma_f32 v[28:29], v[28:29], v[32:33], v[36:37]
	flat_store_dwordx4 v[46:47], v[26:29] offset:64
	flat_load_dwordx4 v[26:29], v[42:43] offset:128
	s_nop 0
	flat_load_dwordx4 v[30:33], v[44:45] offset:128
	s_waitcnt vmcnt(0) lgkmcnt(0)
	v_pk_fma_f32 v[22:23], v[22:23], v[26:27], v[30:31]
	v_pk_fma_f32 v[24:25], v[24:25], v[28:29], v[32:33]
	flat_store_dwordx4 v[46:47], v[22:25] offset:128
	flat_load_dwordx4 v[22:25], v[42:43] offset:192
	s_nop 0
	flat_load_dwordx4 v[26:29], v[44:45] offset:192
	s_waitcnt vmcnt(0) lgkmcnt(0)
	v_pk_fma_f32 v[18:19], v[18:19], v[22:23], v[26:27]
	v_pk_fma_f32 v[20:21], v[20:21], v[24:25], v[28:29]
	flat_store_dwordx4 v[46:47], v[18:21] offset:192
	s_nop 1
	v_add_u32_e32 v18, 0x70, v116
	v_min_i32_e32 v0, 0x8000, v18
	v_cmp_gt_i32_e32 vcc, s58, v18
	v_ashrrev_i32_e32 v24, 12, v0
	v_add_u32_e32 v0, 0xffff8070, v116
	v_ashrrev_i32_e32 v19, 31, v18
	v_cndmask_b32_e32 v21, 0, v19, vcc
	v_cndmask_b32_e32 v20, v0, v18, vcc
	v_cndmask_b32_e32 v23, v118, v119, vcc
	v_cndmask_b32_e32 v22, v120, v121, vcc
	v_lshlrev_b64 v[20:21], 12, v[20:21]
	v_lshl_add_u64 v[20:21], v[22:23], 0, v[20:21]
	v_lshlrev_b64 v[18:19], 12, v[18:19]
	v_lshlrev_b64 v[22:23], 12, v[0:1]
	v_lshl_add_u64 v[18:19], s[48:49], 0, v[18:19]
	v_lshl_add_u64 v[22:23], s[94:95], 0, v[22:23]
	v_cndmask_b32_e32 v19, v23, v19, vcc
	v_cndmask_b32_e32 v18, v22, v18, vcc
	v_mul_hi_i32_i24_e32 v23, 0x6000, v24
	v_mul_i32_i24_e32 v22, 0x6000, v24
	v_lshl_add_u64 v[22:23], s[82:83], 0, v[22:23]
	v_lshl_add_u64 v[26:27], v[22:23], 0, v[114:115]
	v_lshl_add_u64 v[28:29], v[20:21], 0, v[114:115]
	v_lshl_add_u64 v[30:31], v[18:19], 0, v[114:115]
	flat_load_dwordx4 v[18:21], v[26:27]
	flat_load_dwordx4 v[22:25], v[28:29]
	s_waitcnt vmcnt(0) lgkmcnt(0)
	v_pk_fma_f32 v[14:15], v[14:15], v[18:19], v[22:23]
	v_pk_fma_f32 v[16:17], v[16:17], v[20:21], v[24:25]
	flat_store_dwordx4 v[30:31], v[14:17]
	flat_load_dwordx4 v[14:17], v[26:27] offset:64
	s_nop 0
	flat_load_dwordx4 v[18:21], v[28:29] offset:64
	s_waitcnt vmcnt(0) lgkmcnt(0)
	v_pk_fma_f32 v[2:3], v[2:3], v[14:15], v[18:19]
	v_pk_fma_f32 v[4:5], v[4:5], v[16:17], v[20:21]
	flat_store_dwordx4 v[30:31], v[2:5] offset:64
	flat_load_dwordx4 v[2:5], v[26:27] offset:128
	s_nop 0
	flat_load_dwordx4 v[14:17], v[28:29] offset:128
	s_waitcnt vmcnt(0) lgkmcnt(0)
	v_pk_fma_f32 v[2:3], v[6:7], v[2:3], v[14:15]
	v_pk_fma_f32 v[4:5], v[8:9], v[4:5], v[16:17]
	flat_store_dwordx4 v[30:31], v[2:5] offset:128
	flat_load_dwordx4 v[2:5], v[26:27] offset:192
	s_nop 0
	flat_load_dwordx4 v[6:9], v[28:29] offset:192
	s_waitcnt vmcnt(0) lgkmcnt(0)
	v_pk_fma_f32 v[2:3], v[10:11], v[2:3], v[6:7]
	v_pk_fma_f32 v[4:5], v[12:13], v[4:5], v[8:9]
	flat_store_dwordx4 v[30:31], v[2:5] offset:192
	s_add_i32 s7, s7, 1
	s_mul_i32 s0, s7, s39
	s_add_i32 s0, s0, s5
	s_cmpk_gt_i32 s0, 0x7f
	s_cbranch_scc0 .LBB0_961

; template <int MI, int NI>
; DI void gemm256(f32x4 (&acc)[MI][NI], const u16* __restrict__ A, int lda, const u16* __restrict__ Bt, int ldb, int K, int m0, int n0, char* smem) {
;     ...
;   for (int kt = 0; kt < nk; ++kt) {
;     if (kt + 1 < nk) asm volatile("s_waitcnt vmcnt(%0) lgkmcnt(0)" :: "n"(LPS) : "memory");
;     else asm volatile("s_waitcnt vmcnt(0) lgkmcnt(0)" ::: "memory");
;     __builtin_amdgcn_s_barrier();
;     __builtin_amdgcn_s_setprio(1);
;     const char* sb = smem + st * STAGE + foff;
;     bf16x8 af[MI], bfr[NI];
; #pragma unroll
;     for (int mi = 0; mi < MI; ++mi) af[mi] = *(const bf16x8*)(sb + (wr * MI + mi) * 1024);
; #pragma unroll
;     for (int ni = 0; ni < NI; ++ni) bfr[ni] = *(const bf16x8*)(sb + ABYTES + (wc * NI + ni) * 1024);
;     __builtin_amdgcn_sched_barrier(0x0);
;     if (kt + 2 < nk) { const int s2 = st >= 1 ? st - 1 : 2; G256_ISSUE(s2, (kt + 2) * 32); }
;     __builtin_amdgcn_s_setprio(0);
; #pragma unroll
;     for (int mi = 0; mi < MI; ++mi)
; #pragma unroll
;       for (int ni = 0; ni < NI; ++ni)
;         acc[mi][ni] = __builtin_amdgcn_mfma_f32_16x16x32_bf16(bfr[ni], af[mi], acc[mi][ni], 0, 0, 0);
;     st = st == 2 ? 0 : st + 1;
;   }
; DI void phase_resid(const Params& p, const u16* A, int K, const u16* Bt, const float* gate  ,
;                     const float* xl_in, const float* xc_in, float* xl_out, float* xc_out, int Mout, char* smem) {
;     ...
;     for (int t = blk__; t < (NTC / 64) * 16; t += gridDim.x) {
;       const int tm = t >> 4, tn = t & 15;
;       resid_tile<2, 2>(A, K, Bt, gate, xl_in, xc_in, xl_out, xc_out, NTL + tm * 64, tn * 64, smem);
;     }
.LBB0_967:
	s_waitcnt vmcnt(2) lgkmcnt(0)
	s_barrier
	s_setprio 1
	s_lshl_b32 s10, s9, 13
	v_or_b32_e32 v0, s10, v24
	v_add_u32_e32 v28, v0, v26
	v_add_u32_e32 v32, v0, v25
	v_add_u32_e32 v0, v0, v23
	ds_read_b128 v[28:31], v28
	ds_read_b128 v[32:35], v32
	ds_read_b128 v[36:39], v0 offset:4096
	ds_read_b128 v[40:43], v0 offset:5120
	s_addk_i32 s10, 0xe000
	s_cmp_gt_i32 s9, 0
	s_cselect_b32 s10, s10, 0x4000
	v_add_u32_e32 v0, s10, v27
	v_add_u32_e32 v52, 0x1000, v0
	v_lshl_add_u64 v[48:49], v[18:19], 0, s[0:1]
	v_lshl_add_u64 v[48:49], v[48:49], 0, s[0:1]
	v_readfirstlane_b32 s10, v0
	v_lshl_add_u64 v[44:45], v[20:21], 0, s[0:1]
	v_lshl_add_u64 v[44:45], v[44:45], 0, s[0:1]
	s_mov_b64 s[98:99], 0x47e1100
	v_lshl_add_u64 v[50:51], v[48:49], 0, s[98:99]
	s_mov_b32 m0, s10
	v_readfirstlane_b32 s10, v52
	s_mov_b64 s[98:99], 0x2061100
	v_lshl_add_u64 v[46:47], v[44:45], 0, s[98:99]
	global_load_lds_dwordx4 v[50:51], off
	s_mov_b32 m0, s10
	s_nop 0
	global_load_lds_dwordx4 v[46:47], off
	s_setprio 0
	s_waitcnt lgkmcnt(0)
	v_mfma_f32_16x16x32_bf16 v[14:17], v[36:39], v[28:31], v[14:17]
	s_add_i32 s10, s9, 1
	s_waitcnt vmcnt(2) lgkmcnt(0)
	s_cmp_lg_u32 s9, 2
	v_mfma_f32_16x16x32_bf16 v[10:13], v[40:43], v[28:31], v[10:13]
	s_cselect_b32 s9, s10, 0
	s_barrier
	v_mfma_f32_16x16x32_bf16 v[2:5], v[36:39], v[32:35], v[2:5]
	v_mfma_f32_16x16x32_bf16 v[6:9], v[40:43], v[32:35], v[6:9]
	s_setprio 1
	s_lshl_b32 s10, s9, 13
	v_or_b32_e32 v0, s10, v24
	v_add_u32_e32 v28, v0, v26
	v_add_u32_e32 v32, v0, v25
	v_add_u32_e32 v0, v0, v23
	ds_read_b128 v[28:31], v28
	ds_read_b128 v[32:35], v32
	ds_read_b128 v[36:39], v0 offset:4096
	ds_read_b128 v[40:43], v0 offset:5120
	s_addk_i32 s10, 0xe000
	s_cmp_gt_i32 s9, 0
	s_cselect_b32 s10, s10, 0x4000
	v_add_u32_e32 v0, s10, v27
	s_mov_b64 s[10:11], 0x20610c0
	v_add_u32_e32 v52, 0x1000, v0
	s_mov_b64 s[98:99], 0x2061180
	v_lshl_add_u64 v[46:47], v[44:45], 0, s[98:99]
	v_readfirstlane_b32 s10, v0
	s_mov_b64 s[98:99], 0x47e1180
	v_lshl_add_u64 v[50:51], v[48:49], 0, s[98:99]
	s_mov_b32 m0, s10
	v_readfirstlane_b32 s10, v52
	global_load_lds_dwordx4 v[50:51], off
	s_mov_b32 m0, s10
	s_nop 0
	global_load_lds_dwordx4 v[46:47], off
	s_setprio 0
	s_waitcnt lgkmcnt(0)
	v_mfma_f32_16x16x32_bf16 v[14:17], v[36:39], v[28:31], v[14:17]
	s_add_i32 s10, s9, 1
	s_waitcnt vmcnt(2) lgkmcnt(0)
	s_cmp_lg_u32 s9, 2
	v_mfma_f32_16x16x32_bf16 v[10:13], v[40:43], v[28:31], v[10:13]
	s_cselect_b32 s9, s10, 0
	s_barrier
	v_mfma_f32_16x16x32_bf16 v[2:5], v[36:39], v[32:35], v[2:5]
	v_mfma_f32_16x16x32_bf16 v[6:9], v[40:43], v[32:35], v[6:9]
	s_setprio 1
	s_lshl_b32 s10, s9, 13
	v_or_b32_e32 v0, s10, v24
	v_add_u32_e32 v28, v0, v26
	v_add_u32_e32 v32, v0, v25
	v_add_u32_e32 v0, v0, v23
	ds_read_b128 v[28:31], v28
	ds_read_b128 v[32:35], v32
	ds_read_b128 v[36:39], v0 offset:4096
	ds_read_b128 v[40:43], v0 offset:5120
	s_addk_i32 s10, 0xe000
	s_cmp_gt_i32 s9, 0
	s_cselect_b32 s10, s10, 0x4000
	v_add_u32_e32 v0, s10, v27
	s_mov_b64 s[10:11], 0x2061100
	v_add_u32_e32 v50, 0x1000, v0
	s_mov_b64 s[98:99], 0x2061200
	v_lshl_add_u64 v[44:45], v[44:45], 0, s[98:99]
	v_readfirstlane_b32 s10, v0
	s_mov_b64 s[98:99], 0x47e1200
	v_lshl_add_u64 v[46:47], v[48:49], 0, s[98:99]
	s_mov_b32 m0, s10
	v_readfirstlane_b32 s10, v50
	global_load_lds_dwordx4 v[46:47], off
	s_mov_b32 m0, s10
	s_nop 0
	global_load_lds_dwordx4 v[44:45], off
	s_setprio 0
	s_add_i32 s10, s9, 1
	s_waitcnt lgkmcnt(0)
	v_mfma_f32_16x16x32_bf16 v[14:17], v[36:39], v[28:31], v[14:17]
	s_cmp_lg_u32 s9, 2
	s_cselect_b32 s9, s10, 0
	s_add_u32 s0, s0, 0xc0
	v_mfma_f32_16x16x32_bf16 v[10:13], v[40:43], v[28:31], v[10:13]
	s_addc_u32 s1, s1, 0
	s_cmpk_eq_i32 s0, 0x1f80
	v_mfma_f32_16x16x32_bf16 v[2:5], v[36:39], v[32:35], v[2:5]
	v_mfma_f32_16x16x32_bf16 v[6:9], v[40:43], v[32:35], v[6:9]
	s_cbranch_scc0 .LBB0_967
	s_waitcnt vmcnt(2) lgkmcnt(0)
	s_barrier
	s_setprio 1
	s_lshl_b32 s0, s9, 13
	v_or_b32_e32 v0, s0, v24
	v_add_u32_e32 v18, v0, v26
	v_add_u32_e32 v27, v0, v25
	v_add_u32_e32 v0, v0, v23
	ds_read_b128 v[18:21], v18
	ds_read_b128 v[28:31], v27
	ds_read_b128 v[32:35], v0 offset:4096
	ds_read_b128 v[36:39], v0 offset:5120
	v_bfe_u32 v0, v22, 6, 1
	s_setprio 0
	s_waitcnt vmcnt(0) lgkmcnt(0)
	s_waitcnt lgkmcnt(1)
	v_mfma_f32_16x16x32_bf16 v[14:17], v[32:35], v[18:21], v[14:17]
	v_ashrrev_i32_e32 v40, 7, v22
	v_and_b32_e32 v41, 15, v22
	v_bfe_u32 v22, v22, 4, 2
	s_waitcnt lgkmcnt(0)
	v_mfma_f32_16x16x32_bf16 v[10:13], v[36:39], v[18:21], v[10:13]
	s_barrier
; template <int MI, int NI>
; DI void gemm256(f32x4 (&acc)[MI][NI], const u16* __restrict__ A, int lda, const u16* __restrict__ Bt, int ldb, int K, int m0, int n0, char* smem) {
;     ...
; #pragma unroll
;     for (int mi = 0; mi < MI; ++mi)
; #pragma unroll
;       for (int ni = 0; ni < NI; ++ni)
;         acc[mi][ni] = __builtin_amdgcn_mfma_f32_16x16x32_bf16(bfr[ni], af[mi], acc[mi][ni], 0, 0, 0);
;     st = st == 2 ? 0 : st + 1;
;   }
;   asm volatile("s_waitcnt lgkmcnt(0)" ::: "memory");
;   __builtin_amdgcn_s_barrier();
; template <int MI, int NI>
; DI void resid_tile(const u16* A, int K, const u16* Bt, const float* gate, const float* xl_in, const float* xc_in, float* xl_out, float* xc_out,
;                    int m0, int n0, char* smem) {
;     ...
; #pragma unroll
;   for (int mi = 0; mi < MI; ++mi) {
;     const int m = m0 + wr * 16 * MI + mi * 16 + lr;
;     const int b9 = m < NTL ? m >> 12 : 8;
;     const float* xi = xrow(xl_in, xc_in, m);
;     float* xo = m < NTL ? xl_out + (size_t)m * D : xc_out + (size_t)(m - NTL) * D;
; #pragma unroll
;     for (int ni = 0; ni < NI; ++ni) {
;       const int n = n0 + wc * 16 * NI + ni * 16 + lq * 4;
;       const float4 g = *(const float4*)(gate + (size_t)b9 * 6144 + n);
;       const float4 xv = *(const float4*)(xi + n);
;       float4 ov;
;       ov.x = xv.x + g.x * acc[mi][ni][0]; ov.y = xv.y + g.y * acc[mi][ni][1]; ov.z = xv.z + g.z * acc[mi][ni][2]; ov.w = xv.w + g.w * acc[mi][ni][3];
;       *(float4*)(xo + n) = ov;
;     }
;     __builtin_amdgcn_sched_barrier(0);
;   }
	v_mfma_f32_16x16x32_bf16 v[2:5], v[32:35], v[28:31], v[2:5]
	v_mfma_f32_16x16x32_bf16 v[18:21], v[36:39], v[28:31], v[6:9]
	s_setprio 1
	s_addk_i32 s0, 0x2000
	s_cmp_lg_u32 s9, 2
	s_cselect_b32 s0, s0, 0
	v_or_b32_e32 v28, s0, v24
	v_add_u32_e32 v6, v28, v26
	v_add_u32_e32 v24, v28, v25
	v_add_u32_e32 v23, v28, v23
	ds_read_b128 v[6:9], v6
	ds_read_b128 v[24:27], v24
	ds_read_b128 v[28:31], v23 offset:4096
	ds_read_b128 v[32:35], v23 offset:5120
	s_setprio 0
	s_waitcnt lgkmcnt(1)
	v_mfma_f32_16x16x32_bf16 v[14:17], v[28:31], v[6:9], v[14:17]
	s_waitcnt lgkmcnt(0)
	s_barrier
	s_waitcnt lgkmcnt(0)
	v_mfma_f32_16x16x32_bf16 v[10:13], v[32:35], v[6:9], v[10:13]
	v_mfma_f32_16x16x32_bf16 v[6:9], v[28:31], v[24:27], v[2:5]
	v_lshlrev_b32_e32 v0, 5, v0
	v_mov_b32_e32 v36, s95
	v_mov_b32_e32 v37, s49
	v_mfma_f32_16x16x32_bf16 v[2:5], v[32:35], v[24:27], v[18:21]
	v_mov_b32_e32 v38, s94
	v_mov_b32_e32 v39, s48
	s_nop 0
	v_lshlrev_b32_e32 v18, 5, v40
	v_add3_u32 v26, v41, s8, v18
	v_lshlrev_b32_e32 v18, 2, v22
	v_add3_u32 v18, v18, s7, v0
	v_min_i32_e32 v0, 0x8000, v26
	v_cmp_gt_i32_e32 vcc, s58, v26
	v_ashrrev_i32_e32 v28, 12, v0
	v_add_u32_e32 v0, 0xffff8000, v26
	v_ashrrev_i32_e32 v27, 31, v26
	v_cndmask_b32_e32 v21, 0, v27, vcc
	v_cndmask_b32_e32 v20, v0, v26, vcc
	v_cndmask_b32_e32 v23, v36, v37, vcc
	v_cndmask_b32_e32 v22, v38, v39, vcc
	v_lshlrev_b64 v[20:21], 12, v[20:21]
	v_lshl_add_u64 v[20:21], v[22:23], 0, v[20:21]
	v_lshlrev_b64 v[22:23], 12, v[26:27]
	v_lshlrev_b64 v[24:25], 12, v[0:1]
	v_lshl_add_u64 v[22:23], s[48:49], 0, v[22:23]
	v_lshl_add_u64 v[24:25], s[94:95], 0, v[24:25]
	v_ashrrev_i32_e32 v19, 31, v18
	v_cndmask_b32_e32 v23, v25, v23, vcc
	v_cndmask_b32_e32 v22, v24, v22, vcc
	v_mul_hi_i32_i24_e32 v25, 0x6000, v28
	v_mul_i32_i24_e32 v24, 0x6000, v28
	v_lshl_add_u64 v[24:25], s[82:83], 0, v[24:25]
	v_lshlrev_b64 v[28:29], 2, v[18:19]
	v_lshl_add_u64 v[30:31], v[24:25], 0, v[28:29]
	v_lshl_add_u64 v[32:33], v[20:21], 0, v[28:29]
	v_lshl_add_u64 v[34:35], v[22:23], 0, v[28:29]
	flat_load_dwordx4 v[18:21], v[30:31]
	flat_load_dwordx4 v[22:25], v[32:33]
	s_waitcnt vmcnt(0) lgkmcnt(0)
	v_pk_fma_f32 v[14:15], v[14:15], v[18:19], v[22:23]
	v_pk_fma_f32 v[16:17], v[16:17], v[20:21], v[24:25]
	flat_store_dwordx4 v[34:35], v[14:17]
	flat_load_dwordx4 v[14:17], v[30:31] offset:64
	s_nop 0
	flat_load_dwordx4 v[18:21], v[32:33] offset:64
	s_waitcnt vmcnt(0) lgkmcnt(0)
	v_pk_fma_f32 v[10:11], v[10:11], v[14:15], v[18:19]
	v_pk_fma_f32 v[12:13], v[12:13], v[16:17], v[20:21]
	flat_store_dwordx4 v[34:35], v[10:13] offset:64
	s_nop 1
	v_add_u32_e32 v10, 16, v26
	v_min_i32_e32 v0, 0x8000, v10
	v_cmp_gt_i32_e32 vcc, s58, v10
	v_ashrrev_i32_e32 v16, 12, v0
	v_add_u32_e32 v0, 0xffff8010, v26
	v_ashrrev_i32_e32 v11, 31, v10
	v_cndmask_b32_e32 v13, 0, v11, vcc
	v_cndmask_b32_e32 v12, v0, v10, vcc
	v_cndmask_b32_e32 v15, v36, v37, vcc
	v_cndmask_b32_e32 v14, v38, v39, vcc
	v_lshlrev_b64 v[12:13], 12, v[12:13]
	v_lshl_add_u64 v[12:13], v[14:15], 0, v[12:13]
	v_lshlrev_b64 v[10:11], 12, v[10:11]
	v_lshlrev_b64 v[14:15], 12, v[0:1]
	v_lshl_add_u64 v[10:11], s[48:49], 0, v[10:11]
	v_lshl_add_u64 v[14:15], s[94:95], 0, v[14:15]
	v_cndmask_b32_e32 v11, v15, v11, vcc
	v_cndmask_b32_e32 v10, v14, v10, vcc
	v_mul_hi_i32_i24_e32 v15, 0x6000, v16
	v_mul_i32_i24_e32 v14, 0x6000, v16
	v_lshl_add_u64 v[14:15], s[82:83], 0, v[14:15]
	v_lshl_add_u64 v[18:19], v[14:15], 0, v[28:29]
	v_lshl_add_u64 v[20:21], v[12:13], 0, v[28:29]
	v_lshl_add_u64 v[22:23], v[10:11], 0, v[28:29]
	flat_load_dwordx4 v[10:13], v[18:19]
	flat_load_dwordx4 v[14:17], v[20:21]
	s_waitcnt vmcnt(0) lgkmcnt(0)
	v_pk_fma_f32 v[6:7], v[6:7], v[10:11], v[14:15]
	v_pk_fma_f32 v[8:9], v[8:9], v[12:13], v[16:17]
	flat_store_dwordx4 v[22:23], v[6:9]
	flat_load_dwordx4 v[6:9], v[18:19] offset:64
	s_nop 0
	flat_load_dwordx4 v[10:13], v[20:21] offset:64
	s_waitcnt vmcnt(0) lgkmcnt(0)
	v_pk_fma_f32 v[2:3], v[2:3], v[6:7], v[10:11]
	v_pk_fma_f32 v[4:5], v[4:5], v[8:9], v[12:13]
	flat_store_dwordx4 v[22:23], v[2:5] offset:64
	s_add_i32 s4, s4, s79
	s_add_i32 s5, s5, s40
	s_add_i32 s6, s6, s41
	s_cmpk_gt_i32 s4, 0x1ff
	s_cbranch_scc0 .LBB0_966
